# lean hand-pipelined row-pass loops for P3, P10, P13 (two-row batches, loads two batches ahead, packed f32, DPP wave_sum)
# speedup vs baseline: 1.0082x; 1.0082x over previous
;     __device__ __forceinline__ const float* in(int i) const { return karg_in(i); }
; __device__ __forceinline__ const float* xrow_ptr(const Ctx& C, int row) { return row < MPROMPT ? C.in(0) + (size_t)row * DM : C.in(1) + (size_t)(row - MPROMPT) * DM; }
; __device__ __forceinline__ v4f ld4_bf16(const bf16* p) { const v2u w = *(const v2u*)p; return (v4f){bf_lo(w.x), bf_hi(w.x), bf_lo(w.y), bf_hi(w.y)}; }
; __device__ __forceinline__ float ssq4(v4f v) { return (v.x * v.x + v.y * v.y) + (v.z * v.z + v.w * v.w); }
; #define FTID const int ftid_ = fresh_tid()
; template <int R, bool BASE_F32, bool OUT_F32>
; __device__ __forceinline__ void rows_res(const Ctx& C, int m0, int stride, int mx, const float* gpost, float scale, int lane) {
;     v4f d[R][4], b[R][4]; int mr[R]; bool ok[R]; float r1[R];
;     const bf16* D = C.D(); bf16* XN = C.XN();
; #pragma unroll
;     for (int r = 0; r < R; ++r) { mr[r] = (r == 4) ? mx : m0 + r * stride; ok[r] = (r == 4) ? (mx < M) : (mr[r] < MPROMPT); const int mm = ok[r] ? mr[r] : 0;
; #pragma unroll
;         for (int j = 0; j < 4; ++j) d[r][j] = ld4_bf16(D + (size_t)mm * DM + 4 * lane + 256 * j);
;         if (BASE_F32) { const float* x = xrow_ptr(C, mm);
; #pragma unroll
;             for (int j = 0; j < 4; ++j) b[r][j] = ld4_f32(x + 4 * lane + 256 * j);
;         } else { const float inv = C.RS()[mm];
; #pragma unroll
;             for (int j = 0; j < 4; ++j) b[r][j] = ld4_bf16(XN + (size_t)mm * DM + 4 * lane + 256 * j) * inv;
;         } }
; #pragma unroll
;     for (int r = 0; r < R; ++r) { float s = 0.f;
; #pragma unroll
;         for (int j = 0; j < 4; ++j) s += ssq4(d[r][j]);
;         r1[r] = s; }
; #pragma unroll
;     for (int r = 0; r < R; ++r) r1[r] = rsqrtf(wave_sum(r1[r]) * (1.f / DM) + EPS) * scale;
; __global__ void __launch_bounds__(NTHREADS, 2) fwd_kernel(Args args) {
;     ...
;     { FTID; const float* gp = C.in(8); { const int gw_ = GWV, ngw_ = NGWV, nit = (MPROMPT + 4 * ngw_ - 1) / (4 * ngw_);
;       for (int it = 0; it < nit - 1; ++it) rows_res<4, false, false>(C, gw_ + 4 * it * ngw_, ngw_, M, gp, 0.5f, LANE);
.LBB0_366:
	s_or_b64 exec, exec, s[6:7]
	s_waitcnt lgkmcnt(0)
	v_mov_b32_e32 v0, v182
	s_mov_b64 s[0:1], s[80:81]
	s_barrier
	s_load_dwordx2 s[14:15], s[0:1], 0x40
	v_readfirstlane_b32 s0, v0
	s_ashr_i32 s47, s0, 6
	v_readlane_b32 s0, v232, 0
	s_add_i32 s42, s47, s0
	v_readlane_b32 s0, v232, 1
	v_and_b32_e32 v189, 63, v0
	v_readlane_b32 s1, v232, 2
	v_lshlrev_b32_e32 v0, 2, v189
	v_mov_b32_e32 v1, 0
	v_cndmask_b32_e64 v2, 0, 1, s[0:1]
	v_cmp_ne_u32_e64 s[6:7], 1, v2
	s_andn2_b64 vcc, exec, s[0:1]
	v_lshlrev_b32_e32 v2, 2, v0
	v_cmp_ne_u32_e64 s[8:9], 0, v189
	v_lshlrev_b32_e32 v0, 1, v0
	s_load_dwordx2 s[98:99], s[80:81], 0x110
	s_load_dwordx2 s[100:101], s[80:81], 0x40
	v_and_b32_e32 v176, 63, v182
	v_lshlrev_b32_e32 v170, 3, v176
	s_lshl_b32 vcc_lo, s42, 11
	v_add_u32_e32 v170, vcc_lo, v170
	v_add_u32_e32 v171, 0x3000000, v170
	v_add_u32_e32 v170, 0x7100000, v170
	v_mov_b32_e32 v173, v171
	s_lshl_b32 vcc_lo, s42, 2
	v_mov_b32_e32 v172, 0x2a80000
	v_add_u32_e32 v172, vcc_lo, v172
	v_mov_b32_e32 v174, v172
	v_lshlrev_b32_e32 v176, 4, v176
	v_mov_b32_e32 v138, 0x358637bd
	s_waitcnt lgkmcnt(0)
	global_load_dwordx4 v[192:195], v176, s[100:101]
	global_load_dwordx4 v[196:199], v176, s[100:101] offset:1024
	global_load_dwordx4 v[200:203], v176, s[100:101] offset:2048
	global_load_dwordx4 v[204:207], v176, s[100:101] offset:3072
	global_load_dword v52, v172, s[98:99]
	global_load_dwordx2 v[20:21], v170, s[98:99]
	global_load_dwordx2 v[22:23], v170, s[98:99] offset:512
	global_load_dwordx2 v[24:25], v170, s[98:99] offset:1024
	global_load_dwordx2 v[26:27], v170, s[98:99] offset:1536
	global_load_dwordx2 v[36:37], v171, s[98:99]
	global_load_dwordx2 v[38:39], v171, s[98:99] offset:512
	global_load_dwordx2 v[40:41], v171, s[98:99] offset:1024
	global_load_dwordx2 v[42:43], v171, s[98:99] offset:1536
	v_add_u32_e32 v170, 0x400000, v170
	v_add_u32_e32 v171, 0x400000, v171
	v_add_u32_e32 v172, 0x2000, v172
	global_load_dword v54, v172, s[98:99]
	global_load_dwordx2 v[28:29], v170, s[98:99]
	global_load_dwordx2 v[30:31], v170, s[98:99] offset:512
	global_load_dwordx2 v[32:33], v170, s[98:99] offset:1024
	global_load_dwordx2 v[34:35], v170, s[98:99] offset:1536
	global_load_dwordx2 v[44:45], v171, s[98:99]
	global_load_dwordx2 v[46:47], v171, s[98:99] offset:512
	global_load_dwordx2 v[48:49], v171, s[98:99] offset:1024
	global_load_dwordx2 v[50:51], v171, s[98:99] offset:1536
	v_add_u32_e32 v170, 0x400000, v170
	v_add_u32_e32 v171, 0x400000, v171
	v_add_u32_e32 v172, 0x2000, v172
	global_load_dword v88, v172, s[98:99]
	global_load_dwordx2 v[56:57], v170, s[98:99]
	global_load_dwordx2 v[58:59], v170, s[98:99] offset:512
	global_load_dwordx2 v[60:61], v170, s[98:99] offset:1024
	global_load_dwordx2 v[62:63], v170, s[98:99] offset:1536
	global_load_dwordx2 v[72:73], v171, s[98:99]
	global_load_dwordx2 v[74:75], v171, s[98:99] offset:512
	global_load_dwordx2 v[76:77], v171, s[98:99] offset:1024
	global_load_dwordx2 v[78:79], v171, s[98:99] offset:1536
	v_add_u32_e32 v170, 0x400000, v170
	v_add_u32_e32 v171, 0x400000, v171
	v_add_u32_e32 v172, 0x2000, v172
	global_load_dword v90, v172, s[98:99]
	global_load_dwordx2 v[64:65], v170, s[98:99]
	global_load_dwordx2 v[66:67], v170, s[98:99] offset:512
	global_load_dwordx2 v[68:69], v170, s[98:99] offset:1024
	global_load_dwordx2 v[70:71], v170, s[98:99] offset:1536
	global_load_dwordx2 v[80:81], v171, s[98:99]
	global_load_dwordx2 v[82:83], v171, s[98:99] offset:512
	global_load_dwordx2 v[84:85], v171, s[98:99] offset:1024
	global_load_dwordx2 v[86:87], v171, s[98:99] offset:1536
	v_add_u32_e32 v170, 0x400000, v170
	v_add_u32_e32 v171, 0x400000, v171
	v_add_u32_e32 v172, 0x2000, v172
	s_waitcnt vmcnt(31)
	v_lshlrev_b32_e32 v96, 16, v20
	v_and_b32_e32 v97, 0xffff0000, v20
	v_lshlrev_b32_e32 v98, 16, v21
	v_and_b32_e32 v99, 0xffff0000, v21
	v_lshlrev_b32_e32 v100, 16, v22
	v_and_b32_e32 v101, 0xffff0000, v22
	v_lshlrev_b32_e32 v102, 16, v23
	v_and_b32_e32 v103, 0xffff0000, v23
	v_lshlrev_b32_e32 v104, 16, v24
	v_and_b32_e32 v105, 0xffff0000, v24
	v_lshlrev_b32_e32 v106, 16, v25
	v_and_b32_e32 v107, 0xffff0000, v25
	v_lshlrev_b32_e32 v108, 16, v26
	v_and_b32_e32 v109, 0xffff0000, v26
	v_lshlrev_b32_e32 v110, 16, v27
	v_and_b32_e32 v111, 0xffff0000, v27
	v_pk_mul_f32 v[128:129], v[96:97], v[96:97]
	v_pk_fma_f32 v[128:129], v[98:99], v[98:99], v[128:129]
	v_pk_fma_f32 v[128:129], v[100:101], v[100:101], v[128:129]
	v_pk_fma_f32 v[128:129], v[102:103], v[102:103], v[128:129]
	v_pk_fma_f32 v[128:129], v[104:105], v[104:105], v[128:129]
	v_pk_fma_f32 v[128:129], v[106:107], v[106:107], v[128:129]
	v_pk_fma_f32 v[128:129], v[108:109], v[108:109], v[128:129]
	v_pk_fma_f32 v[128:129], v[110:111], v[110:111], v[128:129]
	s_nop 0
	v_add_f32_e32 v128, v128, v129
	s_waitcnt vmcnt(22)
; __device__ __forceinline__ float ssq4(v4f v) { return (v.x * v.x + v.y * v.y) + (v.z * v.z + v.w * v.w); }
; __device__ __forceinline__ float wave_sum(float v) {
; #pragma unroll
;     for (int o = 1; o < 64; o <<= 1) v += __shfl_xor(v, o);
;     return v;
; }
; template <int R, bool BASE_F32, bool OUT_F32>
; __device__ __forceinline__ void rows_res(const Ctx& C, int m0, int stride, int mx, const float* gpost, float scale, int lane) {
;     ...
;     for (int r = 0; r < R; ++r) { float s = 0.f;
; #pragma unroll
;         for (int j = 0; j < 4; ++j) s += ssq4(d[r][j]);
;         r1[r] = s; }
; #pragma unroll
;     for (int r = 0; r < R; ++r) r1[r] = rsqrtf(wave_sum(r1[r]) * (1.f / DM) + EPS) * scale;
; #pragma unroll
;     for (int j = 0; j < 4; ++j) { const v4f gp = ld4_f32(gpost + 4 * lane + 256 * j);
; #pragma unroll
;         for (int r = 0; r < R; ++r) d[r][j] = b[r][j] + d[r][j] * r1[r] * gp; }
	v_lshlrev_b32_e32 v112, 16, v28
	v_and_b32_e32 v113, 0xffff0000, v28
	v_lshlrev_b32_e32 v114, 16, v29
	v_and_b32_e32 v115, 0xffff0000, v29
	v_lshlrev_b32_e32 v116, 16, v30
	v_and_b32_e32 v117, 0xffff0000, v30
	v_lshlrev_b32_e32 v118, 16, v31
	v_and_b32_e32 v119, 0xffff0000, v31
	v_lshlrev_b32_e32 v120, 16, v32
	v_and_b32_e32 v121, 0xffff0000, v32
	v_lshlrev_b32_e32 v122, 16, v33
	v_and_b32_e32 v123, 0xffff0000, v33
	v_lshlrev_b32_e32 v124, 16, v34
	v_and_b32_e32 v125, 0xffff0000, v34
	v_lshlrev_b32_e32 v126, 16, v35
	v_and_b32_e32 v127, 0xffff0000, v35
	v_pk_mul_f32 v[130:131], v[112:113], v[112:113]
	v_pk_fma_f32 v[130:131], v[114:115], v[114:115], v[130:131]
	v_pk_fma_f32 v[130:131], v[116:117], v[116:117], v[130:131]
	v_pk_fma_f32 v[130:131], v[118:119], v[118:119], v[130:131]
	v_pk_fma_f32 v[130:131], v[120:121], v[120:121], v[130:131]
	v_pk_fma_f32 v[130:131], v[122:123], v[122:123], v[130:131]
	v_pk_fma_f32 v[130:131], v[124:125], v[124:125], v[130:131]
	v_pk_fma_f32 v[130:131], v[126:127], v[126:127], v[130:131]
	s_nop 0
	v_add_f32_e32 v130, v130, v131
	s_nop 1
	v_add_f32_dpp v128, v128, v128 quad_perm:[1,0,3,2] row_mask:0xf bank_mask:0xf
	v_add_f32_dpp v130, v130, v130 quad_perm:[1,0,3,2] row_mask:0xf bank_mask:0xf
	s_nop 0
	v_add_f32_dpp v128, v128, v128 quad_perm:[2,3,0,1] row_mask:0xf bank_mask:0xf
	v_add_f32_dpp v130, v130, v130 quad_perm:[2,3,0,1] row_mask:0xf bank_mask:0xf
	s_nop 0
	v_add_f32_dpp v128, v128, v128 row_half_mirror row_mask:0xf bank_mask:0xf
	v_add_f32_dpp v130, v130, v130 row_half_mirror row_mask:0xf bank_mask:0xf
	s_nop 0
	v_add_f32_dpp v128, v128, v128 row_mirror row_mask:0xf bank_mask:0xf
	v_add_f32_dpp v130, v130, v130 row_mirror row_mask:0xf bank_mask:0xf
	s_nop 0
	ds_bpermute_b32 v136, v187, v128
	ds_bpermute_b32 v137, v187, v130
	s_waitcnt lgkmcnt(0)
	v_add_f32_e32 v128, v128, v136
	v_add_f32_e32 v130, v130, v137
	ds_bpermute_b32 v136, v188, v128
	ds_bpermute_b32 v137, v188, v130
	s_waitcnt lgkmcnt(0)
	v_add_f32_e32 v128, v128, v136
	v_add_f32_e32 v130, v130, v137
	v_fmamk_f32 v128, v128, 0x3a800000, v138
	v_fmamk_f32 v130, v130, 0x3a800000, v138
	s_nop 0
	v_rsq_f32_e32 v128, v128
	v_rsq_f32_e32 v130, v130
	s_nop 1
	v_mul_f32_e32 v128, 0.5, v128
	v_mul_f32_e32 v130, 0.5, v130
	s_waitcnt vmcnt(18)
	v_pk_mul_f32 v[96:97], v[128:129], v[96:97] op_sel_hi:[0,1]
	v_pk_mul_f32 v[98:99], v[128:129], v[98:99] op_sel_hi:[0,1]
	v_pk_mul_f32 v[100:101], v[128:129], v[100:101] op_sel_hi:[0,1]
	v_pk_mul_f32 v[102:103], v[128:129], v[102:103] op_sel_hi:[0,1]
	v_pk_mul_f32 v[104:105], v[128:129], v[104:105] op_sel_hi:[0,1]
	v_pk_mul_f32 v[106:107], v[128:129], v[106:107] op_sel_hi:[0,1]
	v_pk_mul_f32 v[108:109], v[128:129], v[108:109] op_sel_hi:[0,1]
	v_pk_mul_f32 v[110:111], v[128:129], v[110:111] op_sel_hi:[0,1]
	v_pk_mul_f32 v[96:97], v[96:97], v[192:193]
	v_pk_mul_f32 v[98:99], v[98:99], v[194:195]
	v_pk_mul_f32 v[100:101], v[100:101], v[196:197]
	v_pk_mul_f32 v[102:103], v[102:103], v[198:199]
	v_pk_mul_f32 v[104:105], v[104:105], v[200:201]
	v_pk_mul_f32 v[106:107], v[106:107], v[202:203]
	v_pk_mul_f32 v[108:109], v[108:109], v[204:205]
	v_pk_mul_f32 v[110:111], v[110:111], v[206:207]
	v_lshlrev_b32_e32 v20, 16, v36
	v_and_b32_e32 v21, 0xffff0000, v36
	v_lshlrev_b32_e32 v22, 16, v37
	v_and_b32_e32 v23, 0xffff0000, v37
	v_lshlrev_b32_e32 v24, 16, v38
	v_and_b32_e32 v25, 0xffff0000, v38
	v_lshlrev_b32_e32 v26, 16, v39
	v_and_b32_e32 v27, 0xffff0000, v39
	v_pk_fma_f32 v[96:97], v[52:53], v[20:21], v[96:97] op_sel_hi:[0,1,1]
	v_pk_fma_f32 v[98:99], v[52:53], v[22:23], v[98:99] op_sel_hi:[0,1,1]
	v_pk_fma_f32 v[100:101], v[52:53], v[24:25], v[100:101] op_sel_hi:[0,1,1]
	v_pk_fma_f32 v[102:103], v[52:53], v[26:27], v[102:103] op_sel_hi:[0,1,1]
	v_lshlrev_b32_e32 v20, 16, v40
	v_and_b32_e32 v21, 0xffff0000, v40
	v_lshlrev_b32_e32 v22, 16, v41
	v_and_b32_e32 v23, 0xffff0000, v41
	v_lshlrev_b32_e32 v24, 16, v42
	v_and_b32_e32 v25, 0xffff0000, v42
	v_lshlrev_b32_e32 v26, 16, v43
	v_and_b32_e32 v27, 0xffff0000, v43
	v_pk_fma_f32 v[104:105], v[52:53], v[20:21], v[104:105] op_sel_hi:[0,1,1]
	v_pk_fma_f32 v[106:107], v[52:53], v[22:23], v[106:107] op_sel_hi:[0,1,1]
	v_pk_fma_f32 v[108:109], v[52:53], v[24:25], v[108:109] op_sel_hi:[0,1,1]
	v_pk_fma_f32 v[110:111], v[52:53], v[26:27], v[110:111] op_sel_hi:[0,1,1]
	v_pk_mul_f32 v[132:133], v[96:97], v[96:97]
	v_pk_fma_f32 v[132:133], v[98:99], v[98:99], v[132:133]
	v_pk_fma_f32 v[132:133], v[100:101], v[100:101], v[132:133]
	v_pk_fma_f32 v[132:133], v[102:103], v[102:103], v[132:133]
	v_pk_fma_f32 v[132:133], v[104:105], v[104:105], v[132:133]
	v_pk_fma_f32 v[132:133], v[106:107], v[106:107], v[132:133]
	v_pk_fma_f32 v[132:133], v[108:109], v[108:109], v[132:133]
	v_pk_fma_f32 v[132:133], v[110:111], v[110:111], v[132:133]
	s_nop 0
	v_add_f32_e32 v132, v132, v133
	v_pk_mul_f32 v[112:113], v[130:131], v[112:113] op_sel_hi:[0,1]
	v_pk_mul_f32 v[114:115], v[130:131], v[114:115] op_sel_hi:[0,1]
	v_pk_mul_f32 v[116:117], v[130:131], v[116:117] op_sel_hi:[0,1]
	v_pk_mul_f32 v[118:119], v[130:131], v[118:119] op_sel_hi:[0,1]
	v_pk_mul_f32 v[120:121], v[130:131], v[120:121] op_sel_hi:[0,1]
	v_pk_mul_f32 v[122:123], v[130:131], v[122:123] op_sel_hi:[0,1]
	v_pk_mul_f32 v[124:125], v[130:131], v[124:125] op_sel_hi:[0,1]
	v_pk_mul_f32 v[126:127], v[130:131], v[126:127] op_sel_hi:[0,1]
	v_pk_mul_f32 v[112:113], v[112:113], v[192:193]
	v_pk_mul_f32 v[114:115], v[114:115], v[194:195]
	v_pk_mul_f32 v[116:117], v[116:117], v[196:197]
	v_pk_mul_f32 v[118:119], v[118:119], v[198:199]
	v_pk_mul_f32 v[120:121], v[120:121], v[200:201]
	v_pk_mul_f32 v[122:123], v[122:123], v[202:203]
;     __device__ __forceinline__ float* out() const { return (float*)karg_in(33); }
; __device__ __forceinline__ void st4_bf16(bf16* p, v4f o) { v2u w; w.x = cvt_pk_nv(o.x, o.y); w.y = cvt_pk_nv(o.z, o.w); *(v2u*)p = w; }
; __device__ __forceinline__ float ssq4(v4f v) { return (v.x * v.x + v.y * v.y) + (v.z * v.z + v.w * v.w); }
; template <int R, bool BASE_F32, bool OUT_F32>
; __device__ __forceinline__ void rows_res(const Ctx& C, int m0, int stride, int mx, const float* gpost, float scale, int lane) {
;     ...
;         for (int r = 0; r < R; ++r) d[r][j] = b[r][j] + d[r][j] * r1[r] * gp; }
;     if (OUT_F32) { float* Y = C.out();
; #pragma unroll
;         for (int r = 0; r < R; ++r)
; #pragma unroll
;             for (int j = 0; j < 4; ++j) if (ok[r]) *(v4f*)(Y + (size_t)mr[r] * DM + 4 * lane + 256 * j) = d[r][j];
;     } else { float* rs = C.RS(); float t[R];
; #pragma unroll
;         for (int r = 0; r < R; ++r) { float s = 0.f;
; #pragma unroll
;             for (int j = 0; j < 4; ++j) s += ssq4(d[r][j]);
;             t[r] = s; }
; #pragma unroll
;         for (int r = 0; r < R; ++r) t[r] = wave_sum(t[r]) * (1.f / DM) + EPS;
; #pragma unroll
;         for (int r = 0; r < R; ++r) { const float rstd = rsqrtf(t[r]);
; #pragma unroll
;             for (int j = 0; j < 4; ++j) if (ok[r]) st4_bf16(XN + (size_t)mr[r] * DM + 4 * lane + 256 * j, d[r][j] * rstd);
;             if (lane == 0 && ok[r]) rs[mr[r]] = sqrtf(t[r]); }
	v_pk_mul_f32 v[124:125], v[124:125], v[204:205]
	v_pk_mul_f32 v[126:127], v[126:127], v[206:207]
	v_lshlrev_b32_e32 v28, 16, v44
	v_and_b32_e32 v29, 0xffff0000, v44
	v_lshlrev_b32_e32 v30, 16, v45
	v_and_b32_e32 v31, 0xffff0000, v45
	v_lshlrev_b32_e32 v32, 16, v46
	v_and_b32_e32 v33, 0xffff0000, v46
	v_lshlrev_b32_e32 v34, 16, v47
	v_and_b32_e32 v35, 0xffff0000, v47
	v_pk_fma_f32 v[112:113], v[54:55], v[28:29], v[112:113] op_sel_hi:[0,1,1]
	v_pk_fma_f32 v[114:115], v[54:55], v[30:31], v[114:115] op_sel_hi:[0,1,1]
	v_pk_fma_f32 v[116:117], v[54:55], v[32:33], v[116:117] op_sel_hi:[0,1,1]
	v_pk_fma_f32 v[118:119], v[54:55], v[34:35], v[118:119] op_sel_hi:[0,1,1]
	v_lshlrev_b32_e32 v28, 16, v48
	v_and_b32_e32 v29, 0xffff0000, v48
	v_lshlrev_b32_e32 v30, 16, v49
	v_and_b32_e32 v31, 0xffff0000, v49
	v_lshlrev_b32_e32 v32, 16, v50
	v_and_b32_e32 v33, 0xffff0000, v50
	v_lshlrev_b32_e32 v34, 16, v51
	v_and_b32_e32 v35, 0xffff0000, v51
	v_pk_fma_f32 v[120:121], v[54:55], v[28:29], v[120:121] op_sel_hi:[0,1,1]
	v_pk_fma_f32 v[122:123], v[54:55], v[30:31], v[122:123] op_sel_hi:[0,1,1]
	v_pk_fma_f32 v[124:125], v[54:55], v[32:33], v[124:125] op_sel_hi:[0,1,1]
	v_pk_fma_f32 v[126:127], v[54:55], v[34:35], v[126:127] op_sel_hi:[0,1,1]
	v_pk_mul_f32 v[134:135], v[112:113], v[112:113]
	v_pk_fma_f32 v[134:135], v[114:115], v[114:115], v[134:135]
	v_pk_fma_f32 v[134:135], v[116:117], v[116:117], v[134:135]
	v_pk_fma_f32 v[134:135], v[118:119], v[118:119], v[134:135]
	v_pk_fma_f32 v[134:135], v[120:121], v[120:121], v[134:135]
	v_pk_fma_f32 v[134:135], v[122:123], v[122:123], v[134:135]
	v_pk_fma_f32 v[134:135], v[124:125], v[124:125], v[134:135]
	v_pk_fma_f32 v[134:135], v[126:127], v[126:127], v[134:135]
	s_nop 0
	v_add_f32_e32 v134, v134, v135
	s_nop 1
	v_add_f32_dpp v132, v132, v132 quad_perm:[1,0,3,2] row_mask:0xf bank_mask:0xf
	v_add_f32_dpp v134, v134, v134 quad_perm:[1,0,3,2] row_mask:0xf bank_mask:0xf
	s_nop 0
	v_add_f32_dpp v132, v132, v132 quad_perm:[2,3,0,1] row_mask:0xf bank_mask:0xf
	v_add_f32_dpp v134, v134, v134 quad_perm:[2,3,0,1] row_mask:0xf bank_mask:0xf
	s_nop 0
	v_add_f32_dpp v132, v132, v132 row_half_mirror row_mask:0xf bank_mask:0xf
	v_add_f32_dpp v134, v134, v134 row_half_mirror row_mask:0xf bank_mask:0xf
	s_nop 0
	v_add_f32_dpp v132, v132, v132 row_mirror row_mask:0xf bank_mask:0xf
	v_add_f32_dpp v134, v134, v134 row_mirror row_mask:0xf bank_mask:0xf
	s_nop 0
	ds_bpermute_b32 v136, v187, v132
	ds_bpermute_b32 v137, v187, v134
	s_waitcnt lgkmcnt(0)
	v_add_f32_e32 v132, v132, v136
	v_add_f32_e32 v134, v134, v137
	ds_bpermute_b32 v136, v188, v132
	ds_bpermute_b32 v137, v188, v134
	s_waitcnt lgkmcnt(0)
	v_add_f32_e32 v132, v132, v136
	v_add_f32_e32 v134, v134, v137
	v_fmamk_f32 v164, v132, 0x3a800000, v138
	v_fmamk_f32 v167, v134, 0x3a800000, v138
	s_nop 0
	v_rsq_f32_e32 v132, v164
	v_rsq_f32_e32 v134, v167
	v_sqrt_f32_e32 v165, v164
	v_sqrt_f32_e32 v168, v167
	s_nop 1
	v_pk_mul_f32 v[140:141], v[96:97], v[132:133] op_sel_hi:[1,0]
	v_cvt_pk_bf16_f32 v148, v140, v141
	v_pk_mul_f32 v[142:143], v[98:99], v[132:133] op_sel_hi:[1,0]
	v_cvt_pk_bf16_f32 v149, v142, v143
	v_pk_mul_f32 v[144:145], v[100:101], v[132:133] op_sel_hi:[1,0]
	v_cvt_pk_bf16_f32 v150, v144, v145
	v_pk_mul_f32 v[146:147], v[102:103], v[132:133] op_sel_hi:[1,0]
	v_cvt_pk_bf16_f32 v151, v146, v147
	v_pk_mul_f32 v[140:141], v[104:105], v[132:133] op_sel_hi:[1,0]
	v_cvt_pk_bf16_f32 v152, v140, v141
	v_pk_mul_f32 v[142:143], v[106:107], v[132:133] op_sel_hi:[1,0]
	v_cvt_pk_bf16_f32 v153, v142, v143
	v_pk_mul_f32 v[144:145], v[108:109], v[132:133] op_sel_hi:[1,0]
	v_cvt_pk_bf16_f32 v154, v144, v145
	v_pk_mul_f32 v[146:147], v[110:111], v[132:133] op_sel_hi:[1,0]
	v_cvt_pk_bf16_f32 v155, v146, v147
	global_store_dwordx2 v173, v[148:149], s[98:99]
	global_store_dwordx2 v173, v[150:151], s[98:99] offset:512
	global_store_dwordx2 v173, v[152:153], s[98:99] offset:1024
	global_store_dwordx2 v173, v[154:155], s[98:99] offset:1536
	v_add_u32_e32 v173, 0x400000, v173
	v_pk_mul_f32 v[140:141], v[112:113], v[134:135] op_sel_hi:[1,0]
	v_cvt_pk_bf16_f32 v156, v140, v141
	v_pk_mul_f32 v[142:143], v[114:115], v[134:135] op_sel_hi:[1,0]
	v_cvt_pk_bf16_f32 v157, v142, v143
	v_pk_mul_f32 v[144:145], v[116:117], v[134:135] op_sel_hi:[1,0]
	v_cvt_pk_bf16_f32 v158, v144, v145
	v_pk_mul_f32 v[146:147], v[118:119], v[134:135] op_sel_hi:[1,0]
	v_cvt_pk_bf16_f32 v159, v146, v147
	v_pk_mul_f32 v[140:141], v[120:121], v[134:135] op_sel_hi:[1,0]
	v_cvt_pk_bf16_f32 v160, v140, v141
	v_pk_mul_f32 v[142:143], v[122:123], v[134:135] op_sel_hi:[1,0]
	v_cvt_pk_bf16_f32 v161, v142, v143
	v_pk_mul_f32 v[144:145], v[124:125], v[134:135] op_sel_hi:[1,0]
	v_cvt_pk_bf16_f32 v162, v144, v145
	v_pk_mul_f32 v[146:147], v[126:127], v[134:135] op_sel_hi:[1,0]
	v_cvt_pk_bf16_f32 v163, v146, v147
	global_store_dwordx2 v173, v[156:157], s[98:99]
	global_store_dwordx2 v173, v[158:159], s[98:99] offset:512
	global_store_dwordx2 v173, v[160:161], s[98:99] offset:1024
	global_store_dwordx2 v173, v[162:163], s[98:99] offset:1536
	v_add_u32_e32 v173, 0x400000, v173
	v_add_u32_e32 v166, -1, v165
	v_fma_f32 v140, -v166, v165, v164
	v_cmp_ge_f32_e32 vcc, 0, v140
	v_add_u32_e32 v141, 1, v165
	v_cndmask_b32_e32 v166, v165, v166, vcc
	v_fma_f32 v140, -v141, v165, v164
	v_cmp_lt_f32_e32 vcc, 0, v140
	s_nop 1
	v_cndmask_b32_e32 v165, v166, v141, vcc
	v_add_u32_e32 v169, -1, v168
	v_fma_f32 v142, -v169, v168, v167
	v_cmp_ge_f32_e32 vcc, 0, v142
	v_add_u32_e32 v143, 1, v168
	v_cndmask_b32_e32 v169, v168, v169, vcc
	v_fma_f32 v142, -v143, v168, v167
	v_cmp_lt_f32_e32 vcc, 0, v142
	s_nop 1
	v_cndmask_b32_e32 v168, v169, v143, vcc
	s_mov_b64 exec, 1
	global_store_dword v174, v165, s[98:99]
	v_add_u32_e32 v174, 0x2000, v174
	global_store_dword v174, v168, s[98:99]
	v_add_u32_e32 v174, 0x2000, v174
	s_mov_b64 exec, -1
	global_load_dword v52, v172, s[98:99]
	global_load_dwordx2 v[20:21], v170, s[98:99]
	global_load_dwordx2 v[22:23], v170, s[98:99] offset:512
	global_load_dwordx2 v[24:25], v170, s[98:99] offset:1024
	global_load_dwordx2 v[26:27], v170, s[98:99] offset:1536
	global_load_dwordx2 v[36:37], v171, s[98:99]
	global_load_dwordx2 v[38:39], v171, s[98:99] offset:512
	global_load_dwordx2 v[40:41], v171, s[98:99] offset:1024
	global_load_dwordx2 v[42:43], v171, s[98:99] offset:1536
	v_add_u32_e32 v170, 0x400000, v170
	v_add_u32_e32 v171, 0x400000, v171
	v_add_u32_e32 v172, 0x2000, v172
	global_load_dword v54, v172, s[98:99]
	global_load_dwordx2 v[28:29], v170, s[98:99]
	global_load_dwordx2 v[30:31], v170, s[98:99] offset:512
	global_load_dwordx2 v[32:33], v170, s[98:99] offset:1024
	global_load_dwordx2 v[34:35], v170, s[98:99] offset:1536
	global_load_dwordx2 v[44:45], v171, s[98:99]
	global_load_dwordx2 v[46:47], v171, s[98:99] offset:512
	global_load_dwordx2 v[48:49], v171, s[98:99] offset:1024
	global_load_dwordx2 v[50:51], v171, s[98:99] offset:1536
	v_add_u32_e32 v170, 0x400000, v170
	v_add_u32_e32 v171, 0x400000, v171
	v_add_u32_e32 v172, 0x2000, v172
	s_waitcnt vmcnt(41)
; __device__ __forceinline__ float ssq4(v4f v) { return (v.x * v.x + v.y * v.y) + (v.z * v.z + v.w * v.w); }
; template <int R, bool BASE_F32, bool OUT_F32>
; __device__ __forceinline__ void rows_res(const Ctx& C, int m0, int stride, int mx, const float* gpost, float scale, int lane) {
;     ...
;     for (int r = 0; r < R; ++r) { float s = 0.f;
; #pragma unroll
;         for (int j = 0; j < 4; ++j) s += ssq4(d[r][j]);
;         r1[r] = s; }
; #pragma unroll
;     for (int r = 0; r < R; ++r) r1[r] = rsqrtf(wave_sum(r1[r]) * (1.f / DM) + EPS) * scale;
; #pragma unroll
;     for (int j = 0; j < 4; ++j) { const v4f gp = ld4_f32(gpost + 4 * lane + 256 * j);
; #pragma unroll
;         for (int r = 0; r < R; ++r) d[r][j] = b[r][j] + d[r][j] * r1[r] * gp; }
	v_lshlrev_b32_e32 v96, 16, v56
	v_and_b32_e32 v97, 0xffff0000, v56
	v_lshlrev_b32_e32 v98, 16, v57
	v_and_b32_e32 v99, 0xffff0000, v57
	v_lshlrev_b32_e32 v100, 16, v58
	v_and_b32_e32 v101, 0xffff0000, v58
	v_lshlrev_b32_e32 v102, 16, v59
	v_and_b32_e32 v103, 0xffff0000, v59
	v_lshlrev_b32_e32 v104, 16, v60
	v_and_b32_e32 v105, 0xffff0000, v60
	v_lshlrev_b32_e32 v106, 16, v61
	v_and_b32_e32 v107, 0xffff0000, v61
	v_lshlrev_b32_e32 v108, 16, v62
	v_and_b32_e32 v109, 0xffff0000, v62
	v_lshlrev_b32_e32 v110, 16, v63
	v_and_b32_e32 v111, 0xffff0000, v63
	v_pk_mul_f32 v[128:129], v[96:97], v[96:97]
	v_pk_fma_f32 v[128:129], v[98:99], v[98:99], v[128:129]
	v_pk_fma_f32 v[128:129], v[100:101], v[100:101], v[128:129]
	v_pk_fma_f32 v[128:129], v[102:103], v[102:103], v[128:129]
	v_pk_fma_f32 v[128:129], v[104:105], v[104:105], v[128:129]
	v_pk_fma_f32 v[128:129], v[106:107], v[106:107], v[128:129]
	v_pk_fma_f32 v[128:129], v[108:109], v[108:109], v[128:129]
	v_pk_fma_f32 v[128:129], v[110:111], v[110:111], v[128:129]
	s_nop 0
	v_add_f32_e32 v128, v128, v129
	s_waitcnt vmcnt(32)
	v_lshlrev_b32_e32 v112, 16, v64
	v_and_b32_e32 v113, 0xffff0000, v64
	v_lshlrev_b32_e32 v114, 16, v65
	v_and_b32_e32 v115, 0xffff0000, v65
	v_lshlrev_b32_e32 v116, 16, v66
	v_and_b32_e32 v117, 0xffff0000, v66
	v_lshlrev_b32_e32 v118, 16, v67
	v_and_b32_e32 v119, 0xffff0000, v67
	v_lshlrev_b32_e32 v120, 16, v68
	v_and_b32_e32 v121, 0xffff0000, v68
	v_lshlrev_b32_e32 v122, 16, v69
	v_and_b32_e32 v123, 0xffff0000, v69
	v_lshlrev_b32_e32 v124, 16, v70
	v_and_b32_e32 v125, 0xffff0000, v70
	v_lshlrev_b32_e32 v126, 16, v71
	v_and_b32_e32 v127, 0xffff0000, v71
	v_pk_mul_f32 v[130:131], v[112:113], v[112:113]
	v_pk_fma_f32 v[130:131], v[114:115], v[114:115], v[130:131]
	v_pk_fma_f32 v[130:131], v[116:117], v[116:117], v[130:131]
	v_pk_fma_f32 v[130:131], v[118:119], v[118:119], v[130:131]
	v_pk_fma_f32 v[130:131], v[120:121], v[120:121], v[130:131]
	v_pk_fma_f32 v[130:131], v[122:123], v[122:123], v[130:131]
	v_pk_fma_f32 v[130:131], v[124:125], v[124:125], v[130:131]
	v_pk_fma_f32 v[130:131], v[126:127], v[126:127], v[130:131]
	s_nop 0
	v_add_f32_e32 v130, v130, v131
	s_nop 1
	v_add_f32_dpp v128, v128, v128 quad_perm:[1,0,3,2] row_mask:0xf bank_mask:0xf
	v_add_f32_dpp v130, v130, v130 quad_perm:[1,0,3,2] row_mask:0xf bank_mask:0xf
	s_nop 0
	v_add_f32_dpp v128, v128, v128 quad_perm:[2,3,0,1] row_mask:0xf bank_mask:0xf
	v_add_f32_dpp v130, v130, v130 quad_perm:[2,3,0,1] row_mask:0xf bank_mask:0xf
	s_nop 0
	v_add_f32_dpp v128, v128, v128 row_half_mirror row_mask:0xf bank_mask:0xf
	v_add_f32_dpp v130, v130, v130 row_half_mirror row_mask:0xf bank_mask:0xf
	s_nop 0
	v_add_f32_dpp v128, v128, v128 row_mirror row_mask:0xf bank_mask:0xf
	v_add_f32_dpp v130, v130, v130 row_mirror row_mask:0xf bank_mask:0xf
	s_nop 0
	ds_bpermute_b32 v136, v187, v128
	ds_bpermute_b32 v137, v187, v130
	s_waitcnt lgkmcnt(0)
	v_add_f32_e32 v128, v128, v136
	v_add_f32_e32 v130, v130, v137
	ds_bpermute_b32 v136, v188, v128
	ds_bpermute_b32 v137, v188, v130
	s_waitcnt lgkmcnt(0)
	v_add_f32_e32 v128, v128, v136
	v_add_f32_e32 v130, v130, v137
	v_fmamk_f32 v128, v128, 0x3a800000, v138
	v_fmamk_f32 v130, v130, 0x3a800000, v138
	s_nop 0
	v_rsq_f32_e32 v128, v128
	v_rsq_f32_e32 v130, v130
	s_nop 1
	v_mul_f32_e32 v128, 0.5, v128
	v_mul_f32_e32 v130, 0.5, v130
	s_waitcnt vmcnt(28)
	v_pk_mul_f32 v[96:97], v[128:129], v[96:97] op_sel_hi:[0,1]
	v_pk_mul_f32 v[98:99], v[128:129], v[98:99] op_sel_hi:[0,1]
	v_pk_mul_f32 v[100:101], v[128:129], v[100:101] op_sel_hi:[0,1]
	v_pk_mul_f32 v[102:103], v[128:129], v[102:103] op_sel_hi:[0,1]
	v_pk_mul_f32 v[104:105], v[128:129], v[104:105] op_sel_hi:[0,1]
	v_pk_mul_f32 v[106:107], v[128:129], v[106:107] op_sel_hi:[0,1]
	v_pk_mul_f32 v[108:109], v[128:129], v[108:109] op_sel_hi:[0,1]
	v_pk_mul_f32 v[110:111], v[128:129], v[110:111] op_sel_hi:[0,1]
	v_pk_mul_f32 v[96:97], v[96:97], v[192:193]
	v_pk_mul_f32 v[98:99], v[98:99], v[194:195]
	v_pk_mul_f32 v[100:101], v[100:101], v[196:197]
	v_pk_mul_f32 v[102:103], v[102:103], v[198:199]
	v_pk_mul_f32 v[104:105], v[104:105], v[200:201]
	v_pk_mul_f32 v[106:107], v[106:107], v[202:203]
	v_pk_mul_f32 v[108:109], v[108:109], v[204:205]
	v_pk_mul_f32 v[110:111], v[110:111], v[206:207]
	v_lshlrev_b32_e32 v56, 16, v72
	v_and_b32_e32 v57, 0xffff0000, v72
	v_lshlrev_b32_e32 v58, 16, v73
	v_and_b32_e32 v59, 0xffff0000, v73
	v_lshlrev_b32_e32 v60, 16, v74
	v_and_b32_e32 v61, 0xffff0000, v74
	v_lshlrev_b32_e32 v62, 16, v75
	v_and_b32_e32 v63, 0xffff0000, v75
	v_pk_fma_f32 v[96:97], v[88:89], v[56:57], v[96:97] op_sel_hi:[0,1,1]
	v_pk_fma_f32 v[98:99], v[88:89], v[58:59], v[98:99] op_sel_hi:[0,1,1]
	v_pk_fma_f32 v[100:101], v[88:89], v[60:61], v[100:101] op_sel_hi:[0,1,1]
	v_pk_fma_f32 v[102:103], v[88:89], v[62:63], v[102:103] op_sel_hi:[0,1,1]
	v_lshlrev_b32_e32 v56, 16, v76
	v_and_b32_e32 v57, 0xffff0000, v76
	v_lshlrev_b32_e32 v58, 16, v77
	v_and_b32_e32 v59, 0xffff0000, v77
	v_lshlrev_b32_e32 v60, 16, v78
	v_and_b32_e32 v61, 0xffff0000, v78
	v_lshlrev_b32_e32 v62, 16, v79
	v_and_b32_e32 v63, 0xffff0000, v79
	v_pk_fma_f32 v[104:105], v[88:89], v[56:57], v[104:105] op_sel_hi:[0,1,1]
	v_pk_fma_f32 v[106:107], v[88:89], v[58:59], v[106:107] op_sel_hi:[0,1,1]
	v_pk_fma_f32 v[108:109], v[88:89], v[60:61], v[108:109] op_sel_hi:[0,1,1]
	v_pk_fma_f32 v[110:111], v[88:89], v[62:63], v[110:111] op_sel_hi:[0,1,1]
	v_pk_mul_f32 v[132:133], v[96:97], v[96:97]
	v_pk_fma_f32 v[132:133], v[98:99], v[98:99], v[132:133]
	v_pk_fma_f32 v[132:133], v[100:101], v[100:101], v[132:133]
	v_pk_fma_f32 v[132:133], v[102:103], v[102:103], v[132:133]
;     __device__ __forceinline__ float* out() const { return (float*)karg_in(33); }
; __device__ __forceinline__ void st4_bf16(bf16* p, v4f o) { v2u w; w.x = cvt_pk_nv(o.x, o.y); w.y = cvt_pk_nv(o.z, o.w); *(v2u*)p = w; }
; __device__ __forceinline__ float ssq4(v4f v) { return (v.x * v.x + v.y * v.y) + (v.z * v.z + v.w * v.w); }
; template <int R, bool BASE_F32, bool OUT_F32>
; __device__ __forceinline__ void rows_res(const Ctx& C, int m0, int stride, int mx, const float* gpost, float scale, int lane) {
;     ...
;         for (int r = 0; r < R; ++r) d[r][j] = b[r][j] + d[r][j] * r1[r] * gp; }
;     if (OUT_F32) { float* Y = C.out();
; #pragma unroll
;         for (int r = 0; r < R; ++r)
; #pragma unroll
;             for (int j = 0; j < 4; ++j) if (ok[r]) *(v4f*)(Y + (size_t)mr[r] * DM + 4 * lane + 256 * j) = d[r][j];
;     } else { float* rs = C.RS(); float t[R];
; #pragma unroll
;         for (int r = 0; r < R; ++r) { float s = 0.f;
; #pragma unroll
;             for (int j = 0; j < 4; ++j) s += ssq4(d[r][j]);
;             t[r] = s; }
; #pragma unroll
;         for (int r = 0; r < R; ++r) t[r] = wave_sum(t[r]) * (1.f / DM) + EPS;
; #pragma unroll
;         for (int r = 0; r < R; ++r) { const float rstd = rsqrtf(t[r]);
; #pragma unroll
;             for (int j = 0; j < 4; ++j) if (ok[r]) st4_bf16(XN + (size_t)mr[r] * DM + 4 * lane + 256 * j, d[r][j] * rstd);
;             if (lane == 0 && ok[r]) rs[mr[r]] = sqrtf(t[r]); }
	v_pk_fma_f32 v[132:133], v[104:105], v[104:105], v[132:133]
	v_pk_fma_f32 v[132:133], v[106:107], v[106:107], v[132:133]
	v_pk_fma_f32 v[132:133], v[108:109], v[108:109], v[132:133]
	v_pk_fma_f32 v[132:133], v[110:111], v[110:111], v[132:133]
	s_nop 0
	v_add_f32_e32 v132, v132, v133
	v_pk_mul_f32 v[112:113], v[130:131], v[112:113] op_sel_hi:[0,1]
	v_pk_mul_f32 v[114:115], v[130:131], v[114:115] op_sel_hi:[0,1]
	v_pk_mul_f32 v[116:117], v[130:131], v[116:117] op_sel_hi:[0,1]
	v_pk_mul_f32 v[118:119], v[130:131], v[118:119] op_sel_hi:[0,1]
	v_pk_mul_f32 v[120:121], v[130:131], v[120:121] op_sel_hi:[0,1]
	v_pk_mul_f32 v[122:123], v[130:131], v[122:123] op_sel_hi:[0,1]
	v_pk_mul_f32 v[124:125], v[130:131], v[124:125] op_sel_hi:[0,1]
	v_pk_mul_f32 v[126:127], v[130:131], v[126:127] op_sel_hi:[0,1]
	v_pk_mul_f32 v[112:113], v[112:113], v[192:193]
	v_pk_mul_f32 v[114:115], v[114:115], v[194:195]
	v_pk_mul_f32 v[116:117], v[116:117], v[196:197]
	v_pk_mul_f32 v[118:119], v[118:119], v[198:199]
	v_pk_mul_f32 v[120:121], v[120:121], v[200:201]
	v_pk_mul_f32 v[122:123], v[122:123], v[202:203]
	v_pk_mul_f32 v[124:125], v[124:125], v[204:205]
	v_pk_mul_f32 v[126:127], v[126:127], v[206:207]
	v_lshlrev_b32_e32 v64, 16, v80
	v_and_b32_e32 v65, 0xffff0000, v80
	v_lshlrev_b32_e32 v66, 16, v81
	v_and_b32_e32 v67, 0xffff0000, v81
	v_lshlrev_b32_e32 v68, 16, v82
	v_and_b32_e32 v69, 0xffff0000, v82
	v_lshlrev_b32_e32 v70, 16, v83
	v_and_b32_e32 v71, 0xffff0000, v83
	v_pk_fma_f32 v[112:113], v[90:91], v[64:65], v[112:113] op_sel_hi:[0,1,1]
	v_pk_fma_f32 v[114:115], v[90:91], v[66:67], v[114:115] op_sel_hi:[0,1,1]
	v_pk_fma_f32 v[116:117], v[90:91], v[68:69], v[116:117] op_sel_hi:[0,1,1]
	v_pk_fma_f32 v[118:119], v[90:91], v[70:71], v[118:119] op_sel_hi:[0,1,1]
	v_lshlrev_b32_e32 v64, 16, v84
	v_and_b32_e32 v65, 0xffff0000, v84
	v_lshlrev_b32_e32 v66, 16, v85
	v_and_b32_e32 v67, 0xffff0000, v85
	v_lshlrev_b32_e32 v68, 16, v86
	v_and_b32_e32 v69, 0xffff0000, v86
	v_lshlrev_b32_e32 v70, 16, v87
	v_and_b32_e32 v71, 0xffff0000, v87
	v_pk_fma_f32 v[120:121], v[90:91], v[64:65], v[120:121] op_sel_hi:[0,1,1]
	v_pk_fma_f32 v[122:123], v[90:91], v[66:67], v[122:123] op_sel_hi:[0,1,1]
	v_pk_fma_f32 v[124:125], v[90:91], v[68:69], v[124:125] op_sel_hi:[0,1,1]
	v_pk_fma_f32 v[126:127], v[90:91], v[70:71], v[126:127] op_sel_hi:[0,1,1]
	v_pk_mul_f32 v[134:135], v[112:113], v[112:113]
	v_pk_fma_f32 v[134:135], v[114:115], v[114:115], v[134:135]
	v_pk_fma_f32 v[134:135], v[116:117], v[116:117], v[134:135]
	v_pk_fma_f32 v[134:135], v[118:119], v[118:119], v[134:135]
	v_pk_fma_f32 v[134:135], v[120:121], v[120:121], v[134:135]
	v_pk_fma_f32 v[134:135], v[122:123], v[122:123], v[134:135]
	v_pk_fma_f32 v[134:135], v[124:125], v[124:125], v[134:135]
	v_pk_fma_f32 v[134:135], v[126:127], v[126:127], v[134:135]
	s_nop 0
	v_add_f32_e32 v134, v134, v135
	s_nop 1
	v_add_f32_dpp v132, v132, v132 quad_perm:[1,0,3,2] row_mask:0xf bank_mask:0xf
	v_add_f32_dpp v134, v134, v134 quad_perm:[1,0,3,2] row_mask:0xf bank_mask:0xf
	s_nop 0
	v_add_f32_dpp v132, v132, v132 quad_perm:[2,3,0,1] row_mask:0xf bank_mask:0xf
	v_add_f32_dpp v134, v134, v134 quad_perm:[2,3,0,1] row_mask:0xf bank_mask:0xf
	s_nop 0
	v_add_f32_dpp v132, v132, v132 row_half_mirror row_mask:0xf bank_mask:0xf
	v_add_f32_dpp v134, v134, v134 row_half_mirror row_mask:0xf bank_mask:0xf
	s_nop 0
	v_add_f32_dpp v132, v132, v132 row_mirror row_mask:0xf bank_mask:0xf
	v_add_f32_dpp v134, v134, v134 row_mirror row_mask:0xf bank_mask:0xf
	s_nop 0
	ds_bpermute_b32 v136, v187, v132
	ds_bpermute_b32 v137, v187, v134
	s_waitcnt lgkmcnt(0)
	v_add_f32_e32 v132, v132, v136
	v_add_f32_e32 v134, v134, v137
	ds_bpermute_b32 v136, v188, v132
	ds_bpermute_b32 v137, v188, v134
	s_waitcnt lgkmcnt(0)
	v_add_f32_e32 v132, v132, v136
	v_add_f32_e32 v134, v134, v137
	v_fmamk_f32 v164, v132, 0x3a800000, v138
	v_fmamk_f32 v167, v134, 0x3a800000, v138
	s_nop 0
	v_rsq_f32_e32 v132, v164
	v_rsq_f32_e32 v134, v167
	v_sqrt_f32_e32 v165, v164
	v_sqrt_f32_e32 v168, v167
	s_nop 1
	v_pk_mul_f32 v[140:141], v[96:97], v[132:133] op_sel_hi:[1,0]
	v_cvt_pk_bf16_f32 v148, v140, v141
	v_pk_mul_f32 v[142:143], v[98:99], v[132:133] op_sel_hi:[1,0]
	v_cvt_pk_bf16_f32 v149, v142, v143
	v_pk_mul_f32 v[144:145], v[100:101], v[132:133] op_sel_hi:[1,0]
	v_cvt_pk_bf16_f32 v150, v144, v145
	v_pk_mul_f32 v[146:147], v[102:103], v[132:133] op_sel_hi:[1,0]
	v_cvt_pk_bf16_f32 v151, v146, v147
	v_pk_mul_f32 v[140:141], v[104:105], v[132:133] op_sel_hi:[1,0]
	v_cvt_pk_bf16_f32 v152, v140, v141
	v_pk_mul_f32 v[142:143], v[106:107], v[132:133] op_sel_hi:[1,0]
	v_cvt_pk_bf16_f32 v153, v142, v143
	v_pk_mul_f32 v[144:145], v[108:109], v[132:133] op_sel_hi:[1,0]
	v_cvt_pk_bf16_f32 v154, v144, v145
	v_pk_mul_f32 v[146:147], v[110:111], v[132:133] op_sel_hi:[1,0]
	v_cvt_pk_bf16_f32 v155, v146, v147
	global_store_dwordx2 v173, v[148:149], s[98:99]
	global_store_dwordx2 v173, v[150:151], s[98:99] offset:512
	global_store_dwordx2 v173, v[152:153], s[98:99] offset:1024
	global_store_dwordx2 v173, v[154:155], s[98:99] offset:1536
	v_add_u32_e32 v173, 0x400000, v173
	v_pk_mul_f32 v[140:141], v[112:113], v[134:135] op_sel_hi:[1,0]
	v_cvt_pk_bf16_f32 v156, v140, v141
	v_pk_mul_f32 v[142:143], v[114:115], v[134:135] op_sel_hi:[1,0]
	v_cvt_pk_bf16_f32 v157, v142, v143
	v_pk_mul_f32 v[144:145], v[116:117], v[134:135] op_sel_hi:[1,0]
	v_cvt_pk_bf16_f32 v158, v144, v145
	v_pk_mul_f32 v[146:147], v[118:119], v[134:135] op_sel_hi:[1,0]
	v_cvt_pk_bf16_f32 v159, v146, v147
	v_pk_mul_f32 v[140:141], v[120:121], v[134:135] op_sel_hi:[1,0]
	v_cvt_pk_bf16_f32 v160, v140, v141
	v_pk_mul_f32 v[142:143], v[122:123], v[134:135] op_sel_hi:[1,0]
; __device__ __forceinline__ const float* xrow_ptr(const Ctx& C, int row) { return row < MPROMPT ? C.in(0) + (size_t)row * DM : C.in(1) + (size_t)(row - MPROMPT) * DM; }
; __device__ __forceinline__ v4f ld4_bf16(const bf16* p) { const v2u w = *(const v2u*)p; return (v4f){bf_lo(w.x), bf_hi(w.x), bf_lo(w.y), bf_hi(w.y)}; }
; __device__ __forceinline__ void st4_bf16(bf16* p, v4f o) { v2u w; w.x = cvt_pk_nv(o.x, o.y); w.y = cvt_pk_nv(o.z, o.w); *(v2u*)p = w; }
; __device__ __forceinline__ float ssq4(v4f v) { return (v.x * v.x + v.y * v.y) + (v.z * v.z + v.w * v.w); }
; template <int R, bool BASE_F32, bool OUT_F32>
; __device__ __forceinline__ void rows_res(const Ctx& C, int m0, int stride, int mx, const float* gpost, float scale, int lane) {
;     ...
;     for (int r = 0; r < R; ++r) { mr[r] = (r == 4) ? mx : m0 + r * stride; ok[r] = (r == 4) ? (mx < M) : (mr[r] < MPROMPT); const int mm = ok[r] ? mr[r] : 0;
; #pragma unroll
;         for (int j = 0; j < 4; ++j) d[r][j] = ld4_bf16(D + (size_t)mm * DM + 4 * lane + 256 * j);
;         if (BASE_F32) { const float* x = xrow_ptr(C, mm);
; #pragma unroll
;             for (int j = 0; j < 4; ++j) b[r][j] = ld4_f32(x + 4 * lane + 256 * j);
;         } else { const float inv = C.RS()[mm];
; #pragma unroll
;             for (int j = 0; j < 4; ++j) b[r][j] = ld4_bf16(XN + (size_t)mm * DM + 4 * lane + 256 * j) * inv;
;         } }
; #pragma unroll
;     for (int r = 0; r < R; ++r) { float s = 0.f;
; #pragma unroll
;         for (int j = 0; j < 4; ++j) s += ssq4(d[r][j]);
;         r1[r] = s; }
;     ...
;     } else { float* rs = C.RS(); float t[R];
; #pragma unroll
;         for (int r = 0; r < R; ++r) { float s = 0.f;
; #pragma unroll
;             for (int j = 0; j < 4; ++j) s += ssq4(d[r][j]);
;             t[r] = s; }
; #pragma unroll
;         for (int r = 0; r < R; ++r) t[r] = wave_sum(t[r]) * (1.f / DM) + EPS;
; #pragma unroll
;         for (int r = 0; r < R; ++r) { const float rstd = rsqrtf(t[r]);
; #pragma unroll
;             for (int j = 0; j < 4; ++j) if (ok[r]) st4_bf16(XN + (size_t)mr[r] * DM + 4 * lane + 256 * j, d[r][j] * rstd);
;             if (lane == 0 && ok[r]) rs[mr[r]] = sqrtf(t[r]); }
	v_cvt_pk_bf16_f32 v161, v142, v143
	v_pk_mul_f32 v[144:145], v[124:125], v[134:135] op_sel_hi:[1,0]
	v_cvt_pk_bf16_f32 v162, v144, v145
	v_pk_mul_f32 v[146:147], v[126:127], v[134:135] op_sel_hi:[1,0]
	v_cvt_pk_bf16_f32 v163, v146, v147
	global_store_dwordx2 v173, v[156:157], s[98:99]
	global_store_dwordx2 v173, v[158:159], s[98:99] offset:512
	global_store_dwordx2 v173, v[160:161], s[98:99] offset:1024
	global_store_dwordx2 v173, v[162:163], s[98:99] offset:1536
	v_add_u32_e32 v173, 0x400000, v173
	v_add_u32_e32 v166, -1, v165
	v_fma_f32 v140, -v166, v165, v164
	v_cmp_ge_f32_e32 vcc, 0, v140
	v_add_u32_e32 v141, 1, v165
	v_cndmask_b32_e32 v166, v165, v166, vcc
	v_fma_f32 v140, -v141, v165, v164
	v_cmp_lt_f32_e32 vcc, 0, v140
	s_nop 1
	v_cndmask_b32_e32 v165, v166, v141, vcc
	v_add_u32_e32 v169, -1, v168
	v_fma_f32 v142, -v169, v168, v167
	v_cmp_ge_f32_e32 vcc, 0, v142
	v_add_u32_e32 v143, 1, v168
	v_cndmask_b32_e32 v169, v168, v169, vcc
	v_fma_f32 v142, -v143, v168, v167
	v_cmp_lt_f32_e32 vcc, 0, v142
	s_nop 1
	v_cndmask_b32_e32 v168, v169, v143, vcc
	s_mov_b64 exec, 1
	global_store_dword v174, v165, s[98:99]
	v_add_u32_e32 v174, 0x2000, v174
	global_store_dword v174, v168, s[98:99]
	v_add_u32_e32 v174, 0x2000, v174
	s_mov_b64 exec, -1
	global_load_dword v88, v172, s[98:99]
	global_load_dwordx2 v[56:57], v170, s[98:99]
	global_load_dwordx2 v[58:59], v170, s[98:99] offset:512
	global_load_dwordx2 v[60:61], v170, s[98:99] offset:1024
	global_load_dwordx2 v[62:63], v170, s[98:99] offset:1536
	global_load_dwordx2 v[72:73], v171, s[98:99]
	global_load_dwordx2 v[74:75], v171, s[98:99] offset:512
	global_load_dwordx2 v[76:77], v171, s[98:99] offset:1024
	global_load_dwordx2 v[78:79], v171, s[98:99] offset:1536
	v_add_u32_e32 v170, 0x400000, v170
	v_add_u32_e32 v171, 0x400000, v171
	v_add_u32_e32 v172, 0x2000, v172
	global_load_dword v90, v172, s[98:99]
	global_load_dwordx2 v[64:65], v170, s[98:99]
	global_load_dwordx2 v[66:67], v170, s[98:99] offset:512
	global_load_dwordx2 v[68:69], v170, s[98:99] offset:1024
	global_load_dwordx2 v[70:71], v170, s[98:99] offset:1536
	global_load_dwordx2 v[80:81], v171, s[98:99]
	global_load_dwordx2 v[82:83], v171, s[98:99] offset:512
	global_load_dwordx2 v[84:85], v171, s[98:99] offset:1024
	global_load_dwordx2 v[86:87], v171, s[98:99] offset:1536
	v_add_u32_e32 v170, 0x400000, v170
	v_add_u32_e32 v171, 0x400000, v171
	v_add_u32_e32 v172, 0x2000, v172
	s_waitcnt vmcnt(41)
	v_lshlrev_b32_e32 v96, 16, v20
	v_and_b32_e32 v97, 0xffff0000, v20
	v_lshlrev_b32_e32 v98, 16, v21
	v_and_b32_e32 v99, 0xffff0000, v21
	v_lshlrev_b32_e32 v100, 16, v22
	v_and_b32_e32 v101, 0xffff0000, v22
	v_lshlrev_b32_e32 v102, 16, v23
	v_and_b32_e32 v103, 0xffff0000, v23
	v_lshlrev_b32_e32 v104, 16, v24
	v_and_b32_e32 v105, 0xffff0000, v24
	v_lshlrev_b32_e32 v106, 16, v25
	v_and_b32_e32 v107, 0xffff0000, v25
	v_lshlrev_b32_e32 v108, 16, v26
	v_and_b32_e32 v109, 0xffff0000, v26
	v_lshlrev_b32_e32 v110, 16, v27
	v_and_b32_e32 v111, 0xffff0000, v27
	v_pk_mul_f32 v[128:129], v[96:97], v[96:97]
	v_pk_fma_f32 v[128:129], v[98:99], v[98:99], v[128:129]
	v_pk_fma_f32 v[128:129], v[100:101], v[100:101], v[128:129]
	v_pk_fma_f32 v[128:129], v[102:103], v[102:103], v[128:129]
	v_pk_fma_f32 v[128:129], v[104:105], v[104:105], v[128:129]
	v_pk_fma_f32 v[128:129], v[106:107], v[106:107], v[128:129]
	v_pk_fma_f32 v[128:129], v[108:109], v[108:109], v[128:129]
	v_pk_fma_f32 v[128:129], v[110:111], v[110:111], v[128:129]
	s_nop 0
	v_add_f32_e32 v128, v128, v129
	s_waitcnt vmcnt(32)
	v_lshlrev_b32_e32 v112, 16, v28
	v_and_b32_e32 v113, 0xffff0000, v28
	v_lshlrev_b32_e32 v114, 16, v29
	v_and_b32_e32 v115, 0xffff0000, v29
	v_lshlrev_b32_e32 v116, 16, v30
	v_and_b32_e32 v117, 0xffff0000, v30
	v_lshlrev_b32_e32 v118, 16, v31
	v_and_b32_e32 v119, 0xffff0000, v31
	v_lshlrev_b32_e32 v120, 16, v32
	v_and_b32_e32 v121, 0xffff0000, v32
	v_lshlrev_b32_e32 v122, 16, v33
	v_and_b32_e32 v123, 0xffff0000, v33
	v_lshlrev_b32_e32 v124, 16, v34
	v_and_b32_e32 v125, 0xffff0000, v34
	v_lshlrev_b32_e32 v126, 16, v35
	v_and_b32_e32 v127, 0xffff0000, v35
	v_pk_mul_f32 v[130:131], v[112:113], v[112:113]
	v_pk_fma_f32 v[130:131], v[114:115], v[114:115], v[130:131]
	v_pk_fma_f32 v[130:131], v[116:117], v[116:117], v[130:131]
	v_pk_fma_f32 v[130:131], v[118:119], v[118:119], v[130:131]
	v_pk_fma_f32 v[130:131], v[120:121], v[120:121], v[130:131]
	v_pk_fma_f32 v[130:131], v[122:123], v[122:123], v[130:131]
	v_pk_fma_f32 v[130:131], v[124:125], v[124:125], v[130:131]
	v_pk_fma_f32 v[130:131], v[126:127], v[126:127], v[130:131]
	s_nop 0
	v_add_f32_e32 v130, v130, v131
	s_nop 1
	v_add_f32_dpp v128, v128, v128 quad_perm:[1,0,3,2] row_mask:0xf bank_mask:0xf
	v_add_f32_dpp v130, v130, v130 quad_perm:[1,0,3,2] row_mask:0xf bank_mask:0xf
	s_nop 0
	v_add_f32_dpp v128, v128, v128 quad_perm:[2,3,0,1] row_mask:0xf bank_mask:0xf
	v_add_f32_dpp v130, v130, v130 quad_perm:[2,3,0,1] row_mask:0xf bank_mask:0xf
	s_nop 0
	v_add_f32_dpp v128, v128, v128 row_half_mirror row_mask:0xf bank_mask:0xf
	v_add_f32_dpp v130, v130, v130 row_half_mirror row_mask:0xf bank_mask:0xf
	s_nop 0
	v_add_f32_dpp v128, v128, v128 row_mirror row_mask:0xf bank_mask:0xf
	v_add_f32_dpp v130, v130, v130 row_mirror row_mask:0xf bank_mask:0xf
	s_nop 0
	ds_bpermute_b32 v136, v187, v128
	ds_bpermute_b32 v137, v187, v130
	s_waitcnt lgkmcnt(0)
	v_add_f32_e32 v128, v128, v136
	v_add_f32_e32 v130, v130, v137
	ds_bpermute_b32 v136, v188, v128
	ds_bpermute_b32 v137, v188, v130
	s_waitcnt lgkmcnt(0)
;     __device__ __forceinline__ float* out() const { return (float*)karg_in(33); }
; __device__ __forceinline__ float ssq4(v4f v) { return (v.x * v.x + v.y * v.y) + (v.z * v.z + v.w * v.w); }
; template <int R, bool BASE_F32, bool OUT_F32>
; __device__ __forceinline__ void rows_res(const Ctx& C, int m0, int stride, int mx, const float* gpost, float scale, int lane) {
;     ...
;     for (int r = 0; r < R; ++r) { float s = 0.f;
; #pragma unroll
;         for (int j = 0; j < 4; ++j) s += ssq4(d[r][j]);
;         r1[r] = s; }
; #pragma unroll
;     for (int r = 0; r < R; ++r) r1[r] = rsqrtf(wave_sum(r1[r]) * (1.f / DM) + EPS) * scale;
; #pragma unroll
;     for (int j = 0; j < 4; ++j) { const v4f gp = ld4_f32(gpost + 4 * lane + 256 * j);
; #pragma unroll
;         for (int r = 0; r < R; ++r) d[r][j] = b[r][j] + d[r][j] * r1[r] * gp; }
;     if (OUT_F32) { float* Y = C.out();
; #pragma unroll
;         for (int r = 0; r < R; ++r)
; #pragma unroll
;             for (int j = 0; j < 4; ++j) if (ok[r]) *(v4f*)(Y + (size_t)mr[r] * DM + 4 * lane + 256 * j) = d[r][j];
;     } else { float* rs = C.RS(); float t[R];
; #pragma unroll
;         for (int r = 0; r < R; ++r) { float s = 0.f;
; #pragma unroll
;             for (int j = 0; j < 4; ++j) s += ssq4(d[r][j]);
;             t[r] = s; }
; #pragma unroll
;         for (int r = 0; r < R; ++r) t[r] = wave_sum(t[r]) * (1.f / DM) + EPS;
	v_add_f32_e32 v128, v128, v136
	v_add_f32_e32 v130, v130, v137
	v_fmamk_f32 v128, v128, 0x3a800000, v138
	v_fmamk_f32 v130, v130, 0x3a800000, v138
	s_nop 0
	v_rsq_f32_e32 v128, v128
	v_rsq_f32_e32 v130, v130
	s_nop 1
	v_mul_f32_e32 v128, 0.5, v128
	v_mul_f32_e32 v130, 0.5, v130
	s_waitcnt vmcnt(28)
	v_pk_mul_f32 v[96:97], v[128:129], v[96:97] op_sel_hi:[0,1]
	v_pk_mul_f32 v[98:99], v[128:129], v[98:99] op_sel_hi:[0,1]
	v_pk_mul_f32 v[100:101], v[128:129], v[100:101] op_sel_hi:[0,1]
	v_pk_mul_f32 v[102:103], v[128:129], v[102:103] op_sel_hi:[0,1]
	v_pk_mul_f32 v[104:105], v[128:129], v[104:105] op_sel_hi:[0,1]
	v_pk_mul_f32 v[106:107], v[128:129], v[106:107] op_sel_hi:[0,1]
	v_pk_mul_f32 v[108:109], v[128:129], v[108:109] op_sel_hi:[0,1]
	v_pk_mul_f32 v[110:111], v[128:129], v[110:111] op_sel_hi:[0,1]
	v_pk_mul_f32 v[96:97], v[96:97], v[192:193]
	v_pk_mul_f32 v[98:99], v[98:99], v[194:195]
	v_pk_mul_f32 v[100:101], v[100:101], v[196:197]
	v_pk_mul_f32 v[102:103], v[102:103], v[198:199]
	v_pk_mul_f32 v[104:105], v[104:105], v[200:201]
	v_pk_mul_f32 v[106:107], v[106:107], v[202:203]
	v_pk_mul_f32 v[108:109], v[108:109], v[204:205]
	v_pk_mul_f32 v[110:111], v[110:111], v[206:207]
	v_lshlrev_b32_e32 v20, 16, v36
	v_and_b32_e32 v21, 0xffff0000, v36
	v_lshlrev_b32_e32 v22, 16, v37
	v_and_b32_e32 v23, 0xffff0000, v37
	v_lshlrev_b32_e32 v24, 16, v38
	v_and_b32_e32 v25, 0xffff0000, v38
	v_lshlrev_b32_e32 v26, 16, v39
	v_and_b32_e32 v27, 0xffff0000, v39
	v_pk_fma_f32 v[96:97], v[52:53], v[20:21], v[96:97] op_sel_hi:[0,1,1]
	v_pk_fma_f32 v[98:99], v[52:53], v[22:23], v[98:99] op_sel_hi:[0,1,1]
	v_pk_fma_f32 v[100:101], v[52:53], v[24:25], v[100:101] op_sel_hi:[0,1,1]
	v_pk_fma_f32 v[102:103], v[52:53], v[26:27], v[102:103] op_sel_hi:[0,1,1]
	v_lshlrev_b32_e32 v20, 16, v40
	v_and_b32_e32 v21, 0xffff0000, v40
	v_lshlrev_b32_e32 v22, 16, v41
	v_and_b32_e32 v23, 0xffff0000, v41
	v_lshlrev_b32_e32 v24, 16, v42
	v_and_b32_e32 v25, 0xffff0000, v42
	v_lshlrev_b32_e32 v26, 16, v43
	v_and_b32_e32 v27, 0xffff0000, v43
	v_pk_fma_f32 v[104:105], v[52:53], v[20:21], v[104:105] op_sel_hi:[0,1,1]
	v_pk_fma_f32 v[106:107], v[52:53], v[22:23], v[106:107] op_sel_hi:[0,1,1]
	v_pk_fma_f32 v[108:109], v[52:53], v[24:25], v[108:109] op_sel_hi:[0,1,1]
	v_pk_fma_f32 v[110:111], v[52:53], v[26:27], v[110:111] op_sel_hi:[0,1,1]
	v_pk_mul_f32 v[132:133], v[96:97], v[96:97]
	v_pk_fma_f32 v[132:133], v[98:99], v[98:99], v[132:133]
	v_pk_fma_f32 v[132:133], v[100:101], v[100:101], v[132:133]
	v_pk_fma_f32 v[132:133], v[102:103], v[102:103], v[132:133]
	v_pk_fma_f32 v[132:133], v[104:105], v[104:105], v[132:133]
	v_pk_fma_f32 v[132:133], v[106:107], v[106:107], v[132:133]
	v_pk_fma_f32 v[132:133], v[108:109], v[108:109], v[132:133]
	v_pk_fma_f32 v[132:133], v[110:111], v[110:111], v[132:133]
	s_nop 0
	v_add_f32_e32 v132, v132, v133
	v_pk_mul_f32 v[112:113], v[130:131], v[112:113] op_sel_hi:[0,1]
	v_pk_mul_f32 v[114:115], v[130:131], v[114:115] op_sel_hi:[0,1]
	v_pk_mul_f32 v[116:117], v[130:131], v[116:117] op_sel_hi:[0,1]
	v_pk_mul_f32 v[118:119], v[130:131], v[118:119] op_sel_hi:[0,1]
	v_pk_mul_f32 v[120:121], v[130:131], v[120:121] op_sel_hi:[0,1]
	v_pk_mul_f32 v[122:123], v[130:131], v[122:123] op_sel_hi:[0,1]
	v_pk_mul_f32 v[124:125], v[130:131], v[124:125] op_sel_hi:[0,1]
	v_pk_mul_f32 v[126:127], v[130:131], v[126:127] op_sel_hi:[0,1]
	v_pk_mul_f32 v[112:113], v[112:113], v[192:193]
	v_pk_mul_f32 v[114:115], v[114:115], v[194:195]
	v_pk_mul_f32 v[116:117], v[116:117], v[196:197]
	v_pk_mul_f32 v[118:119], v[118:119], v[198:199]
	v_pk_mul_f32 v[120:121], v[120:121], v[200:201]
	v_pk_mul_f32 v[122:123], v[122:123], v[202:203]
	v_pk_mul_f32 v[124:125], v[124:125], v[204:205]
	v_pk_mul_f32 v[126:127], v[126:127], v[206:207]
	v_lshlrev_b32_e32 v28, 16, v44
	v_and_b32_e32 v29, 0xffff0000, v44
	v_lshlrev_b32_e32 v30, 16, v45
	v_and_b32_e32 v31, 0xffff0000, v45
	v_lshlrev_b32_e32 v32, 16, v46
	v_and_b32_e32 v33, 0xffff0000, v46
	v_lshlrev_b32_e32 v34, 16, v47
	v_and_b32_e32 v35, 0xffff0000, v47
	v_pk_fma_f32 v[112:113], v[54:55], v[28:29], v[112:113] op_sel_hi:[0,1,1]
	v_pk_fma_f32 v[114:115], v[54:55], v[30:31], v[114:115] op_sel_hi:[0,1,1]
	v_pk_fma_f32 v[116:117], v[54:55], v[32:33], v[116:117] op_sel_hi:[0,1,1]
	v_pk_fma_f32 v[118:119], v[54:55], v[34:35], v[118:119] op_sel_hi:[0,1,1]
	v_lshlrev_b32_e32 v28, 16, v48
	v_and_b32_e32 v29, 0xffff0000, v48
	v_lshlrev_b32_e32 v30, 16, v49
	v_and_b32_e32 v31, 0xffff0000, v49
	v_lshlrev_b32_e32 v32, 16, v50
	v_and_b32_e32 v33, 0xffff0000, v50
	v_lshlrev_b32_e32 v34, 16, v51
	v_and_b32_e32 v35, 0xffff0000, v51
	v_pk_fma_f32 v[120:121], v[54:55], v[28:29], v[120:121] op_sel_hi:[0,1,1]
	v_pk_fma_f32 v[122:123], v[54:55], v[30:31], v[122:123] op_sel_hi:[0,1,1]
	v_pk_fma_f32 v[124:125], v[54:55], v[32:33], v[124:125] op_sel_hi:[0,1,1]
	v_pk_fma_f32 v[126:127], v[54:55], v[34:35], v[126:127] op_sel_hi:[0,1,1]
	v_pk_mul_f32 v[134:135], v[112:113], v[112:113]
	v_pk_fma_f32 v[134:135], v[114:115], v[114:115], v[134:135]
	v_pk_fma_f32 v[134:135], v[116:117], v[116:117], v[134:135]
	v_pk_fma_f32 v[134:135], v[118:119], v[118:119], v[134:135]
	v_pk_fma_f32 v[134:135], v[120:121], v[120:121], v[134:135]
	v_pk_fma_f32 v[134:135], v[122:123], v[122:123], v[134:135]
	v_pk_fma_f32 v[134:135], v[124:125], v[124:125], v[134:135]
	v_pk_fma_f32 v[134:135], v[126:127], v[126:127], v[134:135]
	s_nop 0
	v_add_f32_e32 v134, v134, v135
	s_nop 1
	v_add_f32_dpp v132, v132, v132 quad_perm:[1,0,3,2] row_mask:0xf bank_mask:0xf
	v_add_f32_dpp v134, v134, v134 quad_perm:[1,0,3,2] row_mask:0xf bank_mask:0xf
	s_nop 0
	v_add_f32_dpp v132, v132, v132 quad_perm:[2,3,0,1] row_mask:0xf bank_mask:0xf
	v_add_f32_dpp v134, v134, v134 quad_perm:[2,3,0,1] row_mask:0xf bank_mask:0xf
	s_nop 0
	v_add_f32_dpp v132, v132, v132 row_half_mirror row_mask:0xf bank_mask:0xf
	v_add_f32_dpp v134, v134, v134 row_half_mirror row_mask:0xf bank_mask:0xf
	s_nop 0
	v_add_f32_dpp v132, v132, v132 row_mirror row_mask:0xf bank_mask:0xf
	v_add_f32_dpp v134, v134, v134 row_mirror row_mask:0xf bank_mask:0xf
	s_nop 0
	ds_bpermute_b32 v136, v187, v132
	ds_bpermute_b32 v137, v187, v134
	s_waitcnt lgkmcnt(0)
; __device__ __forceinline__ const float* xrow_ptr(const Ctx& C, int row) { return row < MPROMPT ? C.in(0) + (size_t)row * DM : C.in(1) + (size_t)(row - MPROMPT) * DM; }
; __device__ __forceinline__ v4f ld4_bf16(const bf16* p) { const v2u w = *(const v2u*)p; return (v4f){bf_lo(w.x), bf_hi(w.x), bf_lo(w.y), bf_hi(w.y)}; }
; __device__ __forceinline__ void st4_bf16(bf16* p, v4f o) { v2u w; w.x = cvt_pk_nv(o.x, o.y); w.y = cvt_pk_nv(o.z, o.w); *(v2u*)p = w; }
; __device__ __forceinline__ float ssq4(v4f v) { return (v.x * v.x + v.y * v.y) + (v.z * v.z + v.w * v.w); }
; template <int R, bool BASE_F32, bool OUT_F32>
; __device__ __forceinline__ void rows_res(const Ctx& C, int m0, int stride, int mx, const float* gpost, float scale, int lane) {
;     ...
;     for (int r = 0; r < R; ++r) { mr[r] = (r == 4) ? mx : m0 + r * stride; ok[r] = (r == 4) ? (mx < M) : (mr[r] < MPROMPT); const int mm = ok[r] ? mr[r] : 0;
; #pragma unroll
;         for (int j = 0; j < 4; ++j) d[r][j] = ld4_bf16(D + (size_t)mm * DM + 4 * lane + 256 * j);
;         if (BASE_F32) { const float* x = xrow_ptr(C, mm);
; #pragma unroll
;             for (int j = 0; j < 4; ++j) b[r][j] = ld4_f32(x + 4 * lane + 256 * j);
;         } else { const float inv = C.RS()[mm];
; #pragma unroll
;             for (int j = 0; j < 4; ++j) b[r][j] = ld4_bf16(XN + (size_t)mm * DM + 4 * lane + 256 * j) * inv;
;         } }
; #pragma unroll
;     for (int r = 0; r < R; ++r) { float s = 0.f;
; #pragma unroll
;         for (int j = 0; j < 4; ++j) s += ssq4(d[r][j]);
;         r1[r] = s; }
;     ...
;         for (int r = 0; r < R; ++r) t[r] = wave_sum(t[r]) * (1.f / DM) + EPS;
; #pragma unroll
;         for (int r = 0; r < R; ++r) { const float rstd = rsqrtf(t[r]);
; #pragma unroll
;             for (int j = 0; j < 4; ++j) if (ok[r]) st4_bf16(XN + (size_t)mr[r] * DM + 4 * lane + 256 * j, d[r][j] * rstd);
;             if (lane == 0 && ok[r]) rs[mr[r]] = sqrtf(t[r]); }
	v_add_f32_e32 v132, v132, v136
	v_add_f32_e32 v134, v134, v137
	ds_bpermute_b32 v136, v188, v132
	ds_bpermute_b32 v137, v188, v134
	s_waitcnt lgkmcnt(0)
	v_add_f32_e32 v132, v132, v136
	v_add_f32_e32 v134, v134, v137
	v_fmamk_f32 v164, v132, 0x3a800000, v138
	v_fmamk_f32 v167, v134, 0x3a800000, v138
	s_nop 0
	v_rsq_f32_e32 v132, v164
	v_rsq_f32_e32 v134, v167
	v_sqrt_f32_e32 v165, v164
	v_sqrt_f32_e32 v168, v167
	s_nop 1
	v_pk_mul_f32 v[140:141], v[96:97], v[132:133] op_sel_hi:[1,0]
	v_cvt_pk_bf16_f32 v148, v140, v141
	v_pk_mul_f32 v[142:143], v[98:99], v[132:133] op_sel_hi:[1,0]
	v_cvt_pk_bf16_f32 v149, v142, v143
	v_pk_mul_f32 v[144:145], v[100:101], v[132:133] op_sel_hi:[1,0]
	v_cvt_pk_bf16_f32 v150, v144, v145
	v_pk_mul_f32 v[146:147], v[102:103], v[132:133] op_sel_hi:[1,0]
	v_cvt_pk_bf16_f32 v151, v146, v147
	v_pk_mul_f32 v[140:141], v[104:105], v[132:133] op_sel_hi:[1,0]
	v_cvt_pk_bf16_f32 v152, v140, v141
	v_pk_mul_f32 v[142:143], v[106:107], v[132:133] op_sel_hi:[1,0]
	v_cvt_pk_bf16_f32 v153, v142, v143
	v_pk_mul_f32 v[144:145], v[108:109], v[132:133] op_sel_hi:[1,0]
	v_cvt_pk_bf16_f32 v154, v144, v145
	v_pk_mul_f32 v[146:147], v[110:111], v[132:133] op_sel_hi:[1,0]
	v_cvt_pk_bf16_f32 v155, v146, v147
	global_store_dwordx2 v173, v[148:149], s[98:99]
	global_store_dwordx2 v173, v[150:151], s[98:99] offset:512
	global_store_dwordx2 v173, v[152:153], s[98:99] offset:1024
	global_store_dwordx2 v173, v[154:155], s[98:99] offset:1536
	v_add_u32_e32 v173, 0x400000, v173
	v_pk_mul_f32 v[140:141], v[112:113], v[134:135] op_sel_hi:[1,0]
	v_cvt_pk_bf16_f32 v156, v140, v141
	v_pk_mul_f32 v[142:143], v[114:115], v[134:135] op_sel_hi:[1,0]
	v_cvt_pk_bf16_f32 v157, v142, v143
	v_pk_mul_f32 v[144:145], v[116:117], v[134:135] op_sel_hi:[1,0]
	v_cvt_pk_bf16_f32 v158, v144, v145
	v_pk_mul_f32 v[146:147], v[118:119], v[134:135] op_sel_hi:[1,0]
	v_cvt_pk_bf16_f32 v159, v146, v147
	v_pk_mul_f32 v[140:141], v[120:121], v[134:135] op_sel_hi:[1,0]
	v_cvt_pk_bf16_f32 v160, v140, v141
	v_pk_mul_f32 v[142:143], v[122:123], v[134:135] op_sel_hi:[1,0]
	v_cvt_pk_bf16_f32 v161, v142, v143
	v_pk_mul_f32 v[144:145], v[124:125], v[134:135] op_sel_hi:[1,0]
	v_cvt_pk_bf16_f32 v162, v144, v145
	v_pk_mul_f32 v[146:147], v[126:127], v[134:135] op_sel_hi:[1,0]
	v_cvt_pk_bf16_f32 v163, v146, v147
	global_store_dwordx2 v173, v[156:157], s[98:99]
	global_store_dwordx2 v173, v[158:159], s[98:99] offset:512
	global_store_dwordx2 v173, v[160:161], s[98:99] offset:1024
	global_store_dwordx2 v173, v[162:163], s[98:99] offset:1536
	v_add_u32_e32 v173, 0x400000, v173
	v_add_u32_e32 v166, -1, v165
	v_fma_f32 v140, -v166, v165, v164
	v_cmp_ge_f32_e32 vcc, 0, v140
	v_add_u32_e32 v141, 1, v165
	v_cndmask_b32_e32 v166, v165, v166, vcc
	v_fma_f32 v140, -v141, v165, v164
	v_cmp_lt_f32_e32 vcc, 0, v140
	s_nop 1
	v_cndmask_b32_e32 v165, v166, v141, vcc
	v_add_u32_e32 v169, -1, v168
	v_fma_f32 v142, -v169, v168, v167
	v_cmp_ge_f32_e32 vcc, 0, v142
	v_add_u32_e32 v143, 1, v168
	v_cndmask_b32_e32 v169, v168, v169, vcc
	v_fma_f32 v142, -v143, v168, v167
	v_cmp_lt_f32_e32 vcc, 0, v142
	s_nop 1
	v_cndmask_b32_e32 v168, v169, v143, vcc
	s_mov_b64 exec, 1
	global_store_dword v174, v165, s[98:99]
	v_add_u32_e32 v174, 0x2000, v174
	global_store_dword v174, v168, s[98:99]
	v_add_u32_e32 v174, 0x2000, v174
	s_mov_b64 exec, -1
	global_load_dword v52, v172, s[98:99]
	global_load_dwordx2 v[20:21], v170, s[98:99]
	global_load_dwordx2 v[22:23], v170, s[98:99] offset:512
	global_load_dwordx2 v[24:25], v170, s[98:99] offset:1024
	global_load_dwordx2 v[26:27], v170, s[98:99] offset:1536
	global_load_dwordx2 v[36:37], v171, s[98:99]
	global_load_dwordx2 v[38:39], v171, s[98:99] offset:512
	global_load_dwordx2 v[40:41], v171, s[98:99] offset:1024
	global_load_dwordx2 v[42:43], v171, s[98:99] offset:1536
	v_add_u32_e32 v170, 0x400000, v170
	v_add_u32_e32 v171, 0x400000, v171
	v_add_u32_e32 v172, 0x2000, v172
	global_load_dword v54, v172, s[98:99]
	global_load_dwordx2 v[28:29], v170, s[98:99]
	global_load_dwordx2 v[30:31], v170, s[98:99] offset:512
	global_load_dwordx2 v[32:33], v170, s[98:99] offset:1024
	global_load_dwordx2 v[34:35], v170, s[98:99] offset:1536
	global_load_dwordx2 v[44:45], v171, s[98:99]
	global_load_dwordx2 v[46:47], v171, s[98:99] offset:512
	global_load_dwordx2 v[48:49], v171, s[98:99] offset:1024
	global_load_dwordx2 v[50:51], v171, s[98:99] offset:1536
	v_add_u32_e32 v170, 0x400000, v170
	v_add_u32_e32 v171, 0x400000, v171
	v_add_u32_e32 v172, 0x2000, v172
	s_waitcnt vmcnt(41)
	v_lshlrev_b32_e32 v96, 16, v56
	v_and_b32_e32 v97, 0xffff0000, v56
	v_lshlrev_b32_e32 v98, 16, v57
	v_and_b32_e32 v99, 0xffff0000, v57
	v_lshlrev_b32_e32 v100, 16, v58
	v_and_b32_e32 v101, 0xffff0000, v58
	v_lshlrev_b32_e32 v102, 16, v59
	v_and_b32_e32 v103, 0xffff0000, v59
	v_lshlrev_b32_e32 v104, 16, v60
	v_and_b32_e32 v105, 0xffff0000, v60
	v_lshlrev_b32_e32 v106, 16, v61
	v_and_b32_e32 v107, 0xffff0000, v61
	v_lshlrev_b32_e32 v108, 16, v62
	v_and_b32_e32 v109, 0xffff0000, v62
	v_lshlrev_b32_e32 v110, 16, v63
	v_and_b32_e32 v111, 0xffff0000, v63
	v_pk_mul_f32 v[128:129], v[96:97], v[96:97]
	v_pk_fma_f32 v[128:129], v[98:99], v[98:99], v[128:129]
	v_pk_fma_f32 v[128:129], v[100:101], v[100:101], v[128:129]
	v_pk_fma_f32 v[128:129], v[102:103], v[102:103], v[128:129]
	v_pk_fma_f32 v[128:129], v[104:105], v[104:105], v[128:129]
	v_pk_fma_f32 v[128:129], v[106:107], v[106:107], v[128:129]
	v_pk_fma_f32 v[128:129], v[108:109], v[108:109], v[128:129]
	v_pk_fma_f32 v[128:129], v[110:111], v[110:111], v[128:129]
	s_nop 0
	v_add_f32_e32 v128, v128, v129
	s_waitcnt vmcnt(32)
; __device__ __forceinline__ float ssq4(v4f v) { return (v.x * v.x + v.y * v.y) + (v.z * v.z + v.w * v.w); }
; template <int R, bool BASE_F32, bool OUT_F32>
; __device__ __forceinline__ void rows_res(const Ctx& C, int m0, int stride, int mx, const float* gpost, float scale, int lane) {
;     ...
;     for (int r = 0; r < R; ++r) { float s = 0.f;
; #pragma unroll
;         for (int j = 0; j < 4; ++j) s += ssq4(d[r][j]);
;         r1[r] = s; }
; #pragma unroll
;     for (int r = 0; r < R; ++r) r1[r] = rsqrtf(wave_sum(r1[r]) * (1.f / DM) + EPS) * scale;
; #pragma unroll
;     for (int j = 0; j < 4; ++j) { const v4f gp = ld4_f32(gpost + 4 * lane + 256 * j);
; #pragma unroll
;         for (int r = 0; r < R; ++r) d[r][j] = b[r][j] + d[r][j] * r1[r] * gp; }
	v_lshlrev_b32_e32 v112, 16, v64
	v_and_b32_e32 v113, 0xffff0000, v64
	v_lshlrev_b32_e32 v114, 16, v65
	v_and_b32_e32 v115, 0xffff0000, v65
	v_lshlrev_b32_e32 v116, 16, v66
	v_and_b32_e32 v117, 0xffff0000, v66
	v_lshlrev_b32_e32 v118, 16, v67
	v_and_b32_e32 v119, 0xffff0000, v67
	v_lshlrev_b32_e32 v120, 16, v68
	v_and_b32_e32 v121, 0xffff0000, v68
	v_lshlrev_b32_e32 v122, 16, v69
	v_and_b32_e32 v123, 0xffff0000, v69
	v_lshlrev_b32_e32 v124, 16, v70
	v_and_b32_e32 v125, 0xffff0000, v70
	v_lshlrev_b32_e32 v126, 16, v71
	v_and_b32_e32 v127, 0xffff0000, v71
	v_pk_mul_f32 v[130:131], v[112:113], v[112:113]
	v_pk_fma_f32 v[130:131], v[114:115], v[114:115], v[130:131]
	v_pk_fma_f32 v[130:131], v[116:117], v[116:117], v[130:131]
	v_pk_fma_f32 v[130:131], v[118:119], v[118:119], v[130:131]
	v_pk_fma_f32 v[130:131], v[120:121], v[120:121], v[130:131]
	v_pk_fma_f32 v[130:131], v[122:123], v[122:123], v[130:131]
	v_pk_fma_f32 v[130:131], v[124:125], v[124:125], v[130:131]
	v_pk_fma_f32 v[130:131], v[126:127], v[126:127], v[130:131]
	s_nop 0
	v_add_f32_e32 v130, v130, v131
	s_nop 1
	v_add_f32_dpp v128, v128, v128 quad_perm:[1,0,3,2] row_mask:0xf bank_mask:0xf
	v_add_f32_dpp v130, v130, v130 quad_perm:[1,0,3,2] row_mask:0xf bank_mask:0xf
	s_nop 0
	v_add_f32_dpp v128, v128, v128 quad_perm:[2,3,0,1] row_mask:0xf bank_mask:0xf
	v_add_f32_dpp v130, v130, v130 quad_perm:[2,3,0,1] row_mask:0xf bank_mask:0xf
	s_nop 0
	v_add_f32_dpp v128, v128, v128 row_half_mirror row_mask:0xf bank_mask:0xf
	v_add_f32_dpp v130, v130, v130 row_half_mirror row_mask:0xf bank_mask:0xf
	s_nop 0
	v_add_f32_dpp v128, v128, v128 row_mirror row_mask:0xf bank_mask:0xf
	v_add_f32_dpp v130, v130, v130 row_mirror row_mask:0xf bank_mask:0xf
	s_nop 0
	ds_bpermute_b32 v136, v187, v128
	ds_bpermute_b32 v137, v187, v130
	s_waitcnt lgkmcnt(0)
	v_add_f32_e32 v128, v128, v136
	v_add_f32_e32 v130, v130, v137
	ds_bpermute_b32 v136, v188, v128
	ds_bpermute_b32 v137, v188, v130
	s_waitcnt lgkmcnt(0)
	v_add_f32_e32 v128, v128, v136
	v_add_f32_e32 v130, v130, v137
	v_fmamk_f32 v128, v128, 0x3a800000, v138
	v_fmamk_f32 v130, v130, 0x3a800000, v138
	s_nop 0
	v_rsq_f32_e32 v128, v128
	v_rsq_f32_e32 v130, v130
	s_nop 1
	v_mul_f32_e32 v128, 0.5, v128
	v_mul_f32_e32 v130, 0.5, v130
	s_waitcnt vmcnt(28)
	v_pk_mul_f32 v[96:97], v[128:129], v[96:97] op_sel_hi:[0,1]
	v_pk_mul_f32 v[98:99], v[128:129], v[98:99] op_sel_hi:[0,1]
	v_pk_mul_f32 v[100:101], v[128:129], v[100:101] op_sel_hi:[0,1]
	v_pk_mul_f32 v[102:103], v[128:129], v[102:103] op_sel_hi:[0,1]
	v_pk_mul_f32 v[104:105], v[128:129], v[104:105] op_sel_hi:[0,1]
	v_pk_mul_f32 v[106:107], v[128:129], v[106:107] op_sel_hi:[0,1]
	v_pk_mul_f32 v[108:109], v[128:129], v[108:109] op_sel_hi:[0,1]
	v_pk_mul_f32 v[110:111], v[128:129], v[110:111] op_sel_hi:[0,1]
	v_pk_mul_f32 v[96:97], v[96:97], v[192:193]
	v_pk_mul_f32 v[98:99], v[98:99], v[194:195]
	v_pk_mul_f32 v[100:101], v[100:101], v[196:197]
	v_pk_mul_f32 v[102:103], v[102:103], v[198:199]
	v_pk_mul_f32 v[104:105], v[104:105], v[200:201]
	v_pk_mul_f32 v[106:107], v[106:107], v[202:203]
	v_pk_mul_f32 v[108:109], v[108:109], v[204:205]
	v_pk_mul_f32 v[110:111], v[110:111], v[206:207]
	v_lshlrev_b32_e32 v56, 16, v72
	v_and_b32_e32 v57, 0xffff0000, v72
	v_lshlrev_b32_e32 v58, 16, v73
	v_and_b32_e32 v59, 0xffff0000, v73
	v_lshlrev_b32_e32 v60, 16, v74
	v_and_b32_e32 v61, 0xffff0000, v74
	v_lshlrev_b32_e32 v62, 16, v75
	v_and_b32_e32 v63, 0xffff0000, v75
	v_pk_fma_f32 v[96:97], v[88:89], v[56:57], v[96:97] op_sel_hi:[0,1,1]
	v_pk_fma_f32 v[98:99], v[88:89], v[58:59], v[98:99] op_sel_hi:[0,1,1]
	v_pk_fma_f32 v[100:101], v[88:89], v[60:61], v[100:101] op_sel_hi:[0,1,1]
	v_pk_fma_f32 v[102:103], v[88:89], v[62:63], v[102:103] op_sel_hi:[0,1,1]
	v_lshlrev_b32_e32 v56, 16, v76
	v_and_b32_e32 v57, 0xffff0000, v76
	v_lshlrev_b32_e32 v58, 16, v77
	v_and_b32_e32 v59, 0xffff0000, v77
	v_lshlrev_b32_e32 v60, 16, v78
	v_and_b32_e32 v61, 0xffff0000, v78
	v_lshlrev_b32_e32 v62, 16, v79
	v_and_b32_e32 v63, 0xffff0000, v79
	v_pk_fma_f32 v[104:105], v[88:89], v[56:57], v[104:105] op_sel_hi:[0,1,1]
	v_pk_fma_f32 v[106:107], v[88:89], v[58:59], v[106:107] op_sel_hi:[0,1,1]
	v_pk_fma_f32 v[108:109], v[88:89], v[60:61], v[108:109] op_sel_hi:[0,1,1]
	v_pk_fma_f32 v[110:111], v[88:89], v[62:63], v[110:111] op_sel_hi:[0,1,1]
	v_pk_mul_f32 v[132:133], v[96:97], v[96:97]
	v_pk_fma_f32 v[132:133], v[98:99], v[98:99], v[132:133]
	v_pk_fma_f32 v[132:133], v[100:101], v[100:101], v[132:133]
	v_pk_fma_f32 v[132:133], v[102:103], v[102:103], v[132:133]
	v_pk_fma_f32 v[132:133], v[104:105], v[104:105], v[132:133]
	v_pk_fma_f32 v[132:133], v[106:107], v[106:107], v[132:133]
	v_pk_fma_f32 v[132:133], v[108:109], v[108:109], v[132:133]
	v_pk_fma_f32 v[132:133], v[110:111], v[110:111], v[132:133]
	s_nop 0
	v_add_f32_e32 v132, v132, v133
	v_pk_mul_f32 v[112:113], v[130:131], v[112:113] op_sel_hi:[0,1]
	v_pk_mul_f32 v[114:115], v[130:131], v[114:115] op_sel_hi:[0,1]
	v_pk_mul_f32 v[116:117], v[130:131], v[116:117] op_sel_hi:[0,1]
	v_pk_mul_f32 v[118:119], v[130:131], v[118:119] op_sel_hi:[0,1]
	v_pk_mul_f32 v[120:121], v[130:131], v[120:121] op_sel_hi:[0,1]
	v_pk_mul_f32 v[122:123], v[130:131], v[122:123] op_sel_hi:[0,1]
	v_pk_mul_f32 v[124:125], v[130:131], v[124:125] op_sel_hi:[0,1]
	v_pk_mul_f32 v[126:127], v[130:131], v[126:127] op_sel_hi:[0,1]
	v_pk_mul_f32 v[112:113], v[112:113], v[192:193]
	v_pk_mul_f32 v[114:115], v[114:115], v[194:195]
	v_pk_mul_f32 v[116:117], v[116:117], v[196:197]
	v_pk_mul_f32 v[118:119], v[118:119], v[198:199]
	v_pk_mul_f32 v[120:121], v[120:121], v[200:201]
	v_pk_mul_f32 v[122:123], v[122:123], v[202:203]
;     __device__ __forceinline__ float* out() const { return (float*)karg_in(33); }
; __device__ __forceinline__ const float* xrow_ptr(const Ctx& C, int row) { return row < MPROMPT ? C.in(0) + (size_t)row * DM : C.in(1) + (size_t)(row - MPROMPT) * DM; }
; __device__ __forceinline__ v4f ld4_bf16(const bf16* p) { const v2u w = *(const v2u*)p; return (v4f){bf_lo(w.x), bf_hi(w.x), bf_lo(w.y), bf_hi(w.y)}; }
; __device__ __forceinline__ void st4_bf16(bf16* p, v4f o) { v2u w; w.x = cvt_pk_nv(o.x, o.y); w.y = cvt_pk_nv(o.z, o.w); *(v2u*)p = w; }
; __device__ __forceinline__ float ssq4(v4f v) { return (v.x * v.x + v.y * v.y) + (v.z * v.z + v.w * v.w); }
; template <int R, bool BASE_F32, bool OUT_F32>
; __device__ __forceinline__ void rows_res(const Ctx& C, int m0, int stride, int mx, const float* gpost, float scale, int lane) {
;     ...
;     for (int r = 0; r < R; ++r) { mr[r] = (r == 4) ? mx : m0 + r * stride; ok[r] = (r == 4) ? (mx < M) : (mr[r] < MPROMPT); const int mm = ok[r] ? mr[r] : 0;
; #pragma unroll
;         for (int j = 0; j < 4; ++j) d[r][j] = ld4_bf16(D + (size_t)mm * DM + 4 * lane + 256 * j);
;         if (BASE_F32) { const float* x = xrow_ptr(C, mm);
; #pragma unroll
;             for (int j = 0; j < 4; ++j) b[r][j] = ld4_f32(x + 4 * lane + 256 * j);
;         } else { const float inv = C.RS()[mm];
; #pragma unroll
;             for (int j = 0; j < 4; ++j) b[r][j] = ld4_bf16(XN + (size_t)mm * DM + 4 * lane + 256 * j) * inv;
;         } }
;     ...
;         for (int r = 0; r < R; ++r) d[r][j] = b[r][j] + d[r][j] * r1[r] * gp; }
;     if (OUT_F32) { float* Y = C.out();
; #pragma unroll
;         for (int r = 0; r < R; ++r)
; #pragma unroll
;             for (int j = 0; j < 4; ++j) if (ok[r]) *(v4f*)(Y + (size_t)mr[r] * DM + 4 * lane + 256 * j) = d[r][j];
;     } else { float* rs = C.RS(); float t[R];
; #pragma unroll
;         for (int r = 0; r < R; ++r) { float s = 0.f;
; #pragma unroll
;             for (int j = 0; j < 4; ++j) s += ssq4(d[r][j]);
;             t[r] = s; }
; #pragma unroll
;         for (int r = 0; r < R; ++r) t[r] = wave_sum(t[r]) * (1.f / DM) + EPS;
; #pragma unroll
;         for (int r = 0; r < R; ++r) { const float rstd = rsqrtf(t[r]);
; #pragma unroll
;             for (int j = 0; j < 4; ++j) if (ok[r]) st4_bf16(XN + (size_t)mr[r] * DM + 4 * lane + 256 * j, d[r][j] * rstd);
;             if (lane == 0 && ok[r]) rs[mr[r]] = sqrtf(t[r]); }
	v_pk_mul_f32 v[124:125], v[124:125], v[204:205]
	v_pk_mul_f32 v[126:127], v[126:127], v[206:207]
	v_lshlrev_b32_e32 v64, 16, v80
	v_and_b32_e32 v65, 0xffff0000, v80
	v_lshlrev_b32_e32 v66, 16, v81
	v_and_b32_e32 v67, 0xffff0000, v81
	v_lshlrev_b32_e32 v68, 16, v82
	v_and_b32_e32 v69, 0xffff0000, v82
	v_lshlrev_b32_e32 v70, 16, v83
	v_and_b32_e32 v71, 0xffff0000, v83
	v_pk_fma_f32 v[112:113], v[90:91], v[64:65], v[112:113] op_sel_hi:[0,1,1]
	v_pk_fma_f32 v[114:115], v[90:91], v[66:67], v[114:115] op_sel_hi:[0,1,1]
	v_pk_fma_f32 v[116:117], v[90:91], v[68:69], v[116:117] op_sel_hi:[0,1,1]
	v_pk_fma_f32 v[118:119], v[90:91], v[70:71], v[118:119] op_sel_hi:[0,1,1]
	v_lshlrev_b32_e32 v64, 16, v84
	v_and_b32_e32 v65, 0xffff0000, v84
	v_lshlrev_b32_e32 v66, 16, v85
	v_and_b32_e32 v67, 0xffff0000, v85
	v_lshlrev_b32_e32 v68, 16, v86
	v_and_b32_e32 v69, 0xffff0000, v86
	v_lshlrev_b32_e32 v70, 16, v87
	v_and_b32_e32 v71, 0xffff0000, v87
	v_pk_fma_f32 v[120:121], v[90:91], v[64:65], v[120:121] op_sel_hi:[0,1,1]
	v_pk_fma_f32 v[122:123], v[90:91], v[66:67], v[122:123] op_sel_hi:[0,1,1]
	v_pk_fma_f32 v[124:125], v[90:91], v[68:69], v[124:125] op_sel_hi:[0,1,1]
	v_pk_fma_f32 v[126:127], v[90:91], v[70:71], v[126:127] op_sel_hi:[0,1,1]
	v_pk_mul_f32 v[134:135], v[112:113], v[112:113]
	v_pk_fma_f32 v[134:135], v[114:115], v[114:115], v[134:135]
	v_pk_fma_f32 v[134:135], v[116:117], v[116:117], v[134:135]
	v_pk_fma_f32 v[134:135], v[118:119], v[118:119], v[134:135]
	v_pk_fma_f32 v[134:135], v[120:121], v[120:121], v[134:135]
	v_pk_fma_f32 v[134:135], v[122:123], v[122:123], v[134:135]
	v_pk_fma_f32 v[134:135], v[124:125], v[124:125], v[134:135]
	v_pk_fma_f32 v[134:135], v[126:127], v[126:127], v[134:135]
	s_nop 0
	v_add_f32_e32 v134, v134, v135
	s_nop 1
	v_add_f32_dpp v132, v132, v132 quad_perm:[1,0,3,2] row_mask:0xf bank_mask:0xf
	v_add_f32_dpp v134, v134, v134 quad_perm:[1,0,3,2] row_mask:0xf bank_mask:0xf
	s_nop 0
	v_add_f32_dpp v132, v132, v132 quad_perm:[2,3,0,1] row_mask:0xf bank_mask:0xf
	v_add_f32_dpp v134, v134, v134 quad_perm:[2,3,0,1] row_mask:0xf bank_mask:0xf
	s_nop 0
	v_add_f32_dpp v132, v132, v132 row_half_mirror row_mask:0xf bank_mask:0xf
	v_add_f32_dpp v134, v134, v134 row_half_mirror row_mask:0xf bank_mask:0xf
	s_nop 0
	v_add_f32_dpp v132, v132, v132 row_mirror row_mask:0xf bank_mask:0xf
	v_add_f32_dpp v134, v134, v134 row_mirror row_mask:0xf bank_mask:0xf
	s_nop 0
	ds_bpermute_b32 v136, v187, v132
	ds_bpermute_b32 v137, v187, v134
	s_waitcnt lgkmcnt(0)
	v_add_f32_e32 v132, v132, v136
	v_add_f32_e32 v134, v134, v137
	ds_bpermute_b32 v136, v188, v132
	ds_bpermute_b32 v137, v188, v134
	s_waitcnt lgkmcnt(0)
	v_add_f32_e32 v132, v132, v136
	v_add_f32_e32 v134, v134, v137
	v_fmamk_f32 v164, v132, 0x3a800000, v138
	v_fmamk_f32 v167, v134, 0x3a800000, v138
	s_nop 0
	v_rsq_f32_e32 v132, v164
	v_rsq_f32_e32 v134, v167
	v_sqrt_f32_e32 v165, v164
	v_sqrt_f32_e32 v168, v167
	s_nop 1
	v_pk_mul_f32 v[140:141], v[96:97], v[132:133] op_sel_hi:[1,0]
	v_cvt_pk_bf16_f32 v148, v140, v141
	v_pk_mul_f32 v[142:143], v[98:99], v[132:133] op_sel_hi:[1,0]
	v_cvt_pk_bf16_f32 v149, v142, v143
	v_pk_mul_f32 v[144:145], v[100:101], v[132:133] op_sel_hi:[1,0]
	v_cvt_pk_bf16_f32 v150, v144, v145
	v_pk_mul_f32 v[146:147], v[102:103], v[132:133] op_sel_hi:[1,0]
	v_cvt_pk_bf16_f32 v151, v146, v147
	v_pk_mul_f32 v[140:141], v[104:105], v[132:133] op_sel_hi:[1,0]
	v_cvt_pk_bf16_f32 v152, v140, v141
	v_pk_mul_f32 v[142:143], v[106:107], v[132:133] op_sel_hi:[1,0]
	v_cvt_pk_bf16_f32 v153, v142, v143
	v_pk_mul_f32 v[144:145], v[108:109], v[132:133] op_sel_hi:[1,0]
	v_cvt_pk_bf16_f32 v154, v144, v145
	v_pk_mul_f32 v[146:147], v[110:111], v[132:133] op_sel_hi:[1,0]
	v_cvt_pk_bf16_f32 v155, v146, v147
	global_store_dwordx2 v173, v[148:149], s[98:99]
	global_store_dwordx2 v173, v[150:151], s[98:99] offset:512
	global_store_dwordx2 v173, v[152:153], s[98:99] offset:1024
	global_store_dwordx2 v173, v[154:155], s[98:99] offset:1536
	v_add_u32_e32 v173, 0x400000, v173
	v_pk_mul_f32 v[140:141], v[112:113], v[134:135] op_sel_hi:[1,0]
	v_cvt_pk_bf16_f32 v156, v140, v141
	v_pk_mul_f32 v[142:143], v[114:115], v[134:135] op_sel_hi:[1,0]
	v_cvt_pk_bf16_f32 v157, v142, v143
	v_pk_mul_f32 v[144:145], v[116:117], v[134:135] op_sel_hi:[1,0]
	v_cvt_pk_bf16_f32 v158, v144, v145
	v_pk_mul_f32 v[146:147], v[118:119], v[134:135] op_sel_hi:[1,0]
	v_cvt_pk_bf16_f32 v159, v146, v147
	v_pk_mul_f32 v[140:141], v[120:121], v[134:135] op_sel_hi:[1,0]
	v_cvt_pk_bf16_f32 v160, v140, v141
	v_pk_mul_f32 v[142:143], v[122:123], v[134:135] op_sel_hi:[1,0]
	v_cvt_pk_bf16_f32 v161, v142, v143
	v_pk_mul_f32 v[144:145], v[124:125], v[134:135] op_sel_hi:[1,0]
	v_cvt_pk_bf16_f32 v162, v144, v145
	v_pk_mul_f32 v[146:147], v[126:127], v[134:135] op_sel_hi:[1,0]
	v_cvt_pk_bf16_f32 v163, v146, v147
	global_store_dwordx2 v173, v[156:157], s[98:99]
	global_store_dwordx2 v173, v[158:159], s[98:99] offset:512
	global_store_dwordx2 v173, v[160:161], s[98:99] offset:1024
	global_store_dwordx2 v173, v[162:163], s[98:99] offset:1536
	v_add_u32_e32 v173, 0x400000, v173
	v_add_u32_e32 v166, -1, v165
	v_fma_f32 v140, -v166, v165, v164
	v_cmp_ge_f32_e32 vcc, 0, v140
	v_add_u32_e32 v141, 1, v165
	v_cndmask_b32_e32 v166, v165, v166, vcc
	v_fma_f32 v140, -v141, v165, v164
	v_cmp_lt_f32_e32 vcc, 0, v140
	s_nop 1
	v_cndmask_b32_e32 v165, v166, v141, vcc
	v_add_u32_e32 v169, -1, v168
	v_fma_f32 v142, -v169, v168, v167
	v_cmp_ge_f32_e32 vcc, 0, v142
	v_add_u32_e32 v143, 1, v168
	v_cndmask_b32_e32 v169, v168, v169, vcc
	v_fma_f32 v142, -v143, v168, v167
	v_cmp_lt_f32_e32 vcc, 0, v142
	s_nop 1
	v_cndmask_b32_e32 v168, v169, v143, vcc
	s_mov_b64 exec, 1
	global_store_dword v174, v165, s[98:99]
	v_add_u32_e32 v174, 0x2000, v174
	global_store_dword v174, v168, s[98:99]
	v_add_u32_e32 v174, 0x2000, v174
	s_mov_b64 exec, -1
	global_load_dword v88, v172, s[98:99]
	global_load_dwordx2 v[56:57], v170, s[98:99]
	global_load_dwordx2 v[58:59], v170, s[98:99] offset:512
	global_load_dwordx2 v[60:61], v170, s[98:99] offset:1024
	global_load_dwordx2 v[62:63], v170, s[98:99] offset:1536
	global_load_dwordx2 v[72:73], v171, s[98:99]
	global_load_dwordx2 v[74:75], v171, s[98:99] offset:512
	global_load_dwordx2 v[76:77], v171, s[98:99] offset:1024
	global_load_dwordx2 v[78:79], v171, s[98:99] offset:1536
	v_add_u32_e32 v170, 0x400000, v170
	v_add_u32_e32 v171, 0x400000, v171
	v_add_u32_e32 v172, 0x2000, v172
	global_load_dword v90, v172, s[98:99]
	global_load_dwordx2 v[64:65], v170, s[98:99]
	global_load_dwordx2 v[66:67], v170, s[98:99] offset:512
	global_load_dwordx2 v[68:69], v170, s[98:99] offset:1024
	global_load_dwordx2 v[70:71], v170, s[98:99] offset:1536
	global_load_dwordx2 v[80:81], v171, s[98:99]
	global_load_dwordx2 v[82:83], v171, s[98:99] offset:512
	global_load_dwordx2 v[84:85], v171, s[98:99] offset:1024
	global_load_dwordx2 v[86:87], v171, s[98:99] offset:1536
	v_add_u32_e32 v170, 0x400000, v170
	v_add_u32_e32 v171, 0x400000, v171
	v_add_u32_e32 v172, 0x2000, v172
	s_waitcnt vmcnt(41)
;     __device__ __forceinline__ float* out() const { return (float*)karg_in(33); }
; __device__ __forceinline__ float ssq4(v4f v) { return (v.x * v.x + v.y * v.y) + (v.z * v.z + v.w * v.w); }
; template <int R, bool BASE_F32, bool OUT_F32>
; __device__ __forceinline__ void rows_res(const Ctx& C, int m0, int stride, int mx, const float* gpost, float scale, int lane) {
;     ...
;     for (int r = 0; r < R; ++r) { float s = 0.f;
; #pragma unroll
;         for (int j = 0; j < 4; ++j) s += ssq4(d[r][j]);
;         r1[r] = s; }
; #pragma unroll
;     for (int r = 0; r < R; ++r) r1[r] = rsqrtf(wave_sum(r1[r]) * (1.f / DM) + EPS) * scale;
; #pragma unroll
;     for (int j = 0; j < 4; ++j) { const v4f gp = ld4_f32(gpost + 4 * lane + 256 * j);
; #pragma unroll
;         for (int r = 0; r < R; ++r) d[r][j] = b[r][j] + d[r][j] * r1[r] * gp; }
;     if (OUT_F32) { float* Y = C.out();
; #pragma unroll
;         for (int r = 0; r < R; ++r)
; #pragma unroll
;             for (int j = 0; j < 4; ++j) if (ok[r]) *(v4f*)(Y + (size_t)mr[r] * DM + 4 * lane + 256 * j) = d[r][j];
;     } else { float* rs = C.RS(); float t[R];
; #pragma unroll
;         for (int r = 0; r < R; ++r) { float s = 0.f;
; #pragma unroll
;             for (int j = 0; j < 4; ++j) s += ssq4(d[r][j]);
	v_lshlrev_b32_e32 v96, 16, v20
	v_and_b32_e32 v97, 0xffff0000, v20
	v_lshlrev_b32_e32 v98, 16, v21
	v_and_b32_e32 v99, 0xffff0000, v21
	v_lshlrev_b32_e32 v100, 16, v22
	v_and_b32_e32 v101, 0xffff0000, v22
	v_lshlrev_b32_e32 v102, 16, v23
	v_and_b32_e32 v103, 0xffff0000, v23
	v_lshlrev_b32_e32 v104, 16, v24
	v_and_b32_e32 v105, 0xffff0000, v24
	v_lshlrev_b32_e32 v106, 16, v25
	v_and_b32_e32 v107, 0xffff0000, v25
	v_lshlrev_b32_e32 v108, 16, v26
	v_and_b32_e32 v109, 0xffff0000, v26
	v_lshlrev_b32_e32 v110, 16, v27
	v_and_b32_e32 v111, 0xffff0000, v27
	v_pk_mul_f32 v[128:129], v[96:97], v[96:97]
	v_pk_fma_f32 v[128:129], v[98:99], v[98:99], v[128:129]
	v_pk_fma_f32 v[128:129], v[100:101], v[100:101], v[128:129]
	v_pk_fma_f32 v[128:129], v[102:103], v[102:103], v[128:129]
	v_pk_fma_f32 v[128:129], v[104:105], v[104:105], v[128:129]
	v_pk_fma_f32 v[128:129], v[106:107], v[106:107], v[128:129]
	v_pk_fma_f32 v[128:129], v[108:109], v[108:109], v[128:129]
	v_pk_fma_f32 v[128:129], v[110:111], v[110:111], v[128:129]
	s_nop 0
	v_add_f32_e32 v128, v128, v129
	s_waitcnt vmcnt(32)
	v_lshlrev_b32_e32 v112, 16, v28
	v_and_b32_e32 v113, 0xffff0000, v28
	v_lshlrev_b32_e32 v114, 16, v29
	v_and_b32_e32 v115, 0xffff0000, v29
	v_lshlrev_b32_e32 v116, 16, v30
	v_and_b32_e32 v117, 0xffff0000, v30
	v_lshlrev_b32_e32 v118, 16, v31
	v_and_b32_e32 v119, 0xffff0000, v31
	v_lshlrev_b32_e32 v120, 16, v32
	v_and_b32_e32 v121, 0xffff0000, v32
	v_lshlrev_b32_e32 v122, 16, v33
	v_and_b32_e32 v123, 0xffff0000, v33
	v_lshlrev_b32_e32 v124, 16, v34
	v_and_b32_e32 v125, 0xffff0000, v34
	v_lshlrev_b32_e32 v126, 16, v35
	v_and_b32_e32 v127, 0xffff0000, v35
	v_pk_mul_f32 v[130:131], v[112:113], v[112:113]
	v_pk_fma_f32 v[130:131], v[114:115], v[114:115], v[130:131]
	v_pk_fma_f32 v[130:131], v[116:117], v[116:117], v[130:131]
	v_pk_fma_f32 v[130:131], v[118:119], v[118:119], v[130:131]
	v_pk_fma_f32 v[130:131], v[120:121], v[120:121], v[130:131]
	v_pk_fma_f32 v[130:131], v[122:123], v[122:123], v[130:131]
	v_pk_fma_f32 v[130:131], v[124:125], v[124:125], v[130:131]
	v_pk_fma_f32 v[130:131], v[126:127], v[126:127], v[130:131]
	s_nop 0
	v_add_f32_e32 v130, v130, v131
	s_nop 1
	v_add_f32_dpp v128, v128, v128 quad_perm:[1,0,3,2] row_mask:0xf bank_mask:0xf
	v_add_f32_dpp v130, v130, v130 quad_perm:[1,0,3,2] row_mask:0xf bank_mask:0xf
	s_nop 0
	v_add_f32_dpp v128, v128, v128 quad_perm:[2,3,0,1] row_mask:0xf bank_mask:0xf
	v_add_f32_dpp v130, v130, v130 quad_perm:[2,3,0,1] row_mask:0xf bank_mask:0xf
	s_nop 0
	v_add_f32_dpp v128, v128, v128 row_half_mirror row_mask:0xf bank_mask:0xf
	v_add_f32_dpp v130, v130, v130 row_half_mirror row_mask:0xf bank_mask:0xf
	s_nop 0
	v_add_f32_dpp v128, v128, v128 row_mirror row_mask:0xf bank_mask:0xf
	v_add_f32_dpp v130, v130, v130 row_mirror row_mask:0xf bank_mask:0xf
	s_nop 0
	ds_bpermute_b32 v136, v187, v128
	ds_bpermute_b32 v137, v187, v130
	s_waitcnt lgkmcnt(0)
	v_add_f32_e32 v128, v128, v136
	v_add_f32_e32 v130, v130, v137
	ds_bpermute_b32 v136, v188, v128
	ds_bpermute_b32 v137, v188, v130
	s_waitcnt lgkmcnt(0)
	v_add_f32_e32 v128, v128, v136
	v_add_f32_e32 v130, v130, v137
	v_fmamk_f32 v128, v128, 0x3a800000, v138
	v_fmamk_f32 v130, v130, 0x3a800000, v138
	s_nop 0
	v_rsq_f32_e32 v128, v128
	v_rsq_f32_e32 v130, v130
	s_nop 1
	v_mul_f32_e32 v128, 0.5, v128
	v_mul_f32_e32 v130, 0.5, v130
	s_waitcnt vmcnt(28)
	v_pk_mul_f32 v[96:97], v[128:129], v[96:97] op_sel_hi:[0,1]
	v_pk_mul_f32 v[98:99], v[128:129], v[98:99] op_sel_hi:[0,1]
	v_pk_mul_f32 v[100:101], v[128:129], v[100:101] op_sel_hi:[0,1]
	v_pk_mul_f32 v[102:103], v[128:129], v[102:103] op_sel_hi:[0,1]
	v_pk_mul_f32 v[104:105], v[128:129], v[104:105] op_sel_hi:[0,1]
	v_pk_mul_f32 v[106:107], v[128:129], v[106:107] op_sel_hi:[0,1]
	v_pk_mul_f32 v[108:109], v[128:129], v[108:109] op_sel_hi:[0,1]
	v_pk_mul_f32 v[110:111], v[128:129], v[110:111] op_sel_hi:[0,1]
	v_pk_mul_f32 v[96:97], v[96:97], v[192:193]
	v_pk_mul_f32 v[98:99], v[98:99], v[194:195]
	v_pk_mul_f32 v[100:101], v[100:101], v[196:197]
	v_pk_mul_f32 v[102:103], v[102:103], v[198:199]
	v_pk_mul_f32 v[104:105], v[104:105], v[200:201]
	v_pk_mul_f32 v[106:107], v[106:107], v[202:203]
	v_pk_mul_f32 v[108:109], v[108:109], v[204:205]
	v_pk_mul_f32 v[110:111], v[110:111], v[206:207]
	v_lshlrev_b32_e32 v20, 16, v36
	v_and_b32_e32 v21, 0xffff0000, v36
	v_lshlrev_b32_e32 v22, 16, v37
	v_and_b32_e32 v23, 0xffff0000, v37
	v_lshlrev_b32_e32 v24, 16, v38
	v_and_b32_e32 v25, 0xffff0000, v38
	v_lshlrev_b32_e32 v26, 16, v39
	v_and_b32_e32 v27, 0xffff0000, v39
	v_pk_fma_f32 v[96:97], v[52:53], v[20:21], v[96:97] op_sel_hi:[0,1,1]
	v_pk_fma_f32 v[98:99], v[52:53], v[22:23], v[98:99] op_sel_hi:[0,1,1]
	v_pk_fma_f32 v[100:101], v[52:53], v[24:25], v[100:101] op_sel_hi:[0,1,1]
	v_pk_fma_f32 v[102:103], v[52:53], v[26:27], v[102:103] op_sel_hi:[0,1,1]
	v_lshlrev_b32_e32 v20, 16, v40
	v_and_b32_e32 v21, 0xffff0000, v40
	v_lshlrev_b32_e32 v22, 16, v41
	v_and_b32_e32 v23, 0xffff0000, v41
	v_lshlrev_b32_e32 v24, 16, v42
	v_and_b32_e32 v25, 0xffff0000, v42
	v_lshlrev_b32_e32 v26, 16, v43
	v_and_b32_e32 v27, 0xffff0000, v43
	v_pk_fma_f32 v[104:105], v[52:53], v[20:21], v[104:105] op_sel_hi:[0,1,1]
	v_pk_fma_f32 v[106:107], v[52:53], v[22:23], v[106:107] op_sel_hi:[0,1,1]
	v_pk_fma_f32 v[108:109], v[52:53], v[24:25], v[108:109] op_sel_hi:[0,1,1]
	v_pk_fma_f32 v[110:111], v[52:53], v[26:27], v[110:111] op_sel_hi:[0,1,1]
	v_pk_mul_f32 v[132:133], v[96:97], v[96:97]
	v_pk_fma_f32 v[132:133], v[98:99], v[98:99], v[132:133]
	v_pk_fma_f32 v[132:133], v[100:101], v[100:101], v[132:133]
	v_pk_fma_f32 v[132:133], v[102:103], v[102:103], v[132:133]
; __device__ __forceinline__ void st4_bf16(bf16* p, v4f o) { v2u w; w.x = cvt_pk_nv(o.x, o.y); w.y = cvt_pk_nv(o.z, o.w); *(v2u*)p = w; }
; __device__ __forceinline__ float ssq4(v4f v) { return (v.x * v.x + v.y * v.y) + (v.z * v.z + v.w * v.w); }
; template <int R, bool BASE_F32, bool OUT_F32>
; __device__ __forceinline__ void rows_res(const Ctx& C, int m0, int stride, int mx, const float* gpost, float scale, int lane) {
;     ...
;         for (int r = 0; r < R; ++r) { float s = 0.f;
; #pragma unroll
;             for (int j = 0; j < 4; ++j) s += ssq4(d[r][j]);
;             t[r] = s; }
; #pragma unroll
;         for (int r = 0; r < R; ++r) t[r] = wave_sum(t[r]) * (1.f / DM) + EPS;
; #pragma unroll
;         for (int r = 0; r < R; ++r) { const float rstd = rsqrtf(t[r]);
; #pragma unroll
;             for (int j = 0; j < 4; ++j) if (ok[r]) st4_bf16(XN + (size_t)mr[r] * DM + 4 * lane + 256 * j, d[r][j] * rstd);
;             if (lane == 0 && ok[r]) rs[mr[r]] = sqrtf(t[r]); }
	v_pk_fma_f32 v[132:133], v[104:105], v[104:105], v[132:133]
	v_pk_fma_f32 v[132:133], v[106:107], v[106:107], v[132:133]
	v_pk_fma_f32 v[132:133], v[108:109], v[108:109], v[132:133]
	v_pk_fma_f32 v[132:133], v[110:111], v[110:111], v[132:133]
	s_nop 0
	v_add_f32_e32 v132, v132, v133
	v_pk_mul_f32 v[112:113], v[130:131], v[112:113] op_sel_hi:[0,1]
	v_pk_mul_f32 v[114:115], v[130:131], v[114:115] op_sel_hi:[0,1]
	v_pk_mul_f32 v[116:117], v[130:131], v[116:117] op_sel_hi:[0,1]
	v_pk_mul_f32 v[118:119], v[130:131], v[118:119] op_sel_hi:[0,1]
	v_pk_mul_f32 v[120:121], v[130:131], v[120:121] op_sel_hi:[0,1]
	v_pk_mul_f32 v[122:123], v[130:131], v[122:123] op_sel_hi:[0,1]
	v_pk_mul_f32 v[124:125], v[130:131], v[124:125] op_sel_hi:[0,1]
	v_pk_mul_f32 v[126:127], v[130:131], v[126:127] op_sel_hi:[0,1]
	v_pk_mul_f32 v[112:113], v[112:113], v[192:193]
	v_pk_mul_f32 v[114:115], v[114:115], v[194:195]
	v_pk_mul_f32 v[116:117], v[116:117], v[196:197]
	v_pk_mul_f32 v[118:119], v[118:119], v[198:199]
	v_pk_mul_f32 v[120:121], v[120:121], v[200:201]
	v_pk_mul_f32 v[122:123], v[122:123], v[202:203]
	v_pk_mul_f32 v[124:125], v[124:125], v[204:205]
	v_pk_mul_f32 v[126:127], v[126:127], v[206:207]
	v_lshlrev_b32_e32 v28, 16, v44
	v_and_b32_e32 v29, 0xffff0000, v44
	v_lshlrev_b32_e32 v30, 16, v45
	v_and_b32_e32 v31, 0xffff0000, v45
	v_lshlrev_b32_e32 v32, 16, v46
	v_and_b32_e32 v33, 0xffff0000, v46
	v_lshlrev_b32_e32 v34, 16, v47
	v_and_b32_e32 v35, 0xffff0000, v47
	v_pk_fma_f32 v[112:113], v[54:55], v[28:29], v[112:113] op_sel_hi:[0,1,1]
	v_pk_fma_f32 v[114:115], v[54:55], v[30:31], v[114:115] op_sel_hi:[0,1,1]
	v_pk_fma_f32 v[116:117], v[54:55], v[32:33], v[116:117] op_sel_hi:[0,1,1]
	v_pk_fma_f32 v[118:119], v[54:55], v[34:35], v[118:119] op_sel_hi:[0,1,1]
	v_lshlrev_b32_e32 v28, 16, v48
	v_and_b32_e32 v29, 0xffff0000, v48
	v_lshlrev_b32_e32 v30, 16, v49
	v_and_b32_e32 v31, 0xffff0000, v49
	v_lshlrev_b32_e32 v32, 16, v50
	v_and_b32_e32 v33, 0xffff0000, v50
	v_lshlrev_b32_e32 v34, 16, v51
	v_and_b32_e32 v35, 0xffff0000, v51
	v_pk_fma_f32 v[120:121], v[54:55], v[28:29], v[120:121] op_sel_hi:[0,1,1]
	v_pk_fma_f32 v[122:123], v[54:55], v[30:31], v[122:123] op_sel_hi:[0,1,1]
	v_pk_fma_f32 v[124:125], v[54:55], v[32:33], v[124:125] op_sel_hi:[0,1,1]
	v_pk_fma_f32 v[126:127], v[54:55], v[34:35], v[126:127] op_sel_hi:[0,1,1]
	v_pk_mul_f32 v[134:135], v[112:113], v[112:113]
	v_pk_fma_f32 v[134:135], v[114:115], v[114:115], v[134:135]
	v_pk_fma_f32 v[134:135], v[116:117], v[116:117], v[134:135]
	v_pk_fma_f32 v[134:135], v[118:119], v[118:119], v[134:135]
	v_pk_fma_f32 v[134:135], v[120:121], v[120:121], v[134:135]
	v_pk_fma_f32 v[134:135], v[122:123], v[122:123], v[134:135]
	v_pk_fma_f32 v[134:135], v[124:125], v[124:125], v[134:135]
	v_pk_fma_f32 v[134:135], v[126:127], v[126:127], v[134:135]
	s_nop 0
	v_add_f32_e32 v134, v134, v135
	s_nop 1
	v_add_f32_dpp v132, v132, v132 quad_perm:[1,0,3,2] row_mask:0xf bank_mask:0xf
	v_add_f32_dpp v134, v134, v134 quad_perm:[1,0,3,2] row_mask:0xf bank_mask:0xf
	s_nop 0
	v_add_f32_dpp v132, v132, v132 quad_perm:[2,3,0,1] row_mask:0xf bank_mask:0xf
	v_add_f32_dpp v134, v134, v134 quad_perm:[2,3,0,1] row_mask:0xf bank_mask:0xf
	s_nop 0
	v_add_f32_dpp v132, v132, v132 row_half_mirror row_mask:0xf bank_mask:0xf
	v_add_f32_dpp v134, v134, v134 row_half_mirror row_mask:0xf bank_mask:0xf
	s_nop 0
	v_add_f32_dpp v132, v132, v132 row_mirror row_mask:0xf bank_mask:0xf
	v_add_f32_dpp v134, v134, v134 row_mirror row_mask:0xf bank_mask:0xf
	s_nop 0
	ds_bpermute_b32 v136, v187, v132
	ds_bpermute_b32 v137, v187, v134
	s_waitcnt lgkmcnt(0)
	v_add_f32_e32 v132, v132, v136
	v_add_f32_e32 v134, v134, v137
	ds_bpermute_b32 v136, v188, v132
	ds_bpermute_b32 v137, v188, v134
	s_waitcnt lgkmcnt(0)
	v_add_f32_e32 v132, v132, v136
	v_add_f32_e32 v134, v134, v137
	v_fmamk_f32 v164, v132, 0x3a800000, v138
	v_fmamk_f32 v167, v134, 0x3a800000, v138
	s_nop 0
	v_rsq_f32_e32 v132, v164
	v_rsq_f32_e32 v134, v167
	v_sqrt_f32_e32 v165, v164
	v_sqrt_f32_e32 v168, v167
	s_nop 1
	v_pk_mul_f32 v[140:141], v[96:97], v[132:133] op_sel_hi:[1,0]
	v_cvt_pk_bf16_f32 v148, v140, v141
	v_pk_mul_f32 v[142:143], v[98:99], v[132:133] op_sel_hi:[1,0]
	v_cvt_pk_bf16_f32 v149, v142, v143
	v_pk_mul_f32 v[144:145], v[100:101], v[132:133] op_sel_hi:[1,0]
	v_cvt_pk_bf16_f32 v150, v144, v145
	v_pk_mul_f32 v[146:147], v[102:103], v[132:133] op_sel_hi:[1,0]
	v_cvt_pk_bf16_f32 v151, v146, v147
	v_pk_mul_f32 v[140:141], v[104:105], v[132:133] op_sel_hi:[1,0]
	v_cvt_pk_bf16_f32 v152, v140, v141
	v_pk_mul_f32 v[142:143], v[106:107], v[132:133] op_sel_hi:[1,0]
	v_cvt_pk_bf16_f32 v153, v142, v143
	v_pk_mul_f32 v[144:145], v[108:109], v[132:133] op_sel_hi:[1,0]
	v_cvt_pk_bf16_f32 v154, v144, v145
	v_pk_mul_f32 v[146:147], v[110:111], v[132:133] op_sel_hi:[1,0]
	v_cvt_pk_bf16_f32 v155, v146, v147
	global_store_dwordx2 v173, v[148:149], s[98:99]
	global_store_dwordx2 v173, v[150:151], s[98:99] offset:512
	global_store_dwordx2 v173, v[152:153], s[98:99] offset:1024
	global_store_dwordx2 v173, v[154:155], s[98:99] offset:1536
	v_add_u32_e32 v173, 0x400000, v173
	v_pk_mul_f32 v[140:141], v[112:113], v[134:135] op_sel_hi:[1,0]
	v_cvt_pk_bf16_f32 v156, v140, v141
	v_pk_mul_f32 v[142:143], v[114:115], v[134:135] op_sel_hi:[1,0]
	v_cvt_pk_bf16_f32 v157, v142, v143
	v_pk_mul_f32 v[144:145], v[116:117], v[134:135] op_sel_hi:[1,0]
	v_cvt_pk_bf16_f32 v158, v144, v145
	v_pk_mul_f32 v[146:147], v[118:119], v[134:135] op_sel_hi:[1,0]
	v_cvt_pk_bf16_f32 v159, v146, v147
	v_pk_mul_f32 v[140:141], v[120:121], v[134:135] op_sel_hi:[1,0]
	v_cvt_pk_bf16_f32 v160, v140, v141
	v_pk_mul_f32 v[142:143], v[122:123], v[134:135] op_sel_hi:[1,0]
	v_cvt_pk_bf16_f32 v161, v142, v143
	v_pk_mul_f32 v[144:145], v[124:125], v[134:135] op_sel_hi:[1,0]
	v_cvt_pk_bf16_f32 v162, v144, v145
	v_pk_mul_f32 v[146:147], v[126:127], v[134:135] op_sel_hi:[1,0]
	v_cvt_pk_bf16_f32 v163, v146, v147
	global_store_dwordx2 v173, v[156:157], s[98:99]
	global_store_dwordx2 v173, v[158:159], s[98:99] offset:512
	global_store_dwordx2 v173, v[160:161], s[98:99] offset:1024
	global_store_dwordx2 v173, v[162:163], s[98:99] offset:1536
	v_add_u32_e32 v173, 0x400000, v173
	v_add_u32_e32 v166, -1, v165
	v_fma_f32 v140, -v166, v165, v164
	v_cmp_ge_f32_e32 vcc, 0, v140
	v_add_u32_e32 v141, 1, v165
	v_cndmask_b32_e32 v166, v165, v166, vcc
	v_fma_f32 v140, -v141, v165, v164
	v_cmp_lt_f32_e32 vcc, 0, v140
	s_nop 1
	v_cndmask_b32_e32 v165, v166, v141, vcc
	v_add_u32_e32 v169, -1, v168
	v_fma_f32 v142, -v169, v168, v167
	v_cmp_ge_f32_e32 vcc, 0, v142
	v_add_u32_e32 v143, 1, v168
	v_cndmask_b32_e32 v169, v168, v169, vcc
	v_fma_f32 v142, -v143, v168, v167
	v_cmp_lt_f32_e32 vcc, 0, v142
	s_nop 1
	v_cndmask_b32_e32 v168, v169, v143, vcc
	s_mov_b64 exec, 1
	global_store_dword v174, v165, s[98:99]
	v_add_u32_e32 v174, 0x2000, v174
	global_store_dword v174, v168, s[98:99]
	v_add_u32_e32 v174, 0x2000, v174
	s_mov_b64 exec, -1
	s_waitcnt vmcnt(23)
;     __device__ __forceinline__ float* out() const { return (float*)karg_in(33); }
; __device__ __forceinline__ float ssq4(v4f v) { return (v.x * v.x + v.y * v.y) + (v.z * v.z + v.w * v.w); }
; template <int R, bool BASE_F32, bool OUT_F32>
; __device__ __forceinline__ void rows_res(const Ctx& C, int m0, int stride, int mx, const float* gpost, float scale, int lane) {
;     ...
;     for (int r = 0; r < R; ++r) { float s = 0.f;
; #pragma unroll
;         for (int j = 0; j < 4; ++j) s += ssq4(d[r][j]);
;         r1[r] = s; }
; #pragma unroll
;     for (int r = 0; r < R; ++r) r1[r] = rsqrtf(wave_sum(r1[r]) * (1.f / DM) + EPS) * scale;
; #pragma unroll
;     for (int j = 0; j < 4; ++j) { const v4f gp = ld4_f32(gpost + 4 * lane + 256 * j);
; #pragma unroll
;         for (int r = 0; r < R; ++r) d[r][j] = b[r][j] + d[r][j] * r1[r] * gp; }
;     if (OUT_F32) { float* Y = C.out();
; #pragma unroll
;         for (int r = 0; r < R; ++r)
; #pragma unroll
;             for (int j = 0; j < 4; ++j) if (ok[r]) *(v4f*)(Y + (size_t)mr[r] * DM + 4 * lane + 256 * j) = d[r][j];
;     } else { float* rs = C.RS(); float t[R];
; #pragma unroll
;         for (int r = 0; r < R; ++r) { float s = 0.f;
; #pragma unroll
;             for (int j = 0; j < 4; ++j) s += ssq4(d[r][j]);
	v_lshlrev_b32_e32 v96, 16, v56
	v_and_b32_e32 v97, 0xffff0000, v56
	v_lshlrev_b32_e32 v98, 16, v57
	v_and_b32_e32 v99, 0xffff0000, v57
	v_lshlrev_b32_e32 v100, 16, v58
	v_and_b32_e32 v101, 0xffff0000, v58
	v_lshlrev_b32_e32 v102, 16, v59
	v_and_b32_e32 v103, 0xffff0000, v59
	v_lshlrev_b32_e32 v104, 16, v60
	v_and_b32_e32 v105, 0xffff0000, v60
	v_lshlrev_b32_e32 v106, 16, v61
	v_and_b32_e32 v107, 0xffff0000, v61
	v_lshlrev_b32_e32 v108, 16, v62
	v_and_b32_e32 v109, 0xffff0000, v62
	v_lshlrev_b32_e32 v110, 16, v63
	v_and_b32_e32 v111, 0xffff0000, v63
	v_pk_mul_f32 v[128:129], v[96:97], v[96:97]
	v_pk_fma_f32 v[128:129], v[98:99], v[98:99], v[128:129]
	v_pk_fma_f32 v[128:129], v[100:101], v[100:101], v[128:129]
	v_pk_fma_f32 v[128:129], v[102:103], v[102:103], v[128:129]
	v_pk_fma_f32 v[128:129], v[104:105], v[104:105], v[128:129]
	v_pk_fma_f32 v[128:129], v[106:107], v[106:107], v[128:129]
	v_pk_fma_f32 v[128:129], v[108:109], v[108:109], v[128:129]
	v_pk_fma_f32 v[128:129], v[110:111], v[110:111], v[128:129]
	s_nop 0
	v_add_f32_e32 v128, v128, v129
	s_waitcnt vmcnt(14)
	v_lshlrev_b32_e32 v112, 16, v64
	v_and_b32_e32 v113, 0xffff0000, v64
	v_lshlrev_b32_e32 v114, 16, v65
	v_and_b32_e32 v115, 0xffff0000, v65
	v_lshlrev_b32_e32 v116, 16, v66
	v_and_b32_e32 v117, 0xffff0000, v66
	v_lshlrev_b32_e32 v118, 16, v67
	v_and_b32_e32 v119, 0xffff0000, v67
	v_lshlrev_b32_e32 v120, 16, v68
	v_and_b32_e32 v121, 0xffff0000, v68
	v_lshlrev_b32_e32 v122, 16, v69
	v_and_b32_e32 v123, 0xffff0000, v69
	v_lshlrev_b32_e32 v124, 16, v70
	v_and_b32_e32 v125, 0xffff0000, v70
	v_lshlrev_b32_e32 v126, 16, v71
	v_and_b32_e32 v127, 0xffff0000, v71
	v_pk_mul_f32 v[130:131], v[112:113], v[112:113]
	v_pk_fma_f32 v[130:131], v[114:115], v[114:115], v[130:131]
	v_pk_fma_f32 v[130:131], v[116:117], v[116:117], v[130:131]
	v_pk_fma_f32 v[130:131], v[118:119], v[118:119], v[130:131]
	v_pk_fma_f32 v[130:131], v[120:121], v[120:121], v[130:131]
	v_pk_fma_f32 v[130:131], v[122:123], v[122:123], v[130:131]
	v_pk_fma_f32 v[130:131], v[124:125], v[124:125], v[130:131]
	v_pk_fma_f32 v[130:131], v[126:127], v[126:127], v[130:131]
	s_nop 0
	v_add_f32_e32 v130, v130, v131
	s_nop 1
	v_add_f32_dpp v128, v128, v128 quad_perm:[1,0,3,2] row_mask:0xf bank_mask:0xf
	v_add_f32_dpp v130, v130, v130 quad_perm:[1,0,3,2] row_mask:0xf bank_mask:0xf
	s_nop 0
	v_add_f32_dpp v128, v128, v128 quad_perm:[2,3,0,1] row_mask:0xf bank_mask:0xf
	v_add_f32_dpp v130, v130, v130 quad_perm:[2,3,0,1] row_mask:0xf bank_mask:0xf
	s_nop 0
	v_add_f32_dpp v128, v128, v128 row_half_mirror row_mask:0xf bank_mask:0xf
	v_add_f32_dpp v130, v130, v130 row_half_mirror row_mask:0xf bank_mask:0xf
	s_nop 0
	v_add_f32_dpp v128, v128, v128 row_mirror row_mask:0xf bank_mask:0xf
	v_add_f32_dpp v130, v130, v130 row_mirror row_mask:0xf bank_mask:0xf
	s_nop 0
	ds_bpermute_b32 v136, v187, v128
	ds_bpermute_b32 v137, v187, v130
	s_waitcnt lgkmcnt(0)
	v_add_f32_e32 v128, v128, v136
	v_add_f32_e32 v130, v130, v137
	ds_bpermute_b32 v136, v188, v128
	ds_bpermute_b32 v137, v188, v130
	s_waitcnt lgkmcnt(0)
	v_add_f32_e32 v128, v128, v136
	v_add_f32_e32 v130, v130, v137
	v_fmamk_f32 v128, v128, 0x3a800000, v138
	v_fmamk_f32 v130, v130, 0x3a800000, v138
	s_nop 0
	v_rsq_f32_e32 v128, v128
	v_rsq_f32_e32 v130, v130
	s_nop 1
	v_mul_f32_e32 v128, 0.5, v128
	v_mul_f32_e32 v130, 0.5, v130
	s_waitcnt vmcnt(10)
	v_pk_mul_f32 v[96:97], v[128:129], v[96:97] op_sel_hi:[0,1]
	v_pk_mul_f32 v[98:99], v[128:129], v[98:99] op_sel_hi:[0,1]
	v_pk_mul_f32 v[100:101], v[128:129], v[100:101] op_sel_hi:[0,1]
	v_pk_mul_f32 v[102:103], v[128:129], v[102:103] op_sel_hi:[0,1]
	v_pk_mul_f32 v[104:105], v[128:129], v[104:105] op_sel_hi:[0,1]
	v_pk_mul_f32 v[106:107], v[128:129], v[106:107] op_sel_hi:[0,1]
	v_pk_mul_f32 v[108:109], v[128:129], v[108:109] op_sel_hi:[0,1]
	v_pk_mul_f32 v[110:111], v[128:129], v[110:111] op_sel_hi:[0,1]
	v_pk_mul_f32 v[96:97], v[96:97], v[192:193]
	v_pk_mul_f32 v[98:99], v[98:99], v[194:195]
	v_pk_mul_f32 v[100:101], v[100:101], v[196:197]
	v_pk_mul_f32 v[102:103], v[102:103], v[198:199]
	v_pk_mul_f32 v[104:105], v[104:105], v[200:201]
	v_pk_mul_f32 v[106:107], v[106:107], v[202:203]
	v_pk_mul_f32 v[108:109], v[108:109], v[204:205]
	v_pk_mul_f32 v[110:111], v[110:111], v[206:207]
	v_lshlrev_b32_e32 v56, 16, v72
	v_and_b32_e32 v57, 0xffff0000, v72
	v_lshlrev_b32_e32 v58, 16, v73
	v_and_b32_e32 v59, 0xffff0000, v73
	v_lshlrev_b32_e32 v60, 16, v74
	v_and_b32_e32 v61, 0xffff0000, v74
	v_lshlrev_b32_e32 v62, 16, v75
	v_and_b32_e32 v63, 0xffff0000, v75
	v_pk_fma_f32 v[96:97], v[88:89], v[56:57], v[96:97] op_sel_hi:[0,1,1]
	v_pk_fma_f32 v[98:99], v[88:89], v[58:59], v[98:99] op_sel_hi:[0,1,1]
	v_pk_fma_f32 v[100:101], v[88:89], v[60:61], v[100:101] op_sel_hi:[0,1,1]
	v_pk_fma_f32 v[102:103], v[88:89], v[62:63], v[102:103] op_sel_hi:[0,1,1]
	v_lshlrev_b32_e32 v56, 16, v76
	v_and_b32_e32 v57, 0xffff0000, v76
	v_lshlrev_b32_e32 v58, 16, v77
	v_and_b32_e32 v59, 0xffff0000, v77
	v_lshlrev_b32_e32 v60, 16, v78
	v_and_b32_e32 v61, 0xffff0000, v78
	v_lshlrev_b32_e32 v62, 16, v79
	v_and_b32_e32 v63, 0xffff0000, v79
	v_pk_fma_f32 v[104:105], v[88:89], v[56:57], v[104:105] op_sel_hi:[0,1,1]
	v_pk_fma_f32 v[106:107], v[88:89], v[58:59], v[106:107] op_sel_hi:[0,1,1]
	v_pk_fma_f32 v[108:109], v[88:89], v[60:61], v[108:109] op_sel_hi:[0,1,1]
	v_pk_fma_f32 v[110:111], v[88:89], v[62:63], v[110:111] op_sel_hi:[0,1,1]
	v_pk_mul_f32 v[132:133], v[96:97], v[96:97]
	v_pk_fma_f32 v[132:133], v[98:99], v[98:99], v[132:133]
	v_pk_fma_f32 v[132:133], v[100:101], v[100:101], v[132:133]
	v_pk_fma_f32 v[132:133], v[102:103], v[102:103], v[132:133]
; __device__ __forceinline__ void st4_bf16(bf16* p, v4f o) { v2u w; w.x = cvt_pk_nv(o.x, o.y); w.y = cvt_pk_nv(o.z, o.w); *(v2u*)p = w; }
; __device__ __forceinline__ float ssq4(v4f v) { return (v.x * v.x + v.y * v.y) + (v.z * v.z + v.w * v.w); }
; template <int R, bool BASE_F32, bool OUT_F32>
; __device__ __forceinline__ void rows_res(const Ctx& C, int m0, int stride, int mx, const float* gpost, float scale, int lane) {
;     ...
;         for (int r = 0; r < R; ++r) { float s = 0.f;
; #pragma unroll
;             for (int j = 0; j < 4; ++j) s += ssq4(d[r][j]);
;             t[r] = s; }
; #pragma unroll
;         for (int r = 0; r < R; ++r) t[r] = wave_sum(t[r]) * (1.f / DM) + EPS;
; #pragma unroll
;         for (int r = 0; r < R; ++r) { const float rstd = rsqrtf(t[r]);
; #pragma unroll
;             for (int j = 0; j < 4; ++j) if (ok[r]) st4_bf16(XN + (size_t)mr[r] * DM + 4 * lane + 256 * j, d[r][j] * rstd);
;             if (lane == 0 && ok[r]) rs[mr[r]] = sqrtf(t[r]); }
	v_pk_fma_f32 v[132:133], v[104:105], v[104:105], v[132:133]
	v_pk_fma_f32 v[132:133], v[106:107], v[106:107], v[132:133]
	v_pk_fma_f32 v[132:133], v[108:109], v[108:109], v[132:133]
	v_pk_fma_f32 v[132:133], v[110:111], v[110:111], v[132:133]
	s_nop 0
	v_add_f32_e32 v132, v132, v133
	v_pk_mul_f32 v[112:113], v[130:131], v[112:113] op_sel_hi:[0,1]
	v_pk_mul_f32 v[114:115], v[130:131], v[114:115] op_sel_hi:[0,1]
	v_pk_mul_f32 v[116:117], v[130:131], v[116:117] op_sel_hi:[0,1]
	v_pk_mul_f32 v[118:119], v[130:131], v[118:119] op_sel_hi:[0,1]
	v_pk_mul_f32 v[120:121], v[130:131], v[120:121] op_sel_hi:[0,1]
	v_pk_mul_f32 v[122:123], v[130:131], v[122:123] op_sel_hi:[0,1]
	v_pk_mul_f32 v[124:125], v[130:131], v[124:125] op_sel_hi:[0,1]
	v_pk_mul_f32 v[126:127], v[130:131], v[126:127] op_sel_hi:[0,1]
	v_pk_mul_f32 v[112:113], v[112:113], v[192:193]
	v_pk_mul_f32 v[114:115], v[114:115], v[194:195]
	v_pk_mul_f32 v[116:117], v[116:117], v[196:197]
	v_pk_mul_f32 v[118:119], v[118:119], v[198:199]
	v_pk_mul_f32 v[120:121], v[120:121], v[200:201]
	v_pk_mul_f32 v[122:123], v[122:123], v[202:203]
	v_pk_mul_f32 v[124:125], v[124:125], v[204:205]
	v_pk_mul_f32 v[126:127], v[126:127], v[206:207]
	v_lshlrev_b32_e32 v64, 16, v80
	v_and_b32_e32 v65, 0xffff0000, v80
	v_lshlrev_b32_e32 v66, 16, v81
	v_and_b32_e32 v67, 0xffff0000, v81
	v_lshlrev_b32_e32 v68, 16, v82
	v_and_b32_e32 v69, 0xffff0000, v82
	v_lshlrev_b32_e32 v70, 16, v83
	v_and_b32_e32 v71, 0xffff0000, v83
	v_pk_fma_f32 v[112:113], v[90:91], v[64:65], v[112:113] op_sel_hi:[0,1,1]
	v_pk_fma_f32 v[114:115], v[90:91], v[66:67], v[114:115] op_sel_hi:[0,1,1]
	v_pk_fma_f32 v[116:117], v[90:91], v[68:69], v[116:117] op_sel_hi:[0,1,1]
	v_pk_fma_f32 v[118:119], v[90:91], v[70:71], v[118:119] op_sel_hi:[0,1,1]
	v_lshlrev_b32_e32 v64, 16, v84
	v_and_b32_e32 v65, 0xffff0000, v84
	v_lshlrev_b32_e32 v66, 16, v85
	v_and_b32_e32 v67, 0xffff0000, v85
	v_lshlrev_b32_e32 v68, 16, v86
	v_and_b32_e32 v69, 0xffff0000, v86
	v_lshlrev_b32_e32 v70, 16, v87
	v_and_b32_e32 v71, 0xffff0000, v87
	v_pk_fma_f32 v[120:121], v[90:91], v[64:65], v[120:121] op_sel_hi:[0,1,1]
	v_pk_fma_f32 v[122:123], v[90:91], v[66:67], v[122:123] op_sel_hi:[0,1,1]
	v_pk_fma_f32 v[124:125], v[90:91], v[68:69], v[124:125] op_sel_hi:[0,1,1]
	v_pk_fma_f32 v[126:127], v[90:91], v[70:71], v[126:127] op_sel_hi:[0,1,1]
	v_pk_mul_f32 v[134:135], v[112:113], v[112:113]
	v_pk_fma_f32 v[134:135], v[114:115], v[114:115], v[134:135]
	v_pk_fma_f32 v[134:135], v[116:117], v[116:117], v[134:135]
	v_pk_fma_f32 v[134:135], v[118:119], v[118:119], v[134:135]
	v_pk_fma_f32 v[134:135], v[120:121], v[120:121], v[134:135]
	v_pk_fma_f32 v[134:135], v[122:123], v[122:123], v[134:135]
	v_pk_fma_f32 v[134:135], v[124:125], v[124:125], v[134:135]
	v_pk_fma_f32 v[134:135], v[126:127], v[126:127], v[134:135]
	s_nop 0
	v_add_f32_e32 v134, v134, v135
	s_nop 1
	v_add_f32_dpp v132, v132, v132 quad_perm:[1,0,3,2] row_mask:0xf bank_mask:0xf
	v_add_f32_dpp v134, v134, v134 quad_perm:[1,0,3,2] row_mask:0xf bank_mask:0xf
	s_nop 0
	v_add_f32_dpp v132, v132, v132 quad_perm:[2,3,0,1] row_mask:0xf bank_mask:0xf
	v_add_f32_dpp v134, v134, v134 quad_perm:[2,3,0,1] row_mask:0xf bank_mask:0xf
	s_nop 0
	v_add_f32_dpp v132, v132, v132 row_half_mirror row_mask:0xf bank_mask:0xf
	v_add_f32_dpp v134, v134, v134 row_half_mirror row_mask:0xf bank_mask:0xf
	s_nop 0
	v_add_f32_dpp v132, v132, v132 row_mirror row_mask:0xf bank_mask:0xf
	v_add_f32_dpp v134, v134, v134 row_mirror row_mask:0xf bank_mask:0xf
	s_nop 0
	ds_bpermute_b32 v136, v187, v132
	ds_bpermute_b32 v137, v187, v134
	s_waitcnt lgkmcnt(0)
	v_add_f32_e32 v132, v132, v136
	v_add_f32_e32 v134, v134, v137
	ds_bpermute_b32 v136, v188, v132
	ds_bpermute_b32 v137, v188, v134
	s_waitcnt lgkmcnt(0)
	v_add_f32_e32 v132, v132, v136
	v_add_f32_e32 v134, v134, v137
	v_fmamk_f32 v164, v132, 0x3a800000, v138
	v_fmamk_f32 v167, v134, 0x3a800000, v138
	s_nop 0
	v_rsq_f32_e32 v132, v164
	v_rsq_f32_e32 v134, v167
	v_sqrt_f32_e32 v165, v164
	v_sqrt_f32_e32 v168, v167
	s_nop 1
	v_pk_mul_f32 v[140:141], v[96:97], v[132:133] op_sel_hi:[1,0]
	v_cvt_pk_bf16_f32 v148, v140, v141
	v_pk_mul_f32 v[142:143], v[98:99], v[132:133] op_sel_hi:[1,0]
	v_cvt_pk_bf16_f32 v149, v142, v143
	v_pk_mul_f32 v[144:145], v[100:101], v[132:133] op_sel_hi:[1,0]
	v_cvt_pk_bf16_f32 v150, v144, v145
	v_pk_mul_f32 v[146:147], v[102:103], v[132:133] op_sel_hi:[1,0]
	v_cvt_pk_bf16_f32 v151, v146, v147
	v_pk_mul_f32 v[140:141], v[104:105], v[132:133] op_sel_hi:[1,0]
	v_cvt_pk_bf16_f32 v152, v140, v141
	v_pk_mul_f32 v[142:143], v[106:107], v[132:133] op_sel_hi:[1,0]
	v_cvt_pk_bf16_f32 v153, v142, v143
	v_pk_mul_f32 v[144:145], v[108:109], v[132:133] op_sel_hi:[1,0]
	v_cvt_pk_bf16_f32 v154, v144, v145
	v_pk_mul_f32 v[146:147], v[110:111], v[132:133] op_sel_hi:[1,0]
	v_cvt_pk_bf16_f32 v155, v146, v147
	global_store_dwordx2 v173, v[148:149], s[98:99]
	global_store_dwordx2 v173, v[150:151], s[98:99] offset:512
	global_store_dwordx2 v173, v[152:153], s[98:99] offset:1024
	global_store_dwordx2 v173, v[154:155], s[98:99] offset:1536
	v_add_u32_e32 v173, 0x400000, v173
	v_pk_mul_f32 v[140:141], v[112:113], v[134:135] op_sel_hi:[1,0]
	v_cvt_pk_bf16_f32 v156, v140, v141
	v_pk_mul_f32 v[142:143], v[114:115], v[134:135] op_sel_hi:[1,0]
	v_cvt_pk_bf16_f32 v157, v142, v143
	v_pk_mul_f32 v[144:145], v[116:117], v[134:135] op_sel_hi:[1,0]
	v_cvt_pk_bf16_f32 v158, v144, v145
	v_pk_mul_f32 v[146:147], v[118:119], v[134:135] op_sel_hi:[1,0]
	v_cvt_pk_bf16_f32 v159, v146, v147
	v_pk_mul_f32 v[140:141], v[120:121], v[134:135] op_sel_hi:[1,0]
	v_cvt_pk_bf16_f32 v160, v140, v141
	v_pk_mul_f32 v[142:143], v[122:123], v[134:135] op_sel_hi:[1,0]
	v_cvt_pk_bf16_f32 v161, v142, v143
	v_pk_mul_f32 v[144:145], v[124:125], v[134:135] op_sel_hi:[1,0]
	v_cvt_pk_bf16_f32 v162, v144, v145
	v_pk_mul_f32 v[146:147], v[126:127], v[134:135] op_sel_hi:[1,0]
	v_cvt_pk_bf16_f32 v163, v146, v147
	global_store_dwordx2 v173, v[156:157], s[98:99]
	global_store_dwordx2 v173, v[158:159], s[98:99] offset:512
	global_store_dwordx2 v173, v[160:161], s[98:99] offset:1024
	global_store_dwordx2 v173, v[162:163], s[98:99] offset:1536
	v_add_u32_e32 v173, 0x400000, v173
	v_add_u32_e32 v166, -1, v165
	v_fma_f32 v140, -v166, v165, v164
	v_cmp_ge_f32_e32 vcc, 0, v140
	v_add_u32_e32 v141, 1, v165
	v_cndmask_b32_e32 v166, v165, v166, vcc
	v_fma_f32 v140, -v141, v165, v164
	v_cmp_lt_f32_e32 vcc, 0, v140
	s_nop 1
	v_cndmask_b32_e32 v165, v166, v141, vcc
	v_add_u32_e32 v169, -1, v168
	v_fma_f32 v142, -v169, v168, v167
	v_cmp_ge_f32_e32 vcc, 0, v142
	v_add_u32_e32 v143, 1, v168
	v_cndmask_b32_e32 v169, v168, v169, vcc
	v_fma_f32 v142, -v143, v168, v167
	v_cmp_lt_f32_e32 vcc, 0, v142
	s_nop 1
	v_cndmask_b32_e32 v168, v169, v143, vcc
	s_mov_b64 exec, 1
	global_store_dword v174, v165, s[98:99]
	v_add_u32_e32 v174, 0x2000, v174
	global_store_dword v174, v168, s[98:99]
	v_add_u32_e32 v174, 0x2000, v174
	s_mov_b64 exec, -1
	s_branch .LBB0_385
;     __device__ __forceinline__ const float* in(int i) const { return karg_in(i); }
; #define FTID const int ftid_ = fresh_tid()
; __global__ void __launch_bounds__(NTHREADS, 2) fwd_kernel(Args args) {
;     ...
;     { FTID; const float* gp = C.in(8); { const int gw_ = GWV, ngw_ = NGWV, nit = (MPROMPT + 4 * ngw_ - 1) / (4 * ngw_);
;       for (int it = 0; it < nit - 1; ++it) rows_res<4, false, false>(C, gw_ + 4 * it * ngw_, ngw_, M, gp, 0.5f, LANE);
	v_mov_b32_e32 v3, v1
	s_mov_b32 s0, 0x358637bd
	s_waitcnt lgkmcnt(0)
	v_lshl_add_u64 v[4:5], s[14:15], 0, v[2:3]
	s_mov_b64 s[12:13], 0x7100000
	s_mov_b64 s[16:17], 0x3000000
	v_mov_b32_e32 v3, 0x2a80000
	s_mov_b32 s18, 0x3a800000
	v_mov_b64_e32 v[6:7], s[0:1]
	s_mov_b32 s19, 0x800000
	v_mov_b32_e32 v37, 0x358637bd
	s_mov_b32 s43, 0xf800000
	v_mov_b32_e32 v148, 0x260
	s_mov_b32 s20, s42
	v_readlane_b32 s54, v232, 5
	s_branch .LBB0_369

;     __device__ __forceinline__ const float* in(int i) const { return karg_in(i); }
; __device__ __forceinline__ const float* xrow_ptr(const Ctx& C, int row) { return row < MPROMPT ? C.in(0) + (size_t)row * DM : C.in(1) + (size_t)(row - MPROMPT) * DM; }
; __device__ __forceinline__ v4f ld4_bf16(const bf16* p) { const v2u w = *(const v2u*)p; return (v4f){bf_lo(w.x), bf_hi(w.x), bf_lo(w.y), bf_hi(w.y)}; }
; __device__ __forceinline__ float ssq4(v4f v) { return (v.x * v.x + v.y * v.y) + (v.z * v.z + v.w * v.w); }
; #define FTID const int ftid_ = fresh_tid()
; template <int R, bool BASE_F32, bool OUT_F32>
; __device__ __forceinline__ void rows_res(const Ctx& C, int m0, int stride, int mx, const float* gpost, float scale, int lane) {
;     v4f d[R][4], b[R][4]; int mr[R]; bool ok[R]; float r1[R];
;     const bf16* D = C.D(); bf16* XN = C.XN();
; #pragma unroll
;     for (int r = 0; r < R; ++r) { mr[r] = (r == 4) ? mx : m0 + r * stride; ok[r] = (r == 4) ? (mx < M) : (mr[r] < MPROMPT); const int mm = ok[r] ? mr[r] : 0;
; #pragma unroll
;         for (int j = 0; j < 4; ++j) d[r][j] = ld4_bf16(D + (size_t)mm * DM + 4 * lane + 256 * j);
;         if (BASE_F32) { const float* x = xrow_ptr(C, mm);
; #pragma unroll
;             for (int j = 0; j < 4; ++j) b[r][j] = ld4_f32(x + 4 * lane + 256 * j);
;         } else { const float inv = C.RS()[mm];
; #pragma unroll
;             for (int j = 0; j < 4; ++j) b[r][j] = ld4_bf16(XN + (size_t)mm * DM + 4 * lane + 256 * j) * inv;
;         } }
; #pragma unroll
;     for (int r = 0; r < R; ++r) { float s = 0.f;
; #pragma unroll
;         for (int j = 0; j < 4; ++j) s += ssq4(d[r][j]);
;         r1[r] = s; }
; #pragma unroll
;     for (int r = 0; r < R; ++r) r1[r] = rsqrtf(wave_sum(r1[r]) * (1.f / DM) + EPS) * scale;
; __global__ void __launch_bounds__(NTHREADS, 2) fwd_kernel(Args args) {
;     ...
;     { FTID; const float* gp = C.in(27); { const int gw_ = GWV, ngw_ = NGWV, nit = (MPROMPT + 4 * ngw_ - 1) / (4 * ngw_);
;       for (int it = 0; it < nit - 1; ++it) rows_res<4, false, false>(C, gw_ + 4 * it * ngw_, ngw_, M, gp, 1.0f, LANE);
.LBB0_994:
	s_or_b64 exec, exec, s[10:11]
	s_waitcnt lgkmcnt(0)
	v_mov_b32_e32 v0, v182
	s_mov_b64 s[0:1], s[80:81]
	s_barrier
	s_load_dwordx2 s[16:17], s[0:1], 0xd8
	v_readfirstlane_b32 s0, v0
	v_and_b32_e32 v189, 63, v0
	s_ashr_i32 s47, s0, 6
	v_readlane_b32 s0, v232, 0
	v_lshlrev_b32_e32 v0, 2, v189
	s_add_i32 s23, s47, s0
	v_mov_b32_e32 v1, 0
	s_and_b64 vcc, exec, s[6:7]
	v_lshlrev_b32_e32 v2, 2, v0
	v_cmp_ne_u32_e64 s[10:11], 0, v189
	v_lshlrev_b32_e32 v0, 1, v0
	s_load_dwordx2 s[98:99], s[80:81], 0x110
	s_load_dwordx2 s[100:101], s[80:81], 0xd8
	v_and_b32_e32 v176, 63, v182
	v_lshlrev_b32_e32 v170, 3, v176
	s_lshl_b32 vcc_lo, s23, 11
	v_add_u32_e32 v170, vcc_lo, v170
	v_add_u32_e32 v171, 0x3000000, v170
	v_add_u32_e32 v170, 0x7100000, v170
	v_mov_b32_e32 v173, v171
	s_lshl_b32 vcc_lo, s23, 2
	v_mov_b32_e32 v172, 0x2a80000
	v_add_u32_e32 v172, vcc_lo, v172
	v_mov_b32_e32 v174, v172
	v_lshlrev_b32_e32 v176, 4, v176
	v_mov_b32_e32 v138, 0x358637bd
	s_waitcnt lgkmcnt(0)
	global_load_dwordx4 v[192:195], v176, s[100:101]
	global_load_dwordx4 v[196:199], v176, s[100:101] offset:1024
	global_load_dwordx4 v[200:203], v176, s[100:101] offset:2048
	global_load_dwordx4 v[204:207], v176, s[100:101] offset:3072
	global_load_dword v52, v172, s[98:99]
	global_load_dwordx2 v[20:21], v170, s[98:99]
	global_load_dwordx2 v[22:23], v170, s[98:99] offset:512
	global_load_dwordx2 v[24:25], v170, s[98:99] offset:1024
	global_load_dwordx2 v[26:27], v170, s[98:99] offset:1536
	global_load_dwordx2 v[36:37], v171, s[98:99]
	global_load_dwordx2 v[38:39], v171, s[98:99] offset:512
	global_load_dwordx2 v[40:41], v171, s[98:99] offset:1024
	global_load_dwordx2 v[42:43], v171, s[98:99] offset:1536
	v_add_u32_e32 v170, 0x400000, v170
	v_add_u32_e32 v171, 0x400000, v171
	v_add_u32_e32 v172, 0x2000, v172
	global_load_dword v54, v172, s[98:99]
	global_load_dwordx2 v[28:29], v170, s[98:99]
	global_load_dwordx2 v[30:31], v170, s[98:99] offset:512
	global_load_dwordx2 v[32:33], v170, s[98:99] offset:1024
	global_load_dwordx2 v[34:35], v170, s[98:99] offset:1536
	global_load_dwordx2 v[44:45], v171, s[98:99]
	global_load_dwordx2 v[46:47], v171, s[98:99] offset:512
	global_load_dwordx2 v[48:49], v171, s[98:99] offset:1024
	global_load_dwordx2 v[50:51], v171, s[98:99] offset:1536
	v_add_u32_e32 v170, 0x400000, v170
	v_add_u32_e32 v171, 0x400000, v171
	v_add_u32_e32 v172, 0x2000, v172
	global_load_dword v88, v172, s[98:99]
	global_load_dwordx2 v[56:57], v170, s[98:99]
	global_load_dwordx2 v[58:59], v170, s[98:99] offset:512
	global_load_dwordx2 v[60:61], v170, s[98:99] offset:1024
	global_load_dwordx2 v[62:63], v170, s[98:99] offset:1536
	global_load_dwordx2 v[72:73], v171, s[98:99]
	global_load_dwordx2 v[74:75], v171, s[98:99] offset:512
	global_load_dwordx2 v[76:77], v171, s[98:99] offset:1024
	global_load_dwordx2 v[78:79], v171, s[98:99] offset:1536
	v_add_u32_e32 v170, 0x400000, v170
	v_add_u32_e32 v171, 0x400000, v171
	v_add_u32_e32 v172, 0x2000, v172
	global_load_dword v90, v172, s[98:99]
	global_load_dwordx2 v[64:65], v170, s[98:99]
	global_load_dwordx2 v[66:67], v170, s[98:99] offset:512
	global_load_dwordx2 v[68:69], v170, s[98:99] offset:1024
	global_load_dwordx2 v[70:71], v170, s[98:99] offset:1536
	global_load_dwordx2 v[80:81], v171, s[98:99]
	global_load_dwordx2 v[82:83], v171, s[98:99] offset:512
	global_load_dwordx2 v[84:85], v171, s[98:99] offset:1024
	global_load_dwordx2 v[86:87], v171, s[98:99] offset:1536
	v_add_u32_e32 v170, 0x400000, v170
	v_add_u32_e32 v171, 0x400000, v171
	v_add_u32_e32 v172, 0x2000, v172
	s_waitcnt vmcnt(31)
	v_lshlrev_b32_e32 v96, 16, v20
	v_and_b32_e32 v97, 0xffff0000, v20
	v_lshlrev_b32_e32 v98, 16, v21
	v_and_b32_e32 v99, 0xffff0000, v21
	v_lshlrev_b32_e32 v100, 16, v22
	v_and_b32_e32 v101, 0xffff0000, v22
	v_lshlrev_b32_e32 v102, 16, v23
	v_and_b32_e32 v103, 0xffff0000, v23
	v_lshlrev_b32_e32 v104, 16, v24
	v_and_b32_e32 v105, 0xffff0000, v24
	v_lshlrev_b32_e32 v106, 16, v25
	v_and_b32_e32 v107, 0xffff0000, v25
	v_lshlrev_b32_e32 v108, 16, v26
	v_and_b32_e32 v109, 0xffff0000, v26
	v_lshlrev_b32_e32 v110, 16, v27
	v_and_b32_e32 v111, 0xffff0000, v27
	v_pk_mul_f32 v[128:129], v[96:97], v[96:97]
	v_pk_fma_f32 v[128:129], v[98:99], v[98:99], v[128:129]
	v_pk_fma_f32 v[128:129], v[100:101], v[100:101], v[128:129]
	v_pk_fma_f32 v[128:129], v[102:103], v[102:103], v[128:129]
	v_pk_fma_f32 v[128:129], v[104:105], v[104:105], v[128:129]
	v_pk_fma_f32 v[128:129], v[106:107], v[106:107], v[128:129]
	v_pk_fma_f32 v[128:129], v[108:109], v[108:109], v[128:129]
	v_pk_fma_f32 v[128:129], v[110:111], v[110:111], v[128:129]
	s_nop 0
	v_add_f32_e32 v128, v128, v129
	s_waitcnt vmcnt(22)
	v_lshlrev_b32_e32 v112, 16, v28
	v_and_b32_e32 v113, 0xffff0000, v28
	v_lshlrev_b32_e32 v114, 16, v29
	v_and_b32_e32 v115, 0xffff0000, v29
	v_lshlrev_b32_e32 v116, 16, v30
	v_and_b32_e32 v117, 0xffff0000, v30
	v_lshlrev_b32_e32 v118, 16, v31
	v_and_b32_e32 v119, 0xffff0000, v31
	v_lshlrev_b32_e32 v120, 16, v32
	v_and_b32_e32 v121, 0xffff0000, v32
	v_lshlrev_b32_e32 v122, 16, v33
	v_and_b32_e32 v123, 0xffff0000, v33
	v_lshlrev_b32_e32 v124, 16, v34
	v_and_b32_e32 v125, 0xffff0000, v34
	v_lshlrev_b32_e32 v126, 16, v35
	v_and_b32_e32 v127, 0xffff0000, v35
	v_pk_mul_f32 v[130:131], v[112:113], v[112:113]
	v_pk_fma_f32 v[130:131], v[114:115], v[114:115], v[130:131]
	v_pk_fma_f32 v[130:131], v[116:117], v[116:117], v[130:131]
	v_pk_fma_f32 v[130:131], v[118:119], v[118:119], v[130:131]
	v_pk_fma_f32 v[130:131], v[120:121], v[120:121], v[130:131]
	v_pk_fma_f32 v[130:131], v[122:123], v[122:123], v[130:131]
	v_pk_fma_f32 v[130:131], v[124:125], v[124:125], v[130:131]
	v_pk_fma_f32 v[130:131], v[126:127], v[126:127], v[130:131]
	s_nop 0
	v_add_f32_e32 v130, v130, v131
	s_nop 1
	v_add_f32_dpp v128, v128, v128 quad_perm:[1,0,3,2] row_mask:0xf bank_mask:0xf
	v_add_f32_dpp v130, v130, v130 quad_perm:[1,0,3,2] row_mask:0xf bank_mask:0xf
	s_nop 0
	v_add_f32_dpp v128, v128, v128 quad_perm:[2,3,0,1] row_mask:0xf bank_mask:0xf
	v_add_f32_dpp v130, v130, v130 quad_perm:[2,3,0,1] row_mask:0xf bank_mask:0xf
	s_nop 0
	v_add_f32_dpp v128, v128, v128 row_half_mirror row_mask:0xf bank_mask:0xf
	v_add_f32_dpp v130, v130, v130 row_half_mirror row_mask:0xf bank_mask:0xf
	s_nop 0
	v_add_f32_dpp v128, v128, v128 row_mirror row_mask:0xf bank_mask:0xf
	v_add_f32_dpp v130, v130, v130 row_mirror row_mask:0xf bank_mask:0xf
	s_nop 0
	ds_bpermute_b32 v136, v187, v128
	ds_bpermute_b32 v137, v187, v130
	s_waitcnt lgkmcnt(0)
;     __device__ __forceinline__ float* out() const { return (float*)karg_in(33); }
; __device__ __forceinline__ float ssq4(v4f v) { return (v.x * v.x + v.y * v.y) + (v.z * v.z + v.w * v.w); }
; template <int R, bool BASE_F32, bool OUT_F32>
; __device__ __forceinline__ void rows_res(const Ctx& C, int m0, int stride, int mx, const float* gpost, float scale, int lane) {
;     ...
;     for (int r = 0; r < R; ++r) { float s = 0.f;
; #pragma unroll
;         for (int j = 0; j < 4; ++j) s += ssq4(d[r][j]);
;         r1[r] = s; }
; #pragma unroll
;     for (int r = 0; r < R; ++r) r1[r] = rsqrtf(wave_sum(r1[r]) * (1.f / DM) + EPS) * scale;
; #pragma unroll
;     for (int j = 0; j < 4; ++j) { const v4f gp = ld4_f32(gpost + 4 * lane + 256 * j);
; #pragma unroll
;         for (int r = 0; r < R; ++r) d[r][j] = b[r][j] + d[r][j] * r1[r] * gp; }
;     if (OUT_F32) { float* Y = C.out();
; #pragma unroll
;         for (int r = 0; r < R; ++r)
; #pragma unroll
;             for (int j = 0; j < 4; ++j) if (ok[r]) *(v4f*)(Y + (size_t)mr[r] * DM + 4 * lane + 256 * j) = d[r][j];
;     } else { float* rs = C.RS(); float t[R];
; #pragma unroll
;         for (int r = 0; r < R; ++r) { float s = 0.f;
; #pragma unroll
;             for (int j = 0; j < 4; ++j) s += ssq4(d[r][j]);
;             t[r] = s; }
; #pragma unroll
;         for (int r = 0; r < R; ++r) t[r] = wave_sum(t[r]) * (1.f / DM) + EPS;
	v_add_f32_e32 v128, v128, v136
	v_add_f32_e32 v130, v130, v137
	ds_bpermute_b32 v136, v188, v128
	ds_bpermute_b32 v137, v188, v130
	s_waitcnt lgkmcnt(0)
	v_add_f32_e32 v128, v128, v136
	v_add_f32_e32 v130, v130, v137
	v_fmamk_f32 v128, v128, 0x3a800000, v138
	v_fmamk_f32 v130, v130, 0x3a800000, v138
	s_nop 0
	v_rsq_f32_e32 v128, v128
	v_rsq_f32_e32 v130, v130
	s_nop 1
	s_waitcnt vmcnt(18)
	v_pk_mul_f32 v[96:97], v[128:129], v[96:97] op_sel_hi:[0,1]
	v_pk_mul_f32 v[98:99], v[128:129], v[98:99] op_sel_hi:[0,1]
	v_pk_mul_f32 v[100:101], v[128:129], v[100:101] op_sel_hi:[0,1]
	v_pk_mul_f32 v[102:103], v[128:129], v[102:103] op_sel_hi:[0,1]
	v_pk_mul_f32 v[104:105], v[128:129], v[104:105] op_sel_hi:[0,1]
	v_pk_mul_f32 v[106:107], v[128:129], v[106:107] op_sel_hi:[0,1]
	v_pk_mul_f32 v[108:109], v[128:129], v[108:109] op_sel_hi:[0,1]
	v_pk_mul_f32 v[110:111], v[128:129], v[110:111] op_sel_hi:[0,1]
	v_pk_mul_f32 v[96:97], v[96:97], v[192:193]
	v_pk_mul_f32 v[98:99], v[98:99], v[194:195]
	v_pk_mul_f32 v[100:101], v[100:101], v[196:197]
	v_pk_mul_f32 v[102:103], v[102:103], v[198:199]
	v_pk_mul_f32 v[104:105], v[104:105], v[200:201]
	v_pk_mul_f32 v[106:107], v[106:107], v[202:203]
	v_pk_mul_f32 v[108:109], v[108:109], v[204:205]
	v_pk_mul_f32 v[110:111], v[110:111], v[206:207]
	v_lshlrev_b32_e32 v20, 16, v36
	v_and_b32_e32 v21, 0xffff0000, v36
	v_lshlrev_b32_e32 v22, 16, v37
	v_and_b32_e32 v23, 0xffff0000, v37
	v_lshlrev_b32_e32 v24, 16, v38
	v_and_b32_e32 v25, 0xffff0000, v38
	v_lshlrev_b32_e32 v26, 16, v39
	v_and_b32_e32 v27, 0xffff0000, v39
	v_pk_fma_f32 v[96:97], v[52:53], v[20:21], v[96:97] op_sel_hi:[0,1,1]
	v_pk_fma_f32 v[98:99], v[52:53], v[22:23], v[98:99] op_sel_hi:[0,1,1]
	v_pk_fma_f32 v[100:101], v[52:53], v[24:25], v[100:101] op_sel_hi:[0,1,1]
	v_pk_fma_f32 v[102:103], v[52:53], v[26:27], v[102:103] op_sel_hi:[0,1,1]
	v_lshlrev_b32_e32 v20, 16, v40
	v_and_b32_e32 v21, 0xffff0000, v40
	v_lshlrev_b32_e32 v22, 16, v41
	v_and_b32_e32 v23, 0xffff0000, v41
	v_lshlrev_b32_e32 v24, 16, v42
	v_and_b32_e32 v25, 0xffff0000, v42
	v_lshlrev_b32_e32 v26, 16, v43
	v_and_b32_e32 v27, 0xffff0000, v43
	v_pk_fma_f32 v[104:105], v[52:53], v[20:21], v[104:105] op_sel_hi:[0,1,1]
	v_pk_fma_f32 v[106:107], v[52:53], v[22:23], v[106:107] op_sel_hi:[0,1,1]
	v_pk_fma_f32 v[108:109], v[52:53], v[24:25], v[108:109] op_sel_hi:[0,1,1]
	v_pk_fma_f32 v[110:111], v[52:53], v[26:27], v[110:111] op_sel_hi:[0,1,1]
	v_pk_mul_f32 v[132:133], v[96:97], v[96:97]
	v_pk_fma_f32 v[132:133], v[98:99], v[98:99], v[132:133]
	v_pk_fma_f32 v[132:133], v[100:101], v[100:101], v[132:133]
	v_pk_fma_f32 v[132:133], v[102:103], v[102:103], v[132:133]
	v_pk_fma_f32 v[132:133], v[104:105], v[104:105], v[132:133]
	v_pk_fma_f32 v[132:133], v[106:107], v[106:107], v[132:133]
	v_pk_fma_f32 v[132:133], v[108:109], v[108:109], v[132:133]
	v_pk_fma_f32 v[132:133], v[110:111], v[110:111], v[132:133]
	s_nop 0
	v_add_f32_e32 v132, v132, v133
	v_pk_mul_f32 v[112:113], v[130:131], v[112:113] op_sel_hi:[0,1]
	v_pk_mul_f32 v[114:115], v[130:131], v[114:115] op_sel_hi:[0,1]
	v_pk_mul_f32 v[116:117], v[130:131], v[116:117] op_sel_hi:[0,1]
	v_pk_mul_f32 v[118:119], v[130:131], v[118:119] op_sel_hi:[0,1]
	v_pk_mul_f32 v[120:121], v[130:131], v[120:121] op_sel_hi:[0,1]
	v_pk_mul_f32 v[122:123], v[130:131], v[122:123] op_sel_hi:[0,1]
	v_pk_mul_f32 v[124:125], v[130:131], v[124:125] op_sel_hi:[0,1]
	v_pk_mul_f32 v[126:127], v[130:131], v[126:127] op_sel_hi:[0,1]
	v_pk_mul_f32 v[112:113], v[112:113], v[192:193]
	v_pk_mul_f32 v[114:115], v[114:115], v[194:195]
	v_pk_mul_f32 v[116:117], v[116:117], v[196:197]
	v_pk_mul_f32 v[118:119], v[118:119], v[198:199]
	v_pk_mul_f32 v[120:121], v[120:121], v[200:201]
	v_pk_mul_f32 v[122:123], v[122:123], v[202:203]
	v_pk_mul_f32 v[124:125], v[124:125], v[204:205]
	v_pk_mul_f32 v[126:127], v[126:127], v[206:207]
	v_lshlrev_b32_e32 v28, 16, v44
	v_and_b32_e32 v29, 0xffff0000, v44
	v_lshlrev_b32_e32 v30, 16, v45
	v_and_b32_e32 v31, 0xffff0000, v45
	v_lshlrev_b32_e32 v32, 16, v46
	v_and_b32_e32 v33, 0xffff0000, v46
	v_lshlrev_b32_e32 v34, 16, v47
	v_and_b32_e32 v35, 0xffff0000, v47
	v_pk_fma_f32 v[112:113], v[54:55], v[28:29], v[112:113] op_sel_hi:[0,1,1]
	v_pk_fma_f32 v[114:115], v[54:55], v[30:31], v[114:115] op_sel_hi:[0,1,1]
	v_pk_fma_f32 v[116:117], v[54:55], v[32:33], v[116:117] op_sel_hi:[0,1,1]
	v_pk_fma_f32 v[118:119], v[54:55], v[34:35], v[118:119] op_sel_hi:[0,1,1]
	v_lshlrev_b32_e32 v28, 16, v48
	v_and_b32_e32 v29, 0xffff0000, v48
	v_lshlrev_b32_e32 v30, 16, v49
	v_and_b32_e32 v31, 0xffff0000, v49
	v_lshlrev_b32_e32 v32, 16, v50
	v_and_b32_e32 v33, 0xffff0000, v50
	v_lshlrev_b32_e32 v34, 16, v51
	v_and_b32_e32 v35, 0xffff0000, v51
	v_pk_fma_f32 v[120:121], v[54:55], v[28:29], v[120:121] op_sel_hi:[0,1,1]
	v_pk_fma_f32 v[122:123], v[54:55], v[30:31], v[122:123] op_sel_hi:[0,1,1]
	v_pk_fma_f32 v[124:125], v[54:55], v[32:33], v[124:125] op_sel_hi:[0,1,1]
	v_pk_fma_f32 v[126:127], v[54:55], v[34:35], v[126:127] op_sel_hi:[0,1,1]
	v_pk_mul_f32 v[134:135], v[112:113], v[112:113]
	v_pk_fma_f32 v[134:135], v[114:115], v[114:115], v[134:135]
	v_pk_fma_f32 v[134:135], v[116:117], v[116:117], v[134:135]
	v_pk_fma_f32 v[134:135], v[118:119], v[118:119], v[134:135]
	v_pk_fma_f32 v[134:135], v[120:121], v[120:121], v[134:135]
	v_pk_fma_f32 v[134:135], v[122:123], v[122:123], v[134:135]
	v_pk_fma_f32 v[134:135], v[124:125], v[124:125], v[134:135]
	v_pk_fma_f32 v[134:135], v[126:127], v[126:127], v[134:135]
	s_nop 0
	v_add_f32_e32 v134, v134, v135
	s_nop 1
	v_add_f32_dpp v132, v132, v132 quad_perm:[1,0,3,2] row_mask:0xf bank_mask:0xf
	v_add_f32_dpp v134, v134, v134 quad_perm:[1,0,3,2] row_mask:0xf bank_mask:0xf
	s_nop 0
	v_add_f32_dpp v132, v132, v132 quad_perm:[2,3,0,1] row_mask:0xf bank_mask:0xf
	v_add_f32_dpp v134, v134, v134 quad_perm:[2,3,0,1] row_mask:0xf bank_mask:0xf
	s_nop 0
	v_add_f32_dpp v132, v132, v132 row_half_mirror row_mask:0xf bank_mask:0xf
	v_add_f32_dpp v134, v134, v134 row_half_mirror row_mask:0xf bank_mask:0xf
	s_nop 0
	v_add_f32_dpp v132, v132, v132 row_mirror row_mask:0xf bank_mask:0xf
	v_add_f32_dpp v134, v134, v134 row_mirror row_mask:0xf bank_mask:0xf
	s_nop 0
	ds_bpermute_b32 v136, v187, v132
	ds_bpermute_b32 v137, v187, v134
	s_waitcnt lgkmcnt(0)
; __device__ __forceinline__ const float* xrow_ptr(const Ctx& C, int row) { return row < MPROMPT ? C.in(0) + (size_t)row * DM : C.in(1) + (size_t)(row - MPROMPT) * DM; }
; __device__ __forceinline__ v4f ld4_bf16(const bf16* p) { const v2u w = *(const v2u*)p; return (v4f){bf_lo(w.x), bf_hi(w.x), bf_lo(w.y), bf_hi(w.y)}; }
; __device__ __forceinline__ void st4_bf16(bf16* p, v4f o) { v2u w; w.x = cvt_pk_nv(o.x, o.y); w.y = cvt_pk_nv(o.z, o.w); *(v2u*)p = w; }
; __device__ __forceinline__ float ssq4(v4f v) { return (v.x * v.x + v.y * v.y) + (v.z * v.z + v.w * v.w); }
; template <int R, bool BASE_F32, bool OUT_F32>
; __device__ __forceinline__ void rows_res(const Ctx& C, int m0, int stride, int mx, const float* gpost, float scale, int lane) {
;     ...
;     for (int r = 0; r < R; ++r) { mr[r] = (r == 4) ? mx : m0 + r * stride; ok[r] = (r == 4) ? (mx < M) : (mr[r] < MPROMPT); const int mm = ok[r] ? mr[r] : 0;
; #pragma unroll
;         for (int j = 0; j < 4; ++j) d[r][j] = ld4_bf16(D + (size_t)mm * DM + 4 * lane + 256 * j);
;         if (BASE_F32) { const float* x = xrow_ptr(C, mm);
; #pragma unroll
;             for (int j = 0; j < 4; ++j) b[r][j] = ld4_f32(x + 4 * lane + 256 * j);
;         } else { const float inv = C.RS()[mm];
; #pragma unroll
;             for (int j = 0; j < 4; ++j) b[r][j] = ld4_bf16(XN + (size_t)mm * DM + 4 * lane + 256 * j) * inv;
;         } }
; #pragma unroll
;     for (int r = 0; r < R; ++r) { float s = 0.f;
; #pragma unroll
;         for (int j = 0; j < 4; ++j) s += ssq4(d[r][j]);
;         r1[r] = s; }
;     ...
;         for (int r = 0; r < R; ++r) t[r] = wave_sum(t[r]) * (1.f / DM) + EPS;
; #pragma unroll
;         for (int r = 0; r < R; ++r) { const float rstd = rsqrtf(t[r]);
; #pragma unroll
;             for (int j = 0; j < 4; ++j) if (ok[r]) st4_bf16(XN + (size_t)mr[r] * DM + 4 * lane + 256 * j, d[r][j] * rstd);
;             if (lane == 0 && ok[r]) rs[mr[r]] = sqrtf(t[r]); }
	v_add_f32_e32 v132, v132, v136
	v_add_f32_e32 v134, v134, v137
	ds_bpermute_b32 v136, v188, v132
	ds_bpermute_b32 v137, v188, v134
	s_waitcnt lgkmcnt(0)
	v_add_f32_e32 v132, v132, v136
	v_add_f32_e32 v134, v134, v137
	v_fmamk_f32 v164, v132, 0x3a800000, v138
	v_fmamk_f32 v167, v134, 0x3a800000, v138
	s_nop 0
	v_rsq_f32_e32 v132, v164
	v_rsq_f32_e32 v134, v167
	v_sqrt_f32_e32 v165, v164
	v_sqrt_f32_e32 v168, v167
	s_nop 1
	v_pk_mul_f32 v[140:141], v[96:97], v[132:133] op_sel_hi:[1,0]
	v_cvt_pk_bf16_f32 v148, v140, v141
	v_pk_mul_f32 v[142:143], v[98:99], v[132:133] op_sel_hi:[1,0]
	v_cvt_pk_bf16_f32 v149, v142, v143
	v_pk_mul_f32 v[144:145], v[100:101], v[132:133] op_sel_hi:[1,0]
	v_cvt_pk_bf16_f32 v150, v144, v145
	v_pk_mul_f32 v[146:147], v[102:103], v[132:133] op_sel_hi:[1,0]
	v_cvt_pk_bf16_f32 v151, v146, v147
	v_pk_mul_f32 v[140:141], v[104:105], v[132:133] op_sel_hi:[1,0]
	v_cvt_pk_bf16_f32 v152, v140, v141
	v_pk_mul_f32 v[142:143], v[106:107], v[132:133] op_sel_hi:[1,0]
	v_cvt_pk_bf16_f32 v153, v142, v143
	v_pk_mul_f32 v[144:145], v[108:109], v[132:133] op_sel_hi:[1,0]
	v_cvt_pk_bf16_f32 v154, v144, v145
	v_pk_mul_f32 v[146:147], v[110:111], v[132:133] op_sel_hi:[1,0]
	v_cvt_pk_bf16_f32 v155, v146, v147
	global_store_dwordx2 v173, v[148:149], s[98:99]
	global_store_dwordx2 v173, v[150:151], s[98:99] offset:512
	global_store_dwordx2 v173, v[152:153], s[98:99] offset:1024
	global_store_dwordx2 v173, v[154:155], s[98:99] offset:1536
	v_add_u32_e32 v173, 0x400000, v173
	v_pk_mul_f32 v[140:141], v[112:113], v[134:135] op_sel_hi:[1,0]
	v_cvt_pk_bf16_f32 v156, v140, v141
	v_pk_mul_f32 v[142:143], v[114:115], v[134:135] op_sel_hi:[1,0]
	v_cvt_pk_bf16_f32 v157, v142, v143
	v_pk_mul_f32 v[144:145], v[116:117], v[134:135] op_sel_hi:[1,0]
	v_cvt_pk_bf16_f32 v158, v144, v145
	v_pk_mul_f32 v[146:147], v[118:119], v[134:135] op_sel_hi:[1,0]
	v_cvt_pk_bf16_f32 v159, v146, v147
	v_pk_mul_f32 v[140:141], v[120:121], v[134:135] op_sel_hi:[1,0]
	v_cvt_pk_bf16_f32 v160, v140, v141
	v_pk_mul_f32 v[142:143], v[122:123], v[134:135] op_sel_hi:[1,0]
	v_cvt_pk_bf16_f32 v161, v142, v143
	v_pk_mul_f32 v[144:145], v[124:125], v[134:135] op_sel_hi:[1,0]
	v_cvt_pk_bf16_f32 v162, v144, v145
	v_pk_mul_f32 v[146:147], v[126:127], v[134:135] op_sel_hi:[1,0]
	v_cvt_pk_bf16_f32 v163, v146, v147
	global_store_dwordx2 v173, v[156:157], s[98:99]
	global_store_dwordx2 v173, v[158:159], s[98:99] offset:512
	global_store_dwordx2 v173, v[160:161], s[98:99] offset:1024
	global_store_dwordx2 v173, v[162:163], s[98:99] offset:1536
	v_add_u32_e32 v173, 0x400000, v173
	v_add_u32_e32 v166, -1, v165
	v_fma_f32 v140, -v166, v165, v164
	v_cmp_ge_f32_e32 vcc, 0, v140
	v_add_u32_e32 v141, 1, v165
	v_cndmask_b32_e32 v166, v165, v166, vcc
	v_fma_f32 v140, -v141, v165, v164
	v_cmp_lt_f32_e32 vcc, 0, v140
	s_nop 1
	v_cndmask_b32_e32 v165, v166, v141, vcc
	v_add_u32_e32 v169, -1, v168
	v_fma_f32 v142, -v169, v168, v167
	v_cmp_ge_f32_e32 vcc, 0, v142
	v_add_u32_e32 v143, 1, v168
	v_cndmask_b32_e32 v169, v168, v169, vcc
	v_fma_f32 v142, -v143, v168, v167
	v_cmp_lt_f32_e32 vcc, 0, v142
	s_nop 1
	v_cndmask_b32_e32 v168, v169, v143, vcc
	s_mov_b64 exec, 1
	global_store_dword v174, v165, s[98:99]
	v_add_u32_e32 v174, 0x2000, v174
	global_store_dword v174, v168, s[98:99]
	v_add_u32_e32 v174, 0x2000, v174
	s_mov_b64 exec, -1
	global_load_dword v52, v172, s[98:99]
	global_load_dwordx2 v[20:21], v170, s[98:99]
	global_load_dwordx2 v[22:23], v170, s[98:99] offset:512
	global_load_dwordx2 v[24:25], v170, s[98:99] offset:1024
	global_load_dwordx2 v[26:27], v170, s[98:99] offset:1536
	global_load_dwordx2 v[36:37], v171, s[98:99]
	global_load_dwordx2 v[38:39], v171, s[98:99] offset:512
	global_load_dwordx2 v[40:41], v171, s[98:99] offset:1024
	global_load_dwordx2 v[42:43], v171, s[98:99] offset:1536
	v_add_u32_e32 v170, 0x400000, v170
	v_add_u32_e32 v171, 0x400000, v171
	v_add_u32_e32 v172, 0x2000, v172
	global_load_dword v54, v172, s[98:99]
	global_load_dwordx2 v[28:29], v170, s[98:99]
	global_load_dwordx2 v[30:31], v170, s[98:99] offset:512
	global_load_dwordx2 v[32:33], v170, s[98:99] offset:1024
	global_load_dwordx2 v[34:35], v170, s[98:99] offset:1536
	global_load_dwordx2 v[44:45], v171, s[98:99]
	global_load_dwordx2 v[46:47], v171, s[98:99] offset:512
	global_load_dwordx2 v[48:49], v171, s[98:99] offset:1024
	global_load_dwordx2 v[50:51], v171, s[98:99] offset:1536
	v_add_u32_e32 v170, 0x400000, v170
	v_add_u32_e32 v171, 0x400000, v171
	v_add_u32_e32 v172, 0x2000, v172
	s_waitcnt vmcnt(41)
	v_lshlrev_b32_e32 v96, 16, v56
	v_and_b32_e32 v97, 0xffff0000, v56
	v_lshlrev_b32_e32 v98, 16, v57
	v_and_b32_e32 v99, 0xffff0000, v57
	v_lshlrev_b32_e32 v100, 16, v58
	v_and_b32_e32 v101, 0xffff0000, v58
	v_lshlrev_b32_e32 v102, 16, v59
	v_and_b32_e32 v103, 0xffff0000, v59
	v_lshlrev_b32_e32 v104, 16, v60
	v_and_b32_e32 v105, 0xffff0000, v60
	v_lshlrev_b32_e32 v106, 16, v61
	v_and_b32_e32 v107, 0xffff0000, v61
	v_lshlrev_b32_e32 v108, 16, v62
	v_and_b32_e32 v109, 0xffff0000, v62
	v_lshlrev_b32_e32 v110, 16, v63
	v_and_b32_e32 v111, 0xffff0000, v63
	v_pk_mul_f32 v[128:129], v[96:97], v[96:97]
	v_pk_fma_f32 v[128:129], v[98:99], v[98:99], v[128:129]
	v_pk_fma_f32 v[128:129], v[100:101], v[100:101], v[128:129]
	v_pk_fma_f32 v[128:129], v[102:103], v[102:103], v[128:129]
	v_pk_fma_f32 v[128:129], v[104:105], v[104:105], v[128:129]
	v_pk_fma_f32 v[128:129], v[106:107], v[106:107], v[128:129]
	v_pk_fma_f32 v[128:129], v[108:109], v[108:109], v[128:129]
	v_pk_fma_f32 v[128:129], v[110:111], v[110:111], v[128:129]
	s_nop 0
	v_add_f32_e32 v128, v128, v129
	s_waitcnt vmcnt(32)
;     __device__ __forceinline__ float* out() const { return (float*)karg_in(33); }
; __device__ __forceinline__ float ssq4(v4f v) { return (v.x * v.x + v.y * v.y) + (v.z * v.z + v.w * v.w); }
; template <int R, bool BASE_F32, bool OUT_F32>
; __device__ __forceinline__ void rows_res(const Ctx& C, int m0, int stride, int mx, const float* gpost, float scale, int lane) {
;     ...
;     for (int r = 0; r < R; ++r) { float s = 0.f;
; #pragma unroll
;         for (int j = 0; j < 4; ++j) s += ssq4(d[r][j]);
;         r1[r] = s; }
; #pragma unroll
;     for (int r = 0; r < R; ++r) r1[r] = rsqrtf(wave_sum(r1[r]) * (1.f / DM) + EPS) * scale;
; #pragma unroll
;     for (int j = 0; j < 4; ++j) { const v4f gp = ld4_f32(gpost + 4 * lane + 256 * j);
; #pragma unroll
;         for (int r = 0; r < R; ++r) d[r][j] = b[r][j] + d[r][j] * r1[r] * gp; }
;     if (OUT_F32) { float* Y = C.out();
; #pragma unroll
;         for (int r = 0; r < R; ++r)
; #pragma unroll
;             for (int j = 0; j < 4; ++j) if (ok[r]) *(v4f*)(Y + (size_t)mr[r] * DM + 4 * lane + 256 * j) = d[r][j];
;     } else { float* rs = C.RS(); float t[R];
; #pragma unroll
;         for (int r = 0; r < R; ++r) { float s = 0.f;
; #pragma unroll
;             for (int j = 0; j < 4; ++j) s += ssq4(d[r][j]);
;             t[r] = s; }
	v_lshlrev_b32_e32 v112, 16, v64
	v_and_b32_e32 v113, 0xffff0000, v64
	v_lshlrev_b32_e32 v114, 16, v65
	v_and_b32_e32 v115, 0xffff0000, v65
	v_lshlrev_b32_e32 v116, 16, v66
	v_and_b32_e32 v117, 0xffff0000, v66
	v_lshlrev_b32_e32 v118, 16, v67
	v_and_b32_e32 v119, 0xffff0000, v67
	v_lshlrev_b32_e32 v120, 16, v68
	v_and_b32_e32 v121, 0xffff0000, v68
	v_lshlrev_b32_e32 v122, 16, v69
	v_and_b32_e32 v123, 0xffff0000, v69
	v_lshlrev_b32_e32 v124, 16, v70
	v_and_b32_e32 v125, 0xffff0000, v70
	v_lshlrev_b32_e32 v126, 16, v71
	v_and_b32_e32 v127, 0xffff0000, v71
	v_pk_mul_f32 v[130:131], v[112:113], v[112:113]
	v_pk_fma_f32 v[130:131], v[114:115], v[114:115], v[130:131]
	v_pk_fma_f32 v[130:131], v[116:117], v[116:117], v[130:131]
	v_pk_fma_f32 v[130:131], v[118:119], v[118:119], v[130:131]
	v_pk_fma_f32 v[130:131], v[120:121], v[120:121], v[130:131]
	v_pk_fma_f32 v[130:131], v[122:123], v[122:123], v[130:131]
	v_pk_fma_f32 v[130:131], v[124:125], v[124:125], v[130:131]
	v_pk_fma_f32 v[130:131], v[126:127], v[126:127], v[130:131]
	s_nop 0
	v_add_f32_e32 v130, v130, v131
	s_nop 1
	v_add_f32_dpp v128, v128, v128 quad_perm:[1,0,3,2] row_mask:0xf bank_mask:0xf
	v_add_f32_dpp v130, v130, v130 quad_perm:[1,0,3,2] row_mask:0xf bank_mask:0xf
	s_nop 0
	v_add_f32_dpp v128, v128, v128 quad_perm:[2,3,0,1] row_mask:0xf bank_mask:0xf
	v_add_f32_dpp v130, v130, v130 quad_perm:[2,3,0,1] row_mask:0xf bank_mask:0xf
	s_nop 0
	v_add_f32_dpp v128, v128, v128 row_half_mirror row_mask:0xf bank_mask:0xf
	v_add_f32_dpp v130, v130, v130 row_half_mirror row_mask:0xf bank_mask:0xf
	s_nop 0
	v_add_f32_dpp v128, v128, v128 row_mirror row_mask:0xf bank_mask:0xf
	v_add_f32_dpp v130, v130, v130 row_mirror row_mask:0xf bank_mask:0xf
	s_nop 0
	ds_bpermute_b32 v136, v187, v128
	ds_bpermute_b32 v137, v187, v130
	s_waitcnt lgkmcnt(0)
	v_add_f32_e32 v128, v128, v136
	v_add_f32_e32 v130, v130, v137
	ds_bpermute_b32 v136, v188, v128
	ds_bpermute_b32 v137, v188, v130
	s_waitcnt lgkmcnt(0)
	v_add_f32_e32 v128, v128, v136
	v_add_f32_e32 v130, v130, v137
	v_fmamk_f32 v128, v128, 0x3a800000, v138
	v_fmamk_f32 v130, v130, 0x3a800000, v138
	s_nop 0
	v_rsq_f32_e32 v128, v128
	v_rsq_f32_e32 v130, v130
	s_nop 1
	s_waitcnt vmcnt(28)
	v_pk_mul_f32 v[96:97], v[128:129], v[96:97] op_sel_hi:[0,1]
	v_pk_mul_f32 v[98:99], v[128:129], v[98:99] op_sel_hi:[0,1]
	v_pk_mul_f32 v[100:101], v[128:129], v[100:101] op_sel_hi:[0,1]
	v_pk_mul_f32 v[102:103], v[128:129], v[102:103] op_sel_hi:[0,1]
	v_pk_mul_f32 v[104:105], v[128:129], v[104:105] op_sel_hi:[0,1]
	v_pk_mul_f32 v[106:107], v[128:129], v[106:107] op_sel_hi:[0,1]
	v_pk_mul_f32 v[108:109], v[128:129], v[108:109] op_sel_hi:[0,1]
	v_pk_mul_f32 v[110:111], v[128:129], v[110:111] op_sel_hi:[0,1]
	v_pk_mul_f32 v[96:97], v[96:97], v[192:193]
	v_pk_mul_f32 v[98:99], v[98:99], v[194:195]
	v_pk_mul_f32 v[100:101], v[100:101], v[196:197]
	v_pk_mul_f32 v[102:103], v[102:103], v[198:199]
	v_pk_mul_f32 v[104:105], v[104:105], v[200:201]
	v_pk_mul_f32 v[106:107], v[106:107], v[202:203]
	v_pk_mul_f32 v[108:109], v[108:109], v[204:205]
	v_pk_mul_f32 v[110:111], v[110:111], v[206:207]
	v_lshlrev_b32_e32 v56, 16, v72
	v_and_b32_e32 v57, 0xffff0000, v72
	v_lshlrev_b32_e32 v58, 16, v73
	v_and_b32_e32 v59, 0xffff0000, v73
	v_lshlrev_b32_e32 v60, 16, v74
	v_and_b32_e32 v61, 0xffff0000, v74
	v_lshlrev_b32_e32 v62, 16, v75
	v_and_b32_e32 v63, 0xffff0000, v75
	v_pk_fma_f32 v[96:97], v[88:89], v[56:57], v[96:97] op_sel_hi:[0,1,1]
	v_pk_fma_f32 v[98:99], v[88:89], v[58:59], v[98:99] op_sel_hi:[0,1,1]
	v_pk_fma_f32 v[100:101], v[88:89], v[60:61], v[100:101] op_sel_hi:[0,1,1]
	v_pk_fma_f32 v[102:103], v[88:89], v[62:63], v[102:103] op_sel_hi:[0,1,1]
	v_lshlrev_b32_e32 v56, 16, v76
	v_and_b32_e32 v57, 0xffff0000, v76
	v_lshlrev_b32_e32 v58, 16, v77
	v_and_b32_e32 v59, 0xffff0000, v77
	v_lshlrev_b32_e32 v60, 16, v78
	v_and_b32_e32 v61, 0xffff0000, v78
	v_lshlrev_b32_e32 v62, 16, v79
	v_and_b32_e32 v63, 0xffff0000, v79
	v_pk_fma_f32 v[104:105], v[88:89], v[56:57], v[104:105] op_sel_hi:[0,1,1]
	v_pk_fma_f32 v[106:107], v[88:89], v[58:59], v[106:107] op_sel_hi:[0,1,1]
	v_pk_fma_f32 v[108:109], v[88:89], v[60:61], v[108:109] op_sel_hi:[0,1,1]
	v_pk_fma_f32 v[110:111], v[88:89], v[62:63], v[110:111] op_sel_hi:[0,1,1]
	v_pk_mul_f32 v[132:133], v[96:97], v[96:97]
	v_pk_fma_f32 v[132:133], v[98:99], v[98:99], v[132:133]
	v_pk_fma_f32 v[132:133], v[100:101], v[100:101], v[132:133]
	v_pk_fma_f32 v[132:133], v[102:103], v[102:103], v[132:133]
	v_pk_fma_f32 v[132:133], v[104:105], v[104:105], v[132:133]
	v_pk_fma_f32 v[132:133], v[106:107], v[106:107], v[132:133]
	v_pk_fma_f32 v[132:133], v[108:109], v[108:109], v[132:133]
	v_pk_fma_f32 v[132:133], v[110:111], v[110:111], v[132:133]
	s_nop 0
	v_add_f32_e32 v132, v132, v133
	v_pk_mul_f32 v[112:113], v[130:131], v[112:113] op_sel_hi:[0,1]
	v_pk_mul_f32 v[114:115], v[130:131], v[114:115] op_sel_hi:[0,1]
	v_pk_mul_f32 v[116:117], v[130:131], v[116:117] op_sel_hi:[0,1]
	v_pk_mul_f32 v[118:119], v[130:131], v[118:119] op_sel_hi:[0,1]
	v_pk_mul_f32 v[120:121], v[130:131], v[120:121] op_sel_hi:[0,1]
	v_pk_mul_f32 v[122:123], v[130:131], v[122:123] op_sel_hi:[0,1]
	v_pk_mul_f32 v[124:125], v[130:131], v[124:125] op_sel_hi:[0,1]
	v_pk_mul_f32 v[126:127], v[130:131], v[126:127] op_sel_hi:[0,1]
	v_pk_mul_f32 v[112:113], v[112:113], v[192:193]
	v_pk_mul_f32 v[114:115], v[114:115], v[194:195]
	v_pk_mul_f32 v[116:117], v[116:117], v[196:197]
	v_pk_mul_f32 v[118:119], v[118:119], v[198:199]
	v_pk_mul_f32 v[120:121], v[120:121], v[200:201]
	v_pk_mul_f32 v[122:123], v[122:123], v[202:203]
	v_pk_mul_f32 v[124:125], v[124:125], v[204:205]
	v_pk_mul_f32 v[126:127], v[126:127], v[206:207]
; __device__ __forceinline__ const float* xrow_ptr(const Ctx& C, int row) { return row < MPROMPT ? C.in(0) + (size_t)row * DM : C.in(1) + (size_t)(row - MPROMPT) * DM; }
; __device__ __forceinline__ v4f ld4_bf16(const bf16* p) { const v2u w = *(const v2u*)p; return (v4f){bf_lo(w.x), bf_hi(w.x), bf_lo(w.y), bf_hi(w.y)}; }
; __device__ __forceinline__ void st4_bf16(bf16* p, v4f o) { v2u w; w.x = cvt_pk_nv(o.x, o.y); w.y = cvt_pk_nv(o.z, o.w); *(v2u*)p = w; }
; __device__ __forceinline__ float ssq4(v4f v) { return (v.x * v.x + v.y * v.y) + (v.z * v.z + v.w * v.w); }
; template <int R, bool BASE_F32, bool OUT_F32>
; __device__ __forceinline__ void rows_res(const Ctx& C, int m0, int stride, int mx, const float* gpost, float scale, int lane) {
;     ...
;     for (int r = 0; r < R; ++r) { mr[r] = (r == 4) ? mx : m0 + r * stride; ok[r] = (r == 4) ? (mx < M) : (mr[r] < MPROMPT); const int mm = ok[r] ? mr[r] : 0;
; #pragma unroll
;         for (int j = 0; j < 4; ++j) d[r][j] = ld4_bf16(D + (size_t)mm * DM + 4 * lane + 256 * j);
;         if (BASE_F32) { const float* x = xrow_ptr(C, mm);
; #pragma unroll
;             for (int j = 0; j < 4; ++j) b[r][j] = ld4_f32(x + 4 * lane + 256 * j);
;         } else { const float inv = C.RS()[mm];
; #pragma unroll
;             for (int j = 0; j < 4; ++j) b[r][j] = ld4_bf16(XN + (size_t)mm * DM + 4 * lane + 256 * j) * inv;
;         } }
;     ...
;         for (int r = 0; r < R; ++r) { float s = 0.f;
; #pragma unroll
;             for (int j = 0; j < 4; ++j) s += ssq4(d[r][j]);
;             t[r] = s; }
; #pragma unroll
;         for (int r = 0; r < R; ++r) t[r] = wave_sum(t[r]) * (1.f / DM) + EPS;
; #pragma unroll
;         for (int r = 0; r < R; ++r) { const float rstd = rsqrtf(t[r]);
; #pragma unroll
;             for (int j = 0; j < 4; ++j) if (ok[r]) st4_bf16(XN + (size_t)mr[r] * DM + 4 * lane + 256 * j, d[r][j] * rstd);
;             if (lane == 0 && ok[r]) rs[mr[r]] = sqrtf(t[r]); }
	v_lshlrev_b32_e32 v64, 16, v80
	v_and_b32_e32 v65, 0xffff0000, v80
	v_lshlrev_b32_e32 v66, 16, v81
	v_and_b32_e32 v67, 0xffff0000, v81
	v_lshlrev_b32_e32 v68, 16, v82
	v_and_b32_e32 v69, 0xffff0000, v82
	v_lshlrev_b32_e32 v70, 16, v83
	v_and_b32_e32 v71, 0xffff0000, v83
	v_pk_fma_f32 v[112:113], v[90:91], v[64:65], v[112:113] op_sel_hi:[0,1,1]
	v_pk_fma_f32 v[114:115], v[90:91], v[66:67], v[114:115] op_sel_hi:[0,1,1]
	v_pk_fma_f32 v[116:117], v[90:91], v[68:69], v[116:117] op_sel_hi:[0,1,1]
	v_pk_fma_f32 v[118:119], v[90:91], v[70:71], v[118:119] op_sel_hi:[0,1,1]
	v_lshlrev_b32_e32 v64, 16, v84
	v_and_b32_e32 v65, 0xffff0000, v84
	v_lshlrev_b32_e32 v66, 16, v85
	v_and_b32_e32 v67, 0xffff0000, v85
	v_lshlrev_b32_e32 v68, 16, v86
	v_and_b32_e32 v69, 0xffff0000, v86
	v_lshlrev_b32_e32 v70, 16, v87
	v_and_b32_e32 v71, 0xffff0000, v87
	v_pk_fma_f32 v[120:121], v[90:91], v[64:65], v[120:121] op_sel_hi:[0,1,1]
	v_pk_fma_f32 v[122:123], v[90:91], v[66:67], v[122:123] op_sel_hi:[0,1,1]
	v_pk_fma_f32 v[124:125], v[90:91], v[68:69], v[124:125] op_sel_hi:[0,1,1]
	v_pk_fma_f32 v[126:127], v[90:91], v[70:71], v[126:127] op_sel_hi:[0,1,1]
	v_pk_mul_f32 v[134:135], v[112:113], v[112:113]
	v_pk_fma_f32 v[134:135], v[114:115], v[114:115], v[134:135]
	v_pk_fma_f32 v[134:135], v[116:117], v[116:117], v[134:135]
	v_pk_fma_f32 v[134:135], v[118:119], v[118:119], v[134:135]
	v_pk_fma_f32 v[134:135], v[120:121], v[120:121], v[134:135]
	v_pk_fma_f32 v[134:135], v[122:123], v[122:123], v[134:135]
	v_pk_fma_f32 v[134:135], v[124:125], v[124:125], v[134:135]
	v_pk_fma_f32 v[134:135], v[126:127], v[126:127], v[134:135]
	s_nop 0
	v_add_f32_e32 v134, v134, v135
	s_nop 1
	v_add_f32_dpp v132, v132, v132 quad_perm:[1,0,3,2] row_mask:0xf bank_mask:0xf
	v_add_f32_dpp v134, v134, v134 quad_perm:[1,0,3,2] row_mask:0xf bank_mask:0xf
	s_nop 0
	v_add_f32_dpp v132, v132, v132 quad_perm:[2,3,0,1] row_mask:0xf bank_mask:0xf
	v_add_f32_dpp v134, v134, v134 quad_perm:[2,3,0,1] row_mask:0xf bank_mask:0xf
	s_nop 0
	v_add_f32_dpp v132, v132, v132 row_half_mirror row_mask:0xf bank_mask:0xf
	v_add_f32_dpp v134, v134, v134 row_half_mirror row_mask:0xf bank_mask:0xf
	s_nop 0
	v_add_f32_dpp v132, v132, v132 row_mirror row_mask:0xf bank_mask:0xf
	v_add_f32_dpp v134, v134, v134 row_mirror row_mask:0xf bank_mask:0xf
	s_nop 0
	ds_bpermute_b32 v136, v187, v132
	ds_bpermute_b32 v137, v187, v134
	s_waitcnt lgkmcnt(0)
	v_add_f32_e32 v132, v132, v136
	v_add_f32_e32 v134, v134, v137
	ds_bpermute_b32 v136, v188, v132
	ds_bpermute_b32 v137, v188, v134
	s_waitcnt lgkmcnt(0)
	v_add_f32_e32 v132, v132, v136
	v_add_f32_e32 v134, v134, v137
	v_fmamk_f32 v164, v132, 0x3a800000, v138
	v_fmamk_f32 v167, v134, 0x3a800000, v138
	s_nop 0
	v_rsq_f32_e32 v132, v164
	v_rsq_f32_e32 v134, v167
	v_sqrt_f32_e32 v165, v164
	v_sqrt_f32_e32 v168, v167
	s_nop 1
	v_pk_mul_f32 v[140:141], v[96:97], v[132:133] op_sel_hi:[1,0]
	v_cvt_pk_bf16_f32 v148, v140, v141
	v_pk_mul_f32 v[142:143], v[98:99], v[132:133] op_sel_hi:[1,0]
	v_cvt_pk_bf16_f32 v149, v142, v143
	v_pk_mul_f32 v[144:145], v[100:101], v[132:133] op_sel_hi:[1,0]
	v_cvt_pk_bf16_f32 v150, v144, v145
	v_pk_mul_f32 v[146:147], v[102:103], v[132:133] op_sel_hi:[1,0]
	v_cvt_pk_bf16_f32 v151, v146, v147
	v_pk_mul_f32 v[140:141], v[104:105], v[132:133] op_sel_hi:[1,0]
	v_cvt_pk_bf16_f32 v152, v140, v141
	v_pk_mul_f32 v[142:143], v[106:107], v[132:133] op_sel_hi:[1,0]
	v_cvt_pk_bf16_f32 v153, v142, v143
	v_pk_mul_f32 v[144:145], v[108:109], v[132:133] op_sel_hi:[1,0]
	v_cvt_pk_bf16_f32 v154, v144, v145
	v_pk_mul_f32 v[146:147], v[110:111], v[132:133] op_sel_hi:[1,0]
	v_cvt_pk_bf16_f32 v155, v146, v147
	global_store_dwordx2 v173, v[148:149], s[98:99]
	global_store_dwordx2 v173, v[150:151], s[98:99] offset:512
	global_store_dwordx2 v173, v[152:153], s[98:99] offset:1024
	global_store_dwordx2 v173, v[154:155], s[98:99] offset:1536
	v_add_u32_e32 v173, 0x400000, v173
	v_pk_mul_f32 v[140:141], v[112:113], v[134:135] op_sel_hi:[1,0]
	v_cvt_pk_bf16_f32 v156, v140, v141
	v_pk_mul_f32 v[142:143], v[114:115], v[134:135] op_sel_hi:[1,0]
	v_cvt_pk_bf16_f32 v157, v142, v143
	v_pk_mul_f32 v[144:145], v[116:117], v[134:135] op_sel_hi:[1,0]
	v_cvt_pk_bf16_f32 v158, v144, v145
	v_pk_mul_f32 v[146:147], v[118:119], v[134:135] op_sel_hi:[1,0]
	v_cvt_pk_bf16_f32 v159, v146, v147
	v_pk_mul_f32 v[140:141], v[120:121], v[134:135] op_sel_hi:[1,0]
	v_cvt_pk_bf16_f32 v160, v140, v141
	v_pk_mul_f32 v[142:143], v[122:123], v[134:135] op_sel_hi:[1,0]
	v_cvt_pk_bf16_f32 v161, v142, v143
	v_pk_mul_f32 v[144:145], v[124:125], v[134:135] op_sel_hi:[1,0]
	v_cvt_pk_bf16_f32 v162, v144, v145
	v_pk_mul_f32 v[146:147], v[126:127], v[134:135] op_sel_hi:[1,0]
	v_cvt_pk_bf16_f32 v163, v146, v147
	global_store_dwordx2 v173, v[156:157], s[98:99]
	global_store_dwordx2 v173, v[158:159], s[98:99] offset:512
	global_store_dwordx2 v173, v[160:161], s[98:99] offset:1024
	global_store_dwordx2 v173, v[162:163], s[98:99] offset:1536
	v_add_u32_e32 v173, 0x400000, v173
	v_add_u32_e32 v166, -1, v165
	v_fma_f32 v140, -v166, v165, v164
	v_cmp_ge_f32_e32 vcc, 0, v140
	v_add_u32_e32 v141, 1, v165
	v_cndmask_b32_e32 v166, v165, v166, vcc
	v_fma_f32 v140, -v141, v165, v164
	v_cmp_lt_f32_e32 vcc, 0, v140
	s_nop 1
	v_cndmask_b32_e32 v165, v166, v141, vcc
	v_add_u32_e32 v169, -1, v168
	v_fma_f32 v142, -v169, v168, v167
	v_cmp_ge_f32_e32 vcc, 0, v142
	v_add_u32_e32 v143, 1, v168
	v_cndmask_b32_e32 v169, v168, v169, vcc
	v_fma_f32 v142, -v143, v168, v167
	v_cmp_lt_f32_e32 vcc, 0, v142
	s_nop 1
	v_cndmask_b32_e32 v168, v169, v143, vcc
	s_mov_b64 exec, 1
	global_store_dword v174, v165, s[98:99]
	v_add_u32_e32 v174, 0x2000, v174
	global_store_dword v174, v168, s[98:99]
	v_add_u32_e32 v174, 0x2000, v174
	s_mov_b64 exec, -1
	global_load_dword v88, v172, s[98:99]
	global_load_dwordx2 v[56:57], v170, s[98:99]
	global_load_dwordx2 v[58:59], v170, s[98:99] offset:512
	global_load_dwordx2 v[60:61], v170, s[98:99] offset:1024
	global_load_dwordx2 v[62:63], v170, s[98:99] offset:1536
	global_load_dwordx2 v[72:73], v171, s[98:99]
	global_load_dwordx2 v[74:75], v171, s[98:99] offset:512
	global_load_dwordx2 v[76:77], v171, s[98:99] offset:1024
	global_load_dwordx2 v[78:79], v171, s[98:99] offset:1536
	v_add_u32_e32 v170, 0x400000, v170
	v_add_u32_e32 v171, 0x400000, v171
	v_add_u32_e32 v172, 0x2000, v172
	global_load_dword v90, v172, s[98:99]
	global_load_dwordx2 v[64:65], v170, s[98:99]
	global_load_dwordx2 v[66:67], v170, s[98:99] offset:512
	global_load_dwordx2 v[68:69], v170, s[98:99] offset:1024
	global_load_dwordx2 v[70:71], v170, s[98:99] offset:1536
	global_load_dwordx2 v[80:81], v171, s[98:99]
	global_load_dwordx2 v[82:83], v171, s[98:99] offset:512
	global_load_dwordx2 v[84:85], v171, s[98:99] offset:1024
	global_load_dwordx2 v[86:87], v171, s[98:99] offset:1536
	v_add_u32_e32 v170, 0x400000, v170
	v_add_u32_e32 v171, 0x400000, v171
	v_add_u32_e32 v172, 0x2000, v172
	s_waitcnt vmcnt(41)
;     __device__ __forceinline__ float* out() const { return (float*)karg_in(33); }
; __device__ __forceinline__ float ssq4(v4f v) { return (v.x * v.x + v.y * v.y) + (v.z * v.z + v.w * v.w); }
; template <int R, bool BASE_F32, bool OUT_F32>
; __device__ __forceinline__ void rows_res(const Ctx& C, int m0, int stride, int mx, const float* gpost, float scale, int lane) {
;     ...
;     for (int r = 0; r < R; ++r) { float s = 0.f;
; #pragma unroll
;         for (int j = 0; j < 4; ++j) s += ssq4(d[r][j]);
;         r1[r] = s; }
; #pragma unroll
;     for (int r = 0; r < R; ++r) r1[r] = rsqrtf(wave_sum(r1[r]) * (1.f / DM) + EPS) * scale;
; #pragma unroll
;     for (int j = 0; j < 4; ++j) { const v4f gp = ld4_f32(gpost + 4 * lane + 256 * j);
; #pragma unroll
;         for (int r = 0; r < R; ++r) d[r][j] = b[r][j] + d[r][j] * r1[r] * gp; }
;     if (OUT_F32) { float* Y = C.out();
; #pragma unroll
;         for (int r = 0; r < R; ++r)
; #pragma unroll
;             for (int j = 0; j < 4; ++j) if (ok[r]) *(v4f*)(Y + (size_t)mr[r] * DM + 4 * lane + 256 * j) = d[r][j];
;     } else { float* rs = C.RS(); float t[R];
; #pragma unroll
;         for (int r = 0; r < R; ++r) { float s = 0.f;
; #pragma unroll
;             for (int j = 0; j < 4; ++j) s += ssq4(d[r][j]);
;             t[r] = s; }
	v_lshlrev_b32_e32 v96, 16, v20
	v_and_b32_e32 v97, 0xffff0000, v20
	v_lshlrev_b32_e32 v98, 16, v21
	v_and_b32_e32 v99, 0xffff0000, v21
	v_lshlrev_b32_e32 v100, 16, v22
	v_and_b32_e32 v101, 0xffff0000, v22
	v_lshlrev_b32_e32 v102, 16, v23
	v_and_b32_e32 v103, 0xffff0000, v23
	v_lshlrev_b32_e32 v104, 16, v24
	v_and_b32_e32 v105, 0xffff0000, v24
	v_lshlrev_b32_e32 v106, 16, v25
	v_and_b32_e32 v107, 0xffff0000, v25
	v_lshlrev_b32_e32 v108, 16, v26
	v_and_b32_e32 v109, 0xffff0000, v26
	v_lshlrev_b32_e32 v110, 16, v27
	v_and_b32_e32 v111, 0xffff0000, v27
	v_pk_mul_f32 v[128:129], v[96:97], v[96:97]
	v_pk_fma_f32 v[128:129], v[98:99], v[98:99], v[128:129]
	v_pk_fma_f32 v[128:129], v[100:101], v[100:101], v[128:129]
	v_pk_fma_f32 v[128:129], v[102:103], v[102:103], v[128:129]
	v_pk_fma_f32 v[128:129], v[104:105], v[104:105], v[128:129]
	v_pk_fma_f32 v[128:129], v[106:107], v[106:107], v[128:129]
	v_pk_fma_f32 v[128:129], v[108:109], v[108:109], v[128:129]
	v_pk_fma_f32 v[128:129], v[110:111], v[110:111], v[128:129]
	s_nop 0
	v_add_f32_e32 v128, v128, v129
	s_waitcnt vmcnt(32)
	v_lshlrev_b32_e32 v112, 16, v28
	v_and_b32_e32 v113, 0xffff0000, v28
	v_lshlrev_b32_e32 v114, 16, v29
	v_and_b32_e32 v115, 0xffff0000, v29
	v_lshlrev_b32_e32 v116, 16, v30
	v_and_b32_e32 v117, 0xffff0000, v30
	v_lshlrev_b32_e32 v118, 16, v31
	v_and_b32_e32 v119, 0xffff0000, v31
	v_lshlrev_b32_e32 v120, 16, v32
	v_and_b32_e32 v121, 0xffff0000, v32
	v_lshlrev_b32_e32 v122, 16, v33
	v_and_b32_e32 v123, 0xffff0000, v33
	v_lshlrev_b32_e32 v124, 16, v34
	v_and_b32_e32 v125, 0xffff0000, v34
	v_lshlrev_b32_e32 v126, 16, v35
	v_and_b32_e32 v127, 0xffff0000, v35
	v_pk_mul_f32 v[130:131], v[112:113], v[112:113]
	v_pk_fma_f32 v[130:131], v[114:115], v[114:115], v[130:131]
	v_pk_fma_f32 v[130:131], v[116:117], v[116:117], v[130:131]
	v_pk_fma_f32 v[130:131], v[118:119], v[118:119], v[130:131]
	v_pk_fma_f32 v[130:131], v[120:121], v[120:121], v[130:131]
	v_pk_fma_f32 v[130:131], v[122:123], v[122:123], v[130:131]
	v_pk_fma_f32 v[130:131], v[124:125], v[124:125], v[130:131]
	v_pk_fma_f32 v[130:131], v[126:127], v[126:127], v[130:131]
	s_nop 0
	v_add_f32_e32 v130, v130, v131
	s_nop 1
	v_add_f32_dpp v128, v128, v128 quad_perm:[1,0,3,2] row_mask:0xf bank_mask:0xf
	v_add_f32_dpp v130, v130, v130 quad_perm:[1,0,3,2] row_mask:0xf bank_mask:0xf
	s_nop 0
	v_add_f32_dpp v128, v128, v128 quad_perm:[2,3,0,1] row_mask:0xf bank_mask:0xf
	v_add_f32_dpp v130, v130, v130 quad_perm:[2,3,0,1] row_mask:0xf bank_mask:0xf
	s_nop 0
	v_add_f32_dpp v128, v128, v128 row_half_mirror row_mask:0xf bank_mask:0xf
	v_add_f32_dpp v130, v130, v130 row_half_mirror row_mask:0xf bank_mask:0xf
	s_nop 0
	v_add_f32_dpp v128, v128, v128 row_mirror row_mask:0xf bank_mask:0xf
	v_add_f32_dpp v130, v130, v130 row_mirror row_mask:0xf bank_mask:0xf
	s_nop 0
	ds_bpermute_b32 v136, v187, v128
	ds_bpermute_b32 v137, v187, v130
	s_waitcnt lgkmcnt(0)
	v_add_f32_e32 v128, v128, v136
	v_add_f32_e32 v130, v130, v137
	ds_bpermute_b32 v136, v188, v128
	ds_bpermute_b32 v137, v188, v130
	s_waitcnt lgkmcnt(0)
	v_add_f32_e32 v128, v128, v136
	v_add_f32_e32 v130, v130, v137
	v_fmamk_f32 v128, v128, 0x3a800000, v138
	v_fmamk_f32 v130, v130, 0x3a800000, v138
	s_nop 0
	v_rsq_f32_e32 v128, v128
	v_rsq_f32_e32 v130, v130
	s_nop 1
	s_waitcnt vmcnt(28)
	v_pk_mul_f32 v[96:97], v[128:129], v[96:97] op_sel_hi:[0,1]
	v_pk_mul_f32 v[98:99], v[128:129], v[98:99] op_sel_hi:[0,1]
	v_pk_mul_f32 v[100:101], v[128:129], v[100:101] op_sel_hi:[0,1]
	v_pk_mul_f32 v[102:103], v[128:129], v[102:103] op_sel_hi:[0,1]
	v_pk_mul_f32 v[104:105], v[128:129], v[104:105] op_sel_hi:[0,1]
	v_pk_mul_f32 v[106:107], v[128:129], v[106:107] op_sel_hi:[0,1]
	v_pk_mul_f32 v[108:109], v[128:129], v[108:109] op_sel_hi:[0,1]
	v_pk_mul_f32 v[110:111], v[128:129], v[110:111] op_sel_hi:[0,1]
	v_pk_mul_f32 v[96:97], v[96:97], v[192:193]
	v_pk_mul_f32 v[98:99], v[98:99], v[194:195]
	v_pk_mul_f32 v[100:101], v[100:101], v[196:197]
	v_pk_mul_f32 v[102:103], v[102:103], v[198:199]
	v_pk_mul_f32 v[104:105], v[104:105], v[200:201]
	v_pk_mul_f32 v[106:107], v[106:107], v[202:203]
	v_pk_mul_f32 v[108:109], v[108:109], v[204:205]
	v_pk_mul_f32 v[110:111], v[110:111], v[206:207]
	v_lshlrev_b32_e32 v20, 16, v36
	v_and_b32_e32 v21, 0xffff0000, v36
	v_lshlrev_b32_e32 v22, 16, v37
	v_and_b32_e32 v23, 0xffff0000, v37
	v_lshlrev_b32_e32 v24, 16, v38
	v_and_b32_e32 v25, 0xffff0000, v38
	v_lshlrev_b32_e32 v26, 16, v39
	v_and_b32_e32 v27, 0xffff0000, v39
	v_pk_fma_f32 v[96:97], v[52:53], v[20:21], v[96:97] op_sel_hi:[0,1,1]
	v_pk_fma_f32 v[98:99], v[52:53], v[22:23], v[98:99] op_sel_hi:[0,1,1]
	v_pk_fma_f32 v[100:101], v[52:53], v[24:25], v[100:101] op_sel_hi:[0,1,1]
	v_pk_fma_f32 v[102:103], v[52:53], v[26:27], v[102:103] op_sel_hi:[0,1,1]
	v_lshlrev_b32_e32 v20, 16, v40
	v_and_b32_e32 v21, 0xffff0000, v40
	v_lshlrev_b32_e32 v22, 16, v41
	v_and_b32_e32 v23, 0xffff0000, v41
	v_lshlrev_b32_e32 v24, 16, v42
	v_and_b32_e32 v25, 0xffff0000, v42
	v_lshlrev_b32_e32 v26, 16, v43
	v_and_b32_e32 v27, 0xffff0000, v43
	v_pk_fma_f32 v[104:105], v[52:53], v[20:21], v[104:105] op_sel_hi:[0,1,1]
	v_pk_fma_f32 v[106:107], v[52:53], v[22:23], v[106:107] op_sel_hi:[0,1,1]
	v_pk_fma_f32 v[108:109], v[52:53], v[24:25], v[108:109] op_sel_hi:[0,1,1]
	v_pk_fma_f32 v[110:111], v[52:53], v[26:27], v[110:111] op_sel_hi:[0,1,1]
	v_pk_mul_f32 v[132:133], v[96:97], v[96:97]
	v_pk_fma_f32 v[132:133], v[98:99], v[98:99], v[132:133]
	v_pk_fma_f32 v[132:133], v[100:101], v[100:101], v[132:133]
	v_pk_fma_f32 v[132:133], v[102:103], v[102:103], v[132:133]
	v_pk_fma_f32 v[132:133], v[104:105], v[104:105], v[132:133]
;     __device__ __forceinline__ float* out() const { return (float*)karg_in(33); }
; __device__ __forceinline__ void st4_bf16(bf16* p, v4f o) { v2u w; w.x = cvt_pk_nv(o.x, o.y); w.y = cvt_pk_nv(o.z, o.w); *(v2u*)p = w; }
; __device__ __forceinline__ float ssq4(v4f v) { return (v.x * v.x + v.y * v.y) + (v.z * v.z + v.w * v.w); }
; template <int R, bool BASE_F32, bool OUT_F32>
; __device__ __forceinline__ void rows_res(const Ctx& C, int m0, int stride, int mx, const float* gpost, float scale, int lane) {
;     ...
;     for (int r = 0; r < R; ++r) { float s = 0.f;
; #pragma unroll
;         for (int j = 0; j < 4; ++j) s += ssq4(d[r][j]);
;         r1[r] = s; }
; #pragma unroll
;     for (int r = 0; r < R; ++r) r1[r] = rsqrtf(wave_sum(r1[r]) * (1.f / DM) + EPS) * scale;
; #pragma unroll
;     for (int j = 0; j < 4; ++j) { const v4f gp = ld4_f32(gpost + 4 * lane + 256 * j);
; #pragma unroll
;         for (int r = 0; r < R; ++r) d[r][j] = b[r][j] + d[r][j] * r1[r] * gp; }
;     if (OUT_F32) { float* Y = C.out();
; #pragma unroll
;         for (int r = 0; r < R; ++r)
; #pragma unroll
;             for (int j = 0; j < 4; ++j) if (ok[r]) *(v4f*)(Y + (size_t)mr[r] * DM + 4 * lane + 256 * j) = d[r][j];
;     } else { float* rs = C.RS(); float t[R];
; #pragma unroll
;         for (int r = 0; r < R; ++r) { float s = 0.f;
; #pragma unroll
;             for (int j = 0; j < 4; ++j) s += ssq4(d[r][j]);
;             t[r] = s; }
; #pragma unroll
;         for (int r = 0; r < R; ++r) t[r] = wave_sum(t[r]) * (1.f / DM) + EPS;
; #pragma unroll
;         for (int r = 0; r < R; ++r) { const float rstd = rsqrtf(t[r]);
; #pragma unroll
;             for (int j = 0; j < 4; ++j) if (ok[r]) st4_bf16(XN + (size_t)mr[r] * DM + 4 * lane + 256 * j, d[r][j] * rstd);
;             if (lane == 0 && ok[r]) rs[mr[r]] = sqrtf(t[r]); }
	v_pk_fma_f32 v[132:133], v[106:107], v[106:107], v[132:133]
	v_pk_fma_f32 v[132:133], v[108:109], v[108:109], v[132:133]
	v_pk_fma_f32 v[132:133], v[110:111], v[110:111], v[132:133]
	s_nop 0
	v_add_f32_e32 v132, v132, v133
	v_pk_mul_f32 v[112:113], v[130:131], v[112:113] op_sel_hi:[0,1]
	v_pk_mul_f32 v[114:115], v[130:131], v[114:115] op_sel_hi:[0,1]
	v_pk_mul_f32 v[116:117], v[130:131], v[116:117] op_sel_hi:[0,1]
	v_pk_mul_f32 v[118:119], v[130:131], v[118:119] op_sel_hi:[0,1]
	v_pk_mul_f32 v[120:121], v[130:131], v[120:121] op_sel_hi:[0,1]
	v_pk_mul_f32 v[122:123], v[130:131], v[122:123] op_sel_hi:[0,1]
	v_pk_mul_f32 v[124:125], v[130:131], v[124:125] op_sel_hi:[0,1]
	v_pk_mul_f32 v[126:127], v[130:131], v[126:127] op_sel_hi:[0,1]
	v_pk_mul_f32 v[112:113], v[112:113], v[192:193]
	v_pk_mul_f32 v[114:115], v[114:115], v[194:195]
	v_pk_mul_f32 v[116:117], v[116:117], v[196:197]
	v_pk_mul_f32 v[118:119], v[118:119], v[198:199]
	v_pk_mul_f32 v[120:121], v[120:121], v[200:201]
	v_pk_mul_f32 v[122:123], v[122:123], v[202:203]
	v_pk_mul_f32 v[124:125], v[124:125], v[204:205]
	v_pk_mul_f32 v[126:127], v[126:127], v[206:207]
	v_lshlrev_b32_e32 v28, 16, v44
	v_and_b32_e32 v29, 0xffff0000, v44
	v_lshlrev_b32_e32 v30, 16, v45
	v_and_b32_e32 v31, 0xffff0000, v45
	v_lshlrev_b32_e32 v32, 16, v46
	v_and_b32_e32 v33, 0xffff0000, v46
	v_lshlrev_b32_e32 v34, 16, v47
	v_and_b32_e32 v35, 0xffff0000, v47
	v_pk_fma_f32 v[112:113], v[54:55], v[28:29], v[112:113] op_sel_hi:[0,1,1]
	v_pk_fma_f32 v[114:115], v[54:55], v[30:31], v[114:115] op_sel_hi:[0,1,1]
	v_pk_fma_f32 v[116:117], v[54:55], v[32:33], v[116:117] op_sel_hi:[0,1,1]
	v_pk_fma_f32 v[118:119], v[54:55], v[34:35], v[118:119] op_sel_hi:[0,1,1]
	v_lshlrev_b32_e32 v28, 16, v48
	v_and_b32_e32 v29, 0xffff0000, v48
	v_lshlrev_b32_e32 v30, 16, v49
	v_and_b32_e32 v31, 0xffff0000, v49
	v_lshlrev_b32_e32 v32, 16, v50
	v_and_b32_e32 v33, 0xffff0000, v50
	v_lshlrev_b32_e32 v34, 16, v51
	v_and_b32_e32 v35, 0xffff0000, v51
	v_pk_fma_f32 v[120:121], v[54:55], v[28:29], v[120:121] op_sel_hi:[0,1,1]
	v_pk_fma_f32 v[122:123], v[54:55], v[30:31], v[122:123] op_sel_hi:[0,1,1]
	v_pk_fma_f32 v[124:125], v[54:55], v[32:33], v[124:125] op_sel_hi:[0,1,1]
	v_pk_fma_f32 v[126:127], v[54:55], v[34:35], v[126:127] op_sel_hi:[0,1,1]
	v_pk_mul_f32 v[134:135], v[112:113], v[112:113]
	v_pk_fma_f32 v[134:135], v[114:115], v[114:115], v[134:135]
	v_pk_fma_f32 v[134:135], v[116:117], v[116:117], v[134:135]
	v_pk_fma_f32 v[134:135], v[118:119], v[118:119], v[134:135]
	v_pk_fma_f32 v[134:135], v[120:121], v[120:121], v[134:135]
	v_pk_fma_f32 v[134:135], v[122:123], v[122:123], v[134:135]
	v_pk_fma_f32 v[134:135], v[124:125], v[124:125], v[134:135]
	v_pk_fma_f32 v[134:135], v[126:127], v[126:127], v[134:135]
	s_nop 0
	v_add_f32_e32 v134, v134, v135
	s_nop 1
	v_add_f32_dpp v132, v132, v132 quad_perm:[1,0,3,2] row_mask:0xf bank_mask:0xf
	v_add_f32_dpp v134, v134, v134 quad_perm:[1,0,3,2] row_mask:0xf bank_mask:0xf
	s_nop 0
	v_add_f32_dpp v132, v132, v132 quad_perm:[2,3,0,1] row_mask:0xf bank_mask:0xf
	v_add_f32_dpp v134, v134, v134 quad_perm:[2,3,0,1] row_mask:0xf bank_mask:0xf
	s_nop 0
	v_add_f32_dpp v132, v132, v132 row_half_mirror row_mask:0xf bank_mask:0xf
	v_add_f32_dpp v134, v134, v134 row_half_mirror row_mask:0xf bank_mask:0xf
	s_nop 0
	v_add_f32_dpp v132, v132, v132 row_mirror row_mask:0xf bank_mask:0xf
	v_add_f32_dpp v134, v134, v134 row_mirror row_mask:0xf bank_mask:0xf
	s_nop 0
	ds_bpermute_b32 v136, v187, v132
	ds_bpermute_b32 v137, v187, v134
	s_waitcnt lgkmcnt(0)
	v_add_f32_e32 v132, v132, v136
	v_add_f32_e32 v134, v134, v137
	ds_bpermute_b32 v136, v188, v132
	ds_bpermute_b32 v137, v188, v134
	s_waitcnt lgkmcnt(0)
	v_add_f32_e32 v132, v132, v136
	v_add_f32_e32 v134, v134, v137
	v_fmamk_f32 v164, v132, 0x3a800000, v138
	v_fmamk_f32 v167, v134, 0x3a800000, v138
	s_nop 0
	v_rsq_f32_e32 v132, v164
	v_rsq_f32_e32 v134, v167
	v_sqrt_f32_e32 v165, v164
	v_sqrt_f32_e32 v168, v167
	s_nop 1
	v_pk_mul_f32 v[140:141], v[96:97], v[132:133] op_sel_hi:[1,0]
	v_cvt_pk_bf16_f32 v148, v140, v141
	v_pk_mul_f32 v[142:143], v[98:99], v[132:133] op_sel_hi:[1,0]
	v_cvt_pk_bf16_f32 v149, v142, v143
	v_pk_mul_f32 v[144:145], v[100:101], v[132:133] op_sel_hi:[1,0]
	v_cvt_pk_bf16_f32 v150, v144, v145
	v_pk_mul_f32 v[146:147], v[102:103], v[132:133] op_sel_hi:[1,0]
	v_cvt_pk_bf16_f32 v151, v146, v147
	v_pk_mul_f32 v[140:141], v[104:105], v[132:133] op_sel_hi:[1,0]
	v_cvt_pk_bf16_f32 v152, v140, v141
	v_pk_mul_f32 v[142:143], v[106:107], v[132:133] op_sel_hi:[1,0]
	v_cvt_pk_bf16_f32 v153, v142, v143
	v_pk_mul_f32 v[144:145], v[108:109], v[132:133] op_sel_hi:[1,0]
	v_cvt_pk_bf16_f32 v154, v144, v145
	v_pk_mul_f32 v[146:147], v[110:111], v[132:133] op_sel_hi:[1,0]
	v_cvt_pk_bf16_f32 v155, v146, v147
	global_store_dwordx2 v173, v[148:149], s[98:99]
	global_store_dwordx2 v173, v[150:151], s[98:99] offset:512
	global_store_dwordx2 v173, v[152:153], s[98:99] offset:1024
	global_store_dwordx2 v173, v[154:155], s[98:99] offset:1536
	v_add_u32_e32 v173, 0x400000, v173
	v_pk_mul_f32 v[140:141], v[112:113], v[134:135] op_sel_hi:[1,0]
	v_cvt_pk_bf16_f32 v156, v140, v141
	v_pk_mul_f32 v[142:143], v[114:115], v[134:135] op_sel_hi:[1,0]
	v_cvt_pk_bf16_f32 v157, v142, v143
	v_pk_mul_f32 v[144:145], v[116:117], v[134:135] op_sel_hi:[1,0]
	v_cvt_pk_bf16_f32 v158, v144, v145
	v_pk_mul_f32 v[146:147], v[118:119], v[134:135] op_sel_hi:[1,0]
	v_cvt_pk_bf16_f32 v159, v146, v147
	v_pk_mul_f32 v[140:141], v[120:121], v[134:135] op_sel_hi:[1,0]
	v_cvt_pk_bf16_f32 v160, v140, v141
	v_pk_mul_f32 v[142:143], v[122:123], v[134:135] op_sel_hi:[1,0]
	v_cvt_pk_bf16_f32 v161, v142, v143
; __device__ __forceinline__ const float* xrow_ptr(const Ctx& C, int row) { return row < MPROMPT ? C.in(0) + (size_t)row * DM : C.in(1) + (size_t)(row - MPROMPT) * DM; }
; __device__ __forceinline__ v4f ld4_bf16(const bf16* p) { const v2u w = *(const v2u*)p; return (v4f){bf_lo(w.x), bf_hi(w.x), bf_lo(w.y), bf_hi(w.y)}; }
; __device__ __forceinline__ void st4_bf16(bf16* p, v4f o) { v2u w; w.x = cvt_pk_nv(o.x, o.y); w.y = cvt_pk_nv(o.z, o.w); *(v2u*)p = w; }
; __device__ __forceinline__ float ssq4(v4f v) { return (v.x * v.x + v.y * v.y) + (v.z * v.z + v.w * v.w); }
; template <int R, bool BASE_F32, bool OUT_F32>
; __device__ __forceinline__ void rows_res(const Ctx& C, int m0, int stride, int mx, const float* gpost, float scale, int lane) {
;     ...
;     for (int r = 0; r < R; ++r) { mr[r] = (r == 4) ? mx : m0 + r * stride; ok[r] = (r == 4) ? (mx < M) : (mr[r] < MPROMPT); const int mm = ok[r] ? mr[r] : 0;
; #pragma unroll
;         for (int j = 0; j < 4; ++j) d[r][j] = ld4_bf16(D + (size_t)mm * DM + 4 * lane + 256 * j);
;         if (BASE_F32) { const float* x = xrow_ptr(C, mm);
; #pragma unroll
;             for (int j = 0; j < 4; ++j) b[r][j] = ld4_f32(x + 4 * lane + 256 * j);
;         } else { const float inv = C.RS()[mm];
; #pragma unroll
;             for (int j = 0; j < 4; ++j) b[r][j] = ld4_bf16(XN + (size_t)mm * DM + 4 * lane + 256 * j) * inv;
;         } }
; #pragma unroll
;     for (int r = 0; r < R; ++r) { float s = 0.f;
; #pragma unroll
;         for (int j = 0; j < 4; ++j) s += ssq4(d[r][j]);
;         r1[r] = s; }
; #pragma unroll
;     for (int r = 0; r < R; ++r) r1[r] = rsqrtf(wave_sum(r1[r]) * (1.f / DM) + EPS) * scale;
;     ...
;         for (int r = 0; r < R; ++r) { const float rstd = rsqrtf(t[r]);
; #pragma unroll
;             for (int j = 0; j < 4; ++j) if (ok[r]) st4_bf16(XN + (size_t)mr[r] * DM + 4 * lane + 256 * j, d[r][j] * rstd);
;             if (lane == 0 && ok[r]) rs[mr[r]] = sqrtf(t[r]); }
	v_pk_mul_f32 v[144:145], v[124:125], v[134:135] op_sel_hi:[1,0]
	v_cvt_pk_bf16_f32 v162, v144, v145
	v_pk_mul_f32 v[146:147], v[126:127], v[134:135] op_sel_hi:[1,0]
	v_cvt_pk_bf16_f32 v163, v146, v147
	global_store_dwordx2 v173, v[156:157], s[98:99]
	global_store_dwordx2 v173, v[158:159], s[98:99] offset:512
	global_store_dwordx2 v173, v[160:161], s[98:99] offset:1024
	global_store_dwordx2 v173, v[162:163], s[98:99] offset:1536
	v_add_u32_e32 v173, 0x400000, v173
	v_add_u32_e32 v166, -1, v165
	v_fma_f32 v140, -v166, v165, v164
	v_cmp_ge_f32_e32 vcc, 0, v140
	v_add_u32_e32 v141, 1, v165
	v_cndmask_b32_e32 v166, v165, v166, vcc
	v_fma_f32 v140, -v141, v165, v164
	v_cmp_lt_f32_e32 vcc, 0, v140
	s_nop 1
	v_cndmask_b32_e32 v165, v166, v141, vcc
	v_add_u32_e32 v169, -1, v168
	v_fma_f32 v142, -v169, v168, v167
	v_cmp_ge_f32_e32 vcc, 0, v142
	v_add_u32_e32 v143, 1, v168
	v_cndmask_b32_e32 v169, v168, v169, vcc
	v_fma_f32 v142, -v143, v168, v167
	v_cmp_lt_f32_e32 vcc, 0, v142
	s_nop 1
	v_cndmask_b32_e32 v168, v169, v143, vcc
	s_mov_b64 exec, 1
	global_store_dword v174, v165, s[98:99]
	v_add_u32_e32 v174, 0x2000, v174
	global_store_dword v174, v168, s[98:99]
	v_add_u32_e32 v174, 0x2000, v174
	s_mov_b64 exec, -1
	global_load_dword v52, v172, s[98:99]
	global_load_dwordx2 v[20:21], v170, s[98:99]
	global_load_dwordx2 v[22:23], v170, s[98:99] offset:512
	global_load_dwordx2 v[24:25], v170, s[98:99] offset:1024
	global_load_dwordx2 v[26:27], v170, s[98:99] offset:1536
	global_load_dwordx2 v[36:37], v171, s[98:99]
	global_load_dwordx2 v[38:39], v171, s[98:99] offset:512
	global_load_dwordx2 v[40:41], v171, s[98:99] offset:1024
	global_load_dwordx2 v[42:43], v171, s[98:99] offset:1536
	v_add_u32_e32 v170, 0x400000, v170
	v_add_u32_e32 v171, 0x400000, v171
	v_add_u32_e32 v172, 0x2000, v172
	global_load_dword v54, v172, s[98:99]
	global_load_dwordx2 v[28:29], v170, s[98:99]
	global_load_dwordx2 v[30:31], v170, s[98:99] offset:512
	global_load_dwordx2 v[32:33], v170, s[98:99] offset:1024
	global_load_dwordx2 v[34:35], v170, s[98:99] offset:1536
	global_load_dwordx2 v[44:45], v171, s[98:99]
	global_load_dwordx2 v[46:47], v171, s[98:99] offset:512
	global_load_dwordx2 v[48:49], v171, s[98:99] offset:1024
	global_load_dwordx2 v[50:51], v171, s[98:99] offset:1536
	v_add_u32_e32 v170, 0x400000, v170
	v_add_u32_e32 v171, 0x400000, v171
	v_add_u32_e32 v172, 0x2000, v172
	s_waitcnt vmcnt(41)
	v_lshlrev_b32_e32 v96, 16, v56
	v_and_b32_e32 v97, 0xffff0000, v56
	v_lshlrev_b32_e32 v98, 16, v57
	v_and_b32_e32 v99, 0xffff0000, v57
	v_lshlrev_b32_e32 v100, 16, v58
	v_and_b32_e32 v101, 0xffff0000, v58
	v_lshlrev_b32_e32 v102, 16, v59
	v_and_b32_e32 v103, 0xffff0000, v59
	v_lshlrev_b32_e32 v104, 16, v60
	v_and_b32_e32 v105, 0xffff0000, v60
	v_lshlrev_b32_e32 v106, 16, v61
	v_and_b32_e32 v107, 0xffff0000, v61
	v_lshlrev_b32_e32 v108, 16, v62
	v_and_b32_e32 v109, 0xffff0000, v62
	v_lshlrev_b32_e32 v110, 16, v63
	v_and_b32_e32 v111, 0xffff0000, v63
	v_pk_mul_f32 v[128:129], v[96:97], v[96:97]
	v_pk_fma_f32 v[128:129], v[98:99], v[98:99], v[128:129]
	v_pk_fma_f32 v[128:129], v[100:101], v[100:101], v[128:129]
	v_pk_fma_f32 v[128:129], v[102:103], v[102:103], v[128:129]
	v_pk_fma_f32 v[128:129], v[104:105], v[104:105], v[128:129]
	v_pk_fma_f32 v[128:129], v[106:107], v[106:107], v[128:129]
	v_pk_fma_f32 v[128:129], v[108:109], v[108:109], v[128:129]
	v_pk_fma_f32 v[128:129], v[110:111], v[110:111], v[128:129]
	s_nop 0
	v_add_f32_e32 v128, v128, v129
	s_waitcnt vmcnt(32)
	v_lshlrev_b32_e32 v112, 16, v64
	v_and_b32_e32 v113, 0xffff0000, v64
	v_lshlrev_b32_e32 v114, 16, v65
	v_and_b32_e32 v115, 0xffff0000, v65
	v_lshlrev_b32_e32 v116, 16, v66
	v_and_b32_e32 v117, 0xffff0000, v66
	v_lshlrev_b32_e32 v118, 16, v67
	v_and_b32_e32 v119, 0xffff0000, v67
	v_lshlrev_b32_e32 v120, 16, v68
	v_and_b32_e32 v121, 0xffff0000, v68
	v_lshlrev_b32_e32 v122, 16, v69
	v_and_b32_e32 v123, 0xffff0000, v69
	v_lshlrev_b32_e32 v124, 16, v70
	v_and_b32_e32 v125, 0xffff0000, v70
	v_lshlrev_b32_e32 v126, 16, v71
	v_and_b32_e32 v127, 0xffff0000, v71
	v_pk_mul_f32 v[130:131], v[112:113], v[112:113]
	v_pk_fma_f32 v[130:131], v[114:115], v[114:115], v[130:131]
	v_pk_fma_f32 v[130:131], v[116:117], v[116:117], v[130:131]
	v_pk_fma_f32 v[130:131], v[118:119], v[118:119], v[130:131]
	v_pk_fma_f32 v[130:131], v[120:121], v[120:121], v[130:131]
	v_pk_fma_f32 v[130:131], v[122:123], v[122:123], v[130:131]
	v_pk_fma_f32 v[130:131], v[124:125], v[124:125], v[130:131]
	v_pk_fma_f32 v[130:131], v[126:127], v[126:127], v[130:131]
	s_nop 0
	v_add_f32_e32 v130, v130, v131
	s_nop 1
	v_add_f32_dpp v128, v128, v128 quad_perm:[1,0,3,2] row_mask:0xf bank_mask:0xf
	v_add_f32_dpp v130, v130, v130 quad_perm:[1,0,3,2] row_mask:0xf bank_mask:0xf
	s_nop 0
	v_add_f32_dpp v128, v128, v128 quad_perm:[2,3,0,1] row_mask:0xf bank_mask:0xf
	v_add_f32_dpp v130, v130, v130 quad_perm:[2,3,0,1] row_mask:0xf bank_mask:0xf
	s_nop 0
	v_add_f32_dpp v128, v128, v128 row_half_mirror row_mask:0xf bank_mask:0xf
	v_add_f32_dpp v130, v130, v130 row_half_mirror row_mask:0xf bank_mask:0xf
	s_nop 0
	v_add_f32_dpp v128, v128, v128 row_mirror row_mask:0xf bank_mask:0xf
	v_add_f32_dpp v130, v130, v130 row_mirror row_mask:0xf bank_mask:0xf
	s_nop 0
	ds_bpermute_b32 v136, v187, v128
	ds_bpermute_b32 v137, v187, v130
	s_waitcnt lgkmcnt(0)
	v_add_f32_e32 v128, v128, v136
	v_add_f32_e32 v130, v130, v137
	ds_bpermute_b32 v136, v188, v128
	ds_bpermute_b32 v137, v188, v130
	s_waitcnt lgkmcnt(0)
	v_add_f32_e32 v128, v128, v136
	v_add_f32_e32 v130, v130, v137
	v_fmamk_f32 v128, v128, 0x3a800000, v138
	v_fmamk_f32 v130, v130, 0x3a800000, v138
	s_nop 0
	v_rsq_f32_e32 v128, v128
	v_rsq_f32_e32 v130, v130
	s_nop 1
	s_waitcnt vmcnt(28)
;     __device__ __forceinline__ float* out() const { return (float*)karg_in(33); }
; __device__ __forceinline__ float ssq4(v4f v) { return (v.x * v.x + v.y * v.y) + (v.z * v.z + v.w * v.w); }
; template <int R, bool BASE_F32, bool OUT_F32>
; __device__ __forceinline__ void rows_res(const Ctx& C, int m0, int stride, int mx, const float* gpost, float scale, int lane) {
;     ...
;     for (int r = 0; r < R; ++r) r1[r] = rsqrtf(wave_sum(r1[r]) * (1.f / DM) + EPS) * scale;
; #pragma unroll
;     for (int j = 0; j < 4; ++j) { const v4f gp = ld4_f32(gpost + 4 * lane + 256 * j);
; #pragma unroll
;         for (int r = 0; r < R; ++r) d[r][j] = b[r][j] + d[r][j] * r1[r] * gp; }
;     if (OUT_F32) { float* Y = C.out();
; #pragma unroll
;         for (int r = 0; r < R; ++r)
; #pragma unroll
;             for (int j = 0; j < 4; ++j) if (ok[r]) *(v4f*)(Y + (size_t)mr[r] * DM + 4 * lane + 256 * j) = d[r][j];
;     } else { float* rs = C.RS(); float t[R];
; #pragma unroll
;         for (int r = 0; r < R; ++r) { float s = 0.f;
; #pragma unroll
;             for (int j = 0; j < 4; ++j) s += ssq4(d[r][j]);
;             t[r] = s; }
; #pragma unroll
;         for (int r = 0; r < R; ++r) t[r] = wave_sum(t[r]) * (1.f / DM) + EPS;
	v_pk_mul_f32 v[96:97], v[128:129], v[96:97] op_sel_hi:[0,1]
	v_pk_mul_f32 v[98:99], v[128:129], v[98:99] op_sel_hi:[0,1]
	v_pk_mul_f32 v[100:101], v[128:129], v[100:101] op_sel_hi:[0,1]
	v_pk_mul_f32 v[102:103], v[128:129], v[102:103] op_sel_hi:[0,1]
	v_pk_mul_f32 v[104:105], v[128:129], v[104:105] op_sel_hi:[0,1]
	v_pk_mul_f32 v[106:107], v[128:129], v[106:107] op_sel_hi:[0,1]
	v_pk_mul_f32 v[108:109], v[128:129], v[108:109] op_sel_hi:[0,1]
	v_pk_mul_f32 v[110:111], v[128:129], v[110:111] op_sel_hi:[0,1]
	v_pk_mul_f32 v[96:97], v[96:97], v[192:193]
	v_pk_mul_f32 v[98:99], v[98:99], v[194:195]
	v_pk_mul_f32 v[100:101], v[100:101], v[196:197]
	v_pk_mul_f32 v[102:103], v[102:103], v[198:199]
	v_pk_mul_f32 v[104:105], v[104:105], v[200:201]
	v_pk_mul_f32 v[106:107], v[106:107], v[202:203]
	v_pk_mul_f32 v[108:109], v[108:109], v[204:205]
	v_pk_mul_f32 v[110:111], v[110:111], v[206:207]
	v_lshlrev_b32_e32 v56, 16, v72
	v_and_b32_e32 v57, 0xffff0000, v72
	v_lshlrev_b32_e32 v58, 16, v73
	v_and_b32_e32 v59, 0xffff0000, v73
	v_lshlrev_b32_e32 v60, 16, v74
	v_and_b32_e32 v61, 0xffff0000, v74
	v_lshlrev_b32_e32 v62, 16, v75
	v_and_b32_e32 v63, 0xffff0000, v75
	v_pk_fma_f32 v[96:97], v[88:89], v[56:57], v[96:97] op_sel_hi:[0,1,1]
	v_pk_fma_f32 v[98:99], v[88:89], v[58:59], v[98:99] op_sel_hi:[0,1,1]
	v_pk_fma_f32 v[100:101], v[88:89], v[60:61], v[100:101] op_sel_hi:[0,1,1]
	v_pk_fma_f32 v[102:103], v[88:89], v[62:63], v[102:103] op_sel_hi:[0,1,1]
	v_lshlrev_b32_e32 v56, 16, v76
	v_and_b32_e32 v57, 0xffff0000, v76
	v_lshlrev_b32_e32 v58, 16, v77
	v_and_b32_e32 v59, 0xffff0000, v77
	v_lshlrev_b32_e32 v60, 16, v78
	v_and_b32_e32 v61, 0xffff0000, v78
	v_lshlrev_b32_e32 v62, 16, v79
	v_and_b32_e32 v63, 0xffff0000, v79
	v_pk_fma_f32 v[104:105], v[88:89], v[56:57], v[104:105] op_sel_hi:[0,1,1]
	v_pk_fma_f32 v[106:107], v[88:89], v[58:59], v[106:107] op_sel_hi:[0,1,1]
	v_pk_fma_f32 v[108:109], v[88:89], v[60:61], v[108:109] op_sel_hi:[0,1,1]
	v_pk_fma_f32 v[110:111], v[88:89], v[62:63], v[110:111] op_sel_hi:[0,1,1]
	v_pk_mul_f32 v[132:133], v[96:97], v[96:97]
	v_pk_fma_f32 v[132:133], v[98:99], v[98:99], v[132:133]
	v_pk_fma_f32 v[132:133], v[100:101], v[100:101], v[132:133]
	v_pk_fma_f32 v[132:133], v[102:103], v[102:103], v[132:133]
	v_pk_fma_f32 v[132:133], v[104:105], v[104:105], v[132:133]
	v_pk_fma_f32 v[132:133], v[106:107], v[106:107], v[132:133]
	v_pk_fma_f32 v[132:133], v[108:109], v[108:109], v[132:133]
	v_pk_fma_f32 v[132:133], v[110:111], v[110:111], v[132:133]
	s_nop 0
	v_add_f32_e32 v132, v132, v133
	v_pk_mul_f32 v[112:113], v[130:131], v[112:113] op_sel_hi:[0,1]
	v_pk_mul_f32 v[114:115], v[130:131], v[114:115] op_sel_hi:[0,1]
	v_pk_mul_f32 v[116:117], v[130:131], v[116:117] op_sel_hi:[0,1]
	v_pk_mul_f32 v[118:119], v[130:131], v[118:119] op_sel_hi:[0,1]
	v_pk_mul_f32 v[120:121], v[130:131], v[120:121] op_sel_hi:[0,1]
	v_pk_mul_f32 v[122:123], v[130:131], v[122:123] op_sel_hi:[0,1]
	v_pk_mul_f32 v[124:125], v[130:131], v[124:125] op_sel_hi:[0,1]
	v_pk_mul_f32 v[126:127], v[130:131], v[126:127] op_sel_hi:[0,1]
	v_pk_mul_f32 v[112:113], v[112:113], v[192:193]
	v_pk_mul_f32 v[114:115], v[114:115], v[194:195]
	v_pk_mul_f32 v[116:117], v[116:117], v[196:197]
	v_pk_mul_f32 v[118:119], v[118:119], v[198:199]
	v_pk_mul_f32 v[120:121], v[120:121], v[200:201]
	v_pk_mul_f32 v[122:123], v[122:123], v[202:203]
	v_pk_mul_f32 v[124:125], v[124:125], v[204:205]
	v_pk_mul_f32 v[126:127], v[126:127], v[206:207]
	v_lshlrev_b32_e32 v64, 16, v80
	v_and_b32_e32 v65, 0xffff0000, v80
	v_lshlrev_b32_e32 v66, 16, v81
	v_and_b32_e32 v67, 0xffff0000, v81
	v_lshlrev_b32_e32 v68, 16, v82
	v_and_b32_e32 v69, 0xffff0000, v82
	v_lshlrev_b32_e32 v70, 16, v83
	v_and_b32_e32 v71, 0xffff0000, v83
	v_pk_fma_f32 v[112:113], v[90:91], v[64:65], v[112:113] op_sel_hi:[0,1,1]
	v_pk_fma_f32 v[114:115], v[90:91], v[66:67], v[114:115] op_sel_hi:[0,1,1]
	v_pk_fma_f32 v[116:117], v[90:91], v[68:69], v[116:117] op_sel_hi:[0,1,1]
	v_pk_fma_f32 v[118:119], v[90:91], v[70:71], v[118:119] op_sel_hi:[0,1,1]
	v_lshlrev_b32_e32 v64, 16, v84
	v_and_b32_e32 v65, 0xffff0000, v84
	v_lshlrev_b32_e32 v66, 16, v85
	v_and_b32_e32 v67, 0xffff0000, v85
	v_lshlrev_b32_e32 v68, 16, v86
	v_and_b32_e32 v69, 0xffff0000, v86
	v_lshlrev_b32_e32 v70, 16, v87
	v_and_b32_e32 v71, 0xffff0000, v87
	v_pk_fma_f32 v[120:121], v[90:91], v[64:65], v[120:121] op_sel_hi:[0,1,1]
	v_pk_fma_f32 v[122:123], v[90:91], v[66:67], v[122:123] op_sel_hi:[0,1,1]
	v_pk_fma_f32 v[124:125], v[90:91], v[68:69], v[124:125] op_sel_hi:[0,1,1]
	v_pk_fma_f32 v[126:127], v[90:91], v[70:71], v[126:127] op_sel_hi:[0,1,1]
	v_pk_mul_f32 v[134:135], v[112:113], v[112:113]
	v_pk_fma_f32 v[134:135], v[114:115], v[114:115], v[134:135]
	v_pk_fma_f32 v[134:135], v[116:117], v[116:117], v[134:135]
	v_pk_fma_f32 v[134:135], v[118:119], v[118:119], v[134:135]
	v_pk_fma_f32 v[134:135], v[120:121], v[120:121], v[134:135]
	v_pk_fma_f32 v[134:135], v[122:123], v[122:123], v[134:135]
	v_pk_fma_f32 v[134:135], v[124:125], v[124:125], v[134:135]
	v_pk_fma_f32 v[134:135], v[126:127], v[126:127], v[134:135]
	s_nop 0
	v_add_f32_e32 v134, v134, v135
	s_nop 1
	v_add_f32_dpp v132, v132, v132 quad_perm:[1,0,3,2] row_mask:0xf bank_mask:0xf
	v_add_f32_dpp v134, v134, v134 quad_perm:[1,0,3,2] row_mask:0xf bank_mask:0xf
	s_nop 0
	v_add_f32_dpp v132, v132, v132 quad_perm:[2,3,0,1] row_mask:0xf bank_mask:0xf
	v_add_f32_dpp v134, v134, v134 quad_perm:[2,3,0,1] row_mask:0xf bank_mask:0xf
	s_nop 0
	v_add_f32_dpp v132, v132, v132 row_half_mirror row_mask:0xf bank_mask:0xf
	v_add_f32_dpp v134, v134, v134 row_half_mirror row_mask:0xf bank_mask:0xf
	s_nop 0
	v_add_f32_dpp v132, v132, v132 row_mirror row_mask:0xf bank_mask:0xf
	v_add_f32_dpp v134, v134, v134 row_mirror row_mask:0xf bank_mask:0xf
	s_nop 0
	ds_bpermute_b32 v136, v187, v132
	ds_bpermute_b32 v137, v187, v134
	s_waitcnt lgkmcnt(0)
; __device__ __forceinline__ const float* xrow_ptr(const Ctx& C, int row) { return row < MPROMPT ? C.in(0) + (size_t)row * DM : C.in(1) + (size_t)(row - MPROMPT) * DM; }
; __device__ __forceinline__ v4f ld4_bf16(const bf16* p) { const v2u w = *(const v2u*)p; return (v4f){bf_lo(w.x), bf_hi(w.x), bf_lo(w.y), bf_hi(w.y)}; }
; __device__ __forceinline__ void st4_bf16(bf16* p, v4f o) { v2u w; w.x = cvt_pk_nv(o.x, o.y); w.y = cvt_pk_nv(o.z, o.w); *(v2u*)p = w; }
; __device__ __forceinline__ float ssq4(v4f v) { return (v.x * v.x + v.y * v.y) + (v.z * v.z + v.w * v.w); }
; template <int R, bool BASE_F32, bool OUT_F32>
; __device__ __forceinline__ void rows_res(const Ctx& C, int m0, int stride, int mx, const float* gpost, float scale, int lane) {
;     ...
;     for (int r = 0; r < R; ++r) { mr[r] = (r == 4) ? mx : m0 + r * stride; ok[r] = (r == 4) ? (mx < M) : (mr[r] < MPROMPT); const int mm = ok[r] ? mr[r] : 0;
; #pragma unroll
;         for (int j = 0; j < 4; ++j) d[r][j] = ld4_bf16(D + (size_t)mm * DM + 4 * lane + 256 * j);
;         if (BASE_F32) { const float* x = xrow_ptr(C, mm);
; #pragma unroll
;             for (int j = 0; j < 4; ++j) b[r][j] = ld4_f32(x + 4 * lane + 256 * j);
;         } else { const float inv = C.RS()[mm];
; #pragma unroll
;             for (int j = 0; j < 4; ++j) b[r][j] = ld4_bf16(XN + (size_t)mm * DM + 4 * lane + 256 * j) * inv;
;         } }
; #pragma unroll
;     for (int r = 0; r < R; ++r) { float s = 0.f;
; #pragma unroll
;         for (int j = 0; j < 4; ++j) s += ssq4(d[r][j]);
;         r1[r] = s; }
;     ...
;         for (int r = 0; r < R; ++r) t[r] = wave_sum(t[r]) * (1.f / DM) + EPS;
; #pragma unroll
;         for (int r = 0; r < R; ++r) { const float rstd = rsqrtf(t[r]);
; #pragma unroll
;             for (int j = 0; j < 4; ++j) if (ok[r]) st4_bf16(XN + (size_t)mr[r] * DM + 4 * lane + 256 * j, d[r][j] * rstd);
;             if (lane == 0 && ok[r]) rs[mr[r]] = sqrtf(t[r]); }
	v_add_f32_e32 v132, v132, v136
	v_add_f32_e32 v134, v134, v137
	ds_bpermute_b32 v136, v188, v132
	ds_bpermute_b32 v137, v188, v134
	s_waitcnt lgkmcnt(0)
	v_add_f32_e32 v132, v132, v136
	v_add_f32_e32 v134, v134, v137
	v_fmamk_f32 v164, v132, 0x3a800000, v138
	v_fmamk_f32 v167, v134, 0x3a800000, v138
	s_nop 0
	v_rsq_f32_e32 v132, v164
	v_rsq_f32_e32 v134, v167
	v_sqrt_f32_e32 v165, v164
	v_sqrt_f32_e32 v168, v167
	s_nop 1
	v_pk_mul_f32 v[140:141], v[96:97], v[132:133] op_sel_hi:[1,0]
	v_cvt_pk_bf16_f32 v148, v140, v141
	v_pk_mul_f32 v[142:143], v[98:99], v[132:133] op_sel_hi:[1,0]
	v_cvt_pk_bf16_f32 v149, v142, v143
	v_pk_mul_f32 v[144:145], v[100:101], v[132:133] op_sel_hi:[1,0]
	v_cvt_pk_bf16_f32 v150, v144, v145
	v_pk_mul_f32 v[146:147], v[102:103], v[132:133] op_sel_hi:[1,0]
	v_cvt_pk_bf16_f32 v151, v146, v147
	v_pk_mul_f32 v[140:141], v[104:105], v[132:133] op_sel_hi:[1,0]
	v_cvt_pk_bf16_f32 v152, v140, v141
	v_pk_mul_f32 v[142:143], v[106:107], v[132:133] op_sel_hi:[1,0]
	v_cvt_pk_bf16_f32 v153, v142, v143
	v_pk_mul_f32 v[144:145], v[108:109], v[132:133] op_sel_hi:[1,0]
	v_cvt_pk_bf16_f32 v154, v144, v145
	v_pk_mul_f32 v[146:147], v[110:111], v[132:133] op_sel_hi:[1,0]
	v_cvt_pk_bf16_f32 v155, v146, v147
	global_store_dwordx2 v173, v[148:149], s[98:99]
	global_store_dwordx2 v173, v[150:151], s[98:99] offset:512
	global_store_dwordx2 v173, v[152:153], s[98:99] offset:1024
	global_store_dwordx2 v173, v[154:155], s[98:99] offset:1536
	v_add_u32_e32 v173, 0x400000, v173
	v_pk_mul_f32 v[140:141], v[112:113], v[134:135] op_sel_hi:[1,0]
	v_cvt_pk_bf16_f32 v156, v140, v141
	v_pk_mul_f32 v[142:143], v[114:115], v[134:135] op_sel_hi:[1,0]
	v_cvt_pk_bf16_f32 v157, v142, v143
	v_pk_mul_f32 v[144:145], v[116:117], v[134:135] op_sel_hi:[1,0]
	v_cvt_pk_bf16_f32 v158, v144, v145
	v_pk_mul_f32 v[146:147], v[118:119], v[134:135] op_sel_hi:[1,0]
	v_cvt_pk_bf16_f32 v159, v146, v147
	v_pk_mul_f32 v[140:141], v[120:121], v[134:135] op_sel_hi:[1,0]
	v_cvt_pk_bf16_f32 v160, v140, v141
	v_pk_mul_f32 v[142:143], v[122:123], v[134:135] op_sel_hi:[1,0]
	v_cvt_pk_bf16_f32 v161, v142, v143
	v_pk_mul_f32 v[144:145], v[124:125], v[134:135] op_sel_hi:[1,0]
	v_cvt_pk_bf16_f32 v162, v144, v145
	v_pk_mul_f32 v[146:147], v[126:127], v[134:135] op_sel_hi:[1,0]
	v_cvt_pk_bf16_f32 v163, v146, v147
	global_store_dwordx2 v173, v[156:157], s[98:99]
	global_store_dwordx2 v173, v[158:159], s[98:99] offset:512
	global_store_dwordx2 v173, v[160:161], s[98:99] offset:1024
	global_store_dwordx2 v173, v[162:163], s[98:99] offset:1536
	v_add_u32_e32 v173, 0x400000, v173
	v_add_u32_e32 v166, -1, v165
	v_fma_f32 v140, -v166, v165, v164
	v_cmp_ge_f32_e32 vcc, 0, v140
	v_add_u32_e32 v141, 1, v165
	v_cndmask_b32_e32 v166, v165, v166, vcc
	v_fma_f32 v140, -v141, v165, v164
	v_cmp_lt_f32_e32 vcc, 0, v140
	s_nop 1
	v_cndmask_b32_e32 v165, v166, v141, vcc
	v_add_u32_e32 v169, -1, v168
	v_fma_f32 v142, -v169, v168, v167
	v_cmp_ge_f32_e32 vcc, 0, v142
	v_add_u32_e32 v143, 1, v168
	v_cndmask_b32_e32 v169, v168, v169, vcc
	v_fma_f32 v142, -v143, v168, v167
	v_cmp_lt_f32_e32 vcc, 0, v142
	s_nop 1
	v_cndmask_b32_e32 v168, v169, v143, vcc
	s_mov_b64 exec, 1
	global_store_dword v174, v165, s[98:99]
	v_add_u32_e32 v174, 0x2000, v174
	global_store_dword v174, v168, s[98:99]
	v_add_u32_e32 v174, 0x2000, v174
	s_mov_b64 exec, -1
	global_load_dword v88, v172, s[98:99]
	global_load_dwordx2 v[56:57], v170, s[98:99]
	global_load_dwordx2 v[58:59], v170, s[98:99] offset:512
	global_load_dwordx2 v[60:61], v170, s[98:99] offset:1024
	global_load_dwordx2 v[62:63], v170, s[98:99] offset:1536
	global_load_dwordx2 v[72:73], v171, s[98:99]
	global_load_dwordx2 v[74:75], v171, s[98:99] offset:512
	global_load_dwordx2 v[76:77], v171, s[98:99] offset:1024
	global_load_dwordx2 v[78:79], v171, s[98:99] offset:1536
	v_add_u32_e32 v170, 0x400000, v170
	v_add_u32_e32 v171, 0x400000, v171
	v_add_u32_e32 v172, 0x2000, v172
	global_load_dword v90, v172, s[98:99]
	global_load_dwordx2 v[64:65], v170, s[98:99]
	global_load_dwordx2 v[66:67], v170, s[98:99] offset:512
	global_load_dwordx2 v[68:69], v170, s[98:99] offset:1024
	global_load_dwordx2 v[70:71], v170, s[98:99] offset:1536
	global_load_dwordx2 v[80:81], v171, s[98:99]
	global_load_dwordx2 v[82:83], v171, s[98:99] offset:512
	global_load_dwordx2 v[84:85], v171, s[98:99] offset:1024
	global_load_dwordx2 v[86:87], v171, s[98:99] offset:1536
	v_add_u32_e32 v170, 0x400000, v170
	v_add_u32_e32 v171, 0x400000, v171
	v_add_u32_e32 v172, 0x2000, v172
	s_waitcnt vmcnt(41)
	v_lshlrev_b32_e32 v96, 16, v20
	v_and_b32_e32 v97, 0xffff0000, v20
	v_lshlrev_b32_e32 v98, 16, v21
	v_and_b32_e32 v99, 0xffff0000, v21
	v_lshlrev_b32_e32 v100, 16, v22
	v_and_b32_e32 v101, 0xffff0000, v22
	v_lshlrev_b32_e32 v102, 16, v23
	v_and_b32_e32 v103, 0xffff0000, v23
	v_lshlrev_b32_e32 v104, 16, v24
	v_and_b32_e32 v105, 0xffff0000, v24
	v_lshlrev_b32_e32 v106, 16, v25
	v_and_b32_e32 v107, 0xffff0000, v25
	v_lshlrev_b32_e32 v108, 16, v26
	v_and_b32_e32 v109, 0xffff0000, v26
	v_lshlrev_b32_e32 v110, 16, v27
	v_and_b32_e32 v111, 0xffff0000, v27
	v_pk_mul_f32 v[128:129], v[96:97], v[96:97]
	v_pk_fma_f32 v[128:129], v[98:99], v[98:99], v[128:129]
	v_pk_fma_f32 v[128:129], v[100:101], v[100:101], v[128:129]
	v_pk_fma_f32 v[128:129], v[102:103], v[102:103], v[128:129]
	v_pk_fma_f32 v[128:129], v[104:105], v[104:105], v[128:129]
	v_pk_fma_f32 v[128:129], v[106:107], v[106:107], v[128:129]
	v_pk_fma_f32 v[128:129], v[108:109], v[108:109], v[128:129]
	v_pk_fma_f32 v[128:129], v[110:111], v[110:111], v[128:129]
	s_nop 0
	v_add_f32_e32 v128, v128, v129
	s_waitcnt vmcnt(32)
;     __device__ __forceinline__ float* out() const { return (float*)karg_in(33); }
; __device__ __forceinline__ float ssq4(v4f v) { return (v.x * v.x + v.y * v.y) + (v.z * v.z + v.w * v.w); }
; template <int R, bool BASE_F32, bool OUT_F32>
; __device__ __forceinline__ void rows_res(const Ctx& C, int m0, int stride, int mx, const float* gpost, float scale, int lane) {
;     ...
;     for (int r = 0; r < R; ++r) { float s = 0.f;
; #pragma unroll
;         for (int j = 0; j < 4; ++j) s += ssq4(d[r][j]);
;         r1[r] = s; }
; #pragma unroll
;     for (int r = 0; r < R; ++r) r1[r] = rsqrtf(wave_sum(r1[r]) * (1.f / DM) + EPS) * scale;
; #pragma unroll
;     for (int j = 0; j < 4; ++j) { const v4f gp = ld4_f32(gpost + 4 * lane + 256 * j);
; #pragma unroll
;         for (int r = 0; r < R; ++r) d[r][j] = b[r][j] + d[r][j] * r1[r] * gp; }
;     if (OUT_F32) { float* Y = C.out();
; #pragma unroll
;         for (int r = 0; r < R; ++r)
; #pragma unroll
;             for (int j = 0; j < 4; ++j) if (ok[r]) *(v4f*)(Y + (size_t)mr[r] * DM + 4 * lane + 256 * j) = d[r][j];
;     } else { float* rs = C.RS(); float t[R];
; #pragma unroll
;         for (int r = 0; r < R; ++r) { float s = 0.f;
; #pragma unroll
;             for (int j = 0; j < 4; ++j) s += ssq4(d[r][j]);
;             t[r] = s; }
	v_lshlrev_b32_e32 v112, 16, v28
	v_and_b32_e32 v113, 0xffff0000, v28
	v_lshlrev_b32_e32 v114, 16, v29
	v_and_b32_e32 v115, 0xffff0000, v29
	v_lshlrev_b32_e32 v116, 16, v30
	v_and_b32_e32 v117, 0xffff0000, v30
	v_lshlrev_b32_e32 v118, 16, v31
	v_and_b32_e32 v119, 0xffff0000, v31
	v_lshlrev_b32_e32 v120, 16, v32
	v_and_b32_e32 v121, 0xffff0000, v32
	v_lshlrev_b32_e32 v122, 16, v33
	v_and_b32_e32 v123, 0xffff0000, v33
	v_lshlrev_b32_e32 v124, 16, v34
	v_and_b32_e32 v125, 0xffff0000, v34
	v_lshlrev_b32_e32 v126, 16, v35
	v_and_b32_e32 v127, 0xffff0000, v35
	v_pk_mul_f32 v[130:131], v[112:113], v[112:113]
	v_pk_fma_f32 v[130:131], v[114:115], v[114:115], v[130:131]
	v_pk_fma_f32 v[130:131], v[116:117], v[116:117], v[130:131]
	v_pk_fma_f32 v[130:131], v[118:119], v[118:119], v[130:131]
	v_pk_fma_f32 v[130:131], v[120:121], v[120:121], v[130:131]
	v_pk_fma_f32 v[130:131], v[122:123], v[122:123], v[130:131]
	v_pk_fma_f32 v[130:131], v[124:125], v[124:125], v[130:131]
	v_pk_fma_f32 v[130:131], v[126:127], v[126:127], v[130:131]
	s_nop 0
	v_add_f32_e32 v130, v130, v131
	s_nop 1
	v_add_f32_dpp v128, v128, v128 quad_perm:[1,0,3,2] row_mask:0xf bank_mask:0xf
	v_add_f32_dpp v130, v130, v130 quad_perm:[1,0,3,2] row_mask:0xf bank_mask:0xf
	s_nop 0
	v_add_f32_dpp v128, v128, v128 quad_perm:[2,3,0,1] row_mask:0xf bank_mask:0xf
	v_add_f32_dpp v130, v130, v130 quad_perm:[2,3,0,1] row_mask:0xf bank_mask:0xf
	s_nop 0
	v_add_f32_dpp v128, v128, v128 row_half_mirror row_mask:0xf bank_mask:0xf
	v_add_f32_dpp v130, v130, v130 row_half_mirror row_mask:0xf bank_mask:0xf
	s_nop 0
	v_add_f32_dpp v128, v128, v128 row_mirror row_mask:0xf bank_mask:0xf
	v_add_f32_dpp v130, v130, v130 row_mirror row_mask:0xf bank_mask:0xf
	s_nop 0
	ds_bpermute_b32 v136, v187, v128
	ds_bpermute_b32 v137, v187, v130
	s_waitcnt lgkmcnt(0)
	v_add_f32_e32 v128, v128, v136
	v_add_f32_e32 v130, v130, v137
	ds_bpermute_b32 v136, v188, v128
	ds_bpermute_b32 v137, v188, v130
	s_waitcnt lgkmcnt(0)
	v_add_f32_e32 v128, v128, v136
	v_add_f32_e32 v130, v130, v137
	v_fmamk_f32 v128, v128, 0x3a800000, v138
	v_fmamk_f32 v130, v130, 0x3a800000, v138
	s_nop 0
	v_rsq_f32_e32 v128, v128
	v_rsq_f32_e32 v130, v130
	s_nop 1
	s_waitcnt vmcnt(28)
	v_pk_mul_f32 v[96:97], v[128:129], v[96:97] op_sel_hi:[0,1]
	v_pk_mul_f32 v[98:99], v[128:129], v[98:99] op_sel_hi:[0,1]
	v_pk_mul_f32 v[100:101], v[128:129], v[100:101] op_sel_hi:[0,1]
	v_pk_mul_f32 v[102:103], v[128:129], v[102:103] op_sel_hi:[0,1]
	v_pk_mul_f32 v[104:105], v[128:129], v[104:105] op_sel_hi:[0,1]
	v_pk_mul_f32 v[106:107], v[128:129], v[106:107] op_sel_hi:[0,1]
	v_pk_mul_f32 v[108:109], v[128:129], v[108:109] op_sel_hi:[0,1]
	v_pk_mul_f32 v[110:111], v[128:129], v[110:111] op_sel_hi:[0,1]
	v_pk_mul_f32 v[96:97], v[96:97], v[192:193]
	v_pk_mul_f32 v[98:99], v[98:99], v[194:195]
	v_pk_mul_f32 v[100:101], v[100:101], v[196:197]
	v_pk_mul_f32 v[102:103], v[102:103], v[198:199]
	v_pk_mul_f32 v[104:105], v[104:105], v[200:201]
	v_pk_mul_f32 v[106:107], v[106:107], v[202:203]
	v_pk_mul_f32 v[108:109], v[108:109], v[204:205]
	v_pk_mul_f32 v[110:111], v[110:111], v[206:207]
	v_lshlrev_b32_e32 v20, 16, v36
	v_and_b32_e32 v21, 0xffff0000, v36
	v_lshlrev_b32_e32 v22, 16, v37
	v_and_b32_e32 v23, 0xffff0000, v37
	v_lshlrev_b32_e32 v24, 16, v38
	v_and_b32_e32 v25, 0xffff0000, v38
	v_lshlrev_b32_e32 v26, 16, v39
	v_and_b32_e32 v27, 0xffff0000, v39
	v_pk_fma_f32 v[96:97], v[52:53], v[20:21], v[96:97] op_sel_hi:[0,1,1]
	v_pk_fma_f32 v[98:99], v[52:53], v[22:23], v[98:99] op_sel_hi:[0,1,1]
	v_pk_fma_f32 v[100:101], v[52:53], v[24:25], v[100:101] op_sel_hi:[0,1,1]
	v_pk_fma_f32 v[102:103], v[52:53], v[26:27], v[102:103] op_sel_hi:[0,1,1]
	v_lshlrev_b32_e32 v20, 16, v40
	v_and_b32_e32 v21, 0xffff0000, v40
	v_lshlrev_b32_e32 v22, 16, v41
	v_and_b32_e32 v23, 0xffff0000, v41
	v_lshlrev_b32_e32 v24, 16, v42
	v_and_b32_e32 v25, 0xffff0000, v42
	v_lshlrev_b32_e32 v26, 16, v43
	v_and_b32_e32 v27, 0xffff0000, v43
	v_pk_fma_f32 v[104:105], v[52:53], v[20:21], v[104:105] op_sel_hi:[0,1,1]
	v_pk_fma_f32 v[106:107], v[52:53], v[22:23], v[106:107] op_sel_hi:[0,1,1]
	v_pk_fma_f32 v[108:109], v[52:53], v[24:25], v[108:109] op_sel_hi:[0,1,1]
	v_pk_fma_f32 v[110:111], v[52:53], v[26:27], v[110:111] op_sel_hi:[0,1,1]
	v_pk_mul_f32 v[132:133], v[96:97], v[96:97]
	v_pk_fma_f32 v[132:133], v[98:99], v[98:99], v[132:133]
	v_pk_fma_f32 v[132:133], v[100:101], v[100:101], v[132:133]
	v_pk_fma_f32 v[132:133], v[102:103], v[102:103], v[132:133]
	v_pk_fma_f32 v[132:133], v[104:105], v[104:105], v[132:133]
	v_pk_fma_f32 v[132:133], v[106:107], v[106:107], v[132:133]
	v_pk_fma_f32 v[132:133], v[108:109], v[108:109], v[132:133]
	v_pk_fma_f32 v[132:133], v[110:111], v[110:111], v[132:133]
	s_nop 0
	v_add_f32_e32 v132, v132, v133
	v_pk_mul_f32 v[112:113], v[130:131], v[112:113] op_sel_hi:[0,1]
	v_pk_mul_f32 v[114:115], v[130:131], v[114:115] op_sel_hi:[0,1]
	v_pk_mul_f32 v[116:117], v[130:131], v[116:117] op_sel_hi:[0,1]
	v_pk_mul_f32 v[118:119], v[130:131], v[118:119] op_sel_hi:[0,1]
	v_pk_mul_f32 v[120:121], v[130:131], v[120:121] op_sel_hi:[0,1]
	v_pk_mul_f32 v[122:123], v[130:131], v[122:123] op_sel_hi:[0,1]
	v_pk_mul_f32 v[124:125], v[130:131], v[124:125] op_sel_hi:[0,1]
	v_pk_mul_f32 v[126:127], v[130:131], v[126:127] op_sel_hi:[0,1]
	v_pk_mul_f32 v[112:113], v[112:113], v[192:193]
	v_pk_mul_f32 v[114:115], v[114:115], v[194:195]
	v_pk_mul_f32 v[116:117], v[116:117], v[196:197]
	v_pk_mul_f32 v[118:119], v[118:119], v[198:199]
	v_pk_mul_f32 v[120:121], v[120:121], v[200:201]
	v_pk_mul_f32 v[122:123], v[122:123], v[202:203]
	v_pk_mul_f32 v[124:125], v[124:125], v[204:205]
	v_pk_mul_f32 v[126:127], v[126:127], v[206:207]
;     __device__ __forceinline__ float* out() const { return (float*)karg_in(33); }
; __device__ __forceinline__ void st4_bf16(bf16* p, v4f o) { v2u w; w.x = cvt_pk_nv(o.x, o.y); w.y = cvt_pk_nv(o.z, o.w); *(v2u*)p = w; }
; __device__ __forceinline__ float ssq4(v4f v) { return (v.x * v.x + v.y * v.y) + (v.z * v.z + v.w * v.w); }
; template <int R, bool BASE_F32, bool OUT_F32>
; __device__ __forceinline__ void rows_res(const Ctx& C, int m0, int stride, int mx, const float* gpost, float scale, int lane) {
;     ...
;     for (int j = 0; j < 4; ++j) { const v4f gp = ld4_f32(gpost + 4 * lane + 256 * j);
; #pragma unroll
;         for (int r = 0; r < R; ++r) d[r][j] = b[r][j] + d[r][j] * r1[r] * gp; }
;     if (OUT_F32) { float* Y = C.out();
; #pragma unroll
;         for (int r = 0; r < R; ++r)
; #pragma unroll
;             for (int j = 0; j < 4; ++j) if (ok[r]) *(v4f*)(Y + (size_t)mr[r] * DM + 4 * lane + 256 * j) = d[r][j];
;     } else { float* rs = C.RS(); float t[R];
; #pragma unroll
;         for (int r = 0; r < R; ++r) { float s = 0.f;
; #pragma unroll
;             for (int j = 0; j < 4; ++j) s += ssq4(d[r][j]);
;             t[r] = s; }
; #pragma unroll
;         for (int r = 0; r < R; ++r) t[r] = wave_sum(t[r]) * (1.f / DM) + EPS;
; #pragma unroll
;         for (int r = 0; r < R; ++r) { const float rstd = rsqrtf(t[r]);
; #pragma unroll
;             for (int j = 0; j < 4; ++j) if (ok[r]) st4_bf16(XN + (size_t)mr[r] * DM + 4 * lane + 256 * j, d[r][j] * rstd);
;             if (lane == 0 && ok[r]) rs[mr[r]] = sqrtf(t[r]); }
	v_lshlrev_b32_e32 v28, 16, v44
	v_and_b32_e32 v29, 0xffff0000, v44
	v_lshlrev_b32_e32 v30, 16, v45
	v_and_b32_e32 v31, 0xffff0000, v45
	v_lshlrev_b32_e32 v32, 16, v46
	v_and_b32_e32 v33, 0xffff0000, v46
	v_lshlrev_b32_e32 v34, 16, v47
	v_and_b32_e32 v35, 0xffff0000, v47
	v_pk_fma_f32 v[112:113], v[54:55], v[28:29], v[112:113] op_sel_hi:[0,1,1]
	v_pk_fma_f32 v[114:115], v[54:55], v[30:31], v[114:115] op_sel_hi:[0,1,1]
	v_pk_fma_f32 v[116:117], v[54:55], v[32:33], v[116:117] op_sel_hi:[0,1,1]
	v_pk_fma_f32 v[118:119], v[54:55], v[34:35], v[118:119] op_sel_hi:[0,1,1]
	v_lshlrev_b32_e32 v28, 16, v48
	v_and_b32_e32 v29, 0xffff0000, v48
	v_lshlrev_b32_e32 v30, 16, v49
	v_and_b32_e32 v31, 0xffff0000, v49
	v_lshlrev_b32_e32 v32, 16, v50
	v_and_b32_e32 v33, 0xffff0000, v50
	v_lshlrev_b32_e32 v34, 16, v51
	v_and_b32_e32 v35, 0xffff0000, v51
	v_pk_fma_f32 v[120:121], v[54:55], v[28:29], v[120:121] op_sel_hi:[0,1,1]
	v_pk_fma_f32 v[122:123], v[54:55], v[30:31], v[122:123] op_sel_hi:[0,1,1]
	v_pk_fma_f32 v[124:125], v[54:55], v[32:33], v[124:125] op_sel_hi:[0,1,1]
	v_pk_fma_f32 v[126:127], v[54:55], v[34:35], v[126:127] op_sel_hi:[0,1,1]
	v_pk_mul_f32 v[134:135], v[112:113], v[112:113]
	v_pk_fma_f32 v[134:135], v[114:115], v[114:115], v[134:135]
	v_pk_fma_f32 v[134:135], v[116:117], v[116:117], v[134:135]
	v_pk_fma_f32 v[134:135], v[118:119], v[118:119], v[134:135]
	v_pk_fma_f32 v[134:135], v[120:121], v[120:121], v[134:135]
	v_pk_fma_f32 v[134:135], v[122:123], v[122:123], v[134:135]
	v_pk_fma_f32 v[134:135], v[124:125], v[124:125], v[134:135]
	v_pk_fma_f32 v[134:135], v[126:127], v[126:127], v[134:135]
	s_nop 0
	v_add_f32_e32 v134, v134, v135
	s_nop 1
	v_add_f32_dpp v132, v132, v132 quad_perm:[1,0,3,2] row_mask:0xf bank_mask:0xf
	v_add_f32_dpp v134, v134, v134 quad_perm:[1,0,3,2] row_mask:0xf bank_mask:0xf
	s_nop 0
	v_add_f32_dpp v132, v132, v132 quad_perm:[2,3,0,1] row_mask:0xf bank_mask:0xf
	v_add_f32_dpp v134, v134, v134 quad_perm:[2,3,0,1] row_mask:0xf bank_mask:0xf
	s_nop 0
	v_add_f32_dpp v132, v132, v132 row_half_mirror row_mask:0xf bank_mask:0xf
	v_add_f32_dpp v134, v134, v134 row_half_mirror row_mask:0xf bank_mask:0xf
	s_nop 0
	v_add_f32_dpp v132, v132, v132 row_mirror row_mask:0xf bank_mask:0xf
	v_add_f32_dpp v134, v134, v134 row_mirror row_mask:0xf bank_mask:0xf
	s_nop 0
	ds_bpermute_b32 v136, v187, v132
	ds_bpermute_b32 v137, v187, v134
	s_waitcnt lgkmcnt(0)
	v_add_f32_e32 v132, v132, v136
	v_add_f32_e32 v134, v134, v137
	ds_bpermute_b32 v136, v188, v132
	ds_bpermute_b32 v137, v188, v134
	s_waitcnt lgkmcnt(0)
	v_add_f32_e32 v132, v132, v136
	v_add_f32_e32 v134, v134, v137
	v_fmamk_f32 v164, v132, 0x3a800000, v138
	v_fmamk_f32 v167, v134, 0x3a800000, v138
	s_nop 0
	v_rsq_f32_e32 v132, v164
	v_rsq_f32_e32 v134, v167
	v_sqrt_f32_e32 v165, v164
	v_sqrt_f32_e32 v168, v167
	s_nop 1
	v_pk_mul_f32 v[140:141], v[96:97], v[132:133] op_sel_hi:[1,0]
	v_cvt_pk_bf16_f32 v148, v140, v141
	v_pk_mul_f32 v[142:143], v[98:99], v[132:133] op_sel_hi:[1,0]
	v_cvt_pk_bf16_f32 v149, v142, v143
	v_pk_mul_f32 v[144:145], v[100:101], v[132:133] op_sel_hi:[1,0]
	v_cvt_pk_bf16_f32 v150, v144, v145
	v_pk_mul_f32 v[146:147], v[102:103], v[132:133] op_sel_hi:[1,0]
	v_cvt_pk_bf16_f32 v151, v146, v147
	v_pk_mul_f32 v[140:141], v[104:105], v[132:133] op_sel_hi:[1,0]
	v_cvt_pk_bf16_f32 v152, v140, v141
	v_pk_mul_f32 v[142:143], v[106:107], v[132:133] op_sel_hi:[1,0]
	v_cvt_pk_bf16_f32 v153, v142, v143
	v_pk_mul_f32 v[144:145], v[108:109], v[132:133] op_sel_hi:[1,0]
	v_cvt_pk_bf16_f32 v154, v144, v145
	v_pk_mul_f32 v[146:147], v[110:111], v[132:133] op_sel_hi:[1,0]
	v_cvt_pk_bf16_f32 v155, v146, v147
	global_store_dwordx2 v173, v[148:149], s[98:99]
	global_store_dwordx2 v173, v[150:151], s[98:99] offset:512
	global_store_dwordx2 v173, v[152:153], s[98:99] offset:1024
	global_store_dwordx2 v173, v[154:155], s[98:99] offset:1536
	v_add_u32_e32 v173, 0x400000, v173
	v_pk_mul_f32 v[140:141], v[112:113], v[134:135] op_sel_hi:[1,0]
	v_cvt_pk_bf16_f32 v156, v140, v141
	v_pk_mul_f32 v[142:143], v[114:115], v[134:135] op_sel_hi:[1,0]
	v_cvt_pk_bf16_f32 v157, v142, v143
	v_pk_mul_f32 v[144:145], v[116:117], v[134:135] op_sel_hi:[1,0]
	v_cvt_pk_bf16_f32 v158, v144, v145
	v_pk_mul_f32 v[146:147], v[118:119], v[134:135] op_sel_hi:[1,0]
	v_cvt_pk_bf16_f32 v159, v146, v147
	v_pk_mul_f32 v[140:141], v[120:121], v[134:135] op_sel_hi:[1,0]
	v_cvt_pk_bf16_f32 v160, v140, v141
	v_pk_mul_f32 v[142:143], v[122:123], v[134:135] op_sel_hi:[1,0]
	v_cvt_pk_bf16_f32 v161, v142, v143
	v_pk_mul_f32 v[144:145], v[124:125], v[134:135] op_sel_hi:[1,0]
	v_cvt_pk_bf16_f32 v162, v144, v145
	v_pk_mul_f32 v[146:147], v[126:127], v[134:135] op_sel_hi:[1,0]
	v_cvt_pk_bf16_f32 v163, v146, v147
	global_store_dwordx2 v173, v[156:157], s[98:99]
	global_store_dwordx2 v173, v[158:159], s[98:99] offset:512
	global_store_dwordx2 v173, v[160:161], s[98:99] offset:1024
	global_store_dwordx2 v173, v[162:163], s[98:99] offset:1536
	v_add_u32_e32 v173, 0x400000, v173
	v_add_u32_e32 v166, -1, v165
	v_fma_f32 v140, -v166, v165, v164
	v_cmp_ge_f32_e32 vcc, 0, v140
	v_add_u32_e32 v141, 1, v165
	v_cndmask_b32_e32 v166, v165, v166, vcc
	v_fma_f32 v140, -v141, v165, v164
	v_cmp_lt_f32_e32 vcc, 0, v140
	s_nop 1
	v_cndmask_b32_e32 v165, v166, v141, vcc
	v_add_u32_e32 v169, -1, v168
	v_fma_f32 v142, -v169, v168, v167
	v_cmp_ge_f32_e32 vcc, 0, v142
	v_add_u32_e32 v143, 1, v168
	v_cndmask_b32_e32 v169, v168, v169, vcc
	v_fma_f32 v142, -v143, v168, v167
	v_cmp_lt_f32_e32 vcc, 0, v142
	s_nop 1
	v_cndmask_b32_e32 v168, v169, v143, vcc
	s_mov_b64 exec, 1
	global_store_dword v174, v165, s[98:99]
	v_add_u32_e32 v174, 0x2000, v174
	global_store_dword v174, v168, s[98:99]
	v_add_u32_e32 v174, 0x2000, v174
	s_mov_b64 exec, -1
	s_waitcnt vmcnt(23)
;     __device__ __forceinline__ float* out() const { return (float*)karg_in(33); }
; __device__ __forceinline__ float ssq4(v4f v) { return (v.x * v.x + v.y * v.y) + (v.z * v.z + v.w * v.w); }
; template <int R, bool BASE_F32, bool OUT_F32>
; __device__ __forceinline__ void rows_res(const Ctx& C, int m0, int stride, int mx, const float* gpost, float scale, int lane) {
;     ...
;     for (int r = 0; r < R; ++r) { float s = 0.f;
; #pragma unroll
;         for (int j = 0; j < 4; ++j) s += ssq4(d[r][j]);
;         r1[r] = s; }
; #pragma unroll
;     for (int r = 0; r < R; ++r) r1[r] = rsqrtf(wave_sum(r1[r]) * (1.f / DM) + EPS) * scale;
; #pragma unroll
;     for (int j = 0; j < 4; ++j) { const v4f gp = ld4_f32(gpost + 4 * lane + 256 * j);
; #pragma unroll
;         for (int r = 0; r < R; ++r) d[r][j] = b[r][j] + d[r][j] * r1[r] * gp; }
;     if (OUT_F32) { float* Y = C.out();
; #pragma unroll
;         for (int r = 0; r < R; ++r)
; #pragma unroll
;             for (int j = 0; j < 4; ++j) if (ok[r]) *(v4f*)(Y + (size_t)mr[r] * DM + 4 * lane + 256 * j) = d[r][j];
;     } else { float* rs = C.RS(); float t[R];
; #pragma unroll
;         for (int r = 0; r < R; ++r) { float s = 0.f;
; #pragma unroll
;             for (int j = 0; j < 4; ++j) s += ssq4(d[r][j]);
;             t[r] = s; }
	v_lshlrev_b32_e32 v96, 16, v56
	v_and_b32_e32 v97, 0xffff0000, v56
	v_lshlrev_b32_e32 v98, 16, v57
	v_and_b32_e32 v99, 0xffff0000, v57
	v_lshlrev_b32_e32 v100, 16, v58
	v_and_b32_e32 v101, 0xffff0000, v58
	v_lshlrev_b32_e32 v102, 16, v59
	v_and_b32_e32 v103, 0xffff0000, v59
	v_lshlrev_b32_e32 v104, 16, v60
	v_and_b32_e32 v105, 0xffff0000, v60
	v_lshlrev_b32_e32 v106, 16, v61
	v_and_b32_e32 v107, 0xffff0000, v61
	v_lshlrev_b32_e32 v108, 16, v62
	v_and_b32_e32 v109, 0xffff0000, v62
	v_lshlrev_b32_e32 v110, 16, v63
	v_and_b32_e32 v111, 0xffff0000, v63
	v_pk_mul_f32 v[128:129], v[96:97], v[96:97]
	v_pk_fma_f32 v[128:129], v[98:99], v[98:99], v[128:129]
	v_pk_fma_f32 v[128:129], v[100:101], v[100:101], v[128:129]
	v_pk_fma_f32 v[128:129], v[102:103], v[102:103], v[128:129]
	v_pk_fma_f32 v[128:129], v[104:105], v[104:105], v[128:129]
	v_pk_fma_f32 v[128:129], v[106:107], v[106:107], v[128:129]
	v_pk_fma_f32 v[128:129], v[108:109], v[108:109], v[128:129]
	v_pk_fma_f32 v[128:129], v[110:111], v[110:111], v[128:129]
	s_nop 0
	v_add_f32_e32 v128, v128, v129
	s_waitcnt vmcnt(14)
	v_lshlrev_b32_e32 v112, 16, v64
	v_and_b32_e32 v113, 0xffff0000, v64
	v_lshlrev_b32_e32 v114, 16, v65
	v_and_b32_e32 v115, 0xffff0000, v65
	v_lshlrev_b32_e32 v116, 16, v66
	v_and_b32_e32 v117, 0xffff0000, v66
	v_lshlrev_b32_e32 v118, 16, v67
	v_and_b32_e32 v119, 0xffff0000, v67
	v_lshlrev_b32_e32 v120, 16, v68
	v_and_b32_e32 v121, 0xffff0000, v68
	v_lshlrev_b32_e32 v122, 16, v69
	v_and_b32_e32 v123, 0xffff0000, v69
	v_lshlrev_b32_e32 v124, 16, v70
	v_and_b32_e32 v125, 0xffff0000, v70
	v_lshlrev_b32_e32 v126, 16, v71
	v_and_b32_e32 v127, 0xffff0000, v71
	v_pk_mul_f32 v[130:131], v[112:113], v[112:113]
	v_pk_fma_f32 v[130:131], v[114:115], v[114:115], v[130:131]
	v_pk_fma_f32 v[130:131], v[116:117], v[116:117], v[130:131]
	v_pk_fma_f32 v[130:131], v[118:119], v[118:119], v[130:131]
	v_pk_fma_f32 v[130:131], v[120:121], v[120:121], v[130:131]
	v_pk_fma_f32 v[130:131], v[122:123], v[122:123], v[130:131]
	v_pk_fma_f32 v[130:131], v[124:125], v[124:125], v[130:131]
	v_pk_fma_f32 v[130:131], v[126:127], v[126:127], v[130:131]
	s_nop 0
	v_add_f32_e32 v130, v130, v131
	s_nop 1
	v_add_f32_dpp v128, v128, v128 quad_perm:[1,0,3,2] row_mask:0xf bank_mask:0xf
	v_add_f32_dpp v130, v130, v130 quad_perm:[1,0,3,2] row_mask:0xf bank_mask:0xf
	s_nop 0
	v_add_f32_dpp v128, v128, v128 quad_perm:[2,3,0,1] row_mask:0xf bank_mask:0xf
	v_add_f32_dpp v130, v130, v130 quad_perm:[2,3,0,1] row_mask:0xf bank_mask:0xf
	s_nop 0
	v_add_f32_dpp v128, v128, v128 row_half_mirror row_mask:0xf bank_mask:0xf
	v_add_f32_dpp v130, v130, v130 row_half_mirror row_mask:0xf bank_mask:0xf
	s_nop 0
	v_add_f32_dpp v128, v128, v128 row_mirror row_mask:0xf bank_mask:0xf
	v_add_f32_dpp v130, v130, v130 row_mirror row_mask:0xf bank_mask:0xf
	s_nop 0
	ds_bpermute_b32 v136, v187, v128
	ds_bpermute_b32 v137, v187, v130
	s_waitcnt lgkmcnt(0)
	v_add_f32_e32 v128, v128, v136
	v_add_f32_e32 v130, v130, v137
	ds_bpermute_b32 v136, v188, v128
	ds_bpermute_b32 v137, v188, v130
	s_waitcnt lgkmcnt(0)
	v_add_f32_e32 v128, v128, v136
	v_add_f32_e32 v130, v130, v137
	v_fmamk_f32 v128, v128, 0x3a800000, v138
	v_fmamk_f32 v130, v130, 0x3a800000, v138
	s_nop 0
	v_rsq_f32_e32 v128, v128
	v_rsq_f32_e32 v130, v130
	s_nop 1
	s_waitcnt vmcnt(10)
	v_pk_mul_f32 v[96:97], v[128:129], v[96:97] op_sel_hi:[0,1]
	v_pk_mul_f32 v[98:99], v[128:129], v[98:99] op_sel_hi:[0,1]
	v_pk_mul_f32 v[100:101], v[128:129], v[100:101] op_sel_hi:[0,1]
	v_pk_mul_f32 v[102:103], v[128:129], v[102:103] op_sel_hi:[0,1]
	v_pk_mul_f32 v[104:105], v[128:129], v[104:105] op_sel_hi:[0,1]
	v_pk_mul_f32 v[106:107], v[128:129], v[106:107] op_sel_hi:[0,1]
	v_pk_mul_f32 v[108:109], v[128:129], v[108:109] op_sel_hi:[0,1]
	v_pk_mul_f32 v[110:111], v[128:129], v[110:111] op_sel_hi:[0,1]
	v_pk_mul_f32 v[96:97], v[96:97], v[192:193]
	v_pk_mul_f32 v[98:99], v[98:99], v[194:195]
	v_pk_mul_f32 v[100:101], v[100:101], v[196:197]
	v_pk_mul_f32 v[102:103], v[102:103], v[198:199]
	v_pk_mul_f32 v[104:105], v[104:105], v[200:201]
	v_pk_mul_f32 v[106:107], v[106:107], v[202:203]
	v_pk_mul_f32 v[108:109], v[108:109], v[204:205]
	v_pk_mul_f32 v[110:111], v[110:111], v[206:207]
	v_lshlrev_b32_e32 v56, 16, v72
	v_and_b32_e32 v57, 0xffff0000, v72
	v_lshlrev_b32_e32 v58, 16, v73
	v_and_b32_e32 v59, 0xffff0000, v73
	v_lshlrev_b32_e32 v60, 16, v74
	v_and_b32_e32 v61, 0xffff0000, v74
	v_lshlrev_b32_e32 v62, 16, v75
	v_and_b32_e32 v63, 0xffff0000, v75
	v_pk_fma_f32 v[96:97], v[88:89], v[56:57], v[96:97] op_sel_hi:[0,1,1]
	v_pk_fma_f32 v[98:99], v[88:89], v[58:59], v[98:99] op_sel_hi:[0,1,1]
	v_pk_fma_f32 v[100:101], v[88:89], v[60:61], v[100:101] op_sel_hi:[0,1,1]
	v_pk_fma_f32 v[102:103], v[88:89], v[62:63], v[102:103] op_sel_hi:[0,1,1]
	v_lshlrev_b32_e32 v56, 16, v76
	v_and_b32_e32 v57, 0xffff0000, v76
	v_lshlrev_b32_e32 v58, 16, v77
	v_and_b32_e32 v59, 0xffff0000, v77
	v_lshlrev_b32_e32 v60, 16, v78
	v_and_b32_e32 v61, 0xffff0000, v78
	v_lshlrev_b32_e32 v62, 16, v79
	v_and_b32_e32 v63, 0xffff0000, v79
	v_pk_fma_f32 v[104:105], v[88:89], v[56:57], v[104:105] op_sel_hi:[0,1,1]
	v_pk_fma_f32 v[106:107], v[88:89], v[58:59], v[106:107] op_sel_hi:[0,1,1]
	v_pk_fma_f32 v[108:109], v[88:89], v[60:61], v[108:109] op_sel_hi:[0,1,1]
	v_pk_fma_f32 v[110:111], v[88:89], v[62:63], v[110:111] op_sel_hi:[0,1,1]
	v_pk_mul_f32 v[132:133], v[96:97], v[96:97]
	v_pk_fma_f32 v[132:133], v[98:99], v[98:99], v[132:133]
	v_pk_fma_f32 v[132:133], v[100:101], v[100:101], v[132:133]
	v_pk_fma_f32 v[132:133], v[102:103], v[102:103], v[132:133]
	v_pk_fma_f32 v[132:133], v[104:105], v[104:105], v[132:133]
;     __device__ __forceinline__ float* out() const { return (float*)karg_in(33); }
; __device__ __forceinline__ void st4_bf16(bf16* p, v4f o) { v2u w; w.x = cvt_pk_nv(o.x, o.y); w.y = cvt_pk_nv(o.z, o.w); *(v2u*)p = w; }
; __device__ __forceinline__ float ssq4(v4f v) { return (v.x * v.x + v.y * v.y) + (v.z * v.z + v.w * v.w); }
; template <int R, bool BASE_F32, bool OUT_F32>
; __device__ __forceinline__ void rows_res(const Ctx& C, int m0, int stride, int mx, const float* gpost, float scale, int lane) {
;     ...
;     for (int j = 0; j < 4; ++j) { const v4f gp = ld4_f32(gpost + 4 * lane + 256 * j);
; #pragma unroll
;         for (int r = 0; r < R; ++r) d[r][j] = b[r][j] + d[r][j] * r1[r] * gp; }
;     if (OUT_F32) { float* Y = C.out();
; #pragma unroll
;         for (int r = 0; r < R; ++r)
; #pragma unroll
;             for (int j = 0; j < 4; ++j) if (ok[r]) *(v4f*)(Y + (size_t)mr[r] * DM + 4 * lane + 256 * j) = d[r][j];
;     } else { float* rs = C.RS(); float t[R];
; #pragma unroll
;         for (int r = 0; r < R; ++r) { float s = 0.f;
; #pragma unroll
;             for (int j = 0; j < 4; ++j) s += ssq4(d[r][j]);
;             t[r] = s; }
; #pragma unroll
;         for (int r = 0; r < R; ++r) t[r] = wave_sum(t[r]) * (1.f / DM) + EPS;
; #pragma unroll
;         for (int r = 0; r < R; ++r) { const float rstd = rsqrtf(t[r]);
; #pragma unroll
;             for (int j = 0; j < 4; ++j) if (ok[r]) st4_bf16(XN + (size_t)mr[r] * DM + 4 * lane + 256 * j, d[r][j] * rstd);
;             if (lane == 0 && ok[r]) rs[mr[r]] = sqrtf(t[r]); }
	v_pk_fma_f32 v[132:133], v[106:107], v[106:107], v[132:133]
	v_pk_fma_f32 v[132:133], v[108:109], v[108:109], v[132:133]
	v_pk_fma_f32 v[132:133], v[110:111], v[110:111], v[132:133]
	s_nop 0
	v_add_f32_e32 v132, v132, v133
	v_pk_mul_f32 v[112:113], v[130:131], v[112:113] op_sel_hi:[0,1]
	v_pk_mul_f32 v[114:115], v[130:131], v[114:115] op_sel_hi:[0,1]
	v_pk_mul_f32 v[116:117], v[130:131], v[116:117] op_sel_hi:[0,1]
	v_pk_mul_f32 v[118:119], v[130:131], v[118:119] op_sel_hi:[0,1]
	v_pk_mul_f32 v[120:121], v[130:131], v[120:121] op_sel_hi:[0,1]
	v_pk_mul_f32 v[122:123], v[130:131], v[122:123] op_sel_hi:[0,1]
	v_pk_mul_f32 v[124:125], v[130:131], v[124:125] op_sel_hi:[0,1]
	v_pk_mul_f32 v[126:127], v[130:131], v[126:127] op_sel_hi:[0,1]
	v_pk_mul_f32 v[112:113], v[112:113], v[192:193]
	v_pk_mul_f32 v[114:115], v[114:115], v[194:195]
	v_pk_mul_f32 v[116:117], v[116:117], v[196:197]
	v_pk_mul_f32 v[118:119], v[118:119], v[198:199]
	v_pk_mul_f32 v[120:121], v[120:121], v[200:201]
	v_pk_mul_f32 v[122:123], v[122:123], v[202:203]
	v_pk_mul_f32 v[124:125], v[124:125], v[204:205]
	v_pk_mul_f32 v[126:127], v[126:127], v[206:207]
	v_lshlrev_b32_e32 v64, 16, v80
	v_and_b32_e32 v65, 0xffff0000, v80
	v_lshlrev_b32_e32 v66, 16, v81
	v_and_b32_e32 v67, 0xffff0000, v81
	v_lshlrev_b32_e32 v68, 16, v82
	v_and_b32_e32 v69, 0xffff0000, v82
	v_lshlrev_b32_e32 v70, 16, v83
	v_and_b32_e32 v71, 0xffff0000, v83
	v_pk_fma_f32 v[112:113], v[90:91], v[64:65], v[112:113] op_sel_hi:[0,1,1]
	v_pk_fma_f32 v[114:115], v[90:91], v[66:67], v[114:115] op_sel_hi:[0,1,1]
	v_pk_fma_f32 v[116:117], v[90:91], v[68:69], v[116:117] op_sel_hi:[0,1,1]
	v_pk_fma_f32 v[118:119], v[90:91], v[70:71], v[118:119] op_sel_hi:[0,1,1]
	v_lshlrev_b32_e32 v64, 16, v84
	v_and_b32_e32 v65, 0xffff0000, v84
	v_lshlrev_b32_e32 v66, 16, v85
	v_and_b32_e32 v67, 0xffff0000, v85
	v_lshlrev_b32_e32 v68, 16, v86
	v_and_b32_e32 v69, 0xffff0000, v86
	v_lshlrev_b32_e32 v70, 16, v87
	v_and_b32_e32 v71, 0xffff0000, v87
	v_pk_fma_f32 v[120:121], v[90:91], v[64:65], v[120:121] op_sel_hi:[0,1,1]
	v_pk_fma_f32 v[122:123], v[90:91], v[66:67], v[122:123] op_sel_hi:[0,1,1]
	v_pk_fma_f32 v[124:125], v[90:91], v[68:69], v[124:125] op_sel_hi:[0,1,1]
	v_pk_fma_f32 v[126:127], v[90:91], v[70:71], v[126:127] op_sel_hi:[0,1,1]
	v_pk_mul_f32 v[134:135], v[112:113], v[112:113]
	v_pk_fma_f32 v[134:135], v[114:115], v[114:115], v[134:135]
	v_pk_fma_f32 v[134:135], v[116:117], v[116:117], v[134:135]
	v_pk_fma_f32 v[134:135], v[118:119], v[118:119], v[134:135]
	v_pk_fma_f32 v[134:135], v[120:121], v[120:121], v[134:135]
	v_pk_fma_f32 v[134:135], v[122:123], v[122:123], v[134:135]
	v_pk_fma_f32 v[134:135], v[124:125], v[124:125], v[134:135]
	v_pk_fma_f32 v[134:135], v[126:127], v[126:127], v[134:135]
	s_nop 0
	v_add_f32_e32 v134, v134, v135
	s_nop 1
	v_add_f32_dpp v132, v132, v132 quad_perm:[1,0,3,2] row_mask:0xf bank_mask:0xf
	v_add_f32_dpp v134, v134, v134 quad_perm:[1,0,3,2] row_mask:0xf bank_mask:0xf
	s_nop 0
	v_add_f32_dpp v132, v132, v132 quad_perm:[2,3,0,1] row_mask:0xf bank_mask:0xf
	v_add_f32_dpp v134, v134, v134 quad_perm:[2,3,0,1] row_mask:0xf bank_mask:0xf
	s_nop 0
	v_add_f32_dpp v132, v132, v132 row_half_mirror row_mask:0xf bank_mask:0xf
	v_add_f32_dpp v134, v134, v134 row_half_mirror row_mask:0xf bank_mask:0xf
	s_nop 0
	v_add_f32_dpp v132, v132, v132 row_mirror row_mask:0xf bank_mask:0xf
	v_add_f32_dpp v134, v134, v134 row_mirror row_mask:0xf bank_mask:0xf
	s_nop 0
	ds_bpermute_b32 v136, v187, v132
	ds_bpermute_b32 v137, v187, v134
	s_waitcnt lgkmcnt(0)
	v_add_f32_e32 v132, v132, v136
	v_add_f32_e32 v134, v134, v137
	ds_bpermute_b32 v136, v188, v132
	ds_bpermute_b32 v137, v188, v134
	s_waitcnt lgkmcnt(0)
	v_add_f32_e32 v132, v132, v136
	v_add_f32_e32 v134, v134, v137
	v_fmamk_f32 v164, v132, 0x3a800000, v138
	v_fmamk_f32 v167, v134, 0x3a800000, v138
	s_nop 0
	v_rsq_f32_e32 v132, v164
	v_rsq_f32_e32 v134, v167
	v_sqrt_f32_e32 v165, v164
	v_sqrt_f32_e32 v168, v167
	s_nop 1
	v_pk_mul_f32 v[140:141], v[96:97], v[132:133] op_sel_hi:[1,0]
	v_cvt_pk_bf16_f32 v148, v140, v141
	v_pk_mul_f32 v[142:143], v[98:99], v[132:133] op_sel_hi:[1,0]
	v_cvt_pk_bf16_f32 v149, v142, v143
	v_pk_mul_f32 v[144:145], v[100:101], v[132:133] op_sel_hi:[1,0]
	v_cvt_pk_bf16_f32 v150, v144, v145
	v_pk_mul_f32 v[146:147], v[102:103], v[132:133] op_sel_hi:[1,0]
	v_cvt_pk_bf16_f32 v151, v146, v147
	v_pk_mul_f32 v[140:141], v[104:105], v[132:133] op_sel_hi:[1,0]
	v_cvt_pk_bf16_f32 v152, v140, v141
	v_pk_mul_f32 v[142:143], v[106:107], v[132:133] op_sel_hi:[1,0]
	v_cvt_pk_bf16_f32 v153, v142, v143
	v_pk_mul_f32 v[144:145], v[108:109], v[132:133] op_sel_hi:[1,0]
	v_cvt_pk_bf16_f32 v154, v144, v145
	v_pk_mul_f32 v[146:147], v[110:111], v[132:133] op_sel_hi:[1,0]
	v_cvt_pk_bf16_f32 v155, v146, v147
	global_store_dwordx2 v173, v[148:149], s[98:99]
	global_store_dwordx2 v173, v[150:151], s[98:99] offset:512
	global_store_dwordx2 v173, v[152:153], s[98:99] offset:1024
	global_store_dwordx2 v173, v[154:155], s[98:99] offset:1536
	v_add_u32_e32 v173, 0x400000, v173
	v_pk_mul_f32 v[140:141], v[112:113], v[134:135] op_sel_hi:[1,0]
	v_cvt_pk_bf16_f32 v156, v140, v141
	v_pk_mul_f32 v[142:143], v[114:115], v[134:135] op_sel_hi:[1,0]
	v_cvt_pk_bf16_f32 v157, v142, v143
	v_pk_mul_f32 v[144:145], v[116:117], v[134:135] op_sel_hi:[1,0]
	v_cvt_pk_bf16_f32 v158, v144, v145
	v_pk_mul_f32 v[146:147], v[118:119], v[134:135] op_sel_hi:[1,0]
	v_cvt_pk_bf16_f32 v159, v146, v147
	v_pk_mul_f32 v[140:141], v[120:121], v[134:135] op_sel_hi:[1,0]
	v_cvt_pk_bf16_f32 v160, v140, v141
	v_pk_mul_f32 v[142:143], v[122:123], v[134:135] op_sel_hi:[1,0]
	v_cvt_pk_bf16_f32 v161, v142, v143
	v_pk_mul_f32 v[144:145], v[124:125], v[134:135] op_sel_hi:[1,0]
	v_cvt_pk_bf16_f32 v162, v144, v145
	v_pk_mul_f32 v[146:147], v[126:127], v[134:135] op_sel_hi:[1,0]
	v_cvt_pk_bf16_f32 v163, v146, v147
	global_store_dwordx2 v173, v[156:157], s[98:99]
	global_store_dwordx2 v173, v[158:159], s[98:99] offset:512
	global_store_dwordx2 v173, v[160:161], s[98:99] offset:1024
	global_store_dwordx2 v173, v[162:163], s[98:99] offset:1536
	v_add_u32_e32 v173, 0x400000, v173
	v_add_u32_e32 v166, -1, v165
	v_fma_f32 v140, -v166, v165, v164
	v_cmp_ge_f32_e32 vcc, 0, v140
	v_add_u32_e32 v141, 1, v165
	v_cndmask_b32_e32 v166, v165, v166, vcc
	v_fma_f32 v140, -v141, v165, v164
	v_cmp_lt_f32_e32 vcc, 0, v140
	s_nop 1
	v_cndmask_b32_e32 v165, v166, v141, vcc
	v_add_u32_e32 v169, -1, v168
	v_fma_f32 v142, -v169, v168, v167
	v_cmp_ge_f32_e32 vcc, 0, v142
	v_add_u32_e32 v143, 1, v168
	v_cndmask_b32_e32 v169, v168, v169, vcc
	v_fma_f32 v142, -v143, v168, v167
	v_cmp_lt_f32_e32 vcc, 0, v142
	s_nop 1
	v_cndmask_b32_e32 v168, v169, v143, vcc
	s_mov_b64 exec, 1
	global_store_dword v174, v165, s[98:99]
	v_add_u32_e32 v174, 0x2000, v174
	global_store_dword v174, v168, s[98:99]
	v_add_u32_e32 v174, 0x2000, v174
	s_mov_b64 exec, -1
	s_branch .LBB0_1013
; __device__ __forceinline__ const float* xrow_ptr(const Ctx& C, int row) { return row < MPROMPT ? C.in(0) + (size_t)row * DM : C.in(1) + (size_t)(row - MPROMPT) * DM; }
; __device__ __forceinline__ v4f ld4_bf16(const bf16* p) { const v2u w = *(const v2u*)p; return (v4f){bf_lo(w.x), bf_hi(w.x), bf_lo(w.y), bf_hi(w.y)}; }
; template <int R, bool BASE_F32, bool OUT_F32>
; __device__ __forceinline__ void rows_res(const Ctx& C, int m0, int stride, int mx, const float* gpost, float scale, int lane) {
;     ...
;     const bf16* D = C.D(); bf16* XN = C.XN();
; #pragma unroll
;     for (int r = 0; r < R; ++r) { mr[r] = (r == 4) ? mx : m0 + r * stride; ok[r] = (r == 4) ? (mx < M) : (mr[r] < MPROMPT); const int mm = ok[r] ? mr[r] : 0;
; #pragma unroll
;         for (int j = 0; j < 4; ++j) d[r][j] = ld4_bf16(D + (size_t)mm * DM + 4 * lane + 256 * j);
;         if (BASE_F32) { const float* x = xrow_ptr(C, mm);
; #pragma unroll
;             for (int j = 0; j < 4; ++j) b[r][j] = ld4_f32(x + 4 * lane + 256 * j);
;         } else { const float inv = C.RS()[mm];
; #pragma unroll
;             for (int j = 0; j < 4; ++j) b[r][j] = ld4_bf16(XN + (size_t)mm * DM + 4 * lane + 256 * j) * inv;
;         } }
	v_mov_b32_e32 v3, v1
	s_mov_b32 s0, 0x358637bd
	s_waitcnt lgkmcnt(0)
	v_lshl_add_u64 v[4:5], s[16:17], 0, v[2:3]
	s_mov_b64 s[18:19], 0x7100000
	s_mov_b64 s[20:21], 0x3000000
	v_mov_b32_e32 v3, 0x2a80000
	s_mov_b32 s22, 0x3a800000
	v_mov_b64_e32 v[6:7], s[0:1]
	s_mov_b32 s42, 0x800000
	v_mov_b32_e32 v41, 0x358637bd
	s_mov_b32 s43, 0xf800000
	v_mov_b32_e32 v148, 0x260
	s_mov_b32 s24, s23
	v_readlane_b32 s56, v232, 5
	s_branch .LBB0_997

;     __device__ __forceinline__ const float* in(int i) const { return karg_in(i); }
; __device__ __forceinline__ const float* xrow_ptr(const Ctx& C, int row) { return row < MPROMPT ? C.in(0) + (size_t)row * DM : C.in(1) + (size_t)(row - MPROMPT) * DM; }
; __device__ __forceinline__ v4f ld4_bf16(const bf16* p) { const v2u w = *(const v2u*)p; return (v4f){bf_lo(w.x), bf_hi(w.x), bf_lo(w.y), bf_hi(w.y)}; }
; __device__ __forceinline__ float ssq4(v4f v) { return (v.x * v.x + v.y * v.y) + (v.z * v.z + v.w * v.w); }
; #define FTID const int ftid_ = fresh_tid()
; template <int R, bool BASE_F32, bool OUT_F32>
; __device__ __forceinline__ void rows_res(const Ctx& C, int m0, int stride, int mx, const float* gpost, float scale, int lane) {
;     ...
;     const bf16* D = C.D(); bf16* XN = C.XN();
; #pragma unroll
;     for (int r = 0; r < R; ++r) { mr[r] = (r == 4) ? mx : m0 + r * stride; ok[r] = (r == 4) ? (mx < M) : (mr[r] < MPROMPT); const int mm = ok[r] ? mr[r] : 0;
; #pragma unroll
;         for (int j = 0; j < 4; ++j) d[r][j] = ld4_bf16(D + (size_t)mm * DM + 4 * lane + 256 * j);
;         if (BASE_F32) { const float* x = xrow_ptr(C, mm);
; #pragma unroll
;             for (int j = 0; j < 4; ++j) b[r][j] = ld4_f32(x + 4 * lane + 256 * j);
;         } else { const float inv = C.RS()[mm];
; #pragma unroll
;             for (int j = 0; j < 4; ++j) b[r][j] = ld4_bf16(XN + (size_t)mm * DM + 4 * lane + 256 * j) * inv;
;         } }
; #pragma unroll
;     for (int r = 0; r < R; ++r) { float s = 0.f;
; #pragma unroll
;         for (int j = 0; j < 4; ++j) s += ssq4(d[r][j]);
; __global__ void __launch_bounds__(NTHREADS, 2) fwd_kernel(Args args) {
;     ...
;     { FTID; const float* gp = C.in(32); { const int gw_ = GWV, ngw_ = NGWV, nit = (MPROMPT + 4 * ngw_ - 1) / (4 * ngw_);
;       for (int it = 0; it < nit - 1; ++it) rows_res<4, false, true>(C, gw_ + 4 * it * ngw_, ngw_, M, gp, 0.5f, LANE);
;       rows_res<5, false, true>(C, gw_ + 4 * (nit - 1) * ngw_, ngw_, MPROMPT + gw_, gp, 0.5f, LANE);
;       for (int ms = MPROMPT + gw_ + ngw_; ms < M; ms += ngw_) rows_res<5, false, true>(C, MPROMPT, ngw_, ms, gp, 0.5f, LANE); } }
.LBB0_1272:
	s_or_b64 exec, exec, s[4:5]
	s_mov_b64 s[0:1], s[80:81]
	s_waitcnt lgkmcnt(0)
	s_barrier
	s_load_dwordx2 s[8:9], s[0:1], 0x100
	v_readfirstlane_b32 s0, v182
	v_lshlrev_b32_e32 v0, 2, v182
	s_ashr_i32 s26, s0, 6
	v_readlane_b32 s0, v232, 0
	v_and_b32_e32 v0, 0xfc, v0
	s_add_i32 s15, s26, s0
	v_mov_b32_e32 v17, 0
	s_and_b64 vcc, exec, s[6:7]
	v_lshlrev_b32_e32 v16, 2, v0
	v_lshlrev_b32_e32 v18, 1, v0
	s_load_dwordx2 s[98:99], s[80:81], 0x110
	s_load_dwordx2 s[100:101], s[80:81], 0x100
	v_and_b32_e32 v176, 63, v182
	v_lshlrev_b32_e32 v170, 3, v176
	s_lshl_b32 vcc_lo, s15, 11
	v_add_u32_e32 v170, vcc_lo, v170
	v_add_u32_e32 v171, 0x3000000, v170
	v_add_u32_e32 v170, 0x7100000, v170
	v_mov_b32_e32 v173, v171
	s_lshl_b32 vcc_lo, s15, 2
	v_mov_b32_e32 v172, 0x2a80000
	v_add_u32_e32 v172, vcc_lo, v172
	v_mov_b32_e32 v174, v172
	s_lshl_b32 vcc_lo, s15, 12
	v_lshlrev_b32_e32 v175, 4, v176
	v_add_u32_e32 v175, vcc_lo, v175
	v_lshlrev_b32_e32 v176, 4, v176
	v_mov_b32_e32 v138, 0x358637bd
	s_waitcnt lgkmcnt(0)
	global_load_dwordx4 v[192:195], v176, s[100:101]
	global_load_dwordx4 v[196:199], v176, s[100:101] offset:1024
	global_load_dwordx4 v[200:203], v176, s[100:101] offset:2048
	global_load_dwordx4 v[204:207], v176, s[100:101] offset:3072
	s_load_dwordx2 s[100:101], s[80:81], 0x108
	global_load_dword v52, v172, s[98:99]
	global_load_dwordx2 v[20:21], v170, s[98:99]
	global_load_dwordx2 v[22:23], v170, s[98:99] offset:512
	global_load_dwordx2 v[24:25], v170, s[98:99] offset:1024
	global_load_dwordx2 v[26:27], v170, s[98:99] offset:1536
	global_load_dwordx2 v[36:37], v171, s[98:99]
	global_load_dwordx2 v[38:39], v171, s[98:99] offset:512
	global_load_dwordx2 v[40:41], v171, s[98:99] offset:1024
	global_load_dwordx2 v[42:43], v171, s[98:99] offset:1536
	v_add_u32_e32 v170, 0x400000, v170
	v_add_u32_e32 v171, 0x400000, v171
	v_add_u32_e32 v172, 0x2000, v172
	global_load_dword v54, v172, s[98:99]
	global_load_dwordx2 v[28:29], v170, s[98:99]
	global_load_dwordx2 v[30:31], v170, s[98:99] offset:512
	global_load_dwordx2 v[32:33], v170, s[98:99] offset:1024
	global_load_dwordx2 v[34:35], v170, s[98:99] offset:1536
	global_load_dwordx2 v[44:45], v171, s[98:99]
	global_load_dwordx2 v[46:47], v171, s[98:99] offset:512
	global_load_dwordx2 v[48:49], v171, s[98:99] offset:1024
	global_load_dwordx2 v[50:51], v171, s[98:99] offset:1536
	v_add_u32_e32 v170, 0x400000, v170
	v_add_u32_e32 v171, 0x400000, v171
	v_add_u32_e32 v172, 0x2000, v172
	global_load_dword v88, v172, s[98:99]
	global_load_dwordx2 v[56:57], v170, s[98:99]
	global_load_dwordx2 v[58:59], v170, s[98:99] offset:512
	global_load_dwordx2 v[60:61], v170, s[98:99] offset:1024
	global_load_dwordx2 v[62:63], v170, s[98:99] offset:1536
	global_load_dwordx2 v[72:73], v171, s[98:99]
	global_load_dwordx2 v[74:75], v171, s[98:99] offset:512
	global_load_dwordx2 v[76:77], v171, s[98:99] offset:1024
	global_load_dwordx2 v[78:79], v171, s[98:99] offset:1536
	v_add_u32_e32 v170, 0x400000, v170
	v_add_u32_e32 v171, 0x400000, v171
	v_add_u32_e32 v172, 0x2000, v172
	global_load_dword v90, v172, s[98:99]
	global_load_dwordx2 v[64:65], v170, s[98:99]
	global_load_dwordx2 v[66:67], v170, s[98:99] offset:512
	global_load_dwordx2 v[68:69], v170, s[98:99] offset:1024
	global_load_dwordx2 v[70:71], v170, s[98:99] offset:1536
	global_load_dwordx2 v[80:81], v171, s[98:99]
	global_load_dwordx2 v[82:83], v171, s[98:99] offset:512
	global_load_dwordx2 v[84:85], v171, s[98:99] offset:1024
	global_load_dwordx2 v[86:87], v171, s[98:99] offset:1536
	v_add_u32_e32 v170, 0x400000, v170
	v_add_u32_e32 v171, 0x400000, v171
	v_add_u32_e32 v172, 0x2000, v172
	s_waitcnt vmcnt(31)
	v_lshlrev_b32_e32 v96, 16, v20
	v_and_b32_e32 v97, 0xffff0000, v20
	v_lshlrev_b32_e32 v98, 16, v21
	v_and_b32_e32 v99, 0xffff0000, v21
	v_lshlrev_b32_e32 v100, 16, v22
	v_and_b32_e32 v101, 0xffff0000, v22
	v_lshlrev_b32_e32 v102, 16, v23
	v_and_b32_e32 v103, 0xffff0000, v23
	v_lshlrev_b32_e32 v104, 16, v24
	v_and_b32_e32 v105, 0xffff0000, v24
	v_lshlrev_b32_e32 v106, 16, v25
	v_and_b32_e32 v107, 0xffff0000, v25
	v_lshlrev_b32_e32 v108, 16, v26
	v_and_b32_e32 v109, 0xffff0000, v26
	v_lshlrev_b32_e32 v110, 16, v27
	v_and_b32_e32 v111, 0xffff0000, v27
	v_pk_mul_f32 v[128:129], v[96:97], v[96:97]
	v_pk_fma_f32 v[128:129], v[98:99], v[98:99], v[128:129]
	v_pk_fma_f32 v[128:129], v[100:101], v[100:101], v[128:129]
	v_pk_fma_f32 v[128:129], v[102:103], v[102:103], v[128:129]
	v_pk_fma_f32 v[128:129], v[104:105], v[104:105], v[128:129]
	v_pk_fma_f32 v[128:129], v[106:107], v[106:107], v[128:129]
	v_pk_fma_f32 v[128:129], v[108:109], v[108:109], v[128:129]
	v_pk_fma_f32 v[128:129], v[110:111], v[110:111], v[128:129]
	s_nop 0
	v_add_f32_e32 v128, v128, v129
	s_waitcnt vmcnt(22)
;     __device__ __forceinline__ float* out() const { return (float*)karg_in(33); }
; __device__ __forceinline__ float ssq4(v4f v) { return (v.x * v.x + v.y * v.y) + (v.z * v.z + v.w * v.w); }
; template <int R, bool BASE_F32, bool OUT_F32>
; __device__ __forceinline__ void rows_res(const Ctx& C, int m0, int stride, int mx, const float* gpost, float scale, int lane) {
;     ...
;     for (int r = 0; r < R; ++r) { float s = 0.f;
; #pragma unroll
;         for (int j = 0; j < 4; ++j) s += ssq4(d[r][j]);
;         r1[r] = s; }
; #pragma unroll
;     for (int r = 0; r < R; ++r) r1[r] = rsqrtf(wave_sum(r1[r]) * (1.f / DM) + EPS) * scale;
; #pragma unroll
;     for (int j = 0; j < 4; ++j) { const v4f gp = ld4_f32(gpost + 4 * lane + 256 * j);
; #pragma unroll
;         for (int r = 0; r < R; ++r) d[r][j] = b[r][j] + d[r][j] * r1[r] * gp; }
;     if (OUT_F32) { float* Y = C.out();
; #pragma unroll
;         for (int r = 0; r < R; ++r)
; #pragma unroll
;             for (int j = 0; j < 4; ++j) if (ok[r]) *(v4f*)(Y + (size_t)mr[r] * DM + 4 * lane + 256 * j) = d[r][j];
	v_lshlrev_b32_e32 v112, 16, v28
	v_and_b32_e32 v113, 0xffff0000, v28
	v_lshlrev_b32_e32 v114, 16, v29
	v_and_b32_e32 v115, 0xffff0000, v29
	v_lshlrev_b32_e32 v116, 16, v30
	v_and_b32_e32 v117, 0xffff0000, v30
	v_lshlrev_b32_e32 v118, 16, v31
	v_and_b32_e32 v119, 0xffff0000, v31
	v_lshlrev_b32_e32 v120, 16, v32
	v_and_b32_e32 v121, 0xffff0000, v32
	v_lshlrev_b32_e32 v122, 16, v33
	v_and_b32_e32 v123, 0xffff0000, v33
	v_lshlrev_b32_e32 v124, 16, v34
	v_and_b32_e32 v125, 0xffff0000, v34
	v_lshlrev_b32_e32 v126, 16, v35
	v_and_b32_e32 v127, 0xffff0000, v35
	v_pk_mul_f32 v[130:131], v[112:113], v[112:113]
	v_pk_fma_f32 v[130:131], v[114:115], v[114:115], v[130:131]
	v_pk_fma_f32 v[130:131], v[116:117], v[116:117], v[130:131]
	v_pk_fma_f32 v[130:131], v[118:119], v[118:119], v[130:131]
	v_pk_fma_f32 v[130:131], v[120:121], v[120:121], v[130:131]
	v_pk_fma_f32 v[130:131], v[122:123], v[122:123], v[130:131]
	v_pk_fma_f32 v[130:131], v[124:125], v[124:125], v[130:131]
	v_pk_fma_f32 v[130:131], v[126:127], v[126:127], v[130:131]
	s_nop 0
	v_add_f32_e32 v130, v130, v131
	s_nop 1
	v_add_f32_dpp v128, v128, v128 quad_perm:[1,0,3,2] row_mask:0xf bank_mask:0xf
	v_add_f32_dpp v130, v130, v130 quad_perm:[1,0,3,2] row_mask:0xf bank_mask:0xf
	s_nop 0
	v_add_f32_dpp v128, v128, v128 quad_perm:[2,3,0,1] row_mask:0xf bank_mask:0xf
	v_add_f32_dpp v130, v130, v130 quad_perm:[2,3,0,1] row_mask:0xf bank_mask:0xf
	s_nop 0
	v_add_f32_dpp v128, v128, v128 row_half_mirror row_mask:0xf bank_mask:0xf
	v_add_f32_dpp v130, v130, v130 row_half_mirror row_mask:0xf bank_mask:0xf
	s_nop 0
	v_add_f32_dpp v128, v128, v128 row_mirror row_mask:0xf bank_mask:0xf
	v_add_f32_dpp v130, v130, v130 row_mirror row_mask:0xf bank_mask:0xf
	s_nop 0
	ds_bpermute_b32 v136, v187, v128
	ds_bpermute_b32 v137, v187, v130
	s_waitcnt lgkmcnt(0)
	v_add_f32_e32 v128, v128, v136
	v_add_f32_e32 v130, v130, v137
	ds_bpermute_b32 v136, v188, v128
	ds_bpermute_b32 v137, v188, v130
	s_waitcnt lgkmcnt(0)
	v_add_f32_e32 v128, v128, v136
	v_add_f32_e32 v130, v130, v137
	v_fmamk_f32 v128, v128, 0x3a800000, v138
	v_fmamk_f32 v130, v130, 0x3a800000, v138
	s_nop 0
	v_rsq_f32_e32 v128, v128
	v_rsq_f32_e32 v130, v130
	s_nop 1
	v_mul_f32_e32 v128, 0.5, v128
	v_mul_f32_e32 v130, 0.5, v130
	s_waitcnt vmcnt(18)
	v_pk_mul_f32 v[96:97], v[128:129], v[96:97] op_sel_hi:[0,1]
	v_pk_mul_f32 v[98:99], v[128:129], v[98:99] op_sel_hi:[0,1]
	v_pk_mul_f32 v[100:101], v[128:129], v[100:101] op_sel_hi:[0,1]
	v_pk_mul_f32 v[102:103], v[128:129], v[102:103] op_sel_hi:[0,1]
	v_pk_mul_f32 v[104:105], v[128:129], v[104:105] op_sel_hi:[0,1]
	v_pk_mul_f32 v[106:107], v[128:129], v[106:107] op_sel_hi:[0,1]
	v_pk_mul_f32 v[108:109], v[128:129], v[108:109] op_sel_hi:[0,1]
	v_pk_mul_f32 v[110:111], v[128:129], v[110:111] op_sel_hi:[0,1]
	v_pk_mul_f32 v[96:97], v[96:97], v[192:193]
	v_pk_mul_f32 v[98:99], v[98:99], v[194:195]
	v_pk_mul_f32 v[100:101], v[100:101], v[196:197]
	v_pk_mul_f32 v[102:103], v[102:103], v[198:199]
	v_pk_mul_f32 v[104:105], v[104:105], v[200:201]
	v_pk_mul_f32 v[106:107], v[106:107], v[202:203]
	v_pk_mul_f32 v[108:109], v[108:109], v[204:205]
	v_pk_mul_f32 v[110:111], v[110:111], v[206:207]
	v_lshlrev_b32_e32 v20, 16, v36
	v_and_b32_e32 v21, 0xffff0000, v36
	v_lshlrev_b32_e32 v22, 16, v37
	v_and_b32_e32 v23, 0xffff0000, v37
	v_lshlrev_b32_e32 v24, 16, v38
	v_and_b32_e32 v25, 0xffff0000, v38
	v_lshlrev_b32_e32 v26, 16, v39
	v_and_b32_e32 v27, 0xffff0000, v39
	v_pk_fma_f32 v[96:97], v[52:53], v[20:21], v[96:97] op_sel_hi:[0,1,1]
	v_pk_fma_f32 v[98:99], v[52:53], v[22:23], v[98:99] op_sel_hi:[0,1,1]
	v_pk_fma_f32 v[100:101], v[52:53], v[24:25], v[100:101] op_sel_hi:[0,1,1]
	v_pk_fma_f32 v[102:103], v[52:53], v[26:27], v[102:103] op_sel_hi:[0,1,1]
	v_lshlrev_b32_e32 v20, 16, v40
	v_and_b32_e32 v21, 0xffff0000, v40
	v_lshlrev_b32_e32 v22, 16, v41
	v_and_b32_e32 v23, 0xffff0000, v41
	v_lshlrev_b32_e32 v24, 16, v42
	v_and_b32_e32 v25, 0xffff0000, v42
	v_lshlrev_b32_e32 v26, 16, v43
	v_and_b32_e32 v27, 0xffff0000, v43
	v_pk_fma_f32 v[104:105], v[52:53], v[20:21], v[104:105] op_sel_hi:[0,1,1]
	v_pk_fma_f32 v[106:107], v[52:53], v[22:23], v[106:107] op_sel_hi:[0,1,1]
	v_pk_fma_f32 v[108:109], v[52:53], v[24:25], v[108:109] op_sel_hi:[0,1,1]
	v_pk_fma_f32 v[110:111], v[52:53], v[26:27], v[110:111] op_sel_hi:[0,1,1]
	global_store_dwordx4 v175, v[96:99], s[100:101]
	global_store_dwordx4 v175, v[100:103], s[100:101] offset:1024
	global_store_dwordx4 v175, v[104:107], s[100:101] offset:2048
	global_store_dwordx4 v175, v[108:111], s[100:101] offset:3072
	v_add_u32_e32 v175, 0x800000, v175
	v_pk_mul_f32 v[112:113], v[130:131], v[112:113] op_sel_hi:[0,1]
	v_pk_mul_f32 v[114:115], v[130:131], v[114:115] op_sel_hi:[0,1]
	v_pk_mul_f32 v[116:117], v[130:131], v[116:117] op_sel_hi:[0,1]
	v_pk_mul_f32 v[118:119], v[130:131], v[118:119] op_sel_hi:[0,1]
	v_pk_mul_f32 v[120:121], v[130:131], v[120:121] op_sel_hi:[0,1]
	v_pk_mul_f32 v[122:123], v[130:131], v[122:123] op_sel_hi:[0,1]
	v_pk_mul_f32 v[124:125], v[130:131], v[124:125] op_sel_hi:[0,1]
	v_pk_mul_f32 v[126:127], v[130:131], v[126:127] op_sel_hi:[0,1]
	v_pk_mul_f32 v[112:113], v[112:113], v[192:193]
	v_pk_mul_f32 v[114:115], v[114:115], v[194:195]
	v_pk_mul_f32 v[116:117], v[116:117], v[196:197]
	v_pk_mul_f32 v[118:119], v[118:119], v[198:199]
	v_pk_mul_f32 v[120:121], v[120:121], v[200:201]
	v_pk_mul_f32 v[122:123], v[122:123], v[202:203]
	v_pk_mul_f32 v[124:125], v[124:125], v[204:205]
	v_pk_mul_f32 v[126:127], v[126:127], v[206:207]
	v_lshlrev_b32_e32 v28, 16, v44
	v_and_b32_e32 v29, 0xffff0000, v44
	v_lshlrev_b32_e32 v30, 16, v45
	v_and_b32_e32 v31, 0xffff0000, v45
;     __device__ __forceinline__ float* out() const { return (float*)karg_in(33); }
; __device__ __forceinline__ const float* xrow_ptr(const Ctx& C, int row) { return row < MPROMPT ? C.in(0) + (size_t)row * DM : C.in(1) + (size_t)(row - MPROMPT) * DM; }
; __device__ __forceinline__ v4f ld4_bf16(const bf16* p) { const v2u w = *(const v2u*)p; return (v4f){bf_lo(w.x), bf_hi(w.x), bf_lo(w.y), bf_hi(w.y)}; }
; __device__ __forceinline__ float ssq4(v4f v) { return (v.x * v.x + v.y * v.y) + (v.z * v.z + v.w * v.w); }
; template <int R, bool BASE_F32, bool OUT_F32>
; __device__ __forceinline__ void rows_res(const Ctx& C, int m0, int stride, int mx, const float* gpost, float scale, int lane) {
;     ...
;     for (int r = 0; r < R; ++r) { mr[r] = (r == 4) ? mx : m0 + r * stride; ok[r] = (r == 4) ? (mx < M) : (mr[r] < MPROMPT); const int mm = ok[r] ? mr[r] : 0;
; #pragma unroll
;         for (int j = 0; j < 4; ++j) d[r][j] = ld4_bf16(D + (size_t)mm * DM + 4 * lane + 256 * j);
;         if (BASE_F32) { const float* x = xrow_ptr(C, mm);
; #pragma unroll
;             for (int j = 0; j < 4; ++j) b[r][j] = ld4_f32(x + 4 * lane + 256 * j);
;         } else { const float inv = C.RS()[mm];
; #pragma unroll
;             for (int j = 0; j < 4; ++j) b[r][j] = ld4_bf16(XN + (size_t)mm * DM + 4 * lane + 256 * j) * inv;
;         } }
; #pragma unroll
;     for (int r = 0; r < R; ++r) { float s = 0.f;
; #pragma unroll
;         for (int j = 0; j < 4; ++j) s += ssq4(d[r][j]);
;         r1[r] = s; }
;     ...
;     for (int j = 0; j < 4; ++j) { const v4f gp = ld4_f32(gpost + 4 * lane + 256 * j);
; #pragma unroll
;         for (int r = 0; r < R; ++r) d[r][j] = b[r][j] + d[r][j] * r1[r] * gp; }
;     if (OUT_F32) { float* Y = C.out();
; #pragma unroll
;         for (int r = 0; r < R; ++r)
; #pragma unroll
;             for (int j = 0; j < 4; ++j) if (ok[r]) *(v4f*)(Y + (size_t)mr[r] * DM + 4 * lane + 256 * j) = d[r][j];
	v_lshlrev_b32_e32 v32, 16, v46
	v_and_b32_e32 v33, 0xffff0000, v46
	v_lshlrev_b32_e32 v34, 16, v47
	v_and_b32_e32 v35, 0xffff0000, v47
	v_pk_fma_f32 v[112:113], v[54:55], v[28:29], v[112:113] op_sel_hi:[0,1,1]
	v_pk_fma_f32 v[114:115], v[54:55], v[30:31], v[114:115] op_sel_hi:[0,1,1]
	v_pk_fma_f32 v[116:117], v[54:55], v[32:33], v[116:117] op_sel_hi:[0,1,1]
	v_pk_fma_f32 v[118:119], v[54:55], v[34:35], v[118:119] op_sel_hi:[0,1,1]
	v_lshlrev_b32_e32 v28, 16, v48
	v_and_b32_e32 v29, 0xffff0000, v48
	v_lshlrev_b32_e32 v30, 16, v49
	v_and_b32_e32 v31, 0xffff0000, v49
	v_lshlrev_b32_e32 v32, 16, v50
	v_and_b32_e32 v33, 0xffff0000, v50
	v_lshlrev_b32_e32 v34, 16, v51
	v_and_b32_e32 v35, 0xffff0000, v51
	v_pk_fma_f32 v[120:121], v[54:55], v[28:29], v[120:121] op_sel_hi:[0,1,1]
	v_pk_fma_f32 v[122:123], v[54:55], v[30:31], v[122:123] op_sel_hi:[0,1,1]
	v_pk_fma_f32 v[124:125], v[54:55], v[32:33], v[124:125] op_sel_hi:[0,1,1]
	v_pk_fma_f32 v[126:127], v[54:55], v[34:35], v[126:127] op_sel_hi:[0,1,1]
	global_store_dwordx4 v175, v[112:115], s[100:101]
	global_store_dwordx4 v175, v[116:119], s[100:101] offset:1024
	global_store_dwordx4 v175, v[120:123], s[100:101] offset:2048
	global_store_dwordx4 v175, v[124:127], s[100:101] offset:3072
	v_add_u32_e32 v175, 0x800000, v175
	global_load_dword v52, v172, s[98:99]
	global_load_dwordx2 v[20:21], v170, s[98:99]
	global_load_dwordx2 v[22:23], v170, s[98:99] offset:512
	global_load_dwordx2 v[24:25], v170, s[98:99] offset:1024
	global_load_dwordx2 v[26:27], v170, s[98:99] offset:1536
	global_load_dwordx2 v[36:37], v171, s[98:99]
	global_load_dwordx2 v[38:39], v171, s[98:99] offset:512
	global_load_dwordx2 v[40:41], v171, s[98:99] offset:1024
	global_load_dwordx2 v[42:43], v171, s[98:99] offset:1536
	v_add_u32_e32 v170, 0x400000, v170
	v_add_u32_e32 v171, 0x400000, v171
	v_add_u32_e32 v172, 0x2000, v172
	global_load_dword v54, v172, s[98:99]
	global_load_dwordx2 v[28:29], v170, s[98:99]
	global_load_dwordx2 v[30:31], v170, s[98:99] offset:512
	global_load_dwordx2 v[32:33], v170, s[98:99] offset:1024
	global_load_dwordx2 v[34:35], v170, s[98:99] offset:1536
	global_load_dwordx2 v[44:45], v171, s[98:99]
	global_load_dwordx2 v[46:47], v171, s[98:99] offset:512
	global_load_dwordx2 v[48:49], v171, s[98:99] offset:1024
	global_load_dwordx2 v[50:51], v171, s[98:99] offset:1536
	v_add_u32_e32 v170, 0x400000, v170
	v_add_u32_e32 v171, 0x400000, v171
	v_add_u32_e32 v172, 0x2000, v172
	s_waitcnt vmcnt(39)
	v_lshlrev_b32_e32 v96, 16, v56
	v_and_b32_e32 v97, 0xffff0000, v56
	v_lshlrev_b32_e32 v98, 16, v57
	v_and_b32_e32 v99, 0xffff0000, v57
	v_lshlrev_b32_e32 v100, 16, v58
	v_and_b32_e32 v101, 0xffff0000, v58
	v_lshlrev_b32_e32 v102, 16, v59
	v_and_b32_e32 v103, 0xffff0000, v59
	v_lshlrev_b32_e32 v104, 16, v60
	v_and_b32_e32 v105, 0xffff0000, v60
	v_lshlrev_b32_e32 v106, 16, v61
	v_and_b32_e32 v107, 0xffff0000, v61
	v_lshlrev_b32_e32 v108, 16, v62
	v_and_b32_e32 v109, 0xffff0000, v62
	v_lshlrev_b32_e32 v110, 16, v63
	v_and_b32_e32 v111, 0xffff0000, v63
	v_pk_mul_f32 v[128:129], v[96:97], v[96:97]
	v_pk_fma_f32 v[128:129], v[98:99], v[98:99], v[128:129]
	v_pk_fma_f32 v[128:129], v[100:101], v[100:101], v[128:129]
	v_pk_fma_f32 v[128:129], v[102:103], v[102:103], v[128:129]
	v_pk_fma_f32 v[128:129], v[104:105], v[104:105], v[128:129]
	v_pk_fma_f32 v[128:129], v[106:107], v[106:107], v[128:129]
	v_pk_fma_f32 v[128:129], v[108:109], v[108:109], v[128:129]
	v_pk_fma_f32 v[128:129], v[110:111], v[110:111], v[128:129]
	s_nop 0
	v_add_f32_e32 v128, v128, v129
	s_waitcnt vmcnt(30)
	v_lshlrev_b32_e32 v112, 16, v64
	v_and_b32_e32 v113, 0xffff0000, v64
	v_lshlrev_b32_e32 v114, 16, v65
	v_and_b32_e32 v115, 0xffff0000, v65
	v_lshlrev_b32_e32 v116, 16, v66
	v_and_b32_e32 v117, 0xffff0000, v66
	v_lshlrev_b32_e32 v118, 16, v67
	v_and_b32_e32 v119, 0xffff0000, v67
	v_lshlrev_b32_e32 v120, 16, v68
	v_and_b32_e32 v121, 0xffff0000, v68
	v_lshlrev_b32_e32 v122, 16, v69
	v_and_b32_e32 v123, 0xffff0000, v69
	v_lshlrev_b32_e32 v124, 16, v70
	v_and_b32_e32 v125, 0xffff0000, v70
	v_lshlrev_b32_e32 v126, 16, v71
	v_and_b32_e32 v127, 0xffff0000, v71
	v_pk_mul_f32 v[130:131], v[112:113], v[112:113]
	v_pk_fma_f32 v[130:131], v[114:115], v[114:115], v[130:131]
	v_pk_fma_f32 v[130:131], v[116:117], v[116:117], v[130:131]
	v_pk_fma_f32 v[130:131], v[118:119], v[118:119], v[130:131]
	v_pk_fma_f32 v[130:131], v[120:121], v[120:121], v[130:131]
	v_pk_fma_f32 v[130:131], v[122:123], v[122:123], v[130:131]
	v_pk_fma_f32 v[130:131], v[124:125], v[124:125], v[130:131]
	v_pk_fma_f32 v[130:131], v[126:127], v[126:127], v[130:131]
	s_nop 0
	v_add_f32_e32 v130, v130, v131
	s_nop 1
	v_add_f32_dpp v128, v128, v128 quad_perm:[1,0,3,2] row_mask:0xf bank_mask:0xf
	v_add_f32_dpp v130, v130, v130 quad_perm:[1,0,3,2] row_mask:0xf bank_mask:0xf
	s_nop 0
	v_add_f32_dpp v128, v128, v128 quad_perm:[2,3,0,1] row_mask:0xf bank_mask:0xf
	v_add_f32_dpp v130, v130, v130 quad_perm:[2,3,0,1] row_mask:0xf bank_mask:0xf
	s_nop 0
	v_add_f32_dpp v128, v128, v128 row_half_mirror row_mask:0xf bank_mask:0xf
	v_add_f32_dpp v130, v130, v130 row_half_mirror row_mask:0xf bank_mask:0xf
	s_nop 0
	v_add_f32_dpp v128, v128, v128 row_mirror row_mask:0xf bank_mask:0xf
	v_add_f32_dpp v130, v130, v130 row_mirror row_mask:0xf bank_mask:0xf
	s_nop 0
	ds_bpermute_b32 v136, v187, v128
	ds_bpermute_b32 v137, v187, v130
	s_waitcnt lgkmcnt(0)
	v_add_f32_e32 v128, v128, v136
	v_add_f32_e32 v130, v130, v137
	ds_bpermute_b32 v136, v188, v128
	ds_bpermute_b32 v137, v188, v130
	s_waitcnt lgkmcnt(0)
;     __device__ __forceinline__ float* out() const { return (float*)karg_in(33); }
; __device__ __forceinline__ const float* xrow_ptr(const Ctx& C, int row) { return row < MPROMPT ? C.in(0) + (size_t)row * DM : C.in(1) + (size_t)(row - MPROMPT) * DM; }
; __device__ __forceinline__ v4f ld4_bf16(const bf16* p) { const v2u w = *(const v2u*)p; return (v4f){bf_lo(w.x), bf_hi(w.x), bf_lo(w.y), bf_hi(w.y)}; }
; template <int R, bool BASE_F32, bool OUT_F32>
; __device__ __forceinline__ void rows_res(const Ctx& C, int m0, int stride, int mx, const float* gpost, float scale, int lane) {
;     ...
;     for (int r = 0; r < R; ++r) { mr[r] = (r == 4) ? mx : m0 + r * stride; ok[r] = (r == 4) ? (mx < M) : (mr[r] < MPROMPT); const int mm = ok[r] ? mr[r] : 0;
; #pragma unroll
;         for (int j = 0; j < 4; ++j) d[r][j] = ld4_bf16(D + (size_t)mm * DM + 4 * lane + 256 * j);
;         if (BASE_F32) { const float* x = xrow_ptr(C, mm);
; #pragma unroll
;             for (int j = 0; j < 4; ++j) b[r][j] = ld4_f32(x + 4 * lane + 256 * j);
;         } else { const float inv = C.RS()[mm];
; #pragma unroll
;             for (int j = 0; j < 4; ++j) b[r][j] = ld4_bf16(XN + (size_t)mm * DM + 4 * lane + 256 * j) * inv;
;         } }
;     ...
;     for (int r = 0; r < R; ++r) r1[r] = rsqrtf(wave_sum(r1[r]) * (1.f / DM) + EPS) * scale;
; #pragma unroll
;     for (int j = 0; j < 4; ++j) { const v4f gp = ld4_f32(gpost + 4 * lane + 256 * j);
; #pragma unroll
;         for (int r = 0; r < R; ++r) d[r][j] = b[r][j] + d[r][j] * r1[r] * gp; }
;     if (OUT_F32) { float* Y = C.out();
; #pragma unroll
;         for (int r = 0; r < R; ++r)
; #pragma unroll
;             for (int j = 0; j < 4; ++j) if (ok[r]) *(v4f*)(Y + (size_t)mr[r] * DM + 4 * lane + 256 * j) = d[r][j];
	v_add_f32_e32 v128, v128, v136
	v_add_f32_e32 v130, v130, v137
	v_fmamk_f32 v128, v128, 0x3a800000, v138
	v_fmamk_f32 v130, v130, 0x3a800000, v138
	s_nop 0
	v_rsq_f32_e32 v128, v128
	v_rsq_f32_e32 v130, v130
	s_nop 1
	v_mul_f32_e32 v128, 0.5, v128
	v_mul_f32_e32 v130, 0.5, v130
	s_waitcnt vmcnt(26)
	v_pk_mul_f32 v[96:97], v[128:129], v[96:97] op_sel_hi:[0,1]
	v_pk_mul_f32 v[98:99], v[128:129], v[98:99] op_sel_hi:[0,1]
	v_pk_mul_f32 v[100:101], v[128:129], v[100:101] op_sel_hi:[0,1]
	v_pk_mul_f32 v[102:103], v[128:129], v[102:103] op_sel_hi:[0,1]
	v_pk_mul_f32 v[104:105], v[128:129], v[104:105] op_sel_hi:[0,1]
	v_pk_mul_f32 v[106:107], v[128:129], v[106:107] op_sel_hi:[0,1]
	v_pk_mul_f32 v[108:109], v[128:129], v[108:109] op_sel_hi:[0,1]
	v_pk_mul_f32 v[110:111], v[128:129], v[110:111] op_sel_hi:[0,1]
	v_pk_mul_f32 v[96:97], v[96:97], v[192:193]
	v_pk_mul_f32 v[98:99], v[98:99], v[194:195]
	v_pk_mul_f32 v[100:101], v[100:101], v[196:197]
	v_pk_mul_f32 v[102:103], v[102:103], v[198:199]
	v_pk_mul_f32 v[104:105], v[104:105], v[200:201]
	v_pk_mul_f32 v[106:107], v[106:107], v[202:203]
	v_pk_mul_f32 v[108:109], v[108:109], v[204:205]
	v_pk_mul_f32 v[110:111], v[110:111], v[206:207]
	v_lshlrev_b32_e32 v56, 16, v72
	v_and_b32_e32 v57, 0xffff0000, v72
	v_lshlrev_b32_e32 v58, 16, v73
	v_and_b32_e32 v59, 0xffff0000, v73
	v_lshlrev_b32_e32 v60, 16, v74
	v_and_b32_e32 v61, 0xffff0000, v74
	v_lshlrev_b32_e32 v62, 16, v75
	v_and_b32_e32 v63, 0xffff0000, v75
	v_pk_fma_f32 v[96:97], v[88:89], v[56:57], v[96:97] op_sel_hi:[0,1,1]
	v_pk_fma_f32 v[98:99], v[88:89], v[58:59], v[98:99] op_sel_hi:[0,1,1]
	v_pk_fma_f32 v[100:101], v[88:89], v[60:61], v[100:101] op_sel_hi:[0,1,1]
	v_pk_fma_f32 v[102:103], v[88:89], v[62:63], v[102:103] op_sel_hi:[0,1,1]
	v_lshlrev_b32_e32 v56, 16, v76
	v_and_b32_e32 v57, 0xffff0000, v76
	v_lshlrev_b32_e32 v58, 16, v77
	v_and_b32_e32 v59, 0xffff0000, v77
	v_lshlrev_b32_e32 v60, 16, v78
	v_and_b32_e32 v61, 0xffff0000, v78
	v_lshlrev_b32_e32 v62, 16, v79
	v_and_b32_e32 v63, 0xffff0000, v79
	v_pk_fma_f32 v[104:105], v[88:89], v[56:57], v[104:105] op_sel_hi:[0,1,1]
	v_pk_fma_f32 v[106:107], v[88:89], v[58:59], v[106:107] op_sel_hi:[0,1,1]
	v_pk_fma_f32 v[108:109], v[88:89], v[60:61], v[108:109] op_sel_hi:[0,1,1]
	v_pk_fma_f32 v[110:111], v[88:89], v[62:63], v[110:111] op_sel_hi:[0,1,1]
	global_store_dwordx4 v175, v[96:99], s[100:101]
	global_store_dwordx4 v175, v[100:103], s[100:101] offset:1024
	global_store_dwordx4 v175, v[104:107], s[100:101] offset:2048
	global_store_dwordx4 v175, v[108:111], s[100:101] offset:3072
	v_add_u32_e32 v175, 0x800000, v175
	v_pk_mul_f32 v[112:113], v[130:131], v[112:113] op_sel_hi:[0,1]
	v_pk_mul_f32 v[114:115], v[130:131], v[114:115] op_sel_hi:[0,1]
	v_pk_mul_f32 v[116:117], v[130:131], v[116:117] op_sel_hi:[0,1]
	v_pk_mul_f32 v[118:119], v[130:131], v[118:119] op_sel_hi:[0,1]
	v_pk_mul_f32 v[120:121], v[130:131], v[120:121] op_sel_hi:[0,1]
	v_pk_mul_f32 v[122:123], v[130:131], v[122:123] op_sel_hi:[0,1]
	v_pk_mul_f32 v[124:125], v[130:131], v[124:125] op_sel_hi:[0,1]
	v_pk_mul_f32 v[126:127], v[130:131], v[126:127] op_sel_hi:[0,1]
	v_pk_mul_f32 v[112:113], v[112:113], v[192:193]
	v_pk_mul_f32 v[114:115], v[114:115], v[194:195]
	v_pk_mul_f32 v[116:117], v[116:117], v[196:197]
	v_pk_mul_f32 v[118:119], v[118:119], v[198:199]
	v_pk_mul_f32 v[120:121], v[120:121], v[200:201]
	v_pk_mul_f32 v[122:123], v[122:123], v[202:203]
	v_pk_mul_f32 v[124:125], v[124:125], v[204:205]
	v_pk_mul_f32 v[126:127], v[126:127], v[206:207]
	v_lshlrev_b32_e32 v64, 16, v80
	v_and_b32_e32 v65, 0xffff0000, v80
	v_lshlrev_b32_e32 v66, 16, v81
	v_and_b32_e32 v67, 0xffff0000, v81
	v_lshlrev_b32_e32 v68, 16, v82
	v_and_b32_e32 v69, 0xffff0000, v82
	v_lshlrev_b32_e32 v70, 16, v83
	v_and_b32_e32 v71, 0xffff0000, v83
	v_pk_fma_f32 v[112:113], v[90:91], v[64:65], v[112:113] op_sel_hi:[0,1,1]
	v_pk_fma_f32 v[114:115], v[90:91], v[66:67], v[114:115] op_sel_hi:[0,1,1]
	v_pk_fma_f32 v[116:117], v[90:91], v[68:69], v[116:117] op_sel_hi:[0,1,1]
	v_pk_fma_f32 v[118:119], v[90:91], v[70:71], v[118:119] op_sel_hi:[0,1,1]
	v_lshlrev_b32_e32 v64, 16, v84
	v_and_b32_e32 v65, 0xffff0000, v84
	v_lshlrev_b32_e32 v66, 16, v85
	v_and_b32_e32 v67, 0xffff0000, v85
	v_lshlrev_b32_e32 v68, 16, v86
	v_and_b32_e32 v69, 0xffff0000, v86
	v_lshlrev_b32_e32 v70, 16, v87
	v_and_b32_e32 v71, 0xffff0000, v87
	v_pk_fma_f32 v[120:121], v[90:91], v[64:65], v[120:121] op_sel_hi:[0,1,1]
	v_pk_fma_f32 v[122:123], v[90:91], v[66:67], v[122:123] op_sel_hi:[0,1,1]
	v_pk_fma_f32 v[124:125], v[90:91], v[68:69], v[124:125] op_sel_hi:[0,1,1]
	v_pk_fma_f32 v[126:127], v[90:91], v[70:71], v[126:127] op_sel_hi:[0,1,1]
	global_store_dwordx4 v175, v[112:115], s[100:101]
	global_store_dwordx4 v175, v[116:119], s[100:101] offset:1024
	global_store_dwordx4 v175, v[120:123], s[100:101] offset:2048
	global_store_dwordx4 v175, v[124:127], s[100:101] offset:3072
	v_add_u32_e32 v175, 0x800000, v175
	global_load_dword v88, v172, s[98:99]
	global_load_dwordx2 v[56:57], v170, s[98:99]
	global_load_dwordx2 v[58:59], v170, s[98:99] offset:512
	global_load_dwordx2 v[60:61], v170, s[98:99] offset:1024
	global_load_dwordx2 v[62:63], v170, s[98:99] offset:1536
	global_load_dwordx2 v[72:73], v171, s[98:99]
	global_load_dwordx2 v[74:75], v171, s[98:99] offset:512
	global_load_dwordx2 v[76:77], v171, s[98:99] offset:1024
	global_load_dwordx2 v[78:79], v171, s[98:99] offset:1536
	v_add_u32_e32 v170, 0x400000, v170
	v_add_u32_e32 v171, 0x400000, v171
	v_add_u32_e32 v172, 0x2000, v172
	global_load_dword v90, v172, s[98:99]
	global_load_dwordx2 v[64:65], v170, s[98:99]
	global_load_dwordx2 v[66:67], v170, s[98:99] offset:512
	global_load_dwordx2 v[68:69], v170, s[98:99] offset:1024
	global_load_dwordx2 v[70:71], v170, s[98:99] offset:1536
	global_load_dwordx2 v[80:81], v171, s[98:99]
	global_load_dwordx2 v[82:83], v171, s[98:99] offset:512
	global_load_dwordx2 v[84:85], v171, s[98:99] offset:1024
	global_load_dwordx2 v[86:87], v171, s[98:99] offset:1536
	v_add_u32_e32 v170, 0x400000, v170
	v_add_u32_e32 v171, 0x400000, v171
	v_add_u32_e32 v172, 0x2000, v172
	s_waitcnt vmcnt(39)
;     __device__ __forceinline__ float* out() const { return (float*)karg_in(33); }
; __device__ __forceinline__ float ssq4(v4f v) { return (v.x * v.x + v.y * v.y) + (v.z * v.z + v.w * v.w); }
; template <int R, bool BASE_F32, bool OUT_F32>
; __device__ __forceinline__ void rows_res(const Ctx& C, int m0, int stride, int mx, const float* gpost, float scale, int lane) {
;     ...
;     for (int r = 0; r < R; ++r) { float s = 0.f;
; #pragma unroll
;         for (int j = 0; j < 4; ++j) s += ssq4(d[r][j]);
;         r1[r] = s; }
; #pragma unroll
;     for (int r = 0; r < R; ++r) r1[r] = rsqrtf(wave_sum(r1[r]) * (1.f / DM) + EPS) * scale;
; #pragma unroll
;     for (int j = 0; j < 4; ++j) { const v4f gp = ld4_f32(gpost + 4 * lane + 256 * j);
; #pragma unroll
;         for (int r = 0; r < R; ++r) d[r][j] = b[r][j] + d[r][j] * r1[r] * gp; }
;     if (OUT_F32) { float* Y = C.out();
; #pragma unroll
;         for (int r = 0; r < R; ++r)
; #pragma unroll
;             for (int j = 0; j < 4; ++j) if (ok[r]) *(v4f*)(Y + (size_t)mr[r] * DM + 4 * lane + 256 * j) = d[r][j];
	v_lshlrev_b32_e32 v96, 16, v20
	v_and_b32_e32 v97, 0xffff0000, v20
	v_lshlrev_b32_e32 v98, 16, v21
	v_and_b32_e32 v99, 0xffff0000, v21
	v_lshlrev_b32_e32 v100, 16, v22
	v_and_b32_e32 v101, 0xffff0000, v22
	v_lshlrev_b32_e32 v102, 16, v23
	v_and_b32_e32 v103, 0xffff0000, v23
	v_lshlrev_b32_e32 v104, 16, v24
	v_and_b32_e32 v105, 0xffff0000, v24
	v_lshlrev_b32_e32 v106, 16, v25
	v_and_b32_e32 v107, 0xffff0000, v25
	v_lshlrev_b32_e32 v108, 16, v26
	v_and_b32_e32 v109, 0xffff0000, v26
	v_lshlrev_b32_e32 v110, 16, v27
	v_and_b32_e32 v111, 0xffff0000, v27
	v_pk_mul_f32 v[128:129], v[96:97], v[96:97]
	v_pk_fma_f32 v[128:129], v[98:99], v[98:99], v[128:129]
	v_pk_fma_f32 v[128:129], v[100:101], v[100:101], v[128:129]
	v_pk_fma_f32 v[128:129], v[102:103], v[102:103], v[128:129]
	v_pk_fma_f32 v[128:129], v[104:105], v[104:105], v[128:129]
	v_pk_fma_f32 v[128:129], v[106:107], v[106:107], v[128:129]
	v_pk_fma_f32 v[128:129], v[108:109], v[108:109], v[128:129]
	v_pk_fma_f32 v[128:129], v[110:111], v[110:111], v[128:129]
	s_nop 0
	v_add_f32_e32 v128, v128, v129
	s_waitcnt vmcnt(30)
	v_lshlrev_b32_e32 v112, 16, v28
	v_and_b32_e32 v113, 0xffff0000, v28
	v_lshlrev_b32_e32 v114, 16, v29
	v_and_b32_e32 v115, 0xffff0000, v29
	v_lshlrev_b32_e32 v116, 16, v30
	v_and_b32_e32 v117, 0xffff0000, v30
	v_lshlrev_b32_e32 v118, 16, v31
	v_and_b32_e32 v119, 0xffff0000, v31
	v_lshlrev_b32_e32 v120, 16, v32
	v_and_b32_e32 v121, 0xffff0000, v32
	v_lshlrev_b32_e32 v122, 16, v33
	v_and_b32_e32 v123, 0xffff0000, v33
	v_lshlrev_b32_e32 v124, 16, v34
	v_and_b32_e32 v125, 0xffff0000, v34
	v_lshlrev_b32_e32 v126, 16, v35
	v_and_b32_e32 v127, 0xffff0000, v35
	v_pk_mul_f32 v[130:131], v[112:113], v[112:113]
	v_pk_fma_f32 v[130:131], v[114:115], v[114:115], v[130:131]
	v_pk_fma_f32 v[130:131], v[116:117], v[116:117], v[130:131]
	v_pk_fma_f32 v[130:131], v[118:119], v[118:119], v[130:131]
	v_pk_fma_f32 v[130:131], v[120:121], v[120:121], v[130:131]
	v_pk_fma_f32 v[130:131], v[122:123], v[122:123], v[130:131]
	v_pk_fma_f32 v[130:131], v[124:125], v[124:125], v[130:131]
	v_pk_fma_f32 v[130:131], v[126:127], v[126:127], v[130:131]
	s_nop 0
	v_add_f32_e32 v130, v130, v131
	s_nop 1
	v_add_f32_dpp v128, v128, v128 quad_perm:[1,0,3,2] row_mask:0xf bank_mask:0xf
	v_add_f32_dpp v130, v130, v130 quad_perm:[1,0,3,2] row_mask:0xf bank_mask:0xf
	s_nop 0
	v_add_f32_dpp v128, v128, v128 quad_perm:[2,3,0,1] row_mask:0xf bank_mask:0xf
	v_add_f32_dpp v130, v130, v130 quad_perm:[2,3,0,1] row_mask:0xf bank_mask:0xf
	s_nop 0
	v_add_f32_dpp v128, v128, v128 row_half_mirror row_mask:0xf bank_mask:0xf
	v_add_f32_dpp v130, v130, v130 row_half_mirror row_mask:0xf bank_mask:0xf
	s_nop 0
	v_add_f32_dpp v128, v128, v128 row_mirror row_mask:0xf bank_mask:0xf
	v_add_f32_dpp v130, v130, v130 row_mirror row_mask:0xf bank_mask:0xf
	s_nop 0
	ds_bpermute_b32 v136, v187, v128
	ds_bpermute_b32 v137, v187, v130
	s_waitcnt lgkmcnt(0)
	v_add_f32_e32 v128, v128, v136
	v_add_f32_e32 v130, v130, v137
	ds_bpermute_b32 v136, v188, v128
	ds_bpermute_b32 v137, v188, v130
	s_waitcnt lgkmcnt(0)
	v_add_f32_e32 v128, v128, v136
	v_add_f32_e32 v130, v130, v137
	v_fmamk_f32 v128, v128, 0x3a800000, v138
	v_fmamk_f32 v130, v130, 0x3a800000, v138
	s_nop 0
	v_rsq_f32_e32 v128, v128
	v_rsq_f32_e32 v130, v130
	s_nop 1
	v_mul_f32_e32 v128, 0.5, v128
	v_mul_f32_e32 v130, 0.5, v130
	s_waitcnt vmcnt(26)
	v_pk_mul_f32 v[96:97], v[128:129], v[96:97] op_sel_hi:[0,1]
	v_pk_mul_f32 v[98:99], v[128:129], v[98:99] op_sel_hi:[0,1]
	v_pk_mul_f32 v[100:101], v[128:129], v[100:101] op_sel_hi:[0,1]
	v_pk_mul_f32 v[102:103], v[128:129], v[102:103] op_sel_hi:[0,1]
	v_pk_mul_f32 v[104:105], v[128:129], v[104:105] op_sel_hi:[0,1]
	v_pk_mul_f32 v[106:107], v[128:129], v[106:107] op_sel_hi:[0,1]
	v_pk_mul_f32 v[108:109], v[128:129], v[108:109] op_sel_hi:[0,1]
	v_pk_mul_f32 v[110:111], v[128:129], v[110:111] op_sel_hi:[0,1]
	v_pk_mul_f32 v[96:97], v[96:97], v[192:193]
	v_pk_mul_f32 v[98:99], v[98:99], v[194:195]
	v_pk_mul_f32 v[100:101], v[100:101], v[196:197]
	v_pk_mul_f32 v[102:103], v[102:103], v[198:199]
	v_pk_mul_f32 v[104:105], v[104:105], v[200:201]
	v_pk_mul_f32 v[106:107], v[106:107], v[202:203]
	v_pk_mul_f32 v[108:109], v[108:109], v[204:205]
	v_pk_mul_f32 v[110:111], v[110:111], v[206:207]
	v_lshlrev_b32_e32 v20, 16, v36
	v_and_b32_e32 v21, 0xffff0000, v36
	v_lshlrev_b32_e32 v22, 16, v37
	v_and_b32_e32 v23, 0xffff0000, v37
	v_lshlrev_b32_e32 v24, 16, v38
	v_and_b32_e32 v25, 0xffff0000, v38
	v_lshlrev_b32_e32 v26, 16, v39
	v_and_b32_e32 v27, 0xffff0000, v39
	v_pk_fma_f32 v[96:97], v[52:53], v[20:21], v[96:97] op_sel_hi:[0,1,1]
	v_pk_fma_f32 v[98:99], v[52:53], v[22:23], v[98:99] op_sel_hi:[0,1,1]
	v_pk_fma_f32 v[100:101], v[52:53], v[24:25], v[100:101] op_sel_hi:[0,1,1]
	v_pk_fma_f32 v[102:103], v[52:53], v[26:27], v[102:103] op_sel_hi:[0,1,1]
	v_lshlrev_b32_e32 v20, 16, v40
	v_and_b32_e32 v21, 0xffff0000, v40
	v_lshlrev_b32_e32 v22, 16, v41
	v_and_b32_e32 v23, 0xffff0000, v41
	v_lshlrev_b32_e32 v24, 16, v42
	v_and_b32_e32 v25, 0xffff0000, v42
	v_lshlrev_b32_e32 v26, 16, v43
	v_and_b32_e32 v27, 0xffff0000, v43
	v_pk_fma_f32 v[104:105], v[52:53], v[20:21], v[104:105] op_sel_hi:[0,1,1]
	v_pk_fma_f32 v[106:107], v[52:53], v[22:23], v[106:107] op_sel_hi:[0,1,1]
	v_pk_fma_f32 v[108:109], v[52:53], v[24:25], v[108:109] op_sel_hi:[0,1,1]
	v_pk_fma_f32 v[110:111], v[52:53], v[26:27], v[110:111] op_sel_hi:[0,1,1]
	global_store_dwordx4 v175, v[96:99], s[100:101]
	global_store_dwordx4 v175, v[100:103], s[100:101] offset:1024
	global_store_dwordx4 v175, v[104:107], s[100:101] offset:2048
	global_store_dwordx4 v175, v[108:111], s[100:101] offset:3072
;     __device__ __forceinline__ float* out() const { return (float*)karg_in(33); }
; __device__ __forceinline__ const float* xrow_ptr(const Ctx& C, int row) { return row < MPROMPT ? C.in(0) + (size_t)row * DM : C.in(1) + (size_t)(row - MPROMPT) * DM; }
; __device__ __forceinline__ v4f ld4_bf16(const bf16* p) { const v2u w = *(const v2u*)p; return (v4f){bf_lo(w.x), bf_hi(w.x), bf_lo(w.y), bf_hi(w.y)}; }
; __device__ __forceinline__ float ssq4(v4f v) { return (v.x * v.x + v.y * v.y) + (v.z * v.z + v.w * v.w); }
; template <int R, bool BASE_F32, bool OUT_F32>
; __device__ __forceinline__ void rows_res(const Ctx& C, int m0, int stride, int mx, const float* gpost, float scale, int lane) {
;     ...
;     for (int r = 0; r < R; ++r) { mr[r] = (r == 4) ? mx : m0 + r * stride; ok[r] = (r == 4) ? (mx < M) : (mr[r] < MPROMPT); const int mm = ok[r] ? mr[r] : 0;
; #pragma unroll
;         for (int j = 0; j < 4; ++j) d[r][j] = ld4_bf16(D + (size_t)mm * DM + 4 * lane + 256 * j);
;         if (BASE_F32) { const float* x = xrow_ptr(C, mm);
; #pragma unroll
;             for (int j = 0; j < 4; ++j) b[r][j] = ld4_f32(x + 4 * lane + 256 * j);
;         } else { const float inv = C.RS()[mm];
; #pragma unroll
;             for (int j = 0; j < 4; ++j) b[r][j] = ld4_bf16(XN + (size_t)mm * DM + 4 * lane + 256 * j) * inv;
;         } }
; #pragma unroll
;     for (int r = 0; r < R; ++r) { float s = 0.f;
; #pragma unroll
;         for (int j = 0; j < 4; ++j) s += ssq4(d[r][j]);
;         r1[r] = s; }
;     ...
;     for (int j = 0; j < 4; ++j) { const v4f gp = ld4_f32(gpost + 4 * lane + 256 * j);
; #pragma unroll
;         for (int r = 0; r < R; ++r) d[r][j] = b[r][j] + d[r][j] * r1[r] * gp; }
;     if (OUT_F32) { float* Y = C.out();
; #pragma unroll
;         for (int r = 0; r < R; ++r)
; #pragma unroll
;             for (int j = 0; j < 4; ++j) if (ok[r]) *(v4f*)(Y + (size_t)mr[r] * DM + 4 * lane + 256 * j) = d[r][j];
	v_add_u32_e32 v175, 0x800000, v175
	v_pk_mul_f32 v[112:113], v[130:131], v[112:113] op_sel_hi:[0,1]
	v_pk_mul_f32 v[114:115], v[130:131], v[114:115] op_sel_hi:[0,1]
	v_pk_mul_f32 v[116:117], v[130:131], v[116:117] op_sel_hi:[0,1]
	v_pk_mul_f32 v[118:119], v[130:131], v[118:119] op_sel_hi:[0,1]
	v_pk_mul_f32 v[120:121], v[130:131], v[120:121] op_sel_hi:[0,1]
	v_pk_mul_f32 v[122:123], v[130:131], v[122:123] op_sel_hi:[0,1]
	v_pk_mul_f32 v[124:125], v[130:131], v[124:125] op_sel_hi:[0,1]
	v_pk_mul_f32 v[126:127], v[130:131], v[126:127] op_sel_hi:[0,1]
	v_pk_mul_f32 v[112:113], v[112:113], v[192:193]
	v_pk_mul_f32 v[114:115], v[114:115], v[194:195]
	v_pk_mul_f32 v[116:117], v[116:117], v[196:197]
	v_pk_mul_f32 v[118:119], v[118:119], v[198:199]
	v_pk_mul_f32 v[120:121], v[120:121], v[200:201]
	v_pk_mul_f32 v[122:123], v[122:123], v[202:203]
	v_pk_mul_f32 v[124:125], v[124:125], v[204:205]
	v_pk_mul_f32 v[126:127], v[126:127], v[206:207]
	v_lshlrev_b32_e32 v28, 16, v44
	v_and_b32_e32 v29, 0xffff0000, v44
	v_lshlrev_b32_e32 v30, 16, v45
	v_and_b32_e32 v31, 0xffff0000, v45
	v_lshlrev_b32_e32 v32, 16, v46
	v_and_b32_e32 v33, 0xffff0000, v46
	v_lshlrev_b32_e32 v34, 16, v47
	v_and_b32_e32 v35, 0xffff0000, v47
	v_pk_fma_f32 v[112:113], v[54:55], v[28:29], v[112:113] op_sel_hi:[0,1,1]
	v_pk_fma_f32 v[114:115], v[54:55], v[30:31], v[114:115] op_sel_hi:[0,1,1]
	v_pk_fma_f32 v[116:117], v[54:55], v[32:33], v[116:117] op_sel_hi:[0,1,1]
	v_pk_fma_f32 v[118:119], v[54:55], v[34:35], v[118:119] op_sel_hi:[0,1,1]
	v_lshlrev_b32_e32 v28, 16, v48
	v_and_b32_e32 v29, 0xffff0000, v48
	v_lshlrev_b32_e32 v30, 16, v49
	v_and_b32_e32 v31, 0xffff0000, v49
	v_lshlrev_b32_e32 v32, 16, v50
	v_and_b32_e32 v33, 0xffff0000, v50
	v_lshlrev_b32_e32 v34, 16, v51
	v_and_b32_e32 v35, 0xffff0000, v51
	v_pk_fma_f32 v[120:121], v[54:55], v[28:29], v[120:121] op_sel_hi:[0,1,1]
	v_pk_fma_f32 v[122:123], v[54:55], v[30:31], v[122:123] op_sel_hi:[0,1,1]
	v_pk_fma_f32 v[124:125], v[54:55], v[32:33], v[124:125] op_sel_hi:[0,1,1]
	v_pk_fma_f32 v[126:127], v[54:55], v[34:35], v[126:127] op_sel_hi:[0,1,1]
	global_store_dwordx4 v175, v[112:115], s[100:101]
	global_store_dwordx4 v175, v[116:119], s[100:101] offset:1024
	global_store_dwordx4 v175, v[120:123], s[100:101] offset:2048
	global_store_dwordx4 v175, v[124:127], s[100:101] offset:3072
	v_add_u32_e32 v175, 0x800000, v175
	global_load_dword v52, v172, s[98:99]
	global_load_dwordx2 v[20:21], v170, s[98:99]
	global_load_dwordx2 v[22:23], v170, s[98:99] offset:512
	global_load_dwordx2 v[24:25], v170, s[98:99] offset:1024
	global_load_dwordx2 v[26:27], v170, s[98:99] offset:1536
	global_load_dwordx2 v[36:37], v171, s[98:99]
	global_load_dwordx2 v[38:39], v171, s[98:99] offset:512
	global_load_dwordx2 v[40:41], v171, s[98:99] offset:1024
	global_load_dwordx2 v[42:43], v171, s[98:99] offset:1536
	v_add_u32_e32 v170, 0x400000, v170
	v_add_u32_e32 v171, 0x400000, v171
	v_add_u32_e32 v172, 0x2000, v172
	global_load_dword v54, v172, s[98:99]
	global_load_dwordx2 v[28:29], v170, s[98:99]
	global_load_dwordx2 v[30:31], v170, s[98:99] offset:512
	global_load_dwordx2 v[32:33], v170, s[98:99] offset:1024
	global_load_dwordx2 v[34:35], v170, s[98:99] offset:1536
	global_load_dwordx2 v[44:45], v171, s[98:99]
	global_load_dwordx2 v[46:47], v171, s[98:99] offset:512
	global_load_dwordx2 v[48:49], v171, s[98:99] offset:1024
	global_load_dwordx2 v[50:51], v171, s[98:99] offset:1536
	v_add_u32_e32 v170, 0x400000, v170
	v_add_u32_e32 v171, 0x400000, v171
	v_add_u32_e32 v172, 0x2000, v172
	s_waitcnt vmcnt(39)
	v_lshlrev_b32_e32 v96, 16, v56
	v_and_b32_e32 v97, 0xffff0000, v56
	v_lshlrev_b32_e32 v98, 16, v57
	v_and_b32_e32 v99, 0xffff0000, v57
	v_lshlrev_b32_e32 v100, 16, v58
	v_and_b32_e32 v101, 0xffff0000, v58
	v_lshlrev_b32_e32 v102, 16, v59
	v_and_b32_e32 v103, 0xffff0000, v59
	v_lshlrev_b32_e32 v104, 16, v60
	v_and_b32_e32 v105, 0xffff0000, v60
	v_lshlrev_b32_e32 v106, 16, v61
	v_and_b32_e32 v107, 0xffff0000, v61
	v_lshlrev_b32_e32 v108, 16, v62
	v_and_b32_e32 v109, 0xffff0000, v62
	v_lshlrev_b32_e32 v110, 16, v63
	v_and_b32_e32 v111, 0xffff0000, v63
	v_pk_mul_f32 v[128:129], v[96:97], v[96:97]
	v_pk_fma_f32 v[128:129], v[98:99], v[98:99], v[128:129]
	v_pk_fma_f32 v[128:129], v[100:101], v[100:101], v[128:129]
	v_pk_fma_f32 v[128:129], v[102:103], v[102:103], v[128:129]
	v_pk_fma_f32 v[128:129], v[104:105], v[104:105], v[128:129]
	v_pk_fma_f32 v[128:129], v[106:107], v[106:107], v[128:129]
	v_pk_fma_f32 v[128:129], v[108:109], v[108:109], v[128:129]
	v_pk_fma_f32 v[128:129], v[110:111], v[110:111], v[128:129]
	s_nop 0
	v_add_f32_e32 v128, v128, v129
	s_waitcnt vmcnt(30)
	v_lshlrev_b32_e32 v112, 16, v64
	v_and_b32_e32 v113, 0xffff0000, v64
	v_lshlrev_b32_e32 v114, 16, v65
	v_and_b32_e32 v115, 0xffff0000, v65
	v_lshlrev_b32_e32 v116, 16, v66
	v_and_b32_e32 v117, 0xffff0000, v66
	v_lshlrev_b32_e32 v118, 16, v67
	v_and_b32_e32 v119, 0xffff0000, v67
	v_lshlrev_b32_e32 v120, 16, v68
	v_and_b32_e32 v121, 0xffff0000, v68
	v_lshlrev_b32_e32 v122, 16, v69
	v_and_b32_e32 v123, 0xffff0000, v69
	v_lshlrev_b32_e32 v124, 16, v70
	v_and_b32_e32 v125, 0xffff0000, v70
	v_lshlrev_b32_e32 v126, 16, v71
	v_and_b32_e32 v127, 0xffff0000, v71
	v_pk_mul_f32 v[130:131], v[112:113], v[112:113]
	v_pk_fma_f32 v[130:131], v[114:115], v[114:115], v[130:131]
	v_pk_fma_f32 v[130:131], v[116:117], v[116:117], v[130:131]
	v_pk_fma_f32 v[130:131], v[118:119], v[118:119], v[130:131]
	v_pk_fma_f32 v[130:131], v[120:121], v[120:121], v[130:131]
	v_pk_fma_f32 v[130:131], v[122:123], v[122:123], v[130:131]
	v_pk_fma_f32 v[130:131], v[124:125], v[124:125], v[130:131]
	v_pk_fma_f32 v[130:131], v[126:127], v[126:127], v[130:131]
	s_nop 0
	v_add_f32_e32 v130, v130, v131
	s_nop 1
	v_add_f32_dpp v128, v128, v128 quad_perm:[1,0,3,2] row_mask:0xf bank_mask:0xf
	v_add_f32_dpp v130, v130, v130 quad_perm:[1,0,3,2] row_mask:0xf bank_mask:0xf
	s_nop 0
	v_add_f32_dpp v128, v128, v128 quad_perm:[2,3,0,1] row_mask:0xf bank_mask:0xf
	v_add_f32_dpp v130, v130, v130 quad_perm:[2,3,0,1] row_mask:0xf bank_mask:0xf
	s_nop 0
	v_add_f32_dpp v128, v128, v128 row_half_mirror row_mask:0xf bank_mask:0xf
	v_add_f32_dpp v130, v130, v130 row_half_mirror row_mask:0xf bank_mask:0xf
	s_nop 0
	v_add_f32_dpp v128, v128, v128 row_mirror row_mask:0xf bank_mask:0xf
	v_add_f32_dpp v130, v130, v130 row_mirror row_mask:0xf bank_mask:0xf
	s_nop 0
	ds_bpermute_b32 v136, v187, v128
	ds_bpermute_b32 v137, v187, v130
	s_waitcnt lgkmcnt(0)
;     __device__ __forceinline__ float* out() const { return (float*)karg_in(33); }
; __device__ __forceinline__ const float* xrow_ptr(const Ctx& C, int row) { return row < MPROMPT ? C.in(0) + (size_t)row * DM : C.in(1) + (size_t)(row - MPROMPT) * DM; }
; __device__ __forceinline__ v4f ld4_bf16(const bf16* p) { const v2u w = *(const v2u*)p; return (v4f){bf_lo(w.x), bf_hi(w.x), bf_lo(w.y), bf_hi(w.y)}; }
; template <int R, bool BASE_F32, bool OUT_F32>
; __device__ __forceinline__ void rows_res(const Ctx& C, int m0, int stride, int mx, const float* gpost, float scale, int lane) {
;     ...
;     for (int r = 0; r < R; ++r) { mr[r] = (r == 4) ? mx : m0 + r * stride; ok[r] = (r == 4) ? (mx < M) : (mr[r] < MPROMPT); const int mm = ok[r] ? mr[r] : 0;
; #pragma unroll
;         for (int j = 0; j < 4; ++j) d[r][j] = ld4_bf16(D + (size_t)mm * DM + 4 * lane + 256 * j);
;         if (BASE_F32) { const float* x = xrow_ptr(C, mm);
; #pragma unroll
;             for (int j = 0; j < 4; ++j) b[r][j] = ld4_f32(x + 4 * lane + 256 * j);
;         } else { const float inv = C.RS()[mm];
; #pragma unroll
;             for (int j = 0; j < 4; ++j) b[r][j] = ld4_bf16(XN + (size_t)mm * DM + 4 * lane + 256 * j) * inv;
;         } }
;     ...
;     for (int r = 0; r < R; ++r) r1[r] = rsqrtf(wave_sum(r1[r]) * (1.f / DM) + EPS) * scale;
; #pragma unroll
;     for (int j = 0; j < 4; ++j) { const v4f gp = ld4_f32(gpost + 4 * lane + 256 * j);
; #pragma unroll
;         for (int r = 0; r < R; ++r) d[r][j] = b[r][j] + d[r][j] * r1[r] * gp; }
;     if (OUT_F32) { float* Y = C.out();
; #pragma unroll
;         for (int r = 0; r < R; ++r)
; #pragma unroll
;             for (int j = 0; j < 4; ++j) if (ok[r]) *(v4f*)(Y + (size_t)mr[r] * DM + 4 * lane + 256 * j) = d[r][j];
	v_add_f32_e32 v128, v128, v136
	v_add_f32_e32 v130, v130, v137
	ds_bpermute_b32 v136, v188, v128
	ds_bpermute_b32 v137, v188, v130
	s_waitcnt lgkmcnt(0)
	v_add_f32_e32 v128, v128, v136
	v_add_f32_e32 v130, v130, v137
	v_fmamk_f32 v128, v128, 0x3a800000, v138
	v_fmamk_f32 v130, v130, 0x3a800000, v138
	s_nop 0
	v_rsq_f32_e32 v128, v128
	v_rsq_f32_e32 v130, v130
	s_nop 1
	v_mul_f32_e32 v128, 0.5, v128
	v_mul_f32_e32 v130, 0.5, v130
	s_waitcnt vmcnt(26)
	v_pk_mul_f32 v[96:97], v[128:129], v[96:97] op_sel_hi:[0,1]
	v_pk_mul_f32 v[98:99], v[128:129], v[98:99] op_sel_hi:[0,1]
	v_pk_mul_f32 v[100:101], v[128:129], v[100:101] op_sel_hi:[0,1]
	v_pk_mul_f32 v[102:103], v[128:129], v[102:103] op_sel_hi:[0,1]
	v_pk_mul_f32 v[104:105], v[128:129], v[104:105] op_sel_hi:[0,1]
	v_pk_mul_f32 v[106:107], v[128:129], v[106:107] op_sel_hi:[0,1]
	v_pk_mul_f32 v[108:109], v[128:129], v[108:109] op_sel_hi:[0,1]
	v_pk_mul_f32 v[110:111], v[128:129], v[110:111] op_sel_hi:[0,1]
	v_pk_mul_f32 v[96:97], v[96:97], v[192:193]
	v_pk_mul_f32 v[98:99], v[98:99], v[194:195]
	v_pk_mul_f32 v[100:101], v[100:101], v[196:197]
	v_pk_mul_f32 v[102:103], v[102:103], v[198:199]
	v_pk_mul_f32 v[104:105], v[104:105], v[200:201]
	v_pk_mul_f32 v[106:107], v[106:107], v[202:203]
	v_pk_mul_f32 v[108:109], v[108:109], v[204:205]
	v_pk_mul_f32 v[110:111], v[110:111], v[206:207]
	v_lshlrev_b32_e32 v56, 16, v72
	v_and_b32_e32 v57, 0xffff0000, v72
	v_lshlrev_b32_e32 v58, 16, v73
	v_and_b32_e32 v59, 0xffff0000, v73
	v_lshlrev_b32_e32 v60, 16, v74
	v_and_b32_e32 v61, 0xffff0000, v74
	v_lshlrev_b32_e32 v62, 16, v75
	v_and_b32_e32 v63, 0xffff0000, v75
	v_pk_fma_f32 v[96:97], v[88:89], v[56:57], v[96:97] op_sel_hi:[0,1,1]
	v_pk_fma_f32 v[98:99], v[88:89], v[58:59], v[98:99] op_sel_hi:[0,1,1]
	v_pk_fma_f32 v[100:101], v[88:89], v[60:61], v[100:101] op_sel_hi:[0,1,1]
	v_pk_fma_f32 v[102:103], v[88:89], v[62:63], v[102:103] op_sel_hi:[0,1,1]
	v_lshlrev_b32_e32 v56, 16, v76
	v_and_b32_e32 v57, 0xffff0000, v76
	v_lshlrev_b32_e32 v58, 16, v77
	v_and_b32_e32 v59, 0xffff0000, v77
	v_lshlrev_b32_e32 v60, 16, v78
	v_and_b32_e32 v61, 0xffff0000, v78
	v_lshlrev_b32_e32 v62, 16, v79
	v_and_b32_e32 v63, 0xffff0000, v79
	v_pk_fma_f32 v[104:105], v[88:89], v[56:57], v[104:105] op_sel_hi:[0,1,1]
	v_pk_fma_f32 v[106:107], v[88:89], v[58:59], v[106:107] op_sel_hi:[0,1,1]
	v_pk_fma_f32 v[108:109], v[88:89], v[60:61], v[108:109] op_sel_hi:[0,1,1]
	v_pk_fma_f32 v[110:111], v[88:89], v[62:63], v[110:111] op_sel_hi:[0,1,1]
	global_store_dwordx4 v175, v[96:99], s[100:101]
	global_store_dwordx4 v175, v[100:103], s[100:101] offset:1024
	global_store_dwordx4 v175, v[104:107], s[100:101] offset:2048
	global_store_dwordx4 v175, v[108:111], s[100:101] offset:3072
	v_add_u32_e32 v175, 0x800000, v175
	v_pk_mul_f32 v[112:113], v[130:131], v[112:113] op_sel_hi:[0,1]
	v_pk_mul_f32 v[114:115], v[130:131], v[114:115] op_sel_hi:[0,1]
	v_pk_mul_f32 v[116:117], v[130:131], v[116:117] op_sel_hi:[0,1]
	v_pk_mul_f32 v[118:119], v[130:131], v[118:119] op_sel_hi:[0,1]
	v_pk_mul_f32 v[120:121], v[130:131], v[120:121] op_sel_hi:[0,1]
	v_pk_mul_f32 v[122:123], v[130:131], v[122:123] op_sel_hi:[0,1]
	v_pk_mul_f32 v[124:125], v[130:131], v[124:125] op_sel_hi:[0,1]
	v_pk_mul_f32 v[126:127], v[130:131], v[126:127] op_sel_hi:[0,1]
	v_pk_mul_f32 v[112:113], v[112:113], v[192:193]
	v_pk_mul_f32 v[114:115], v[114:115], v[194:195]
	v_pk_mul_f32 v[116:117], v[116:117], v[196:197]
	v_pk_mul_f32 v[118:119], v[118:119], v[198:199]
	v_pk_mul_f32 v[120:121], v[120:121], v[200:201]
	v_pk_mul_f32 v[122:123], v[122:123], v[202:203]
	v_pk_mul_f32 v[124:125], v[124:125], v[204:205]
	v_pk_mul_f32 v[126:127], v[126:127], v[206:207]
	v_lshlrev_b32_e32 v64, 16, v80
	v_and_b32_e32 v65, 0xffff0000, v80
	v_lshlrev_b32_e32 v66, 16, v81
	v_and_b32_e32 v67, 0xffff0000, v81
	v_lshlrev_b32_e32 v68, 16, v82
	v_and_b32_e32 v69, 0xffff0000, v82
	v_lshlrev_b32_e32 v70, 16, v83
	v_and_b32_e32 v71, 0xffff0000, v83
	v_pk_fma_f32 v[112:113], v[90:91], v[64:65], v[112:113] op_sel_hi:[0,1,1]
	v_pk_fma_f32 v[114:115], v[90:91], v[66:67], v[114:115] op_sel_hi:[0,1,1]
	v_pk_fma_f32 v[116:117], v[90:91], v[68:69], v[116:117] op_sel_hi:[0,1,1]
	v_pk_fma_f32 v[118:119], v[90:91], v[70:71], v[118:119] op_sel_hi:[0,1,1]
	v_lshlrev_b32_e32 v64, 16, v84
	v_and_b32_e32 v65, 0xffff0000, v84
	v_lshlrev_b32_e32 v66, 16, v85
	v_and_b32_e32 v67, 0xffff0000, v85
	v_lshlrev_b32_e32 v68, 16, v86
	v_and_b32_e32 v69, 0xffff0000, v86
	v_lshlrev_b32_e32 v70, 16, v87
	v_and_b32_e32 v71, 0xffff0000, v87
	v_pk_fma_f32 v[120:121], v[90:91], v[64:65], v[120:121] op_sel_hi:[0,1,1]
	v_pk_fma_f32 v[122:123], v[90:91], v[66:67], v[122:123] op_sel_hi:[0,1,1]
	v_pk_fma_f32 v[124:125], v[90:91], v[68:69], v[124:125] op_sel_hi:[0,1,1]
	v_pk_fma_f32 v[126:127], v[90:91], v[70:71], v[126:127] op_sel_hi:[0,1,1]
	global_store_dwordx4 v175, v[112:115], s[100:101]
	global_store_dwordx4 v175, v[116:119], s[100:101] offset:1024
	global_store_dwordx4 v175, v[120:123], s[100:101] offset:2048
	global_store_dwordx4 v175, v[124:127], s[100:101] offset:3072
	v_add_u32_e32 v175, 0x800000, v175
	global_load_dword v88, v172, s[98:99]
	global_load_dwordx2 v[56:57], v170, s[98:99]
	global_load_dwordx2 v[58:59], v170, s[98:99] offset:512
	global_load_dwordx2 v[60:61], v170, s[98:99] offset:1024
	global_load_dwordx2 v[62:63], v170, s[98:99] offset:1536
	global_load_dwordx2 v[72:73], v171, s[98:99]
	global_load_dwordx2 v[74:75], v171, s[98:99] offset:512
	global_load_dwordx2 v[76:77], v171, s[98:99] offset:1024
	global_load_dwordx2 v[78:79], v171, s[98:99] offset:1536
	v_add_u32_e32 v170, 0x400000, v170
	v_add_u32_e32 v171, 0x400000, v171
	v_add_u32_e32 v172, 0x2000, v172
	global_load_dword v90, v172, s[98:99]
	global_load_dwordx2 v[64:65], v170, s[98:99]
	global_load_dwordx2 v[66:67], v170, s[98:99] offset:512
	global_load_dwordx2 v[68:69], v170, s[98:99] offset:1024
	global_load_dwordx2 v[70:71], v170, s[98:99] offset:1536
	global_load_dwordx2 v[80:81], v171, s[98:99]
	global_load_dwordx2 v[82:83], v171, s[98:99] offset:512
	global_load_dwordx2 v[84:85], v171, s[98:99] offset:1024
	global_load_dwordx2 v[86:87], v171, s[98:99] offset:1536
	v_add_u32_e32 v170, 0x400000, v170
	v_add_u32_e32 v171, 0x400000, v171
	v_add_u32_e32 v172, 0x2000, v172
	s_waitcnt vmcnt(39)
;     __device__ __forceinline__ float* out() const { return (float*)karg_in(33); }
; __device__ __forceinline__ float ssq4(v4f v) { return (v.x * v.x + v.y * v.y) + (v.z * v.z + v.w * v.w); }
; template <int R, bool BASE_F32, bool OUT_F32>
; __device__ __forceinline__ void rows_res(const Ctx& C, int m0, int stride, int mx, const float* gpost, float scale, int lane) {
;     ...
;     for (int r = 0; r < R; ++r) { float s = 0.f;
; #pragma unroll
;         for (int j = 0; j < 4; ++j) s += ssq4(d[r][j]);
;         r1[r] = s; }
; #pragma unroll
;     for (int r = 0; r < R; ++r) r1[r] = rsqrtf(wave_sum(r1[r]) * (1.f / DM) + EPS) * scale;
; #pragma unroll
;     for (int j = 0; j < 4; ++j) { const v4f gp = ld4_f32(gpost + 4 * lane + 256 * j);
; #pragma unroll
;         for (int r = 0; r < R; ++r) d[r][j] = b[r][j] + d[r][j] * r1[r] * gp; }
;     if (OUT_F32) { float* Y = C.out();
; #pragma unroll
;         for (int r = 0; r < R; ++r)
; #pragma unroll
;             for (int j = 0; j < 4; ++j) if (ok[r]) *(v4f*)(Y + (size_t)mr[r] * DM + 4 * lane + 256 * j) = d[r][j];
	v_lshlrev_b32_e32 v96, 16, v20
	v_and_b32_e32 v97, 0xffff0000, v20
	v_lshlrev_b32_e32 v98, 16, v21
	v_and_b32_e32 v99, 0xffff0000, v21
	v_lshlrev_b32_e32 v100, 16, v22
	v_and_b32_e32 v101, 0xffff0000, v22
	v_lshlrev_b32_e32 v102, 16, v23
	v_and_b32_e32 v103, 0xffff0000, v23
	v_lshlrev_b32_e32 v104, 16, v24
	v_and_b32_e32 v105, 0xffff0000, v24
	v_lshlrev_b32_e32 v106, 16, v25
	v_and_b32_e32 v107, 0xffff0000, v25
	v_lshlrev_b32_e32 v108, 16, v26
	v_and_b32_e32 v109, 0xffff0000, v26
	v_lshlrev_b32_e32 v110, 16, v27
	v_and_b32_e32 v111, 0xffff0000, v27
	v_pk_mul_f32 v[128:129], v[96:97], v[96:97]
	v_pk_fma_f32 v[128:129], v[98:99], v[98:99], v[128:129]
	v_pk_fma_f32 v[128:129], v[100:101], v[100:101], v[128:129]
	v_pk_fma_f32 v[128:129], v[102:103], v[102:103], v[128:129]
	v_pk_fma_f32 v[128:129], v[104:105], v[104:105], v[128:129]
	v_pk_fma_f32 v[128:129], v[106:107], v[106:107], v[128:129]
	v_pk_fma_f32 v[128:129], v[108:109], v[108:109], v[128:129]
	v_pk_fma_f32 v[128:129], v[110:111], v[110:111], v[128:129]
	s_nop 0
	v_add_f32_e32 v128, v128, v129
	s_waitcnt vmcnt(30)
	v_lshlrev_b32_e32 v112, 16, v28
	v_and_b32_e32 v113, 0xffff0000, v28
	v_lshlrev_b32_e32 v114, 16, v29
	v_and_b32_e32 v115, 0xffff0000, v29
	v_lshlrev_b32_e32 v116, 16, v30
	v_and_b32_e32 v117, 0xffff0000, v30
	v_lshlrev_b32_e32 v118, 16, v31
	v_and_b32_e32 v119, 0xffff0000, v31
	v_lshlrev_b32_e32 v120, 16, v32
	v_and_b32_e32 v121, 0xffff0000, v32
	v_lshlrev_b32_e32 v122, 16, v33
	v_and_b32_e32 v123, 0xffff0000, v33
	v_lshlrev_b32_e32 v124, 16, v34
	v_and_b32_e32 v125, 0xffff0000, v34
	v_lshlrev_b32_e32 v126, 16, v35
	v_and_b32_e32 v127, 0xffff0000, v35
	v_pk_mul_f32 v[130:131], v[112:113], v[112:113]
	v_pk_fma_f32 v[130:131], v[114:115], v[114:115], v[130:131]
	v_pk_fma_f32 v[130:131], v[116:117], v[116:117], v[130:131]
	v_pk_fma_f32 v[130:131], v[118:119], v[118:119], v[130:131]
	v_pk_fma_f32 v[130:131], v[120:121], v[120:121], v[130:131]
	v_pk_fma_f32 v[130:131], v[122:123], v[122:123], v[130:131]
	v_pk_fma_f32 v[130:131], v[124:125], v[124:125], v[130:131]
	v_pk_fma_f32 v[130:131], v[126:127], v[126:127], v[130:131]
	s_nop 0
	v_add_f32_e32 v130, v130, v131
	s_nop 1
	v_add_f32_dpp v128, v128, v128 quad_perm:[1,0,3,2] row_mask:0xf bank_mask:0xf
	v_add_f32_dpp v130, v130, v130 quad_perm:[1,0,3,2] row_mask:0xf bank_mask:0xf
	s_nop 0
	v_add_f32_dpp v128, v128, v128 quad_perm:[2,3,0,1] row_mask:0xf bank_mask:0xf
	v_add_f32_dpp v130, v130, v130 quad_perm:[2,3,0,1] row_mask:0xf bank_mask:0xf
	s_nop 0
	v_add_f32_dpp v128, v128, v128 row_half_mirror row_mask:0xf bank_mask:0xf
	v_add_f32_dpp v130, v130, v130 row_half_mirror row_mask:0xf bank_mask:0xf
	s_nop 0
	v_add_f32_dpp v128, v128, v128 row_mirror row_mask:0xf bank_mask:0xf
	v_add_f32_dpp v130, v130, v130 row_mirror row_mask:0xf bank_mask:0xf
	s_nop 0
	ds_bpermute_b32 v136, v187, v128
	ds_bpermute_b32 v137, v187, v130
	s_waitcnt lgkmcnt(0)
	v_add_f32_e32 v128, v128, v136
	v_add_f32_e32 v130, v130, v137
	ds_bpermute_b32 v136, v188, v128
	ds_bpermute_b32 v137, v188, v130
	s_waitcnt lgkmcnt(0)
	v_add_f32_e32 v128, v128, v136
	v_add_f32_e32 v130, v130, v137
	v_fmamk_f32 v128, v128, 0x3a800000, v138
	v_fmamk_f32 v130, v130, 0x3a800000, v138
	s_nop 0
	v_rsq_f32_e32 v128, v128
	v_rsq_f32_e32 v130, v130
	s_nop 1
	v_mul_f32_e32 v128, 0.5, v128
	v_mul_f32_e32 v130, 0.5, v130
	s_waitcnt vmcnt(26)
	v_pk_mul_f32 v[96:97], v[128:129], v[96:97] op_sel_hi:[0,1]
	v_pk_mul_f32 v[98:99], v[128:129], v[98:99] op_sel_hi:[0,1]
	v_pk_mul_f32 v[100:101], v[128:129], v[100:101] op_sel_hi:[0,1]
	v_pk_mul_f32 v[102:103], v[128:129], v[102:103] op_sel_hi:[0,1]
	v_pk_mul_f32 v[104:105], v[128:129], v[104:105] op_sel_hi:[0,1]
	v_pk_mul_f32 v[106:107], v[128:129], v[106:107] op_sel_hi:[0,1]
	v_pk_mul_f32 v[108:109], v[128:129], v[108:109] op_sel_hi:[0,1]
	v_pk_mul_f32 v[110:111], v[128:129], v[110:111] op_sel_hi:[0,1]
	v_pk_mul_f32 v[96:97], v[96:97], v[192:193]
	v_pk_mul_f32 v[98:99], v[98:99], v[194:195]
	v_pk_mul_f32 v[100:101], v[100:101], v[196:197]
	v_pk_mul_f32 v[102:103], v[102:103], v[198:199]
	v_pk_mul_f32 v[104:105], v[104:105], v[200:201]
	v_pk_mul_f32 v[106:107], v[106:107], v[202:203]
	v_pk_mul_f32 v[108:109], v[108:109], v[204:205]
	v_pk_mul_f32 v[110:111], v[110:111], v[206:207]
	v_lshlrev_b32_e32 v20, 16, v36
	v_and_b32_e32 v21, 0xffff0000, v36
	v_lshlrev_b32_e32 v22, 16, v37
	v_and_b32_e32 v23, 0xffff0000, v37
	v_lshlrev_b32_e32 v24, 16, v38
	v_and_b32_e32 v25, 0xffff0000, v38
	v_lshlrev_b32_e32 v26, 16, v39
	v_and_b32_e32 v27, 0xffff0000, v39
	v_pk_fma_f32 v[96:97], v[52:53], v[20:21], v[96:97] op_sel_hi:[0,1,1]
	v_pk_fma_f32 v[98:99], v[52:53], v[22:23], v[98:99] op_sel_hi:[0,1,1]
	v_pk_fma_f32 v[100:101], v[52:53], v[24:25], v[100:101] op_sel_hi:[0,1,1]
	v_pk_fma_f32 v[102:103], v[52:53], v[26:27], v[102:103] op_sel_hi:[0,1,1]
	v_lshlrev_b32_e32 v20, 16, v40
	v_and_b32_e32 v21, 0xffff0000, v40
	v_lshlrev_b32_e32 v22, 16, v41
	v_and_b32_e32 v23, 0xffff0000, v41
	v_lshlrev_b32_e32 v24, 16, v42
	v_and_b32_e32 v25, 0xffff0000, v42
	v_lshlrev_b32_e32 v26, 16, v43
	v_and_b32_e32 v27, 0xffff0000, v43
	v_pk_fma_f32 v[104:105], v[52:53], v[20:21], v[104:105] op_sel_hi:[0,1,1]
	v_pk_fma_f32 v[106:107], v[52:53], v[22:23], v[106:107] op_sel_hi:[0,1,1]
	v_pk_fma_f32 v[108:109], v[52:53], v[24:25], v[108:109] op_sel_hi:[0,1,1]
	v_pk_fma_f32 v[110:111], v[52:53], v[26:27], v[110:111] op_sel_hi:[0,1,1]
	global_store_dwordx4 v175, v[96:99], s[100:101]
	global_store_dwordx4 v175, v[100:103], s[100:101] offset:1024
	global_store_dwordx4 v175, v[104:107], s[100:101] offset:2048
	global_store_dwordx4 v175, v[108:111], s[100:101] offset:3072
;     __device__ __forceinline__ float* out() const { return (float*)karg_in(33); }
; __device__ __forceinline__ float ssq4(v4f v) { return (v.x * v.x + v.y * v.y) + (v.z * v.z + v.w * v.w); }
; template <int R, bool BASE_F32, bool OUT_F32>
; __device__ __forceinline__ void rows_res(const Ctx& C, int m0, int stride, int mx, const float* gpost, float scale, int lane) {
;     ...
;     for (int r = 0; r < R; ++r) { float s = 0.f;
; #pragma unroll
;         for (int j = 0; j < 4; ++j) s += ssq4(d[r][j]);
;         r1[r] = s; }
; #pragma unroll
;     for (int r = 0; r < R; ++r) r1[r] = rsqrtf(wave_sum(r1[r]) * (1.f / DM) + EPS) * scale;
;     ...
;     for (int j = 0; j < 4; ++j) { const v4f gp = ld4_f32(gpost + 4 * lane + 256 * j);
; #pragma unroll
;         for (int r = 0; r < R; ++r) d[r][j] = b[r][j] + d[r][j] * r1[r] * gp; }
;     if (OUT_F32) { float* Y = C.out();
; #pragma unroll
;         for (int r = 0; r < R; ++r)
; #pragma unroll
;             for (int j = 0; j < 4; ++j) if (ok[r]) *(v4f*)(Y + (size_t)mr[r] * DM + 4 * lane + 256 * j) = d[r][j];
	v_add_u32_e32 v175, 0x800000, v175
	v_pk_mul_f32 v[112:113], v[130:131], v[112:113] op_sel_hi:[0,1]
	v_pk_mul_f32 v[114:115], v[130:131], v[114:115] op_sel_hi:[0,1]
	v_pk_mul_f32 v[116:117], v[130:131], v[116:117] op_sel_hi:[0,1]
	v_pk_mul_f32 v[118:119], v[130:131], v[118:119] op_sel_hi:[0,1]
	v_pk_mul_f32 v[120:121], v[130:131], v[120:121] op_sel_hi:[0,1]
	v_pk_mul_f32 v[122:123], v[130:131], v[122:123] op_sel_hi:[0,1]
	v_pk_mul_f32 v[124:125], v[130:131], v[124:125] op_sel_hi:[0,1]
	v_pk_mul_f32 v[126:127], v[130:131], v[126:127] op_sel_hi:[0,1]
	v_pk_mul_f32 v[112:113], v[112:113], v[192:193]
	v_pk_mul_f32 v[114:115], v[114:115], v[194:195]
	v_pk_mul_f32 v[116:117], v[116:117], v[196:197]
	v_pk_mul_f32 v[118:119], v[118:119], v[198:199]
	v_pk_mul_f32 v[120:121], v[120:121], v[200:201]
	v_pk_mul_f32 v[122:123], v[122:123], v[202:203]
	v_pk_mul_f32 v[124:125], v[124:125], v[204:205]
	v_pk_mul_f32 v[126:127], v[126:127], v[206:207]
	v_lshlrev_b32_e32 v28, 16, v44
	v_and_b32_e32 v29, 0xffff0000, v44
	v_lshlrev_b32_e32 v30, 16, v45
	v_and_b32_e32 v31, 0xffff0000, v45
	v_lshlrev_b32_e32 v32, 16, v46
	v_and_b32_e32 v33, 0xffff0000, v46
	v_lshlrev_b32_e32 v34, 16, v47
	v_and_b32_e32 v35, 0xffff0000, v47
	v_pk_fma_f32 v[112:113], v[54:55], v[28:29], v[112:113] op_sel_hi:[0,1,1]
	v_pk_fma_f32 v[114:115], v[54:55], v[30:31], v[114:115] op_sel_hi:[0,1,1]
	v_pk_fma_f32 v[116:117], v[54:55], v[32:33], v[116:117] op_sel_hi:[0,1,1]
	v_pk_fma_f32 v[118:119], v[54:55], v[34:35], v[118:119] op_sel_hi:[0,1,1]
	v_lshlrev_b32_e32 v28, 16, v48
	v_and_b32_e32 v29, 0xffff0000, v48
	v_lshlrev_b32_e32 v30, 16, v49
	v_and_b32_e32 v31, 0xffff0000, v49
	v_lshlrev_b32_e32 v32, 16, v50
	v_and_b32_e32 v33, 0xffff0000, v50
	v_lshlrev_b32_e32 v34, 16, v51
	v_and_b32_e32 v35, 0xffff0000, v51
	v_pk_fma_f32 v[120:121], v[54:55], v[28:29], v[120:121] op_sel_hi:[0,1,1]
	v_pk_fma_f32 v[122:123], v[54:55], v[30:31], v[122:123] op_sel_hi:[0,1,1]
	v_pk_fma_f32 v[124:125], v[54:55], v[32:33], v[124:125] op_sel_hi:[0,1,1]
	v_pk_fma_f32 v[126:127], v[54:55], v[34:35], v[126:127] op_sel_hi:[0,1,1]
	global_store_dwordx4 v175, v[112:115], s[100:101]
	global_store_dwordx4 v175, v[116:119], s[100:101] offset:1024
	global_store_dwordx4 v175, v[120:123], s[100:101] offset:2048
	global_store_dwordx4 v175, v[124:127], s[100:101] offset:3072
	v_add_u32_e32 v175, 0x800000, v175
	s_waitcnt vmcnt(21)
	v_lshlrev_b32_e32 v96, 16, v56
	v_and_b32_e32 v97, 0xffff0000, v56
	v_lshlrev_b32_e32 v98, 16, v57
	v_and_b32_e32 v99, 0xffff0000, v57
	v_lshlrev_b32_e32 v100, 16, v58
	v_and_b32_e32 v101, 0xffff0000, v58
	v_lshlrev_b32_e32 v102, 16, v59
	v_and_b32_e32 v103, 0xffff0000, v59
	v_lshlrev_b32_e32 v104, 16, v60
	v_and_b32_e32 v105, 0xffff0000, v60
	v_lshlrev_b32_e32 v106, 16, v61
	v_and_b32_e32 v107, 0xffff0000, v61
	v_lshlrev_b32_e32 v108, 16, v62
	v_and_b32_e32 v109, 0xffff0000, v62
	v_lshlrev_b32_e32 v110, 16, v63
	v_and_b32_e32 v111, 0xffff0000, v63
	v_pk_mul_f32 v[128:129], v[96:97], v[96:97]
	v_pk_fma_f32 v[128:129], v[98:99], v[98:99], v[128:129]
	v_pk_fma_f32 v[128:129], v[100:101], v[100:101], v[128:129]
	v_pk_fma_f32 v[128:129], v[102:103], v[102:103], v[128:129]
	v_pk_fma_f32 v[128:129], v[104:105], v[104:105], v[128:129]
	v_pk_fma_f32 v[128:129], v[106:107], v[106:107], v[128:129]
	v_pk_fma_f32 v[128:129], v[108:109], v[108:109], v[128:129]
	v_pk_fma_f32 v[128:129], v[110:111], v[110:111], v[128:129]
	s_nop 0
	v_add_f32_e32 v128, v128, v129
	s_waitcnt vmcnt(12)
	v_lshlrev_b32_e32 v112, 16, v64
	v_and_b32_e32 v113, 0xffff0000, v64
	v_lshlrev_b32_e32 v114, 16, v65
	v_and_b32_e32 v115, 0xffff0000, v65
	v_lshlrev_b32_e32 v116, 16, v66
	v_and_b32_e32 v117, 0xffff0000, v66
	v_lshlrev_b32_e32 v118, 16, v67
	v_and_b32_e32 v119, 0xffff0000, v67
	v_lshlrev_b32_e32 v120, 16, v68
	v_and_b32_e32 v121, 0xffff0000, v68
	v_lshlrev_b32_e32 v122, 16, v69
	v_and_b32_e32 v123, 0xffff0000, v69
	v_lshlrev_b32_e32 v124, 16, v70
	v_and_b32_e32 v125, 0xffff0000, v70
	v_lshlrev_b32_e32 v126, 16, v71
	v_and_b32_e32 v127, 0xffff0000, v71
	v_pk_mul_f32 v[130:131], v[112:113], v[112:113]
	v_pk_fma_f32 v[130:131], v[114:115], v[114:115], v[130:131]
	v_pk_fma_f32 v[130:131], v[116:117], v[116:117], v[130:131]
	v_pk_fma_f32 v[130:131], v[118:119], v[118:119], v[130:131]
	v_pk_fma_f32 v[130:131], v[120:121], v[120:121], v[130:131]
	v_pk_fma_f32 v[130:131], v[122:123], v[122:123], v[130:131]
	v_pk_fma_f32 v[130:131], v[124:125], v[124:125], v[130:131]
	v_pk_fma_f32 v[130:131], v[126:127], v[126:127], v[130:131]
	s_nop 0
	v_add_f32_e32 v130, v130, v131
	s_nop 1
	v_add_f32_dpp v128, v128, v128 quad_perm:[1,0,3,2] row_mask:0xf bank_mask:0xf
	v_add_f32_dpp v130, v130, v130 quad_perm:[1,0,3,2] row_mask:0xf bank_mask:0xf
	s_nop 0
	v_add_f32_dpp v128, v128, v128 quad_perm:[2,3,0,1] row_mask:0xf bank_mask:0xf
	v_add_f32_dpp v130, v130, v130 quad_perm:[2,3,0,1] row_mask:0xf bank_mask:0xf
	s_nop 0
	v_add_f32_dpp v128, v128, v128 row_half_mirror row_mask:0xf bank_mask:0xf
	v_add_f32_dpp v130, v130, v130 row_half_mirror row_mask:0xf bank_mask:0xf
	s_nop 0
	v_add_f32_dpp v128, v128, v128 row_mirror row_mask:0xf bank_mask:0xf
	v_add_f32_dpp v130, v130, v130 row_mirror row_mask:0xf bank_mask:0xf
	s_nop 0
	ds_bpermute_b32 v136, v187, v128
	ds_bpermute_b32 v137, v187, v130
	s_waitcnt lgkmcnt(0)
;     __device__ __forceinline__ const float* in(int i) const { return karg_in(i); }
;     __device__ __forceinline__ float* out() const { return (float*)karg_in(33); }
; #define FTID const int ftid_ = fresh_tid()
; template <int R, bool BASE_F32, bool OUT_F32>
; __device__ __forceinline__ void rows_res(const Ctx& C, int m0, int stride, int mx, const float* gpost, float scale, int lane) {
;     ...
;     for (int r = 0; r < R; ++r) r1[r] = rsqrtf(wave_sum(r1[r]) * (1.f / DM) + EPS) * scale;
; #pragma unroll
;     for (int j = 0; j < 4; ++j) { const v4f gp = ld4_f32(gpost + 4 * lane + 256 * j);
; #pragma unroll
;         for (int r = 0; r < R; ++r) d[r][j] = b[r][j] + d[r][j] * r1[r] * gp; }
;     if (OUT_F32) { float* Y = C.out();
; #pragma unroll
;         for (int r = 0; r < R; ++r)
; #pragma unroll
;             for (int j = 0; j < 4; ++j) if (ok[r]) *(v4f*)(Y + (size_t)mr[r] * DM + 4 * lane + 256 * j) = d[r][j];
; __global__ void __launch_bounds__(NTHREADS, 2) fwd_kernel(Args args) {
;     ...
;     { FTID; const float* gp = C.in(32); { const int gw_ = GWV, ngw_ = NGWV, nit = (MPROMPT + 4 * ngw_ - 1) / (4 * ngw_);
;       for (int it = 0; it < nit - 1; ++it) rows_res<4, false, true>(C, gw_ + 4 * it * ngw_, ngw_, M, gp, 0.5f, LANE);
;       rows_res<5, false, true>(C, gw_ + 4 * (nit - 1) * ngw_, ngw_, MPROMPT + gw_, gp, 0.5f, LANE);
;       for (int ms = MPROMPT + gw_ + ngw_; ms < M; ms += ngw_) rows_res<5, false, true>(C, MPROMPT, ngw_, ms, gp, 0.5f, LANE); } }
	v_add_f32_e32 v128, v128, v136
	v_add_f32_e32 v130, v130, v137
	ds_bpermute_b32 v136, v188, v128
	ds_bpermute_b32 v137, v188, v130
	s_waitcnt lgkmcnt(0)
	v_add_f32_e32 v128, v128, v136
	v_add_f32_e32 v130, v130, v137
	v_fmamk_f32 v128, v128, 0x3a800000, v138
	v_fmamk_f32 v130, v130, 0x3a800000, v138
	s_nop 0
	v_rsq_f32_e32 v128, v128
	v_rsq_f32_e32 v130, v130
	s_nop 1
	v_mul_f32_e32 v128, 0.5, v128
	v_mul_f32_e32 v130, 0.5, v130
	s_waitcnt vmcnt(8)
	v_pk_mul_f32 v[96:97], v[128:129], v[96:97] op_sel_hi:[0,1]
	v_pk_mul_f32 v[98:99], v[128:129], v[98:99] op_sel_hi:[0,1]
	v_pk_mul_f32 v[100:101], v[128:129], v[100:101] op_sel_hi:[0,1]
	v_pk_mul_f32 v[102:103], v[128:129], v[102:103] op_sel_hi:[0,1]
	v_pk_mul_f32 v[104:105], v[128:129], v[104:105] op_sel_hi:[0,1]
	v_pk_mul_f32 v[106:107], v[128:129], v[106:107] op_sel_hi:[0,1]
	v_pk_mul_f32 v[108:109], v[128:129], v[108:109] op_sel_hi:[0,1]
	v_pk_mul_f32 v[110:111], v[128:129], v[110:111] op_sel_hi:[0,1]
	v_pk_mul_f32 v[96:97], v[96:97], v[192:193]
	v_pk_mul_f32 v[98:99], v[98:99], v[194:195]
	v_pk_mul_f32 v[100:101], v[100:101], v[196:197]
	v_pk_mul_f32 v[102:103], v[102:103], v[198:199]
	v_pk_mul_f32 v[104:105], v[104:105], v[200:201]
	v_pk_mul_f32 v[106:107], v[106:107], v[202:203]
	v_pk_mul_f32 v[108:109], v[108:109], v[204:205]
	v_pk_mul_f32 v[110:111], v[110:111], v[206:207]
	v_lshlrev_b32_e32 v56, 16, v72
	v_and_b32_e32 v57, 0xffff0000, v72
	v_lshlrev_b32_e32 v58, 16, v73
	v_and_b32_e32 v59, 0xffff0000, v73
	v_lshlrev_b32_e32 v60, 16, v74
	v_and_b32_e32 v61, 0xffff0000, v74
	v_lshlrev_b32_e32 v62, 16, v75
	v_and_b32_e32 v63, 0xffff0000, v75
	v_pk_fma_f32 v[96:97], v[88:89], v[56:57], v[96:97] op_sel_hi:[0,1,1]
	v_pk_fma_f32 v[98:99], v[88:89], v[58:59], v[98:99] op_sel_hi:[0,1,1]
	v_pk_fma_f32 v[100:101], v[88:89], v[60:61], v[100:101] op_sel_hi:[0,1,1]
	v_pk_fma_f32 v[102:103], v[88:89], v[62:63], v[102:103] op_sel_hi:[0,1,1]
	v_lshlrev_b32_e32 v56, 16, v76
	v_and_b32_e32 v57, 0xffff0000, v76
	v_lshlrev_b32_e32 v58, 16, v77
	v_and_b32_e32 v59, 0xffff0000, v77
	v_lshlrev_b32_e32 v60, 16, v78
	v_and_b32_e32 v61, 0xffff0000, v78
	v_lshlrev_b32_e32 v62, 16, v79
	v_and_b32_e32 v63, 0xffff0000, v79
	v_pk_fma_f32 v[104:105], v[88:89], v[56:57], v[104:105] op_sel_hi:[0,1,1]
	v_pk_fma_f32 v[106:107], v[88:89], v[58:59], v[106:107] op_sel_hi:[0,1,1]
	v_pk_fma_f32 v[108:109], v[88:89], v[60:61], v[108:109] op_sel_hi:[0,1,1]
	v_pk_fma_f32 v[110:111], v[88:89], v[62:63], v[110:111] op_sel_hi:[0,1,1]
	global_store_dwordx4 v175, v[96:99], s[100:101]
	global_store_dwordx4 v175, v[100:103], s[100:101] offset:1024
	global_store_dwordx4 v175, v[104:107], s[100:101] offset:2048
	global_store_dwordx4 v175, v[108:111], s[100:101] offset:3072
	v_add_u32_e32 v175, 0x800000, v175
	v_pk_mul_f32 v[112:113], v[130:131], v[112:113] op_sel_hi:[0,1]
	v_pk_mul_f32 v[114:115], v[130:131], v[114:115] op_sel_hi:[0,1]
	v_pk_mul_f32 v[116:117], v[130:131], v[116:117] op_sel_hi:[0,1]
	v_pk_mul_f32 v[118:119], v[130:131], v[118:119] op_sel_hi:[0,1]
	v_pk_mul_f32 v[120:121], v[130:131], v[120:121] op_sel_hi:[0,1]
	v_pk_mul_f32 v[122:123], v[130:131], v[122:123] op_sel_hi:[0,1]
	v_pk_mul_f32 v[124:125], v[130:131], v[124:125] op_sel_hi:[0,1]
	v_pk_mul_f32 v[126:127], v[130:131], v[126:127] op_sel_hi:[0,1]
	v_pk_mul_f32 v[112:113], v[112:113], v[192:193]
	v_pk_mul_f32 v[114:115], v[114:115], v[194:195]
	v_pk_mul_f32 v[116:117], v[116:117], v[196:197]
	v_pk_mul_f32 v[118:119], v[118:119], v[198:199]
	v_pk_mul_f32 v[120:121], v[120:121], v[200:201]
	v_pk_mul_f32 v[122:123], v[122:123], v[202:203]
	v_pk_mul_f32 v[124:125], v[124:125], v[204:205]
	v_pk_mul_f32 v[126:127], v[126:127], v[206:207]
	v_lshlrev_b32_e32 v64, 16, v80
	v_and_b32_e32 v65, 0xffff0000, v80
	v_lshlrev_b32_e32 v66, 16, v81
	v_and_b32_e32 v67, 0xffff0000, v81
	v_lshlrev_b32_e32 v68, 16, v82
	v_and_b32_e32 v69, 0xffff0000, v82
	v_lshlrev_b32_e32 v70, 16, v83
	v_and_b32_e32 v71, 0xffff0000, v83
	v_pk_fma_f32 v[112:113], v[90:91], v[64:65], v[112:113] op_sel_hi:[0,1,1]
	v_pk_fma_f32 v[114:115], v[90:91], v[66:67], v[114:115] op_sel_hi:[0,1,1]
	v_pk_fma_f32 v[116:117], v[90:91], v[68:69], v[116:117] op_sel_hi:[0,1,1]
	v_pk_fma_f32 v[118:119], v[90:91], v[70:71], v[118:119] op_sel_hi:[0,1,1]
	v_lshlrev_b32_e32 v64, 16, v84
	v_and_b32_e32 v65, 0xffff0000, v84
	v_lshlrev_b32_e32 v66, 16, v85
	v_and_b32_e32 v67, 0xffff0000, v85
	v_lshlrev_b32_e32 v68, 16, v86
	v_and_b32_e32 v69, 0xffff0000, v86
	v_lshlrev_b32_e32 v70, 16, v87
	v_and_b32_e32 v71, 0xffff0000, v87
	v_pk_fma_f32 v[120:121], v[90:91], v[64:65], v[120:121] op_sel_hi:[0,1,1]
	v_pk_fma_f32 v[122:123], v[90:91], v[66:67], v[122:123] op_sel_hi:[0,1,1]
	v_pk_fma_f32 v[124:125], v[90:91], v[68:69], v[124:125] op_sel_hi:[0,1,1]
	v_pk_fma_f32 v[126:127], v[90:91], v[70:71], v[126:127] op_sel_hi:[0,1,1]
	global_store_dwordx4 v175, v[112:115], s[100:101]
	global_store_dwordx4 v175, v[116:119], s[100:101] offset:1024
	global_store_dwordx4 v175, v[120:123], s[100:101] offset:2048
	global_store_dwordx4 v175, v[124:127], s[100:101] offset:3072
	v_add_u32_e32 v175, 0x800000, v175
	s_branch .LBB0_1283
	s_waitcnt lgkmcnt(0)
	v_lshl_add_u64 v[20:21], s[8:9], 0, v[16:17]
	v_mov_b32_e32 v19, v17
	s_mov_b64 s[10:11], 0x7100000
	s_mov_b64 s[12:13], 0x3000000
	v_mov_b32_e32 v23, 0x2a80000
	v_mov_b32_e32 v22, 0x358637bd
	s_mov_b32 s14, 0x3a800000
	s_mov_b32 s27, 0x800000
	s_mov_b32 s16, s15
	s_branch .LBB0_1275
